# GEMM epilogue stores write-through (sc1) so the barrier release fence has less dirty L2 data to write back
# speedup vs baseline: 1.0121x; 1.0115x over previous
; #define MFMA32(a, b, c) __builtin_amdgcn_mfma_f32_32x32x16_bf16((a), (b), (c), 0, 0, 0)
; DI bfr f2bf(float a) { return (bfr)(pack2(a, 0.f) & 0xffffu); }
; #define GA_LOAD(pr_) do { _Pragma("unroll") for (int i = 0; i < 4; ++i) ra[i] = *(const u32x4*)(Ab + (i * 32) * lda + (pr_) * 64); } while (0)
; template <int lda>
; DI void gemm_mainloop(const bfr* __restrict__ A, const bfr* __restrict__ Bt, int NB, int K, int m0, int n0, char* smem, f32x16 (&acc)[2][4]) {
;   bfr* S0 = (bfr*)smem;
;   int tid = threadIdx.x;
;   asm volatile("" : "+v"(tid));
;   const int lane = tid & 63, wid = tid >> 6, wr = wid >> 1, wc = wid & 1;
;   const int r = lane & 31, hl = lane >> 5;
; #pragma unroll
;   for (int i = 0; i < 2; ++i)
; #pragma unroll
;     for (int j = 0; j < 4; ++j)
; #pragma unroll
;       for (int q = 0; q < 16; ++q) acc[i][j][q] = 0.f;
;   u32x4 ra[4], rb[4];
;   const int nk = K >> 5;
;   const int arow = tid >> 3, ac8 = tid & 7, apar = ac8 >> 2;
;   const bfr* Ab = A + (m0 + arow) * lda + ac8 * 8;
;   const int asoff = arow * 40 + (ac8 & 3) * 8;
;   const int brow = tid >> 2, bc4 = tid & 3;
;   const bfr* Bb = Bt + (n0 + brow) * 32 + bc4 * 8;
;   const int bsoff = brow * 40 + bc4 * 8;
;     ...
;   GA_LOAD(0);
;   GB_LOAD(0);
;   G_STORE(0);
;   GB_LOAD(1);
;   __syncthreads();
;   for (int kt = 0; kt < nk; ++kt) {
;     if (kt + 1 < nk) G_STORE(kt + 1);
;     if (kt + 2 < nk) {
;       GB_LOAD(kt + 2);
;       if ((kt & 1) == 0) GA_LOAD((kt >> 1) + 1);
;     }
;     const bfr* As = S0 + (kt & 1) * GSTAGE;
;     const bfr* Bs = As + 128 * 40;
; #pragma unroll
;     for (int ks = 0; ks < 2; ++ks) {
;       bf16x8 af[2], bfg[4];
; #pragma unroll
;       for (int i = 0; i < 2; ++i) af[i] = *(const bf16x8*)(As + (wr * 64 + i * 32 + r) * 40 + ks * 16 + hl * 8);
; #pragma unroll
;       for (int j = 0; j < 4; ++j) bfg[j] = *(const bf16x8*)(Bs + (wc * 128 + j * 32 + r) * 40 + ks * 16 + hl * 8);
; #pragma unroll
;       for (int i = 0; i < 2; ++i)
; #pragma unroll
;         for (int j = 0; j < 4; ++j) acc[i][j] = MFMA32(af[i], bfg[j], acc[i][j]);
;     }
;     __syncthreads();
;   }
; DI void phase_gemm_in_even(const Params& p, char* smem) {
;     ...
;       gemm_tile<1024>(p.H, p.WtInE, 3712, 1024, mt * 128, nt * 256, smem,
;                 [=](int row, int col, float v) { PB[(size_t)row * EINP + col] = f2bf(v); });
.Lp1e_loop:
	s_waitcnt vmcnt(6) lgkmcnt(0)
	s_barrier
	s_mul_i32 s74, s71, 0x6000
	s_add_u32 s75, s74, 0x2000
	s_cmp_eq_u32 s71, 2
	s_cselect_b32 s75, 0x10000, s75
	v_add_u32_e32 v184, s74, v180
	v_add_u32_e32 v186, s75, v182
	v_add_u32_e32 v185, s74, v181
	v_add_u32_e32 v187, s75, v183
	s_add_u32 s71, s71, 1
	s_cmp_eq_u32 s71, 3
	s_cselect_b32 s71, 0, s71
	ds_read_b128 v[128:131], v184
	ds_read_b128 v[144:147], v186
	ds_read_b128 v[148:151], v186 offset:2048
	ds_read_b128 v[152:155], v186 offset:4096
	ds_read_b128 v[156:159], v186 offset:6144
	ds_read_b128 v[132:135], v184 offset:2048
	v_mfma_f32_32x32x16_bf16 v[112:127], v[164:167], v[136:139], v[112:127]
	s_mul_i32 s74, s70, 0x6000
	s_add_u32 s75, s74, s68
	s_mov_b32 m0, s75
	s_add_u32 s76, s74, 0x2000
	s_cmp_eq_u32 s70, 2
	s_cselect_b32 s76, 0x10000, s76
	global_load_lds_dwordx4 v160, s[64:65]
	v_mfma_f32_32x32x16_bf16 v[96:111], v[168:171], v[136:139], v[96:111]
	s_add_u32 m0, s75, 0x400
	s_add_u32 s76, s76, s69
	global_load_lds_dwordx4 v162, s[64:65]
	v_mfma_f32_32x32x16_bf16 v[80:95], v[172:175], v[136:139], v[80:95]
	s_mov_b32 m0, s76
	s_add_u32 s64, s64, 64
	s_addc_u32 s65, s65, 0
	global_load_lds_dwordx4 v163, s[66:67]
	v_mfma_f32_32x32x16_bf16 v[64:79], v[176:179], v[136:139], v[64:79]
	global_load_lds_dwordx4 v163, s[66:67] offset:1024
	v_mfma_f32_32x32x16_bf16 v[48:63], v[164:167], v[140:143], v[48:63]
	global_load_lds_dwordx4 v163, s[66:67] offset:2048
	v_mfma_f32_32x32x16_bf16 v[32:47], v[168:171], v[140:143], v[32:47]
	global_load_lds_dwordx4 v163, s[66:67] offset:3072
	s_add_u32 s66, s66, 0x3a000
	s_addc_u32 s67, s67, 0
	v_mfma_f32_32x32x16_bf16 v[16:31], v[172:175], v[140:143], v[16:31]
	s_add_u32 s70, s70, 1
	s_cmp_eq_u32 s70, 3
	s_cselect_b32 s70, 0, s70
	v_mfma_f32_32x32x16_bf16 v[0:15], v[176:179], v[140:143], v[0:15]
	ds_read_b128 v[136:139], v185
	ds_read_b128 v[164:167], v187
	ds_read_b128 v[168:171], v187 offset:2048
	ds_read_b128 v[172:175], v187 offset:4096
	ds_read_b128 v[176:179], v187 offset:6144
	ds_read_b128 v[140:143], v185 offset:2048
	s_waitcnt lgkmcnt(10)
	v_mfma_f32_32x32x16_bf16 v[112:127], v[144:147], v[128:131], v[112:127]
	s_waitcnt lgkmcnt(9)
	v_mfma_f32_32x32x16_bf16 v[96:111], v[148:151], v[128:131], v[96:111]
	s_waitcnt lgkmcnt(8)
	v_mfma_f32_32x32x16_bf16 v[80:95], v[152:155], v[128:131], v[80:95]
	s_waitcnt lgkmcnt(7)
	v_mfma_f32_32x32x16_bf16 v[64:79], v[156:159], v[128:131], v[64:79]
	s_waitcnt lgkmcnt(6)
	v_mfma_f32_32x32x16_bf16 v[48:63], v[144:147], v[132:135], v[48:63]
	v_mfma_f32_32x32x16_bf16 v[32:47], v[148:151], v[132:135], v[32:47]
	v_mfma_f32_32x32x16_bf16 v[16:31], v[152:155], v[132:135], v[16:31]
	v_mfma_f32_32x32x16_bf16 v[0:15], v[156:159], v[132:135], v[0:15]
	s_add_u32 s72, s72, 1
	s_cmp_lt_u32 s72, 29
	s_cbranch_scc1 .Lp1e_loop
	s_waitcnt vmcnt(6) lgkmcnt(0)
	s_barrier
	s_mul_i32 s74, s71, 0x6000
	s_add_u32 s75, s74, 0x2000
	s_cmp_eq_u32 s71, 2
	s_cselect_b32 s75, 0x10000, s75
	v_add_u32_e32 v184, s74, v180
	v_add_u32_e32 v186, s75, v182
	v_add_u32_e32 v185, s74, v181
	v_add_u32_e32 v187, s75, v183
	s_add_u32 s71, s71, 1
	s_cmp_eq_u32 s71, 3
	s_cselect_b32 s71, 0, s71
	ds_read_b128 v[128:131], v184
	ds_read_b128 v[144:147], v186
	ds_read_b128 v[148:151], v186 offset:2048
	ds_read_b128 v[152:155], v186 offset:4096
	ds_read_b128 v[156:159], v186 offset:6144
	ds_read_b128 v[132:135], v184 offset:2048
	v_mfma_f32_32x32x16_bf16 v[112:127], v[164:167], v[136:139], v[112:127]
	v_mfma_f32_32x32x16_bf16 v[96:111], v[168:171], v[136:139], v[96:111]
	v_mfma_f32_32x32x16_bf16 v[80:95], v[172:175], v[136:139], v[80:95]
	v_mfma_f32_32x32x16_bf16 v[64:79], v[176:179], v[136:139], v[64:79]
	v_mfma_f32_32x32x16_bf16 v[48:63], v[164:167], v[140:143], v[48:63]
	v_mfma_f32_32x32x16_bf16 v[32:47], v[168:171], v[140:143], v[32:47]
	v_mfma_f32_32x32x16_bf16 v[16:31], v[172:175], v[140:143], v[16:31]
	v_mfma_f32_32x32x16_bf16 v[0:15], v[176:179], v[140:143], v[0:15]
	ds_read_b128 v[136:139], v185
	ds_read_b128 v[164:167], v187
	ds_read_b128 v[168:171], v187 offset:2048
	ds_read_b128 v[172:175], v187 offset:4096
	ds_read_b128 v[176:179], v187 offset:6144
	ds_read_b128 v[140:143], v185 offset:2048
	s_waitcnt lgkmcnt(10)
	v_mfma_f32_32x32x16_bf16 v[112:127], v[144:147], v[128:131], v[112:127]
	s_waitcnt lgkmcnt(9)
	v_mfma_f32_32x32x16_bf16 v[96:111], v[148:151], v[128:131], v[96:111]
	s_waitcnt lgkmcnt(8)
	v_mfma_f32_32x32x16_bf16 v[80:95], v[152:155], v[128:131], v[80:95]
	s_waitcnt lgkmcnt(7)
	v_mfma_f32_32x32x16_bf16 v[64:79], v[156:159], v[128:131], v[64:79]
	s_waitcnt lgkmcnt(6)
	v_mfma_f32_32x32x16_bf16 v[48:63], v[144:147], v[132:135], v[48:63]
	v_mfma_f32_32x32x16_bf16 v[32:47], v[148:151], v[132:135], v[32:47]
	v_mfma_f32_32x32x16_bf16 v[16:31], v[152:155], v[132:135], v[16:31]
	v_mfma_f32_32x32x16_bf16 v[0:15], v[156:159], v[132:135], v[0:15]
	s_waitcnt vmcnt(0) lgkmcnt(0)
	s_barrier
; #define MFMA32(a, b, c) __builtin_amdgcn_mfma_f32_32x32x16_bf16((a), (b), (c), 0, 0, 0)
; DI bfr f2bf(float a) { return (bfr)(pack2(a, 0.f) & 0xffffu); }
; template <int lda>
; DI void gemm_mainloop(const bfr* __restrict__ A, const bfr* __restrict__ Bt, int NB, int K, int m0, int n0, char* smem, f32x16 (&acc)[2][4]) {
;     ...
; #pragma unroll
;       for (int i = 0; i < 2; ++i)
; #pragma unroll
;         for (int j = 0; j < 4; ++j) acc[i][j] = MFMA32(af[i], bfg[j], acc[i][j]);
;     }
;     __syncthreads();
;   }
; template <int lda, class Epi>
; DI void gemm_tile(const bfr* __restrict__ A, const bfr* __restrict__ Bt, int NB, int K, int m0, int n0, char* smem, Epi epi) {
;     ...
;         epi(row, col, acc[i][j][q]);
;       }
; DI void phase_gemm_in_even(const Params& p, char* smem) {
;     ...
;                 [=](int row, int col, float v) { PB[(size_t)row * EINP + col] = f2bf(v); });
	s_mul_i32 s74, s71, 0x6000
	s_add_u32 s75, s74, 0x2000
	s_cmp_eq_u32 s71, 2
	s_cselect_b32 s75, 0x10000, s75
	v_add_u32_e32 v184, s74, v180
	v_add_u32_e32 v186, s75, v182
	v_add_u32_e32 v185, s74, v181
	v_add_u32_e32 v187, s75, v183
	s_add_u32 s71, s71, 1
	s_cmp_eq_u32 s71, 3
	s_cselect_b32 s71, 0, s71
	ds_read_b128 v[128:131], v184
	ds_read_b128 v[144:147], v186
	ds_read_b128 v[148:151], v186 offset:2048
	ds_read_b128 v[152:155], v186 offset:4096
	ds_read_b128 v[156:159], v186 offset:6144
	ds_read_b128 v[132:135], v184 offset:2048
	v_mfma_f32_32x32x16_bf16 v[112:127], v[164:167], v[136:139], v[112:127]
	v_mfma_f32_32x32x16_bf16 v[96:111], v[168:171], v[136:139], v[96:111]
	v_mfma_f32_32x32x16_bf16 v[80:95], v[172:175], v[136:139], v[80:95]
	v_mfma_f32_32x32x16_bf16 v[64:79], v[176:179], v[136:139], v[64:79]
	v_mfma_f32_32x32x16_bf16 v[48:63], v[164:167], v[140:143], v[48:63]
	v_mfma_f32_32x32x16_bf16 v[32:47], v[168:171], v[140:143], v[32:47]
	v_mfma_f32_32x32x16_bf16 v[16:31], v[172:175], v[140:143], v[16:31]
	v_mfma_f32_32x32x16_bf16 v[0:15], v[176:179], v[140:143], v[0:15]
	ds_read_b128 v[136:139], v185
	ds_read_b128 v[164:167], v187
	ds_read_b128 v[168:171], v187 offset:2048
	ds_read_b128 v[172:175], v187 offset:4096
	ds_read_b128 v[176:179], v187 offset:6144
	ds_read_b128 v[140:143], v185 offset:2048
	s_waitcnt lgkmcnt(10)
	v_mfma_f32_32x32x16_bf16 v[112:127], v[144:147], v[128:131], v[112:127]
	s_waitcnt lgkmcnt(9)
	v_mfma_f32_32x32x16_bf16 v[96:111], v[148:151], v[128:131], v[96:111]
	s_waitcnt lgkmcnt(8)
	v_mfma_f32_32x32x16_bf16 v[80:95], v[152:155], v[128:131], v[80:95]
	s_waitcnt lgkmcnt(7)
	v_mfma_f32_32x32x16_bf16 v[64:79], v[156:159], v[128:131], v[64:79]
	s_waitcnt lgkmcnt(6)
	v_mfma_f32_32x32x16_bf16 v[48:63], v[144:147], v[132:135], v[48:63]
	v_mfma_f32_32x32x16_bf16 v[32:47], v[148:151], v[132:135], v[32:47]
	v_mfma_f32_32x32x16_bf16 v[16:31], v[152:155], v[132:135], v[16:31]
	v_mfma_f32_32x32x16_bf16 v[0:15], v[156:159], v[132:135], v[0:15]
	s_waitcnt lgkmcnt(0)
	v_mfma_f32_32x32x16_bf16 v[112:127], v[164:167], v[136:139], v[112:127]
	v_mfma_f32_32x32x16_bf16 v[96:111], v[168:171], v[136:139], v[96:111]
	v_mfma_f32_32x32x16_bf16 v[80:95], v[172:175], v[136:139], v[80:95]
	v_mfma_f32_32x32x16_bf16 v[64:79], v[176:179], v[136:139], v[64:79]
	v_mfma_f32_32x32x16_bf16 v[48:63], v[164:167], v[140:143], v[48:63]
	v_mfma_f32_32x32x16_bf16 v[32:47], v[168:171], v[140:143], v[32:47]
	v_mfma_f32_32x32x16_bf16 v[16:31], v[172:175], v[140:143], v[16:31]
	v_mfma_f32_32x32x16_bf16 v[0:15], v[176:179], v[140:143], v[0:15]
	s_nop 7
	s_nop 3
	s_barrier
	s_load_dwordx2 s[64:65], s[92:93], 0x150
	v_and_b32_e32 v160, 31, v196
	v_bfe_u32 v162, v196, 5, 1
	s_lshr_b32 s74, s73, 1
	s_lshl_b32 s74, s74, 6
	s_add_u32 s74, s74, s77
	v_add_u32_e32 v163, s74, v160
	s_mul_i32 s76, s73, 8704
	v_mul_u32_u24_e32 v181, 272, v160
	v_lshl_add_u32 v181, v162, 3, v181
	v_add_u32_e32 v181, s76, v181
	v_bfe_u32 v186, v196, 4, 2
	v_and_b32_e32 v187, 15, v196
	v_mul_u32_u24_e32 v182, 272, v186
	v_lshl_add_u32 v182, v187, 4, v182
	v_add_u32_e32 v182, s76, v182
	s_and_b32 s75, s73, 1
	s_lshl_b32 s75, s75, 7
	s_add_u32 s75, s75, s78
	v_add_u32_e32 v180, s74, v186
	v_mul_u32_u24_e32 v180, 0xe00, v180
	v_lshl_add_u32 v180, v187, 3, v180
	v_add_lshl_u32 v183, v180, s75, 1
	s_waitcnt lgkmcnt(0)
	v_cvt_pk_bf16_f32 v112, v112, v113
	v_cvt_pk_bf16_f32 v113, v114, v115
	ds_write_b64 v181, v[112:113]
	v_cvt_pk_bf16_f32 v116, v116, v117
	v_cvt_pk_bf16_f32 v117, v118, v119
	ds_write_b64 v181, v[116:117] offset:16
	v_cvt_pk_bf16_f32 v120, v120, v121
	v_cvt_pk_bf16_f32 v121, v122, v123
	ds_write_b64 v181, v[120:121] offset:32
	v_cvt_pk_bf16_f32 v124, v124, v125
	v_cvt_pk_bf16_f32 v125, v126, v127
	ds_write_b64 v181, v[124:125] offset:48
	v_cvt_pk_bf16_f32 v96, v96, v97
	v_cvt_pk_bf16_f32 v97, v98, v99
	ds_write_b64 v181, v[96:97] offset:64
	v_cvt_pk_bf16_f32 v100, v100, v101
	v_cvt_pk_bf16_f32 v101, v102, v103
	ds_write_b64 v181, v[100:101] offset:80
	v_cvt_pk_bf16_f32 v104, v104, v105
	v_cvt_pk_bf16_f32 v105, v106, v107
	ds_write_b64 v181, v[104:105] offset:96
	v_cvt_pk_bf16_f32 v108, v108, v109
	v_cvt_pk_bf16_f32 v109, v110, v111
	ds_write_b64 v181, v[108:109] offset:112
	v_cvt_pk_bf16_f32 v80, v80, v81
	v_cvt_pk_bf16_f32 v81, v82, v83
	ds_write_b64 v181, v[80:81] offset:128
	v_cvt_pk_bf16_f32 v84, v84, v85
	v_cvt_pk_bf16_f32 v85, v86, v87
	ds_write_b64 v181, v[84:85] offset:144
	v_cvt_pk_bf16_f32 v88, v88, v89
	v_cvt_pk_bf16_f32 v89, v90, v91
	ds_write_b64 v181, v[88:89] offset:160
	v_cvt_pk_bf16_f32 v92, v92, v93
	v_cvt_pk_bf16_f32 v93, v94, v95
	ds_write_b64 v181, v[92:93] offset:176
	v_cvt_pk_bf16_f32 v64, v64, v65
	v_cvt_pk_bf16_f32 v65, v66, v67
	ds_write_b64 v181, v[64:65] offset:192
	v_cvt_pk_bf16_f32 v68, v68, v69
	v_cvt_pk_bf16_f32 v69, v70, v71
	ds_write_b64 v181, v[68:69] offset:208
	v_cvt_pk_bf16_f32 v72, v72, v73
	v_cvt_pk_bf16_f32 v73, v74, v75
	ds_write_b64 v181, v[72:73] offset:224
	v_cvt_pk_bf16_f32 v76, v76, v77
	v_cvt_pk_bf16_f32 v77, v78, v79
	ds_write_b64 v181, v[76:77] offset:240
	s_waitcnt lgkmcnt(0)
; DI bfr f2bf(float a) { return (bfr)(pack2(a, 0.f) & 0xffffu); }
; DI int crow(int reg, int h) { return (reg & 3) + 8 * (reg >> 2) + 4 * h; }
; template <int lda, class Epi>
; DI void gemm_tile(const bfr* __restrict__ A, const bfr* __restrict__ Bt, int NB, int K, int m0, int n0, char* smem, Epi epi) {
;     ...
; #pragma unroll
;   for (int i = 0; i < 2; ++i)
; #pragma unroll
;     for (int j = 0; j < 4; ++j)
; #pragma unroll
;       for (int q = 0; q < 16; ++q) {
;         int row = m0 + wr * 64 + i * 32 + crow(q, hl);
;         int col = n0 + wc * 128 + j * 32 + r;
;         epi(row, col, acc[i][j][q]);
;       }
; DI void phase_gemm_in_even(const Params& p, char* smem) {
;     ...
;       gemm_tile<1024>(p.H, p.WtInE, 3712, 1024, mt * 128, nt * 256, smem,
;                 [=](int row, int col, float v) { PB[(size_t)row * EINP + col] = f2bf(v); });
	ds_read_b128 v[112:115], v182
	ds_read_b128 v[116:119], v182 offset:1088
	ds_read_b128 v[120:123], v182 offset:2176
	ds_read_b128 v[124:127], v182 offset:3264
	ds_read_b128 v[96:99], v182 offset:4352
	ds_read_b128 v[100:103], v182 offset:5440
	ds_read_b128 v[104:107], v182 offset:6528
	ds_read_b128 v[108:111], v182 offset:7616
	s_add_u32 s66, s64, 0x0
	s_addc_u32 s67, s65, 0
	s_waitcnt lgkmcnt(7)
	global_store_dwordx4 v183, v[112:115], s[66:67]  sc1
	s_add_u32 s66, s64, 0x7000
	s_addc_u32 s67, s65, 0
	s_waitcnt lgkmcnt(6)
	global_store_dwordx4 v183, v[116:119], s[66:67]  sc1
	s_add_u32 s66, s64, 0xe000
	s_addc_u32 s67, s65, 0
	s_waitcnt lgkmcnt(5)
	global_store_dwordx4 v183, v[120:123], s[66:67]  sc1
	s_add_u32 s66, s64, 0x15000
	s_addc_u32 s67, s65, 0
	s_waitcnt lgkmcnt(4)
	global_store_dwordx4 v183, v[124:127], s[66:67]  sc1
	s_add_u32 s66, s64, 0x1c000
	s_addc_u32 s67, s65, 0
	s_waitcnt lgkmcnt(3)
	global_store_dwordx4 v183, v[96:99], s[66:67]  sc1
	s_add_u32 s66, s64, 0x23000
	s_addc_u32 s67, s65, 0
	s_waitcnt lgkmcnt(2)
	global_store_dwordx4 v183, v[100:103], s[66:67]  sc1
	s_add_u32 s66, s64, 0x2a000
	s_addc_u32 s67, s65, 0
	s_waitcnt lgkmcnt(1)
	global_store_dwordx4 v183, v[104:107], s[66:67]  sc1
	s_add_u32 s66, s64, 0x31000
	s_addc_u32 s67, s65, 0
	s_waitcnt lgkmcnt(0)
	global_store_dwordx4 v183, v[108:111], s[66:67]  sc1
	v_cvt_pk_bf16_f32 v48, v48, v49
	v_cvt_pk_bf16_f32 v49, v50, v51
	ds_write_b64 v181, v[48:49]
	v_cvt_pk_bf16_f32 v52, v52, v53
	v_cvt_pk_bf16_f32 v53, v54, v55
	ds_write_b64 v181, v[52:53] offset:16
	v_cvt_pk_bf16_f32 v56, v56, v57
	v_cvt_pk_bf16_f32 v57, v58, v59
	ds_write_b64 v181, v[56:57] offset:32
	v_cvt_pk_bf16_f32 v60, v60, v61
	v_cvt_pk_bf16_f32 v61, v62, v63
	ds_write_b64 v181, v[60:61] offset:48
	v_cvt_pk_bf16_f32 v32, v32, v33
	v_cvt_pk_bf16_f32 v33, v34, v35
	ds_write_b64 v181, v[32:33] offset:64
	v_cvt_pk_bf16_f32 v36, v36, v37
	v_cvt_pk_bf16_f32 v37, v38, v39
	ds_write_b64 v181, v[36:37] offset:80
	v_cvt_pk_bf16_f32 v40, v40, v41
	v_cvt_pk_bf16_f32 v41, v42, v43
	ds_write_b64 v181, v[40:41] offset:96
	v_cvt_pk_bf16_f32 v44, v44, v45
	v_cvt_pk_bf16_f32 v45, v46, v47
	ds_write_b64 v181, v[44:45] offset:112
	v_cvt_pk_bf16_f32 v16, v16, v17
	v_cvt_pk_bf16_f32 v17, v18, v19
	ds_write_b64 v181, v[16:17] offset:128
	v_cvt_pk_bf16_f32 v20, v20, v21
	v_cvt_pk_bf16_f32 v21, v22, v23
	ds_write_b64 v181, v[20:21] offset:144
	v_cvt_pk_bf16_f32 v24, v24, v25
	v_cvt_pk_bf16_f32 v25, v26, v27
	ds_write_b64 v181, v[24:25] offset:160
	v_cvt_pk_bf16_f32 v28, v28, v29
	v_cvt_pk_bf16_f32 v29, v30, v31
	ds_write_b64 v181, v[28:29] offset:176
	v_cvt_pk_bf16_f32 v0, v0, v1
	v_cvt_pk_bf16_f32 v1, v2, v3
	ds_write_b64 v181, v[0:1] offset:192
	v_cvt_pk_bf16_f32 v4, v4, v5
	v_cvt_pk_bf16_f32 v5, v6, v7
	ds_write_b64 v181, v[4:5] offset:208
	v_cvt_pk_bf16_f32 v8, v8, v9
	v_cvt_pk_bf16_f32 v9, v10, v11
	ds_write_b64 v181, v[8:9] offset:224
	v_cvt_pk_bf16_f32 v12, v12, v13
	v_cvt_pk_bf16_f32 v13, v14, v15
	ds_write_b64 v181, v[12:13] offset:240
	s_waitcnt lgkmcnt(0)
	ds_read_b128 v[48:51], v182
	ds_read_b128 v[52:55], v182 offset:1088
	ds_read_b128 v[56:59], v182 offset:2176
	ds_read_b128 v[60:63], v182 offset:3264
	ds_read_b128 v[32:35], v182 offset:4352
	ds_read_b128 v[36:39], v182 offset:5440
	ds_read_b128 v[40:43], v182 offset:6528
	ds_read_b128 v[44:47], v182 offset:7616
	s_add_u32 s66, s64, 0x38000
	s_addc_u32 s67, s65, 0
	s_waitcnt lgkmcnt(7)
	global_store_dwordx4 v183, v[48:51], s[66:67]  sc1
	s_add_u32 s66, s64, 0x3f000
	s_addc_u32 s67, s65, 0
	s_waitcnt lgkmcnt(6)
	global_store_dwordx4 v183, v[52:55], s[66:67]  sc1
	s_add_u32 s66, s64, 0x46000
	s_addc_u32 s67, s65, 0
	s_waitcnt lgkmcnt(5)
	global_store_dwordx4 v183, v[56:59], s[66:67]  sc1
	s_add_u32 s66, s64, 0x4d000
	s_addc_u32 s67, s65, 0
	s_waitcnt lgkmcnt(4)
	global_store_dwordx4 v183, v[60:63], s[66:67]  sc1
	s_add_u32 s66, s64, 0x54000
	s_addc_u32 s67, s65, 0
	s_waitcnt lgkmcnt(3)
	global_store_dwordx4 v183, v[32:35], s[66:67]  sc1
	s_add_u32 s66, s64, 0x5b000
	s_addc_u32 s67, s65, 0
	s_waitcnt lgkmcnt(2)
	global_store_dwordx4 v183, v[36:39], s[66:67]  sc1
	s_add_u32 s66, s64, 0x62000
	s_addc_u32 s67, s65, 0
	s_waitcnt lgkmcnt(1)
	global_store_dwordx4 v183, v[40:43], s[66:67]  sc1
	s_add_u32 s66, s64, 0x69000
	s_addc_u32 s67, s65, 0
	s_waitcnt lgkmcnt(0)
	global_store_dwordx4 v183, v[44:47], s[66:67]  sc1
	v_readlane_b32 s64, v188, 0
	v_readlane_b32 s65, v188, 1
	v_readlane_b32 s66, v188, 2
	v_readlane_b32 s67, v188, 3
	v_readlane_b32 s68, v188, 4
	v_readlane_b32 s69, v188, 5
	v_readlane_b32 s70, v188, 6
	v_readlane_b32 s71, v188, 7
	v_readlane_b32 s72, v188, 8
	v_readlane_b32 s73, v188, 9
	v_readlane_b32 s74, v188, 10
	v_readlane_b32 s75, v188, 11
	v_readlane_b32 s76, v188, 12
	v_readlane_b32 s77, v188, 13
	v_readlane_b32 s78, v188, 14
	v_readlane_b32 s79, v188, 15
	s_nop 7
	s_branch .LBB0_119

; #define MFMA32(a, b, c) __builtin_amdgcn_mfma_f32_32x32x16_bf16((a), (b), (c), 0, 0, 0)
; #define GA_LOAD(pr_) do { _Pragma("unroll") for (int i = 0; i < 4; ++i) ra[i] = *(const u32x4*)(Ab + (i * 32) * lda + (pr_) * 64); } while (0)
; #define GB_LOAD(kt_) do { const bfr* bk_ = Bb + (kt_) * NB * 32; \
;     _Pragma("unroll") for (int i = 0; i < 4; ++i) rb[i] = *(const u32x4*)(bk_ + (i * 64) * 32); } while (0)
; #define G_STORE(kt_) do { bfr* as_ = S0 + ((kt_) & 1) * GSTAGE; bfr* bs_ = as_ + 128 * 40; \
;     if (apar == ((kt_) & 1)) { _Pragma("unroll") for (int i = 0; i < 4; ++i) *(u32x4*)(as_ + asoff + i * 32 * 40) = ra[i]; } \
;     _Pragma("unroll") for (int i = 0; i < 4; ++i) *(u32x4*)(bs_ + bsoff + i * 64 * 40) = rb[i]; } while (0)
; template <int lda>
; DI void gemm_mainloop(const bfr* __restrict__ A, const bfr* __restrict__ Bt, int NB, int K, int m0, int n0, char* smem, f32x16 (&acc)[2][4]) {
;     ...
;   for (int kt = 0; kt < nk; ++kt) {
;     if (kt + 1 < nk) G_STORE(kt + 1);
;     if (kt + 2 < nk) {
;       GB_LOAD(kt + 2);
;       if ((kt & 1) == 0) GA_LOAD((kt >> 1) + 1);
;     }
;     const bfr* As = S0 + (kt & 1) * GSTAGE;
;     const bfr* Bs = As + 128 * 40;
; #pragma unroll
;     for (int ks = 0; ks < 2; ++ks) {
;       bf16x8 af[2], bfg[4];
; #pragma unroll
;       for (int i = 0; i < 2; ++i) af[i] = *(const bf16x8*)(As + (wr * 64 + i * 32 + r) * 40 + ks * 16 + hl * 8);
; #pragma unroll
;       for (int j = 0; j < 4; ++j) bfg[j] = *(const bf16x8*)(Bs + (wc * 128 + j * 32 + r) * 40 + ks * 16 + hl * 8);
; #pragma unroll
;       for (int i = 0; i < 2; ++i)
; #pragma unroll
;         for (int j = 0; j < 4; ++j) acc[i][j] = MFMA32(af[i], bfg[j], acc[i][j]);
;     }
;     __syncthreads();
.Lp6_loop:
	s_waitcnt vmcnt(6) lgkmcnt(0)
	s_barrier
	s_mul_i32 s74, s71, 0x6000
	s_add_u32 s75, s74, 0x2000
	s_cmp_eq_u32 s71, 2
	s_cselect_b32 s75, 0x10000, s75
	v_add_u32_e32 v199, s74, v192
	v_add_u32_e32 v205, s75, v194
	v_add_u32_e32 v204, s74, v193
	v_add_u32_e32 v206, s75, v198
	s_add_u32 s71, s71, 1
	s_cmp_eq_u32 s71, 3
	s_cselect_b32 s71, 0, s71
	ds_read_b128 v[128:131], v199
	ds_read_b128 v[144:147], v205
	ds_read_b128 v[148:151], v205 offset:2048
	ds_read_b128 v[152:155], v205 offset:4096
	ds_read_b128 v[156:159], v205 offset:6144
	ds_read_b128 v[132:135], v199 offset:2048
	v_mfma_f32_32x32x16_bf16 v[112:127], v[160:163], v[136:139], v[112:127]
	s_mul_i32 s74, s70, 0x6000
	s_add_u32 s75, s74, s68
	s_mov_b32 m0, s75
	s_add_u32 s76, s74, 0x2000
	s_cmp_eq_u32 s70, 2
	s_cselect_b32 s76, 0x10000, s76
	global_load_lds_dwordx4 v188, s[64:65]
	v_mfma_f32_32x32x16_bf16 v[96:111], v[164:167], v[136:139], v[96:111]
	s_add_u32 m0, s75, 0x400
	s_add_u32 s76, s76, s69
	global_load_lds_dwordx4 v190, s[64:65]
	v_mfma_f32_32x32x16_bf16 v[80:95], v[168:171], v[136:139], v[80:95]
	s_mov_b32 m0, s76
	s_add_u32 s64, s64, 64
	s_addc_u32 s65, s65, 0
	global_load_lds_dwordx4 v191, s[66:67]
	v_mfma_f32_32x32x16_bf16 v[64:79], v[172:175], v[136:139], v[64:79]
	global_load_lds_dwordx4 v191, s[66:67] offset:1024
	v_mfma_f32_32x32x16_bf16 v[48:63], v[160:163], v[140:143], v[48:63]
	global_load_lds_dwordx4 v191, s[66:67] offset:2048
	v_mfma_f32_32x32x16_bf16 v[32:47], v[164:167], v[140:143], v[32:47]
	global_load_lds_dwordx4 v191, s[66:67] offset:3072
	s_add_u32 s66, s66, 0x10000
	s_addc_u32 s67, s67, 0
	v_mfma_f32_32x32x16_bf16 v[16:31], v[168:171], v[140:143], v[16:31]
	s_add_u32 s70, s70, 1
	s_cmp_eq_u32 s70, 3
	s_cselect_b32 s70, 0, s70
	v_mfma_f32_32x32x16_bf16 v[0:15], v[172:175], v[140:143], v[0:15]
	ds_read_b128 v[136:139], v204
	ds_read_b128 v[160:163], v206
	ds_read_b128 v[164:167], v206 offset:2048
	ds_read_b128 v[168:171], v206 offset:4096
	ds_read_b128 v[172:175], v206 offset:6144
	ds_read_b128 v[140:143], v204 offset:2048
	s_waitcnt lgkmcnt(10)
	v_mfma_f32_32x32x16_bf16 v[112:127], v[144:147], v[128:131], v[112:127]
	s_waitcnt lgkmcnt(9)
	v_mfma_f32_32x32x16_bf16 v[96:111], v[148:151], v[128:131], v[96:111]
	s_waitcnt lgkmcnt(8)
	v_mfma_f32_32x32x16_bf16 v[80:95], v[152:155], v[128:131], v[80:95]
	s_waitcnt lgkmcnt(7)
	v_mfma_f32_32x32x16_bf16 v[64:79], v[156:159], v[128:131], v[64:79]
	s_waitcnt lgkmcnt(6)
	v_mfma_f32_32x32x16_bf16 v[48:63], v[144:147], v[132:135], v[48:63]
	v_mfma_f32_32x32x16_bf16 v[32:47], v[148:151], v[132:135], v[32:47]
	v_mfma_f32_32x32x16_bf16 v[16:31], v[152:155], v[132:135], v[16:31]
	v_mfma_f32_32x32x16_bf16 v[0:15], v[156:159], v[132:135], v[0:15]
	s_add_u32 s72, s72, 1
	s_cmp_lt_u32 s72, 29
	s_cbranch_scc1 .Lp6_loop
	s_waitcnt vmcnt(6) lgkmcnt(0)
	s_barrier
	s_mul_i32 s74, s71, 0x6000
	s_add_u32 s75, s74, 0x2000
	s_cmp_eq_u32 s71, 2
	s_cselect_b32 s75, 0x10000, s75
	v_add_u32_e32 v199, s74, v192
	v_add_u32_e32 v205, s75, v194
	v_add_u32_e32 v204, s74, v193
	v_add_u32_e32 v206, s75, v198
	s_add_u32 s71, s71, 1
	s_cmp_eq_u32 s71, 3
	s_cselect_b32 s71, 0, s71
	ds_read_b128 v[128:131], v199
	ds_read_b128 v[144:147], v205
	ds_read_b128 v[148:151], v205 offset:2048
	ds_read_b128 v[152:155], v205 offset:4096
	ds_read_b128 v[156:159], v205 offset:6144
	ds_read_b128 v[132:135], v199 offset:2048
	v_mfma_f32_32x32x16_bf16 v[112:127], v[160:163], v[136:139], v[112:127]
	v_mfma_f32_32x32x16_bf16 v[96:111], v[164:167], v[136:139], v[96:111]
	v_mfma_f32_32x32x16_bf16 v[80:95], v[168:171], v[136:139], v[80:95]
	v_mfma_f32_32x32x16_bf16 v[64:79], v[172:175], v[136:139], v[64:79]
	v_mfma_f32_32x32x16_bf16 v[48:63], v[160:163], v[140:143], v[48:63]
	v_mfma_f32_32x32x16_bf16 v[32:47], v[164:167], v[140:143], v[32:47]
	v_mfma_f32_32x32x16_bf16 v[16:31], v[168:171], v[140:143], v[16:31]
	v_mfma_f32_32x32x16_bf16 v[0:15], v[172:175], v[140:143], v[0:15]
	ds_read_b128 v[136:139], v204
	ds_read_b128 v[160:163], v206
	ds_read_b128 v[164:167], v206 offset:2048
	ds_read_b128 v[168:171], v206 offset:4096
	ds_read_b128 v[172:175], v206 offset:6144
	ds_read_b128 v[140:143], v204 offset:2048
	s_waitcnt lgkmcnt(10)
	v_mfma_f32_32x32x16_bf16 v[112:127], v[144:147], v[128:131], v[112:127]
	s_waitcnt lgkmcnt(9)
	v_mfma_f32_32x32x16_bf16 v[96:111], v[148:151], v[128:131], v[96:111]
	s_waitcnt lgkmcnt(8)
	v_mfma_f32_32x32x16_bf16 v[80:95], v[152:155], v[128:131], v[80:95]
	s_waitcnt lgkmcnt(7)
	v_mfma_f32_32x32x16_bf16 v[64:79], v[156:159], v[128:131], v[64:79]
	s_waitcnt lgkmcnt(6)
	v_mfma_f32_32x32x16_bf16 v[48:63], v[144:147], v[132:135], v[48:63]
	v_mfma_f32_32x32x16_bf16 v[32:47], v[148:151], v[132:135], v[32:47]
	v_mfma_f32_32x32x16_bf16 v[16:31], v[152:155], v[132:135], v[16:31]
	v_mfma_f32_32x32x16_bf16 v[0:15], v[156:159], v[132:135], v[0:15]
	s_waitcnt vmcnt(0) lgkmcnt(0)
	s_barrier
; #define MFMA32(a, b, c) __builtin_amdgcn_mfma_f32_32x32x16_bf16((a), (b), (c), 0, 0, 0)
; DI int crow(int reg, int h) { return (reg & 3) + 8 * (reg >> 2) + 4 * h; }
; template <int lda>
; DI void gemm_mainloop(const bfr* __restrict__ A, const bfr* __restrict__ Bt, int NB, int K, int m0, int n0, char* smem, f32x16 (&acc)[2][4]) {
;     ...
;     for (int ks = 0; ks < 2; ++ks) {
;       bf16x8 af[2], bfg[4];
; #pragma unroll
;       for (int i = 0; i < 2; ++i) af[i] = *(const bf16x8*)(As + (wr * 64 + i * 32 + r) * 40 + ks * 16 + hl * 8);
; #pragma unroll
;       for (int j = 0; j < 4; ++j) bfg[j] = *(const bf16x8*)(Bs + (wc * 128 + j * 32 + r) * 40 + ks * 16 + hl * 8);
; #pragma unroll
;       for (int i = 0; i < 2; ++i)
; #pragma unroll
;         for (int j = 0; j < 4; ++j) acc[i][j] = MFMA32(af[i], bfg[j], acc[i][j]);
;     }
;     __syncthreads();
; template <bool FIRST, bool HAS_H>
; DI void phase_gemm_resid(const Params& p, const bfr* A, const bfr* Wt, const float* gnext, float* ss, char* smem) {
;     ...
;     int tid2 = threadIdx.x;
;     asm volatile("" : "+v"(tid2));
;     const int lane = tid2 & 63, wid = tid2 >> 6, wr = wid >> 1, wc = wid & 1, r = lane & 31, hl = lane >> 5;
;     const float* xsrc = FIRST ? p.x_prompt : X;
;     const int rbase = m0 + wr * 64 + 4 * hl, cbase = n0 + wc * 128 + r;
; #pragma unroll
;     for (int i = 0; i < 2; ++i) {
; #pragma unroll
;       for (int qh = 0; qh < 2; ++qh) {
;         float rs[8];
; #pragma unroll
;         for (int q = 0; q < 8; ++q) rs[q] = 0.f;
; #pragma unroll
;         for (int jh = 0; jh < 2; ++jh) {
;           float xo[2][8];
; #pragma unroll
;           for (int jj = 0; jj < 2; ++jj)
; #pragma unroll
;             for (int q = 0; q < 8; ++q)
;               xo[jj][q] = xsrc[(rbase + i * 32 + crow(qh * 8 + q, 0)) * 1024 + cbase + (jh * 2 + jj) * 32];
	s_mul_i32 s74, s71, 0x6000
	s_add_u32 s75, s74, 0x2000
	s_cmp_eq_u32 s71, 2
	s_cselect_b32 s75, 0x10000, s75
	v_add_u32_e32 v199, s74, v192
	v_add_u32_e32 v205, s75, v194
	v_add_u32_e32 v204, s74, v193
	v_add_u32_e32 v206, s75, v198
	s_add_u32 s71, s71, 1
	s_cmp_eq_u32 s71, 3
	s_cselect_b32 s71, 0, s71
	ds_read_b128 v[128:131], v199
	ds_read_b128 v[144:147], v205
	ds_read_b128 v[148:151], v205 offset:2048
	ds_read_b128 v[152:155], v205 offset:4096
	ds_read_b128 v[156:159], v205 offset:6144
	ds_read_b128 v[132:135], v199 offset:2048
	v_mfma_f32_32x32x16_bf16 v[112:127], v[160:163], v[136:139], v[112:127]
	v_mfma_f32_32x32x16_bf16 v[96:111], v[164:167], v[136:139], v[96:111]
	v_mfma_f32_32x32x16_bf16 v[80:95], v[168:171], v[136:139], v[80:95]
	v_mfma_f32_32x32x16_bf16 v[64:79], v[172:175], v[136:139], v[64:79]
	v_mfma_f32_32x32x16_bf16 v[48:63], v[160:163], v[140:143], v[48:63]
	v_mfma_f32_32x32x16_bf16 v[32:47], v[164:167], v[140:143], v[32:47]
	v_mfma_f32_32x32x16_bf16 v[16:31], v[168:171], v[140:143], v[16:31]
	v_mfma_f32_32x32x16_bf16 v[0:15], v[172:175], v[140:143], v[0:15]
	ds_read_b128 v[136:139], v204
	ds_read_b128 v[160:163], v206
	ds_read_b128 v[164:167], v206 offset:2048
	ds_read_b128 v[168:171], v206 offset:4096
	ds_read_b128 v[172:175], v206 offset:6144
	ds_read_b128 v[140:143], v204 offset:2048
	s_waitcnt lgkmcnt(10)
	v_mfma_f32_32x32x16_bf16 v[112:127], v[144:147], v[128:131], v[112:127]
	s_waitcnt lgkmcnt(9)
	v_mfma_f32_32x32x16_bf16 v[96:111], v[148:151], v[128:131], v[96:111]
	s_waitcnt lgkmcnt(8)
	v_mfma_f32_32x32x16_bf16 v[80:95], v[152:155], v[128:131], v[80:95]
	s_waitcnt lgkmcnt(7)
	v_mfma_f32_32x32x16_bf16 v[64:79], v[156:159], v[128:131], v[64:79]
	s_waitcnt lgkmcnt(6)
	v_mfma_f32_32x32x16_bf16 v[48:63], v[144:147], v[132:135], v[48:63]
	v_mfma_f32_32x32x16_bf16 v[32:47], v[148:151], v[132:135], v[32:47]
	v_mfma_f32_32x32x16_bf16 v[16:31], v[152:155], v[132:135], v[16:31]
	v_mfma_f32_32x32x16_bf16 v[0:15], v[156:159], v[132:135], v[0:15]
	s_waitcnt lgkmcnt(0)
	v_mfma_f32_32x32x16_bf16 v[112:127], v[160:163], v[136:139], v[112:127]
	v_mfma_f32_32x32x16_bf16 v[96:111], v[164:167], v[136:139], v[96:111]
	v_mfma_f32_32x32x16_bf16 v[80:95], v[168:171], v[136:139], v[80:95]
	v_mfma_f32_32x32x16_bf16 v[64:79], v[172:175], v[136:139], v[64:79]
	v_mfma_f32_32x32x16_bf16 v[48:63], v[160:163], v[140:143], v[48:63]
	v_mfma_f32_32x32x16_bf16 v[32:47], v[164:167], v[140:143], v[32:47]
	v_mfma_f32_32x32x16_bf16 v[16:31], v[168:171], v[140:143], v[16:31]
	v_mfma_f32_32x32x16_bf16 v[0:15], v[172:175], v[140:143], v[0:15]
	s_nop 7
	s_nop 3
	s_load_dwordx2 s[64:65], s[92:93], 0x0
	s_load_dwordx2 s[66:67], s[92:93], 0x100
	s_load_dwordx2 s[68:69], s[92:93], 0x148
	s_load_dwordx2 s[70:71], s[92:93], 0x50
	s_mul_i32 s76, s73, 8704
	s_lshr_b32 s74, s73, 1
	s_lshl_b32 s74, s74, 6
	s_add_u32 s74, s74, s77
	s_and_b32 s75, s73, 1
	s_lshl_b32 s75, s75, 7
	s_add_u32 s75, s75, s78
	v_and_b32_e32 v208, 31, v196
	v_bfe_u32 v209, v196, 5, 1
	v_mul_u32_u24_e32 v210, 272, v208
	v_add_u32_e32 v210, s76, v210
	v_lshl_add_u32 v188, v209, 4, v210
	v_lshl_add_u32 v190, v209, 3, v210
	v_lshlrev_b32_e32 v210, 2, v209
	v_add_lshl_u32 v198, v210, s75, 2
	v_add_lshl_u32 v205, v208, s74, 2
	v_and_b32_e32 v210, 63, v196
	v_xor_b32_e32 v210, 32, v210
	v_lshlrev_b32_e32 v206, 2, v210
	v_bfe_u32 v208, v196, 4, 2
	v_and_b32_e32 v209, 15, v196
	v_mul_u32_u24_e32 v210, 272, v208
	v_lshl_add_u32 v210, v209, 4, v210
	v_add_u32_e32 v191, s76, v210
	v_add_u32_e32 v210, s74, v208
	v_lshlrev_b32_e32 v210, 10, v210
	v_lshl_add_u32 v210, v209, 2, v210
	v_add_lshl_u32 v193, v210, s75, 2
	s_mov_b32 s79, s74
	s_mov_b32 s72, s75
	s_waitcnt lgkmcnt(0)
	s_add_u32 s74, s64, 0x0
	s_addc_u32 s75, s65, 0
	global_load_dwordx4 v[128:131], v193, s[74:75]
	s_add_u32 s74, s64, 0x4000
	s_addc_u32 s75, s65, 0
	global_load_dwordx4 v[132:135], v193, s[74:75]
	s_add_u32 s74, s64, 0x8000
	s_addc_u32 s75, s65, 0
	global_load_dwordx4 v[136:139], v193, s[74:75]
	s_add_u32 s74, s64, 0xc000
	s_addc_u32 s75, s65, 0
	global_load_dwordx4 v[140:143], v193, s[74:75]
	s_add_u32 s74, s64, 0x10000
	s_addc_u32 s75, s65, 0
	global_load_dwordx4 v[144:147], v193, s[74:75]
	s_add_u32 s74, s64, 0x14000
	s_addc_u32 s75, s65, 0
	global_load_dwordx4 v[148:151], v193, s[74:75]
	s_add_u32 s74, s64, 0x18000
	s_addc_u32 s75, s65, 0
	global_load_dwordx4 v[152:155], v193, s[74:75]
	s_add_u32 s74, s64, 0x1c000
	s_addc_u32 s75, s65, 0
	global_load_dwordx4 v[156:159], v193, s[74:75]
	s_mov_b32 s74, s79
	s_mov_b32 s75, s72
	v_bfe_u32 v208, v196, 3, 3
	v_and_b32_e32 v209, 7, v196
	v_mul_u32_u24_e32 v210, 272, v208
	v_lshl_add_u32 v210, v209, 4, v210
	v_add_u32_e32 v192, s76, v210
	v_add_u32_e32 v210, s74, v208
	v_lshlrev_b32_e32 v210, 10, v210
	v_lshl_add_u32 v210, v209, 3, v210
	v_add_lshl_u32 v194, v210, s75, 1
	v_mov_b32_e32 v199, 0
	v_mov_b32_e32 v204, 0
	s_waitcnt lgkmcnt(0)
	s_barrier
; DI bfr f2bf(float a) { return (bfr)(pack2(a, 0.f) & 0xffffu); }
; DI int crow(int reg, int h) { return (reg & 3) + 8 * (reg >> 2) + 4 * h; }
; template <bool FIRST, bool HAS_H>
; DI void phase_gemm_resid(const Params& p, const bfr* A, const bfr* Wt, const float* gnext, float* ss, char* smem) {
;     ...
; #pragma unroll
;     for (int i = 0; i < 2; ++i) {
; #pragma unroll
;       for (int qh = 0; qh < 2; ++qh) {
;         float rs[8];
; #pragma unroll
;         for (int q = 0; q < 8; ++q) rs[q] = 0.f;
; #pragma unroll
;         for (int jh = 0; jh < 2; ++jh) {
;           float xo[2][8];
; #pragma unroll
;           for (int jj = 0; jj < 2; ++jj)
; #pragma unroll
;             for (int q = 0; q < 8; ++q)
;               xo[jj][q] = xsrc[(rbase + i * 32 + crow(qh * 8 + q, 0)) * 1024 + cbase + (jh * 2 + jj) * 32];
; #pragma unroll
;           for (int q = 0; q < 8; ++q) {
;             const int o = (rbase + i * 32 + crow(qh * 8 + q, 0)) * 1024 + cbase;
; #pragma unroll
;             for (int jj = 0; jj < 2; ++jj) {
;               const int j = jh * 2 + jj;
;               const float xn = xo[jj][q] + acc[i][j][qh * 8 + q];
;               X[o + j * 32] = xn;
;               if (HAS_H) Hn[o + j * 32] = f2bf(xn * gnext[cbase + j * 32]);
;               rs[q] += xn * xn;
;             }
;           }
;         }
	s_waitcnt vmcnt(7)
	ds_write_b128 v191, v[128:131]
	s_waitcnt vmcnt(6)
	ds_write_b128 v191, v[132:135] offset:1088
	s_waitcnt vmcnt(5)
	ds_write_b128 v191, v[136:139] offset:2176
	s_waitcnt vmcnt(4)
	ds_write_b128 v191, v[140:143] offset:3264
	s_waitcnt vmcnt(3)
	ds_write_b128 v191, v[144:147] offset:4352
	s_waitcnt vmcnt(2)
	ds_write_b128 v191, v[148:151] offset:5440
	s_waitcnt vmcnt(1)
	ds_write_b128 v191, v[152:155] offset:6528
	s_waitcnt vmcnt(0)
	ds_write_b128 v191, v[156:159] offset:7616
	s_add_u32 s74, s64, 0x100
	s_addc_u32 s75, s65, 0
	global_load_dwordx4 v[128:131], v193, s[74:75]
	s_add_u32 s74, s64, 0x4100
	s_addc_u32 s75, s65, 0
	global_load_dwordx4 v[132:135], v193, s[74:75]
	s_add_u32 s74, s64, 0x8100
	s_addc_u32 s75, s65, 0
	global_load_dwordx4 v[136:139], v193, s[74:75]
	s_add_u32 s74, s64, 0xc100
	s_addc_u32 s75, s65, 0
	global_load_dwordx4 v[140:143], v193, s[74:75]
	s_add_u32 s74, s64, 0x10100
	s_addc_u32 s75, s65, 0
	global_load_dwordx4 v[144:147], v193, s[74:75]
	s_add_u32 s74, s64, 0x14100
	s_addc_u32 s75, s65, 0
	global_load_dwordx4 v[148:151], v193, s[74:75]
	s_add_u32 s74, s64, 0x18100
	s_addc_u32 s75, s65, 0
	global_load_dwordx4 v[152:155], v193, s[74:75]
	s_add_u32 s74, s64, 0x1c100
	s_addc_u32 s75, s65, 0
	global_load_dwordx4 v[156:159], v193, s[74:75]
	ds_read_b128 v[160:163], v188
	ds_read_b128 v[164:167], v188 offset:32
	ds_read_b128 v[168:171], v188 offset:64
	ds_read_b128 v[172:175], v188 offset:96
	ds_read_b128 v[176:179], v188 offset:128
	ds_read_b128 v[180:183], v188 offset:160
	ds_read_b128 v[184:187], v188 offset:192
	ds_read_b128 v[200:203], v188 offset:224
	s_waitcnt lgkmcnt(7)
	v_add_f32_e32 v112, v160, v112
	v_add_f32_e32 v113, v161, v113
	v_add_f32_e32 v114, v162, v114
	v_add_f32_e32 v115, v163, v115
	v_fmac_f32_e32 v199, v112, v112
	v_fmac_f32_e32 v199, v113, v113
	v_fmac_f32_e32 v199, v114, v114
	v_fmac_f32_e32 v199, v115, v115
	ds_write_b128 v188, v[112:115]
	s_waitcnt lgkmcnt(7)
	v_add_f32_e32 v116, v164, v116
	v_add_f32_e32 v117, v165, v117
	v_add_f32_e32 v118, v166, v118
	v_add_f32_e32 v119, v167, v119
	v_fmac_f32_e32 v199, v116, v116
	v_fmac_f32_e32 v199, v117, v117
	v_fmac_f32_e32 v199, v118, v118
	v_fmac_f32_e32 v199, v119, v119
	ds_write_b128 v188, v[116:119] offset:32
	s_waitcnt lgkmcnt(7)
	v_add_f32_e32 v120, v168, v120
	v_add_f32_e32 v121, v169, v121
	v_add_f32_e32 v122, v170, v122
	v_add_f32_e32 v123, v171, v123
	v_fmac_f32_e32 v199, v120, v120
	v_fmac_f32_e32 v199, v121, v121
	v_fmac_f32_e32 v199, v122, v122
	v_fmac_f32_e32 v199, v123, v123
	ds_write_b128 v188, v[120:123] offset:64
	s_waitcnt lgkmcnt(7)
	v_add_f32_e32 v124, v172, v124
	v_add_f32_e32 v125, v173, v125
	v_add_f32_e32 v126, v174, v126
	v_add_f32_e32 v127, v175, v127
	v_fmac_f32_e32 v199, v124, v124
	v_fmac_f32_e32 v199, v125, v125
	v_fmac_f32_e32 v199, v126, v126
	v_fmac_f32_e32 v199, v127, v127
	ds_write_b128 v188, v[124:127] offset:96
	s_waitcnt lgkmcnt(7)
	v_add_f32_e32 v96, v176, v96
	v_add_f32_e32 v97, v177, v97
	v_add_f32_e32 v98, v178, v98
	v_add_f32_e32 v99, v179, v99
	v_fmac_f32_e32 v199, v96, v96
	v_fmac_f32_e32 v199, v97, v97
	v_fmac_f32_e32 v199, v98, v98
	v_fmac_f32_e32 v199, v99, v99
	ds_write_b128 v188, v[96:99] offset:128
	s_waitcnt lgkmcnt(7)
	v_add_f32_e32 v100, v180, v100
	v_add_f32_e32 v101, v181, v101
	v_add_f32_e32 v102, v182, v102
	v_add_f32_e32 v103, v183, v103
	v_fmac_f32_e32 v199, v100, v100
	v_fmac_f32_e32 v199, v101, v101
	v_fmac_f32_e32 v199, v102, v102
	v_fmac_f32_e32 v199, v103, v103
	ds_write_b128 v188, v[100:103] offset:160
	s_waitcnt lgkmcnt(7)
	v_add_f32_e32 v104, v184, v104
	v_add_f32_e32 v105, v185, v105
	v_add_f32_e32 v106, v186, v106
	v_add_f32_e32 v107, v187, v107
	v_fmac_f32_e32 v199, v104, v104
	v_fmac_f32_e32 v199, v105, v105
	v_fmac_f32_e32 v199, v106, v106
	v_fmac_f32_e32 v199, v107, v107
	ds_write_b128 v188, v[104:107] offset:192
	s_waitcnt lgkmcnt(7)
	v_add_f32_e32 v108, v200, v108
	v_add_f32_e32 v109, v201, v109
	v_add_f32_e32 v110, v202, v110
	v_add_f32_e32 v111, v203, v111
	v_fmac_f32_e32 v199, v108, v108
	v_fmac_f32_e32 v199, v109, v109
	v_fmac_f32_e32 v199, v110, v110
	v_fmac_f32_e32 v199, v111, v111
	ds_write_b128 v188, v[108:111] offset:224
	ds_read_b128 v[160:163], v191
	ds_read_b128 v[164:167], v191 offset:1088
	ds_read_b128 v[168:171], v191 offset:2176
	ds_read_b128 v[172:175], v191 offset:3264
	ds_read_b128 v[176:179], v191 offset:4352
	ds_read_b128 v[180:183], v191 offset:5440
	ds_read_b128 v[184:187], v191 offset:6528
	ds_read_b128 v[200:203], v191 offset:7616
	s_add_u32 s74, s66, 0x0
	s_addc_u32 s75, s67, 0
	s_waitcnt lgkmcnt(7)
	global_store_dwordx4 v193, v[160:163], s[74:75]  sc1
	s_add_u32 s74, s66, 0x4000
	s_addc_u32 s75, s67, 0
	s_waitcnt lgkmcnt(6)
	global_store_dwordx4 v193, v[164:167], s[74:75]  sc1
	s_add_u32 s74, s66, 0x8000
	s_addc_u32 s75, s67, 0
	s_waitcnt lgkmcnt(5)
	global_store_dwordx4 v193, v[168:171], s[74:75]  sc1
	s_add_u32 s74, s66, 0xc000
	s_addc_u32 s75, s67, 0
	s_waitcnt lgkmcnt(4)
	global_store_dwordx4 v193, v[172:175], s[74:75]  sc1
	s_add_u32 s74, s66, 0x10000
	s_addc_u32 s75, s67, 0
	s_waitcnt lgkmcnt(3)
	global_store_dwordx4 v193, v[176:179], s[74:75]  sc1
	s_add_u32 s74, s66, 0x14000
	s_addc_u32 s75, s67, 0
	s_waitcnt lgkmcnt(2)
	global_store_dwordx4 v193, v[180:183], s[74:75]  sc1
	s_add_u32 s74, s66, 0x18000
	s_addc_u32 s75, s67, 0
	s_waitcnt lgkmcnt(1)
	global_store_dwordx4 v193, v[184:187], s[74:75]  sc1
	s_add_u32 s74, s66, 0x1c000
	s_addc_u32 s75, s67, 0
	s_waitcnt lgkmcnt(0)
; DI bfr f2bf(float a) { return (bfr)(pack2(a, 0.f) & 0xffffu); }
; DI int crow(int reg, int h) { return (reg & 3) + 8 * (reg >> 2) + 4 * h; }
; template <bool FIRST, bool HAS_H>
; DI void phase_gemm_resid(const Params& p, const bfr* A, const bfr* Wt, const float* gnext, float* ss, char* smem) {
;     ...
;               xo[jj][q] = xsrc[(rbase + i * 32 + crow(qh * 8 + q, 0)) * 1024 + cbase + (jh * 2 + jj) * 32];
; #pragma unroll
;           for (int q = 0; q < 8; ++q) {
;             const int o = (rbase + i * 32 + crow(qh * 8 + q, 0)) * 1024 + cbase;
; #pragma unroll
;             for (int jj = 0; jj < 2; ++jj) {
;               const int j = jh * 2 + jj;
;               const float xn = xo[jj][q] + acc[i][j][qh * 8 + q];
;               X[o + j * 32] = xn;
;               if (HAS_H) Hn[o + j * 32] = f2bf(xn * gnext[cbase + j * 32]);
;               rs[q] += xn * xn;
;             }
;           }
;         }
	global_store_dwordx4 v193, v[200:203], s[74:75]  sc1
	global_load_dwordx4 v[160:163], v198, s[70:71]
	global_load_dwordx4 v[164:167], v198, s[70:71] offset:32
	global_load_dwordx4 v[168:171], v198, s[70:71] offset:64
	global_load_dwordx4 v[172:175], v198, s[70:71] offset:96
	global_load_dwordx4 v[176:179], v198, s[70:71] offset:128
	global_load_dwordx4 v[180:183], v198, s[70:71] offset:160
	global_load_dwordx4 v[184:187], v198, s[70:71] offset:192
	global_load_dwordx4 v[200:203], v198, s[70:71] offset:224
	s_waitcnt vmcnt(7)
	v_mul_f32_e32 v112, v160, v112
	v_mul_f32_e32 v113, v161, v113
	v_mul_f32_e32 v114, v162, v114
	v_mul_f32_e32 v115, v163, v115
	v_cvt_pk_bf16_f32 v112, v112, v113
	v_cvt_pk_bf16_f32 v113, v114, v115
	ds_write_b64 v190, v[112:113]
	s_waitcnt vmcnt(6)
	v_mul_f32_e32 v116, v164, v116
	v_mul_f32_e32 v117, v165, v117
	v_mul_f32_e32 v118, v166, v118
	v_mul_f32_e32 v119, v167, v119
	v_cvt_pk_bf16_f32 v116, v116, v117
	v_cvt_pk_bf16_f32 v117, v118, v119
	ds_write_b64 v190, v[116:117] offset:16
	s_waitcnt vmcnt(5)
	v_mul_f32_e32 v120, v168, v120
	v_mul_f32_e32 v121, v169, v121
	v_mul_f32_e32 v122, v170, v122
	v_mul_f32_e32 v123, v171, v123
	v_cvt_pk_bf16_f32 v120, v120, v121
	v_cvt_pk_bf16_f32 v121, v122, v123
	ds_write_b64 v190, v[120:121] offset:32
	s_waitcnt vmcnt(4)
	v_mul_f32_e32 v124, v172, v124
	v_mul_f32_e32 v125, v173, v125
	v_mul_f32_e32 v126, v174, v126
	v_mul_f32_e32 v127, v175, v127
	v_cvt_pk_bf16_f32 v124, v124, v125
	v_cvt_pk_bf16_f32 v125, v126, v127
	ds_write_b64 v190, v[124:125] offset:48
	s_waitcnt vmcnt(3)
	v_mul_f32_e32 v96, v176, v96
	v_mul_f32_e32 v97, v177, v97
	v_mul_f32_e32 v98, v178, v98
	v_mul_f32_e32 v99, v179, v99
	v_cvt_pk_bf16_f32 v96, v96, v97
	v_cvt_pk_bf16_f32 v97, v98, v99
	ds_write_b64 v190, v[96:97] offset:64
	s_waitcnt vmcnt(2)
	v_mul_f32_e32 v100, v180, v100
	v_mul_f32_e32 v101, v181, v101
	v_mul_f32_e32 v102, v182, v102
	v_mul_f32_e32 v103, v183, v103
	v_cvt_pk_bf16_f32 v100, v100, v101
	v_cvt_pk_bf16_f32 v101, v102, v103
	ds_write_b64 v190, v[100:101] offset:80
	s_waitcnt vmcnt(1)
	v_mul_f32_e32 v104, v184, v104
	v_mul_f32_e32 v105, v185, v105
	v_mul_f32_e32 v106, v186, v106
	v_mul_f32_e32 v107, v187, v107
	v_cvt_pk_bf16_f32 v104, v104, v105
	v_cvt_pk_bf16_f32 v105, v106, v107
	ds_write_b64 v190, v[104:105] offset:96
	s_waitcnt vmcnt(0)
	v_mul_f32_e32 v108, v200, v108
	v_mul_f32_e32 v109, v201, v109
	v_mul_f32_e32 v110, v202, v110
	v_mul_f32_e32 v111, v203, v111
	v_cvt_pk_bf16_f32 v108, v108, v109
	v_cvt_pk_bf16_f32 v109, v110, v111
	ds_write_b64 v190, v[108:109] offset:112
	ds_read_b128 v[160:163], v192
	ds_read_b128 v[164:167], v192 offset:2176
	ds_read_b128 v[168:171], v192 offset:4352
	ds_read_b128 v[172:175], v192 offset:6528
	s_add_u32 s74, s68, 0x0
	s_addc_u32 s75, s69, 0
	s_waitcnt lgkmcnt(3)
	global_store_dwordx4 v194, v[160:163], s[74:75]  sc1
	s_add_u32 s74, s68, 0x4000
	s_addc_u32 s75, s69, 0
	s_waitcnt lgkmcnt(2)
	global_store_dwordx4 v194, v[164:167], s[74:75]  sc1
	s_add_u32 s74, s68, 0x8000
	s_addc_u32 s75, s69, 0
	s_waitcnt lgkmcnt(1)
	global_store_dwordx4 v194, v[168:171], s[74:75]  sc1
	s_add_u32 s74, s68, 0xc000
	s_addc_u32 s75, s69, 0
	s_waitcnt lgkmcnt(0)
	global_store_dwordx4 v194, v[172:175], s[74:75]  sc1
	s_waitcnt vmcnt(4)
	ds_write_b128 v191, v[128:131]
	s_waitcnt vmcnt(4)
	ds_write_b128 v191, v[132:135] offset:1088
	s_waitcnt vmcnt(4)
	ds_write_b128 v191, v[136:139] offset:2176
	s_waitcnt vmcnt(4)
	ds_write_b128 v191, v[140:143] offset:3264
	s_waitcnt vmcnt(4)
	ds_write_b128 v191, v[144:147] offset:4352
	s_waitcnt vmcnt(4)
	ds_write_b128 v191, v[148:151] offset:5440
	s_waitcnt vmcnt(4)
	ds_write_b128 v191, v[152:155] offset:6528
	s_waitcnt vmcnt(4)
	ds_write_b128 v191, v[156:159] offset:7616
	s_add_u32 s74, s64, 0x20000
	s_addc_u32 s75, s65, 0
	global_load_dwordx4 v[128:131], v193, s[74:75]
	s_add_u32 s74, s64, 0x24000
	s_addc_u32 s75, s65, 0
	global_load_dwordx4 v[132:135], v193, s[74:75]
	s_add_u32 s74, s64, 0x28000
	s_addc_u32 s75, s65, 0
	global_load_dwordx4 v[136:139], v193, s[74:75]
	s_add_u32 s74, s64, 0x2c000
	s_addc_u32 s75, s65, 0
	global_load_dwordx4 v[140:143], v193, s[74:75]
	s_add_u32 s74, s64, 0x30000
	s_addc_u32 s75, s65, 0
	global_load_dwordx4 v[144:147], v193, s[74:75]
	s_add_u32 s74, s64, 0x34000
	s_addc_u32 s75, s65, 0
	global_load_dwordx4 v[148:151], v193, s[74:75]
	s_add_u32 s74, s64, 0x38000
	s_addc_u32 s75, s65, 0
	global_load_dwordx4 v[152:155], v193, s[74:75]
	s_add_u32 s74, s64, 0x3c000
	s_addc_u32 s75, s65, 0
	global_load_dwordx4 v[156:159], v193, s[74:75]
	ds_read_b128 v[160:163], v188
	ds_read_b128 v[164:167], v188 offset:32
	ds_read_b128 v[168:171], v188 offset:64
	ds_read_b128 v[172:175], v188 offset:96
	ds_read_b128 v[176:179], v188 offset:128
	ds_read_b128 v[180:183], v188 offset:160
	ds_read_b128 v[184:187], v188 offset:192
	ds_read_b128 v[200:203], v188 offset:224
	s_waitcnt lgkmcnt(7)
	v_add_f32_e32 v80, v160, v80
	v_add_f32_e32 v81, v161, v81
	v_add_f32_e32 v82, v162, v82
	v_add_f32_e32 v83, v163, v83
	v_fmac_f32_e32 v199, v80, v80
	v_fmac_f32_e32 v199, v81, v81
	v_fmac_f32_e32 v199, v82, v82
	v_fmac_f32_e32 v199, v83, v83
	ds_write_b128 v188, v[80:83]
	s_waitcnt lgkmcnt(7)
	v_add_f32_e32 v84, v164, v84
	v_add_f32_e32 v85, v165, v85
	v_add_f32_e32 v86, v166, v86
	v_add_f32_e32 v87, v167, v87
	v_fmac_f32_e32 v199, v84, v84
	v_fmac_f32_e32 v199, v85, v85
	v_fmac_f32_e32 v199, v86, v86
	v_fmac_f32_e32 v199, v87, v87
	ds_write_b128 v188, v[84:87] offset:32
	s_waitcnt lgkmcnt(7)
; DI bfr f2bf(float a) { return (bfr)(pack2(a, 0.f) & 0xffffu); }
; DI int crow(int reg, int h) { return (reg & 3) + 8 * (reg >> 2) + 4 * h; }
; template <bool FIRST, bool HAS_H>
; DI void phase_gemm_resid(const Params& p, const bfr* A, const bfr* Wt, const float* gnext, float* ss, char* smem) {
;     ...
;               xo[jj][q] = xsrc[(rbase + i * 32 + crow(qh * 8 + q, 0)) * 1024 + cbase + (jh * 2 + jj) * 32];
; #pragma unroll
;           for (int q = 0; q < 8; ++q) {
;             const int o = (rbase + i * 32 + crow(qh * 8 + q, 0)) * 1024 + cbase;
; #pragma unroll
;             for (int jj = 0; jj < 2; ++jj) {
;               const int j = jh * 2 + jj;
;               const float xn = xo[jj][q] + acc[i][j][qh * 8 + q];
;               X[o + j * 32] = xn;
;               if (HAS_H) Hn[o + j * 32] = f2bf(xn * gnext[cbase + j * 32]);
;               rs[q] += xn * xn;
;             }
;           }
;         }
	v_add_f32_e32 v88, v168, v88
	v_add_f32_e32 v89, v169, v89
	v_add_f32_e32 v90, v170, v90
	v_add_f32_e32 v91, v171, v91
	v_fmac_f32_e32 v199, v88, v88
	v_fmac_f32_e32 v199, v89, v89
	v_fmac_f32_e32 v199, v90, v90
	v_fmac_f32_e32 v199, v91, v91
	ds_write_b128 v188, v[88:91] offset:64
	s_waitcnt lgkmcnt(7)
	v_add_f32_e32 v92, v172, v92
	v_add_f32_e32 v93, v173, v93
	v_add_f32_e32 v94, v174, v94
	v_add_f32_e32 v95, v175, v95
	v_fmac_f32_e32 v199, v92, v92
	v_fmac_f32_e32 v199, v93, v93
	v_fmac_f32_e32 v199, v94, v94
	v_fmac_f32_e32 v199, v95, v95
	ds_write_b128 v188, v[92:95] offset:96
	s_waitcnt lgkmcnt(7)
	v_add_f32_e32 v64, v176, v64
	v_add_f32_e32 v65, v177, v65
	v_add_f32_e32 v66, v178, v66
	v_add_f32_e32 v67, v179, v67
	v_fmac_f32_e32 v199, v64, v64
	v_fmac_f32_e32 v199, v65, v65
	v_fmac_f32_e32 v199, v66, v66
	v_fmac_f32_e32 v199, v67, v67
	ds_write_b128 v188, v[64:67] offset:128
	s_waitcnt lgkmcnt(7)
	v_add_f32_e32 v68, v180, v68
	v_add_f32_e32 v69, v181, v69
	v_add_f32_e32 v70, v182, v70
	v_add_f32_e32 v71, v183, v71
	v_fmac_f32_e32 v199, v68, v68
	v_fmac_f32_e32 v199, v69, v69
	v_fmac_f32_e32 v199, v70, v70
	v_fmac_f32_e32 v199, v71, v71
	ds_write_b128 v188, v[68:71] offset:160
	s_waitcnt lgkmcnt(7)
	v_add_f32_e32 v72, v184, v72
	v_add_f32_e32 v73, v185, v73
	v_add_f32_e32 v74, v186, v74
	v_add_f32_e32 v75, v187, v75
	v_fmac_f32_e32 v199, v72, v72
	v_fmac_f32_e32 v199, v73, v73
	v_fmac_f32_e32 v199, v74, v74
	v_fmac_f32_e32 v199, v75, v75
	ds_write_b128 v188, v[72:75] offset:192
	s_waitcnt lgkmcnt(7)
	v_add_f32_e32 v76, v200, v76
	v_add_f32_e32 v77, v201, v77
	v_add_f32_e32 v78, v202, v78
	v_add_f32_e32 v79, v203, v79
	v_fmac_f32_e32 v199, v76, v76
	v_fmac_f32_e32 v199, v77, v77
	v_fmac_f32_e32 v199, v78, v78
	v_fmac_f32_e32 v199, v79, v79
	ds_write_b128 v188, v[76:79] offset:224
	ds_read_b128 v[160:163], v191
	ds_read_b128 v[164:167], v191 offset:1088
	ds_read_b128 v[168:171], v191 offset:2176
	ds_read_b128 v[172:175], v191 offset:3264
	ds_read_b128 v[176:179], v191 offset:4352
	ds_read_b128 v[180:183], v191 offset:5440
	ds_read_b128 v[184:187], v191 offset:6528
	ds_read_b128 v[200:203], v191 offset:7616
	s_add_u32 s74, s66, 0x100
	s_addc_u32 s75, s67, 0
	s_waitcnt lgkmcnt(7)
	global_store_dwordx4 v193, v[160:163], s[74:75]  sc1
	s_add_u32 s74, s66, 0x4100
	s_addc_u32 s75, s67, 0
	s_waitcnt lgkmcnt(6)
	global_store_dwordx4 v193, v[164:167], s[74:75]  sc1
	s_add_u32 s74, s66, 0x8100
	s_addc_u32 s75, s67, 0
	s_waitcnt lgkmcnt(5)
	global_store_dwordx4 v193, v[168:171], s[74:75]  sc1
	s_add_u32 s74, s66, 0xc100
	s_addc_u32 s75, s67, 0
	s_waitcnt lgkmcnt(4)
	global_store_dwordx4 v193, v[172:175], s[74:75]  sc1
	s_add_u32 s74, s66, 0x10100
	s_addc_u32 s75, s67, 0
	s_waitcnt lgkmcnt(3)
	global_store_dwordx4 v193, v[176:179], s[74:75]  sc1
	s_add_u32 s74, s66, 0x14100
	s_addc_u32 s75, s67, 0
	s_waitcnt lgkmcnt(2)
	global_store_dwordx4 v193, v[180:183], s[74:75]  sc1
	s_add_u32 s74, s66, 0x18100
	s_addc_u32 s75, s67, 0
	s_waitcnt lgkmcnt(1)
	global_store_dwordx4 v193, v[184:187], s[74:75]  sc1
	s_add_u32 s74, s66, 0x1c100
	s_addc_u32 s75, s67, 0
	s_waitcnt lgkmcnt(0)
	global_store_dwordx4 v193, v[200:203], s[74:75]  sc1
	global_load_dwordx4 v[160:163], v198, s[70:71] offset:256
	global_load_dwordx4 v[164:167], v198, s[70:71] offset:288
	global_load_dwordx4 v[168:171], v198, s[70:71] offset:320
	global_load_dwordx4 v[172:175], v198, s[70:71] offset:352
	global_load_dwordx4 v[176:179], v198, s[70:71] offset:384
	global_load_dwordx4 v[180:183], v198, s[70:71] offset:416
	global_load_dwordx4 v[184:187], v198, s[70:71] offset:448
	global_load_dwordx4 v[200:203], v198, s[70:71] offset:480
	s_waitcnt vmcnt(7)
	v_mul_f32_e32 v80, v160, v80
	v_mul_f32_e32 v81, v161, v81
	v_mul_f32_e32 v82, v162, v82
	v_mul_f32_e32 v83, v163, v83
	v_cvt_pk_bf16_f32 v80, v80, v81
	v_cvt_pk_bf16_f32 v81, v82, v83
	ds_write_b64 v190, v[80:81]
	s_waitcnt vmcnt(6)
	v_mul_f32_e32 v84, v164, v84
	v_mul_f32_e32 v85, v165, v85
	v_mul_f32_e32 v86, v166, v86
	v_mul_f32_e32 v87, v167, v87
	v_cvt_pk_bf16_f32 v84, v84, v85
	v_cvt_pk_bf16_f32 v85, v86, v87
	ds_write_b64 v190, v[84:85] offset:16
	s_waitcnt vmcnt(5)
	v_mul_f32_e32 v88, v168, v88
	v_mul_f32_e32 v89, v169, v89
	v_mul_f32_e32 v90, v170, v90
	v_mul_f32_e32 v91, v171, v91
	v_cvt_pk_bf16_f32 v88, v88, v89
	v_cvt_pk_bf16_f32 v89, v90, v91
	ds_write_b64 v190, v[88:89] offset:32
	s_waitcnt vmcnt(4)
	v_mul_f32_e32 v92, v172, v92
	v_mul_f32_e32 v93, v173, v93
	v_mul_f32_e32 v94, v174, v94
	v_mul_f32_e32 v95, v175, v95
	v_cvt_pk_bf16_f32 v92, v92, v93
	v_cvt_pk_bf16_f32 v93, v94, v95
	ds_write_b64 v190, v[92:93] offset:48
	s_waitcnt vmcnt(3)
	v_mul_f32_e32 v64, v176, v64
	v_mul_f32_e32 v65, v177, v65
	v_mul_f32_e32 v66, v178, v66
	v_mul_f32_e32 v67, v179, v67
	v_cvt_pk_bf16_f32 v64, v64, v65
	v_cvt_pk_bf16_f32 v65, v66, v67
	ds_write_b64 v190, v[64:65] offset:64
	s_waitcnt vmcnt(2)
	v_mul_f32_e32 v68, v180, v68
	v_mul_f32_e32 v69, v181, v69
	v_mul_f32_e32 v70, v182, v70
	v_mul_f32_e32 v71, v183, v71
	v_cvt_pk_bf16_f32 v68, v68, v69
	v_cvt_pk_bf16_f32 v69, v70, v71
	ds_write_b64 v190, v[68:69] offset:80
	s_waitcnt vmcnt(1)
	v_mul_f32_e32 v72, v184, v72
	v_mul_f32_e32 v73, v185, v73
	v_mul_f32_e32 v74, v186, v74
	v_mul_f32_e32 v75, v187, v75
	v_cvt_pk_bf16_f32 v72, v72, v73
	v_cvt_pk_bf16_f32 v73, v74, v75
	ds_write_b64 v190, v[72:73] offset:96
	s_waitcnt vmcnt(0)
	v_mul_f32_e32 v76, v200, v76
	v_mul_f32_e32 v77, v201, v77
	v_mul_f32_e32 v78, v202, v78
	v_mul_f32_e32 v79, v203, v79
	v_cvt_pk_bf16_f32 v76, v76, v77
	v_cvt_pk_bf16_f32 v77, v78, v79
	ds_write_b64 v190, v[76:77] offset:112
	ds_read_b128 v[160:163], v192
	ds_read_b128 v[164:167], v192 offset:2176
	ds_read_b128 v[168:171], v192 offset:4352
	ds_read_b128 v[172:175], v192 offset:6528
	s_add_u32 s74, s68, 0x80
	s_addc_u32 s75, s69, 0
	s_waitcnt lgkmcnt(3)
; DI bfr f2bf(float a) { return (bfr)(pack2(a, 0.f) & 0xffffu); }
; DI int crow(int reg, int h) { return (reg & 3) + 8 * (reg >> 2) + 4 * h; }
; template <bool FIRST, bool HAS_H>
; DI void phase_gemm_resid(const Params& p, const bfr* A, const bfr* Wt, const float* gnext, float* ss, char* smem) {
;     ...
;               xo[jj][q] = xsrc[(rbase + i * 32 + crow(qh * 8 + q, 0)) * 1024 + cbase + (jh * 2 + jj) * 32];
; #pragma unroll
;           for (int q = 0; q < 8; ++q) {
;             const int o = (rbase + i * 32 + crow(qh * 8 + q, 0)) * 1024 + cbase;
; #pragma unroll
;             for (int jj = 0; jj < 2; ++jj) {
;               const int j = jh * 2 + jj;
;               const float xn = xo[jj][q] + acc[i][j][qh * 8 + q];
;               X[o + j * 32] = xn;
;               if (HAS_H) Hn[o + j * 32] = f2bf(xn * gnext[cbase + j * 32]);
;               rs[q] += xn * xn;
;             }
;           }
;         }
	global_store_dwordx4 v194, v[160:163], s[74:75]  sc1
	s_add_u32 s74, s68, 0x4080
	s_addc_u32 s75, s69, 0
	s_waitcnt lgkmcnt(2)
	global_store_dwordx4 v194, v[164:167], s[74:75]  sc1
	s_add_u32 s74, s68, 0x8080
	s_addc_u32 s75, s69, 0
	s_waitcnt lgkmcnt(1)
	global_store_dwordx4 v194, v[168:171], s[74:75]  sc1
	s_add_u32 s74, s68, 0xc080
	s_addc_u32 s75, s69, 0
	s_waitcnt lgkmcnt(0)
	global_store_dwordx4 v194, v[172:175], s[74:75]  sc1
	s_waitcnt vmcnt(4)
	ds_write_b128 v191, v[128:131]
	s_waitcnt vmcnt(4)
	ds_write_b128 v191, v[132:135] offset:1088
	s_waitcnt vmcnt(4)
	ds_write_b128 v191, v[136:139] offset:2176
	s_waitcnt vmcnt(4)
	ds_write_b128 v191, v[140:143] offset:3264
	s_waitcnt vmcnt(4)
	ds_write_b128 v191, v[144:147] offset:4352
	s_waitcnt vmcnt(4)
	ds_write_b128 v191, v[148:151] offset:5440
	s_waitcnt vmcnt(4)
	ds_write_b128 v191, v[152:155] offset:6528
	s_waitcnt vmcnt(4)
	ds_write_b128 v191, v[156:159] offset:7616
	s_add_u32 s74, s64, 0x20100
	s_addc_u32 s75, s65, 0
	global_load_dwordx4 v[128:131], v193, s[74:75]
	s_add_u32 s74, s64, 0x24100
	s_addc_u32 s75, s65, 0
	global_load_dwordx4 v[132:135], v193, s[74:75]
	s_add_u32 s74, s64, 0x28100
	s_addc_u32 s75, s65, 0
	global_load_dwordx4 v[136:139], v193, s[74:75]
	s_add_u32 s74, s64, 0x2c100
	s_addc_u32 s75, s65, 0
	global_load_dwordx4 v[140:143], v193, s[74:75]
	s_add_u32 s74, s64, 0x30100
	s_addc_u32 s75, s65, 0
	global_load_dwordx4 v[144:147], v193, s[74:75]
	s_add_u32 s74, s64, 0x34100
	s_addc_u32 s75, s65, 0
	global_load_dwordx4 v[148:151], v193, s[74:75]
	s_add_u32 s74, s64, 0x38100
	s_addc_u32 s75, s65, 0
	global_load_dwordx4 v[152:155], v193, s[74:75]
	s_add_u32 s74, s64, 0x3c100
	s_addc_u32 s75, s65, 0
	global_load_dwordx4 v[156:159], v193, s[74:75]
	ds_read_b128 v[160:163], v188
	ds_read_b128 v[164:167], v188 offset:32
	ds_read_b128 v[168:171], v188 offset:64
	ds_read_b128 v[172:175], v188 offset:96
	ds_read_b128 v[176:179], v188 offset:128
	ds_read_b128 v[180:183], v188 offset:160
	ds_read_b128 v[184:187], v188 offset:192
	ds_read_b128 v[200:203], v188 offset:224
	s_waitcnt lgkmcnt(7)
	v_add_f32_e32 v48, v160, v48
	v_add_f32_e32 v49, v161, v49
	v_add_f32_e32 v50, v162, v50
	v_add_f32_e32 v51, v163, v51
	v_fmac_f32_e32 v204, v48, v48
	v_fmac_f32_e32 v204, v49, v49
	v_fmac_f32_e32 v204, v50, v50
	v_fmac_f32_e32 v204, v51, v51
	ds_write_b128 v188, v[48:51]
	s_waitcnt lgkmcnt(7)
	v_add_f32_e32 v52, v164, v52
	v_add_f32_e32 v53, v165, v53
	v_add_f32_e32 v54, v166, v54
	v_add_f32_e32 v55, v167, v55
	v_fmac_f32_e32 v204, v52, v52
	v_fmac_f32_e32 v204, v53, v53
	v_fmac_f32_e32 v204, v54, v54
	v_fmac_f32_e32 v204, v55, v55
	ds_write_b128 v188, v[52:55] offset:32
	s_waitcnt lgkmcnt(7)
	v_add_f32_e32 v56, v168, v56
	v_add_f32_e32 v57, v169, v57
	v_add_f32_e32 v58, v170, v58
	v_add_f32_e32 v59, v171, v59
	v_fmac_f32_e32 v204, v56, v56
	v_fmac_f32_e32 v204, v57, v57
	v_fmac_f32_e32 v204, v58, v58
	v_fmac_f32_e32 v204, v59, v59
	ds_write_b128 v188, v[56:59] offset:64
	s_waitcnt lgkmcnt(7)
	v_add_f32_e32 v60, v172, v60
	v_add_f32_e32 v61, v173, v61
	v_add_f32_e32 v62, v174, v62
	v_add_f32_e32 v63, v175, v63
	v_fmac_f32_e32 v204, v60, v60
	v_fmac_f32_e32 v204, v61, v61
	v_fmac_f32_e32 v204, v62, v62
	v_fmac_f32_e32 v204, v63, v63
	ds_write_b128 v188, v[60:63] offset:96
	s_waitcnt lgkmcnt(7)
	v_add_f32_e32 v32, v176, v32
	v_add_f32_e32 v33, v177, v33
	v_add_f32_e32 v34, v178, v34
	v_add_f32_e32 v35, v179, v35
	v_fmac_f32_e32 v204, v32, v32
	v_fmac_f32_e32 v204, v33, v33
	v_fmac_f32_e32 v204, v34, v34
	v_fmac_f32_e32 v204, v35, v35
	ds_write_b128 v188, v[32:35] offset:128
	s_waitcnt lgkmcnt(7)
	v_add_f32_e32 v36, v180, v36
	v_add_f32_e32 v37, v181, v37
	v_add_f32_e32 v38, v182, v38
	v_add_f32_e32 v39, v183, v39
	v_fmac_f32_e32 v204, v36, v36
	v_fmac_f32_e32 v204, v37, v37
	v_fmac_f32_e32 v204, v38, v38
	v_fmac_f32_e32 v204, v39, v39
	ds_write_b128 v188, v[36:39] offset:160
	s_waitcnt lgkmcnt(7)
	v_add_f32_e32 v40, v184, v40
	v_add_f32_e32 v41, v185, v41
	v_add_f32_e32 v42, v186, v42
	v_add_f32_e32 v43, v187, v43
	v_fmac_f32_e32 v204, v40, v40
	v_fmac_f32_e32 v204, v41, v41
	v_fmac_f32_e32 v204, v42, v42
	v_fmac_f32_e32 v204, v43, v43
	ds_write_b128 v188, v[40:43] offset:192
	s_waitcnt lgkmcnt(7)
	v_add_f32_e32 v44, v200, v44
	v_add_f32_e32 v45, v201, v45
	v_add_f32_e32 v46, v202, v46
	v_add_f32_e32 v47, v203, v47
	v_fmac_f32_e32 v204, v44, v44
	v_fmac_f32_e32 v204, v45, v45
	v_fmac_f32_e32 v204, v46, v46
	v_fmac_f32_e32 v204, v47, v47
	ds_write_b128 v188, v[44:47] offset:224
	ds_read_b128 v[160:163], v191
	ds_read_b128 v[164:167], v191 offset:1088
	ds_read_b128 v[168:171], v191 offset:2176
	ds_read_b128 v[172:175], v191 offset:3264
	ds_read_b128 v[176:179], v191 offset:4352
	ds_read_b128 v[180:183], v191 offset:5440
	ds_read_b128 v[184:187], v191 offset:6528
	ds_read_b128 v[200:203], v191 offset:7616
	s_add_u32 s74, s66, 0x20000
	s_addc_u32 s75, s67, 0
	s_waitcnt lgkmcnt(7)
	global_store_dwordx4 v193, v[160:163], s[74:75]  sc1
	s_add_u32 s74, s66, 0x24000
	s_addc_u32 s75, s67, 0
	s_waitcnt lgkmcnt(6)
	global_store_dwordx4 v193, v[164:167], s[74:75]  sc1
	s_add_u32 s74, s66, 0x28000
	s_addc_u32 s75, s67, 0
	s_waitcnt lgkmcnt(5)
	global_store_dwordx4 v193, v[168:171], s[74:75]  sc1
	s_add_u32 s74, s66, 0x2c000
	s_addc_u32 s75, s67, 0
	s_waitcnt lgkmcnt(4)
	global_store_dwordx4 v193, v[172:175], s[74:75]  sc1
	s_add_u32 s74, s66, 0x30000
	s_addc_u32 s75, s67, 0
	s_waitcnt lgkmcnt(3)
	global_store_dwordx4 v193, v[176:179], s[74:75]  sc1
	s_add_u32 s74, s66, 0x34000
	s_addc_u32 s75, s67, 0
	s_waitcnt lgkmcnt(2)
	global_store_dwordx4 v193, v[180:183], s[74:75]  sc1
	s_add_u32 s74, s66, 0x38000
	s_addc_u32 s75, s67, 0
	s_waitcnt lgkmcnt(1)
; DI bfr f2bf(float a) { return (bfr)(pack2(a, 0.f) & 0xffffu); }
; DI int crow(int reg, int h) { return (reg & 3) + 8 * (reg >> 2) + 4 * h; }
; template <bool FIRST, bool HAS_H>
; DI void phase_gemm_resid(const Params& p, const bfr* A, const bfr* Wt, const float* gnext, float* ss, char* smem) {
;     ...
;               xo[jj][q] = xsrc[(rbase + i * 32 + crow(qh * 8 + q, 0)) * 1024 + cbase + (jh * 2 + jj) * 32];
; #pragma unroll
;           for (int q = 0; q < 8; ++q) {
;             const int o = (rbase + i * 32 + crow(qh * 8 + q, 0)) * 1024 + cbase;
; #pragma unroll
;             for (int jj = 0; jj < 2; ++jj) {
;               const int j = jh * 2 + jj;
;               const float xn = xo[jj][q] + acc[i][j][qh * 8 + q];
;               X[o + j * 32] = xn;
;               if (HAS_H) Hn[o + j * 32] = f2bf(xn * gnext[cbase + j * 32]);
;               rs[q] += xn * xn;
;             }
;           }
;         }
	global_store_dwordx4 v193, v[184:187], s[74:75]  sc1
	s_add_u32 s74, s66, 0x3c000
	s_addc_u32 s75, s67, 0
	s_waitcnt lgkmcnt(0)
	global_store_dwordx4 v193, v[200:203], s[74:75]  sc1
	global_load_dwordx4 v[160:163], v198, s[70:71]
	global_load_dwordx4 v[164:167], v198, s[70:71] offset:32
	global_load_dwordx4 v[168:171], v198, s[70:71] offset:64
	global_load_dwordx4 v[172:175], v198, s[70:71] offset:96
	global_load_dwordx4 v[176:179], v198, s[70:71] offset:128
	global_load_dwordx4 v[180:183], v198, s[70:71] offset:160
	global_load_dwordx4 v[184:187], v198, s[70:71] offset:192
	global_load_dwordx4 v[200:203], v198, s[70:71] offset:224
	s_waitcnt vmcnt(7)
	v_mul_f32_e32 v48, v160, v48
	v_mul_f32_e32 v49, v161, v49
	v_mul_f32_e32 v50, v162, v50
	v_mul_f32_e32 v51, v163, v51
	v_cvt_pk_bf16_f32 v48, v48, v49
	v_cvt_pk_bf16_f32 v49, v50, v51
	ds_write_b64 v190, v[48:49]
	s_waitcnt vmcnt(6)
	v_mul_f32_e32 v52, v164, v52
	v_mul_f32_e32 v53, v165, v53
	v_mul_f32_e32 v54, v166, v54
	v_mul_f32_e32 v55, v167, v55
	v_cvt_pk_bf16_f32 v52, v52, v53
	v_cvt_pk_bf16_f32 v53, v54, v55
	ds_write_b64 v190, v[52:53] offset:16
	s_waitcnt vmcnt(5)
	v_mul_f32_e32 v56, v168, v56
	v_mul_f32_e32 v57, v169, v57
	v_mul_f32_e32 v58, v170, v58
	v_mul_f32_e32 v59, v171, v59
	v_cvt_pk_bf16_f32 v56, v56, v57
	v_cvt_pk_bf16_f32 v57, v58, v59
	ds_write_b64 v190, v[56:57] offset:32
	s_waitcnt vmcnt(4)
	v_mul_f32_e32 v60, v172, v60
	v_mul_f32_e32 v61, v173, v61
	v_mul_f32_e32 v62, v174, v62
	v_mul_f32_e32 v63, v175, v63
	v_cvt_pk_bf16_f32 v60, v60, v61
	v_cvt_pk_bf16_f32 v61, v62, v63
	ds_write_b64 v190, v[60:61] offset:48
	s_waitcnt vmcnt(3)
	v_mul_f32_e32 v32, v176, v32
	v_mul_f32_e32 v33, v177, v33
	v_mul_f32_e32 v34, v178, v34
	v_mul_f32_e32 v35, v179, v35
	v_cvt_pk_bf16_f32 v32, v32, v33
	v_cvt_pk_bf16_f32 v33, v34, v35
	ds_write_b64 v190, v[32:33] offset:64
	s_waitcnt vmcnt(2)
	v_mul_f32_e32 v36, v180, v36
	v_mul_f32_e32 v37, v181, v37
	v_mul_f32_e32 v38, v182, v38
	v_mul_f32_e32 v39, v183, v39
	v_cvt_pk_bf16_f32 v36, v36, v37
	v_cvt_pk_bf16_f32 v37, v38, v39
	ds_write_b64 v190, v[36:37] offset:80
	s_waitcnt vmcnt(1)
	v_mul_f32_e32 v40, v184, v40
	v_mul_f32_e32 v41, v185, v41
	v_mul_f32_e32 v42, v186, v42
	v_mul_f32_e32 v43, v187, v43
	v_cvt_pk_bf16_f32 v40, v40, v41
	v_cvt_pk_bf16_f32 v41, v42, v43
	ds_write_b64 v190, v[40:41] offset:96
	s_waitcnt vmcnt(0)
	v_mul_f32_e32 v44, v200, v44
	v_mul_f32_e32 v45, v201, v45
	v_mul_f32_e32 v46, v202, v46
	v_mul_f32_e32 v47, v203, v47
	v_cvt_pk_bf16_f32 v44, v44, v45
	v_cvt_pk_bf16_f32 v45, v46, v47
	ds_write_b64 v190, v[44:45] offset:112
	ds_read_b128 v[160:163], v192
	ds_read_b128 v[164:167], v192 offset:2176
	ds_read_b128 v[168:171], v192 offset:4352
	ds_read_b128 v[172:175], v192 offset:6528
	s_add_u32 s74, s68, 0x10000
	s_addc_u32 s75, s69, 0
	s_waitcnt lgkmcnt(3)
	global_store_dwordx4 v194, v[160:163], s[74:75]  sc1
	s_add_u32 s74, s68, 0x14000
	s_addc_u32 s75, s69, 0
	s_waitcnt lgkmcnt(2)
	global_store_dwordx4 v194, v[164:167], s[74:75]  sc1
	s_add_u32 s74, s68, 0x18000
	s_addc_u32 s75, s69, 0
	s_waitcnt lgkmcnt(1)
	global_store_dwordx4 v194, v[168:171], s[74:75]  sc1
	s_add_u32 s74, s68, 0x1c000
	s_addc_u32 s75, s69, 0
	s_waitcnt lgkmcnt(0)
	global_store_dwordx4 v194, v[172:175], s[74:75]  sc1
	s_waitcnt vmcnt(4)
	ds_write_b128 v191, v[128:131]
	s_waitcnt vmcnt(4)
	ds_write_b128 v191, v[132:135] offset:1088
	s_waitcnt vmcnt(4)
	ds_write_b128 v191, v[136:139] offset:2176
	s_waitcnt vmcnt(4)
	ds_write_b128 v191, v[140:143] offset:3264
	s_waitcnt vmcnt(4)
	ds_write_b128 v191, v[144:147] offset:4352
	s_waitcnt vmcnt(4)
	ds_write_b128 v191, v[148:151] offset:5440
	s_waitcnt vmcnt(4)
	ds_write_b128 v191, v[152:155] offset:6528
	s_waitcnt vmcnt(4)
	ds_write_b128 v191, v[156:159] offset:7616
	ds_read_b128 v[160:163], v188
	ds_read_b128 v[164:167], v188 offset:32
	ds_read_b128 v[168:171], v188 offset:64
	ds_read_b128 v[172:175], v188 offset:96
	ds_read_b128 v[176:179], v188 offset:128
	ds_read_b128 v[180:183], v188 offset:160
	ds_read_b128 v[184:187], v188 offset:192
	ds_read_b128 v[200:203], v188 offset:224
	s_waitcnt lgkmcnt(7)
	v_add_f32_e32 v16, v160, v16
	v_add_f32_e32 v17, v161, v17
	v_add_f32_e32 v18, v162, v18
	v_add_f32_e32 v19, v163, v19
	v_fmac_f32_e32 v204, v16, v16
	v_fmac_f32_e32 v204, v17, v17
	v_fmac_f32_e32 v204, v18, v18
	v_fmac_f32_e32 v204, v19, v19
	ds_write_b128 v188, v[16:19]
	s_waitcnt lgkmcnt(7)
	v_add_f32_e32 v20, v164, v20
	v_add_f32_e32 v21, v165, v21
	v_add_f32_e32 v22, v166, v22
	v_add_f32_e32 v23, v167, v23
	v_fmac_f32_e32 v204, v20, v20
	v_fmac_f32_e32 v204, v21, v21
	v_fmac_f32_e32 v204, v22, v22
	v_fmac_f32_e32 v204, v23, v23
	ds_write_b128 v188, v[20:23] offset:32
	s_waitcnt lgkmcnt(7)
	v_add_f32_e32 v24, v168, v24
	v_add_f32_e32 v25, v169, v25
	v_add_f32_e32 v26, v170, v26
	v_add_f32_e32 v27, v171, v27
	v_fmac_f32_e32 v204, v24, v24
	v_fmac_f32_e32 v204, v25, v25
	v_fmac_f32_e32 v204, v26, v26
	v_fmac_f32_e32 v204, v27, v27
	ds_write_b128 v188, v[24:27] offset:64
	s_waitcnt lgkmcnt(7)
	v_add_f32_e32 v28, v172, v28
	v_add_f32_e32 v29, v173, v29
	v_add_f32_e32 v30, v174, v30
	v_add_f32_e32 v31, v175, v31
	v_fmac_f32_e32 v204, v28, v28
	v_fmac_f32_e32 v204, v29, v29
	v_fmac_f32_e32 v204, v30, v30
	v_fmac_f32_e32 v204, v31, v31
	ds_write_b128 v188, v[28:31] offset:96
	s_waitcnt lgkmcnt(7)
	v_add_f32_e32 v0, v176, v0
	v_add_f32_e32 v1, v177, v1
	v_add_f32_e32 v2, v178, v2
	v_add_f32_e32 v3, v179, v3
	v_fmac_f32_e32 v204, v0, v0
	v_fmac_f32_e32 v204, v1, v1
	v_fmac_f32_e32 v204, v2, v2
	v_fmac_f32_e32 v204, v3, v3
	ds_write_b128 v188, v[0:3] offset:128
	s_waitcnt lgkmcnt(7)
; DI bfr f2bf(float a) { return (bfr)(pack2(a, 0.f) & 0xffffu); }
; DI int crow(int reg, int h) { return (reg & 3) + 8 * (reg >> 2) + 4 * h; }
; template <bool FIRST, bool HAS_H>
; DI void phase_gemm_resid(const Params& p, const bfr* A, const bfr* Wt, const float* gnext, float* ss, char* smem) {
;     ...
;           for (int q = 0; q < 8; ++q) {
;             const int o = (rbase + i * 32 + crow(qh * 8 + q, 0)) * 1024 + cbase;
; #pragma unroll
;             for (int jj = 0; jj < 2; ++jj) {
;               const int j = jh * 2 + jj;
;               const float xn = xo[jj][q] + acc[i][j][qh * 8 + q];
;               X[o + j * 32] = xn;
;               if (HAS_H) Hn[o + j * 32] = f2bf(xn * gnext[cbase + j * 32]);
;               rs[q] += xn * xn;
;             }
;           }
;         }
; #pragma unroll
;         for (int q = 0; q < 8; ++q) rs[q] = half32_sum_hi(rs[q]);
;         if (r == 31) {
; #pragma unroll
;           for (int q = 0; q < 8; ++q) unsafeAtomicAdd(ss + rbase + i * 32 + crow(qh * 8 + q, 0), rs[q]);
;         }
	v_add_f32_e32 v4, v180, v4
	v_add_f32_e32 v5, v181, v5
	v_add_f32_e32 v6, v182, v6
	v_add_f32_e32 v7, v183, v7
	v_fmac_f32_e32 v204, v4, v4
	v_fmac_f32_e32 v204, v5, v5
	v_fmac_f32_e32 v204, v6, v6
	v_fmac_f32_e32 v204, v7, v7
	ds_write_b128 v188, v[4:7] offset:160
	s_waitcnt lgkmcnt(7)
	v_add_f32_e32 v8, v184, v8
	v_add_f32_e32 v9, v185, v9
	v_add_f32_e32 v10, v186, v10
	v_add_f32_e32 v11, v187, v11
	v_fmac_f32_e32 v204, v8, v8
	v_fmac_f32_e32 v204, v9, v9
	v_fmac_f32_e32 v204, v10, v10
	v_fmac_f32_e32 v204, v11, v11
	ds_write_b128 v188, v[8:11] offset:192
	s_waitcnt lgkmcnt(7)
	v_add_f32_e32 v12, v200, v12
	v_add_f32_e32 v13, v201, v13
	v_add_f32_e32 v14, v202, v14
	v_add_f32_e32 v15, v203, v15
	v_fmac_f32_e32 v204, v12, v12
	v_fmac_f32_e32 v204, v13, v13
	v_fmac_f32_e32 v204, v14, v14
	v_fmac_f32_e32 v204, v15, v15
	ds_write_b128 v188, v[12:15] offset:224
	ds_read_b128 v[160:163], v191
	ds_read_b128 v[164:167], v191 offset:1088
	ds_read_b128 v[168:171], v191 offset:2176
	ds_read_b128 v[172:175], v191 offset:3264
	ds_read_b128 v[176:179], v191 offset:4352
	ds_read_b128 v[180:183], v191 offset:5440
	ds_read_b128 v[184:187], v191 offset:6528
	ds_read_b128 v[200:203], v191 offset:7616
	s_add_u32 s74, s66, 0x20100
	s_addc_u32 s75, s67, 0
	s_waitcnt lgkmcnt(7)
	global_store_dwordx4 v193, v[160:163], s[74:75]  sc1
	s_add_u32 s74, s66, 0x24100
	s_addc_u32 s75, s67, 0
	s_waitcnt lgkmcnt(6)
	global_store_dwordx4 v193, v[164:167], s[74:75]  sc1
	s_add_u32 s74, s66, 0x28100
	s_addc_u32 s75, s67, 0
	s_waitcnt lgkmcnt(5)
	global_store_dwordx4 v193, v[168:171], s[74:75]  sc1
	s_add_u32 s74, s66, 0x2c100
	s_addc_u32 s75, s67, 0
	s_waitcnt lgkmcnt(4)
	global_store_dwordx4 v193, v[172:175], s[74:75]  sc1
	s_add_u32 s74, s66, 0x30100
	s_addc_u32 s75, s67, 0
	s_waitcnt lgkmcnt(3)
	global_store_dwordx4 v193, v[176:179], s[74:75]  sc1
	s_add_u32 s74, s66, 0x34100
	s_addc_u32 s75, s67, 0
	s_waitcnt lgkmcnt(2)
	global_store_dwordx4 v193, v[180:183], s[74:75]  sc1
	s_add_u32 s74, s66, 0x38100
	s_addc_u32 s75, s67, 0
	s_waitcnt lgkmcnt(1)
	global_store_dwordx4 v193, v[184:187], s[74:75]  sc1
	s_add_u32 s74, s66, 0x3c100
	s_addc_u32 s75, s67, 0
	s_waitcnt lgkmcnt(0)
	global_store_dwordx4 v193, v[200:203], s[74:75]  sc1
	global_load_dwordx4 v[160:163], v198, s[70:71] offset:256
	global_load_dwordx4 v[164:167], v198, s[70:71] offset:288
	global_load_dwordx4 v[168:171], v198, s[70:71] offset:320
	global_load_dwordx4 v[172:175], v198, s[70:71] offset:352
	global_load_dwordx4 v[176:179], v198, s[70:71] offset:384
	global_load_dwordx4 v[180:183], v198, s[70:71] offset:416
	global_load_dwordx4 v[184:187], v198, s[70:71] offset:448
	global_load_dwordx4 v[200:203], v198, s[70:71] offset:480
	s_waitcnt vmcnt(7)
	v_mul_f32_e32 v16, v160, v16
	v_mul_f32_e32 v17, v161, v17
	v_mul_f32_e32 v18, v162, v18
	v_mul_f32_e32 v19, v163, v19
	v_cvt_pk_bf16_f32 v16, v16, v17
	v_cvt_pk_bf16_f32 v17, v18, v19
	ds_write_b64 v190, v[16:17]
	s_waitcnt vmcnt(6)
	v_mul_f32_e32 v20, v164, v20
	v_mul_f32_e32 v21, v165, v21
	v_mul_f32_e32 v22, v166, v22
	v_mul_f32_e32 v23, v167, v23
	v_cvt_pk_bf16_f32 v20, v20, v21
	v_cvt_pk_bf16_f32 v21, v22, v23
	ds_write_b64 v190, v[20:21] offset:16
	s_waitcnt vmcnt(5)
	v_mul_f32_e32 v24, v168, v24
	v_mul_f32_e32 v25, v169, v25
	v_mul_f32_e32 v26, v170, v26
	v_mul_f32_e32 v27, v171, v27
	v_cvt_pk_bf16_f32 v24, v24, v25
	v_cvt_pk_bf16_f32 v25, v26, v27
	ds_write_b64 v190, v[24:25] offset:32
	s_waitcnt vmcnt(4)
	v_mul_f32_e32 v28, v172, v28
	v_mul_f32_e32 v29, v173, v29
	v_mul_f32_e32 v30, v174, v30
	v_mul_f32_e32 v31, v175, v31
	v_cvt_pk_bf16_f32 v28, v28, v29
	v_cvt_pk_bf16_f32 v29, v30, v31
	ds_write_b64 v190, v[28:29] offset:48
	s_waitcnt vmcnt(3)
	v_mul_f32_e32 v0, v176, v0
	v_mul_f32_e32 v1, v177, v1
	v_mul_f32_e32 v2, v178, v2
	v_mul_f32_e32 v3, v179, v3
	v_cvt_pk_bf16_f32 v0, v0, v1
	v_cvt_pk_bf16_f32 v1, v2, v3
	ds_write_b64 v190, v[0:1] offset:64
	s_waitcnt vmcnt(2)
	v_mul_f32_e32 v4, v180, v4
	v_mul_f32_e32 v5, v181, v5
	v_mul_f32_e32 v6, v182, v6
	v_mul_f32_e32 v7, v183, v7
	v_cvt_pk_bf16_f32 v4, v4, v5
	v_cvt_pk_bf16_f32 v5, v6, v7
	ds_write_b64 v190, v[4:5] offset:80
	s_waitcnt vmcnt(1)
	v_mul_f32_e32 v8, v184, v8
	v_mul_f32_e32 v9, v185, v9
	v_mul_f32_e32 v10, v186, v10
	v_mul_f32_e32 v11, v187, v11
	v_cvt_pk_bf16_f32 v8, v8, v9
	v_cvt_pk_bf16_f32 v9, v10, v11
	ds_write_b64 v190, v[8:9] offset:96
	s_waitcnt vmcnt(0)
	v_mul_f32_e32 v12, v200, v12
	v_mul_f32_e32 v13, v201, v13
	v_mul_f32_e32 v14, v202, v14
	v_mul_f32_e32 v15, v203, v15
	v_cvt_pk_bf16_f32 v12, v12, v13
	v_cvt_pk_bf16_f32 v13, v14, v15
	ds_write_b64 v190, v[12:13] offset:112
	ds_read_b128 v[160:163], v192
	ds_read_b128 v[164:167], v192 offset:2176
	ds_read_b128 v[168:171], v192 offset:4352
	ds_read_b128 v[172:175], v192 offset:6528
	s_add_u32 s74, s68, 0x10080
	s_addc_u32 s75, s69, 0
	s_waitcnt lgkmcnt(3)
	global_store_dwordx4 v194, v[160:163], s[74:75]  sc1
	s_add_u32 s74, s68, 0x14080
	s_addc_u32 s75, s69, 0
	s_waitcnt lgkmcnt(2)
	global_store_dwordx4 v194, v[164:167], s[74:75]  sc1
	s_add_u32 s74, s68, 0x18080
	s_addc_u32 s75, s69, 0
	s_waitcnt lgkmcnt(1)
	global_store_dwordx4 v194, v[168:171], s[74:75]  sc1
	s_add_u32 s74, s68, 0x1c080
	s_addc_u32 s75, s69, 0
	s_waitcnt lgkmcnt(0)
	global_store_dwordx4 v194, v[172:175], s[74:75]  sc1
	s_load_dwordx2 s[64:65], s[92:93], 0x140
	ds_bpermute_b32 v208, v206, v199
	ds_bpermute_b32 v209, v206, v204
	s_waitcnt lgkmcnt(0)
	v_add_f32_e32 v208, v208, v199
	v_add_f32_e32 v209, v209, v204
	s_mov_b32 exec_hi, 0
	s_nop 1
	global_atomic_add_f32 v205, v208, s[64:65]
	global_atomic_add_f32 v205, v209, s[64:65] offset:128
	s_mov_b64 exec, -1
	v_readlane_b32 s64, v207, 0
	v_readlane_b32 s65, v207, 1
	v_readlane_b32 s66, v207, 2
	v_readlane_b32 s67, v207, 3
	v_readlane_b32 s68, v207, 4
	v_readlane_b32 s69, v207, 5
	v_readlane_b32 s70, v207, 6
	v_readlane_b32 s71, v207, 7
	v_readlane_b32 s72, v207, 8
	v_readlane_b32 s73, v207, 9
	v_readlane_b32 s74, v207, 10
	v_readlane_b32 s75, v207, 11
	v_readlane_b32 s76, v207, 12
	v_readlane_b32 s77, v207, 13
	v_readlane_b32 s78, v207, 14
	v_readlane_b32 s79, v207, 15
	s_nop 7
	s_branch .LBB0_840

; #define MFMA32(a, b, c) __builtin_amdgcn_mfma_f32_32x32x16_bf16((a), (b), (c), 0, 0, 0)
; #define GA_LOAD(pr_) do { _Pragma("unroll") for (int i = 0; i < 4; ++i) ra[i] = *(const u32x4*)(Ab + (i * 32) * lda + (pr_) * 64); } while (0)
; #define GB_LOAD(kt_) do { const bfr* bk_ = Bb + (kt_) * NB * 32; \
;     _Pragma("unroll") for (int i = 0; i < 4; ++i) rb[i] = *(const u32x4*)(bk_ + (i * 64) * 32); } while (0)
; #define G_STORE(kt_) do { bfr* as_ = S0 + ((kt_) & 1) * GSTAGE; bfr* bs_ = as_ + 128 * 40; \
;     if (apar == ((kt_) & 1)) { _Pragma("unroll") for (int i = 0; i < 4; ++i) *(u32x4*)(as_ + asoff + i * 32 * 40) = ra[i]; } \
;     _Pragma("unroll") for (int i = 0; i < 4; ++i) *(u32x4*)(bs_ + bsoff + i * 64 * 40) = rb[i]; } while (0)
; template <int lda>
; DI void gemm_mainloop(const bfr* __restrict__ A, const bfr* __restrict__ Bt, int NB, int K, int m0, int n0, char* smem, f32x16 (&acc)[2][4]) {
;     ...
;   for (int kt = 0; kt < nk; ++kt) {
;     if (kt + 1 < nk) G_STORE(kt + 1);
;     if (kt + 2 < nk) {
;       GB_LOAD(kt + 2);
;       if ((kt & 1) == 0) GA_LOAD((kt >> 1) + 1);
;     }
;     const bfr* As = S0 + (kt & 1) * GSTAGE;
;     const bfr* Bs = As + 128 * 40;
; #pragma unroll
;     for (int ks = 0; ks < 2; ++ks) {
;       bf16x8 af[2], bfg[4];
; #pragma unroll
;       for (int i = 0; i < 2; ++i) af[i] = *(const bf16x8*)(As + (wr * 64 + i * 32 + r) * 40 + ks * 16 + hl * 8);
; #pragma unroll
;       for (int j = 0; j < 4; ++j) bfg[j] = *(const bf16x8*)(Bs + (wc * 128 + j * 32 + r) * 40 + ks * 16 + hl * 8);
; #pragma unroll
;       for (int i = 0; i < 2; ++i)
; #pragma unroll
;         for (int j = 0; j < 4; ++j) acc[i][j] = MFMA32(af[i], bfg[j], acc[i][j]);
;     }
;     __syncthreads();
.Lp8_loop:
	s_waitcnt vmcnt(6) lgkmcnt(0)
	s_barrier
	s_mul_i32 s74, s71, 0x6000
	s_add_u32 s75, s74, 0x2000
	s_cmp_eq_u32 s71, 2
	s_cselect_b32 s75, 0x10000, s75
	v_add_u32_e32 v183, s74, v179
	v_add_u32_e32 v185, s75, v181
	v_add_u32_e32 v184, s74, v180
	v_add_u32_e32 v186, s75, v182
	s_add_u32 s71, s71, 1
	s_cmp_eq_u32 s71, 3
	s_cselect_b32 s71, 0, s71
	ds_read_b128 v[128:131], v183
	ds_read_b128 v[144:147], v185
	ds_read_b128 v[148:151], v185 offset:2048
	ds_read_b128 v[152:155], v185 offset:4096
	ds_read_b128 v[156:159], v185 offset:6144
	ds_read_b128 v[132:135], v183 offset:2048
	v_mfma_f32_32x32x16_bf16 v[112:127], v[160:163], v[136:139], v[112:127]
	s_mul_i32 s74, s70, 0x6000
	s_add_u32 s75, s74, s68
	s_mov_b32 m0, s75
	s_add_u32 s76, s74, 0x2000
	s_cmp_eq_u32 s70, 2
	s_cselect_b32 s76, 0x10000, s76
	global_load_lds_dwordx4 v176, s[64:65]
	v_mfma_f32_32x32x16_bf16 v[96:111], v[164:167], v[136:139], v[96:111]
	s_add_u32 m0, s75, 0x400
	s_add_u32 s76, s76, s69
	global_load_lds_dwordx4 v177, s[64:65]
	v_mfma_f32_32x32x16_bf16 v[80:95], v[168:171], v[136:139], v[80:95]
	s_mov_b32 m0, s76
	s_add_u32 s64, s64, 64
	s_addc_u32 s65, s65, 0
	global_load_lds_dwordx4 v178, s[66:67]
	v_mfma_f32_32x32x16_bf16 v[64:79], v[172:175], v[136:139], v[64:79]
	global_load_lds_dwordx4 v178, s[66:67] offset:1024
	v_mfma_f32_32x32x16_bf16 v[48:63], v[160:163], v[140:143], v[48:63]
	global_load_lds_dwordx4 v178, s[66:67] offset:2048
	v_mfma_f32_32x32x16_bf16 v[32:47], v[164:167], v[140:143], v[32:47]
	global_load_lds_dwordx4 v178, s[66:67] offset:3072
	s_add_u32 s66, s66, 0x10000
	s_addc_u32 s67, s67, 0
	v_mfma_f32_32x32x16_bf16 v[16:31], v[168:171], v[140:143], v[16:31]
	s_add_u32 s70, s70, 1
	s_cmp_eq_u32 s70, 3
	s_cselect_b32 s70, 0, s70
	v_mfma_f32_32x32x16_bf16 v[0:15], v[172:175], v[140:143], v[0:15]
	ds_read_b128 v[136:139], v184
	ds_read_b128 v[160:163], v186
	ds_read_b128 v[164:167], v186 offset:2048
	ds_read_b128 v[168:171], v186 offset:4096
	ds_read_b128 v[172:175], v186 offset:6144
	ds_read_b128 v[140:143], v184 offset:2048
	s_waitcnt lgkmcnt(10)
	v_mfma_f32_32x32x16_bf16 v[112:127], v[144:147], v[128:131], v[112:127]
	s_waitcnt lgkmcnt(9)
	v_mfma_f32_32x32x16_bf16 v[96:111], v[148:151], v[128:131], v[96:111]
	s_waitcnt lgkmcnt(8)
	v_mfma_f32_32x32x16_bf16 v[80:95], v[152:155], v[128:131], v[80:95]
	s_waitcnt lgkmcnt(7)
	v_mfma_f32_32x32x16_bf16 v[64:79], v[156:159], v[128:131], v[64:79]
	s_waitcnt lgkmcnt(6)
	v_mfma_f32_32x32x16_bf16 v[48:63], v[144:147], v[132:135], v[48:63]
	v_mfma_f32_32x32x16_bf16 v[32:47], v[148:151], v[132:135], v[32:47]
	v_mfma_f32_32x32x16_bf16 v[16:31], v[152:155], v[132:135], v[16:31]
	v_mfma_f32_32x32x16_bf16 v[0:15], v[156:159], v[132:135], v[0:15]
	s_add_u32 s72, s72, 1
	s_cmp_lt_u32 s72, 29
	s_cbranch_scc1 .Lp8_loop
	s_waitcnt vmcnt(6) lgkmcnt(0)
	s_barrier
	s_mul_i32 s74, s71, 0x6000
	s_add_u32 s75, s74, 0x2000
	s_cmp_eq_u32 s71, 2
	s_cselect_b32 s75, 0x10000, s75
	v_add_u32_e32 v183, s74, v179
	v_add_u32_e32 v185, s75, v181
	v_add_u32_e32 v184, s74, v180
	v_add_u32_e32 v186, s75, v182
	s_add_u32 s71, s71, 1
	s_cmp_eq_u32 s71, 3
	s_cselect_b32 s71, 0, s71
	ds_read_b128 v[128:131], v183
	ds_read_b128 v[144:147], v185
	ds_read_b128 v[148:151], v185 offset:2048
	ds_read_b128 v[152:155], v185 offset:4096
	ds_read_b128 v[156:159], v185 offset:6144
	ds_read_b128 v[132:135], v183 offset:2048
	v_mfma_f32_32x32x16_bf16 v[112:127], v[160:163], v[136:139], v[112:127]
	v_mfma_f32_32x32x16_bf16 v[96:111], v[164:167], v[136:139], v[96:111]
	v_mfma_f32_32x32x16_bf16 v[80:95], v[168:171], v[136:139], v[80:95]
	v_mfma_f32_32x32x16_bf16 v[64:79], v[172:175], v[136:139], v[64:79]
	v_mfma_f32_32x32x16_bf16 v[48:63], v[160:163], v[140:143], v[48:63]
	v_mfma_f32_32x32x16_bf16 v[32:47], v[164:167], v[140:143], v[32:47]
	v_mfma_f32_32x32x16_bf16 v[16:31], v[168:171], v[140:143], v[16:31]
	v_mfma_f32_32x32x16_bf16 v[0:15], v[172:175], v[140:143], v[0:15]
	ds_read_b128 v[136:139], v184
	ds_read_b128 v[160:163], v186
	ds_read_b128 v[164:167], v186 offset:2048
	ds_read_b128 v[168:171], v186 offset:4096
	ds_read_b128 v[172:175], v186 offset:6144
	ds_read_b128 v[140:143], v184 offset:2048
	s_waitcnt lgkmcnt(10)
	v_mfma_f32_32x32x16_bf16 v[112:127], v[144:147], v[128:131], v[112:127]
	s_waitcnt lgkmcnt(9)
	v_mfma_f32_32x32x16_bf16 v[96:111], v[148:151], v[128:131], v[96:111]
	s_waitcnt lgkmcnt(8)
	v_mfma_f32_32x32x16_bf16 v[80:95], v[152:155], v[128:131], v[80:95]
	s_waitcnt lgkmcnt(7)
	v_mfma_f32_32x32x16_bf16 v[64:79], v[156:159], v[128:131], v[64:79]
	s_waitcnt lgkmcnt(6)
	v_mfma_f32_32x32x16_bf16 v[48:63], v[144:147], v[132:135], v[48:63]
	v_mfma_f32_32x32x16_bf16 v[32:47], v[148:151], v[132:135], v[32:47]
	v_mfma_f32_32x32x16_bf16 v[16:31], v[152:155], v[132:135], v[16:31]
	v_mfma_f32_32x32x16_bf16 v[0:15], v[156:159], v[132:135], v[0:15]
	s_waitcnt vmcnt(0) lgkmcnt(0)
	s_barrier
; DI bfr f2bf(float a) { return (bfr)(pack2(a, 0.f) & 0xffffu); }
; DI int crow(int reg, int h) { return (reg & 3) + 8 * (reg >> 2) + 4 * h; }
; template <int lda, class Epi>
; DI void gemm_tile(const bfr* __restrict__ A, const bfr* __restrict__ Bt, int NB, int K, int m0, int n0, char* smem, Epi epi) {
;     ...
; #pragma unroll
;   for (int i = 0; i < 2; ++i)
; #pragma unroll
;     for (int j = 0; j < 4; ++j)
; #pragma unroll
;       for (int q = 0; q < 16; ++q) {
;         int row = m0 + wr * 64 + i * 32 + crow(q, hl);
;         int col = n0 + wc * 128 + j * 32 + r;
;         epi(row, col, acc[i][j][q]);
;       }
; DI void phase_gemm_bf16out(const Params& p, const bfr* A, const bfr* Wt, bfr* C, int N, const float* ss, char* smem) {
;     ...
;     gemm_tile<1024>(A, Wt, N, 1024, mt * 128, nt * 256, smem,
;               [=](int row, int col, float v) {
;                 float inv = rsqrtf(ss[row] * (1.0f / 1024.0f) + EPSF);
;                 C[(size_t)row * N + col] = f2bf(v * inv);
;               });
	s_mul_i32 s74, s71, 0x6000
	s_add_u32 s75, s74, 0x2000
	s_cmp_eq_u32 s71, 2
	s_cselect_b32 s75, 0x10000, s75
	v_add_u32_e32 v183, s74, v179
	v_add_u32_e32 v185, s75, v181
	v_add_u32_e32 v184, s74, v180
	v_add_u32_e32 v186, s75, v182
	s_add_u32 s71, s71, 1
	s_cmp_eq_u32 s71, 3
	s_cselect_b32 s71, 0, s71
	ds_read_b128 v[128:131], v183
	ds_read_b128 v[144:147], v185
	ds_read_b128 v[148:151], v185 offset:2048
	ds_read_b128 v[152:155], v185 offset:4096
	ds_read_b128 v[156:159], v185 offset:6144
	ds_read_b128 v[132:135], v183 offset:2048
	v_mfma_f32_32x32x16_bf16 v[112:127], v[160:163], v[136:139], v[112:127]
	v_mfma_f32_32x32x16_bf16 v[96:111], v[164:167], v[136:139], v[96:111]
	v_mfma_f32_32x32x16_bf16 v[80:95], v[168:171], v[136:139], v[80:95]
	v_mfma_f32_32x32x16_bf16 v[64:79], v[172:175], v[136:139], v[64:79]
	v_mfma_f32_32x32x16_bf16 v[48:63], v[160:163], v[140:143], v[48:63]
	v_mfma_f32_32x32x16_bf16 v[32:47], v[164:167], v[140:143], v[32:47]
	v_mfma_f32_32x32x16_bf16 v[16:31], v[168:171], v[140:143], v[16:31]
	v_mfma_f32_32x32x16_bf16 v[0:15], v[172:175], v[140:143], v[0:15]
	ds_read_b128 v[136:139], v184
	ds_read_b128 v[160:163], v186
	ds_read_b128 v[164:167], v186 offset:2048
	ds_read_b128 v[168:171], v186 offset:4096
	ds_read_b128 v[172:175], v186 offset:6144
	ds_read_b128 v[140:143], v184 offset:2048
	s_waitcnt lgkmcnt(10)
	v_mfma_f32_32x32x16_bf16 v[112:127], v[144:147], v[128:131], v[112:127]
	s_waitcnt lgkmcnt(9)
	v_mfma_f32_32x32x16_bf16 v[96:111], v[148:151], v[128:131], v[96:111]
	s_waitcnt lgkmcnt(8)
	v_mfma_f32_32x32x16_bf16 v[80:95], v[152:155], v[128:131], v[80:95]
	s_waitcnt lgkmcnt(7)
	v_mfma_f32_32x32x16_bf16 v[64:79], v[156:159], v[128:131], v[64:79]
	s_waitcnt lgkmcnt(6)
	v_mfma_f32_32x32x16_bf16 v[48:63], v[144:147], v[132:135], v[48:63]
	v_mfma_f32_32x32x16_bf16 v[32:47], v[148:151], v[132:135], v[32:47]
	v_mfma_f32_32x32x16_bf16 v[16:31], v[152:155], v[132:135], v[16:31]
	v_mfma_f32_32x32x16_bf16 v[0:15], v[156:159], v[132:135], v[0:15]
	s_waitcnt lgkmcnt(0)
	v_mfma_f32_32x32x16_bf16 v[112:127], v[160:163], v[136:139], v[112:127]
	v_mfma_f32_32x32x16_bf16 v[96:111], v[164:167], v[136:139], v[96:111]
	v_mfma_f32_32x32x16_bf16 v[80:95], v[168:171], v[136:139], v[80:95]
	v_mfma_f32_32x32x16_bf16 v[64:79], v[172:175], v[136:139], v[64:79]
	v_mfma_f32_32x32x16_bf16 v[48:63], v[160:163], v[140:143], v[48:63]
	v_mfma_f32_32x32x16_bf16 v[32:47], v[164:167], v[140:143], v[32:47]
	v_mfma_f32_32x32x16_bf16 v[16:31], v[168:171], v[140:143], v[16:31]
	v_mfma_f32_32x32x16_bf16 v[0:15], v[172:175], v[140:143], v[0:15]
	s_nop 7
	s_nop 3
	s_barrier
	s_load_dwordx2 s[64:65], s[92:93], 0x160
	s_load_dwordx2 s[66:67], s[92:93], 0x140
	v_and_b32_e32 v176, 31, v196
	v_bfe_u32 v177, v196, 5, 1
	s_lshr_b32 s74, s73, 1
	s_lshl_b32 s74, s74, 6
	s_add_u32 s74, s74, s77
	v_add_u32_e32 v178, s74, v176
	s_mul_i32 s76, s73, 8704
	v_mul_u32_u24_e32 v180, 272, v176
	v_lshl_add_u32 v180, v177, 3, v180
	v_add_u32_e32 v180, s76, v180
	v_bfe_u32 v185, v196, 4, 2
	v_and_b32_e32 v186, 15, v196
	v_mul_u32_u24_e32 v181, 272, v185
	v_lshl_add_u32 v181, v186, 4, v181
	v_add_u32_e32 v181, s76, v181
	s_and_b32 s75, s73, 1
	s_lshl_b32 s75, s75, 7
	s_add_u32 s75, s75, s78
	v_add_u32_e32 v179, s74, v185
	v_mul_u32_u24_e32 v179, 0x400, v179
	v_lshl_add_u32 v179, v186, 3, v179
	v_add_lshl_u32 v182, v179, s75, 1
	s_waitcnt lgkmcnt(0)
	v_lshlrev_b32_e32 v179, 2, v178
	global_load_dword v183, v179, s[66:67]
	global_load_dword v184, v179, s[66:67] offset:128
	s_waitcnt vmcnt(0)
	v_mul_f32_e32 v183, 0x3a800000, v183
	v_mul_f32_e32 v184, 0x3a800000, v184
	v_add_f32_e32 v183, 0x358637bd, v183
	v_add_f32_e32 v184, 0x358637bd, v184
	v_rsq_f32_e32 v183, v183
	v_rsq_f32_e32 v184, v184
	s_nop 1
	v_mul_f32_e32 v112, v183, v112
	v_mul_f32_e32 v113, v183, v113
	v_mul_f32_e32 v114, v183, v114
	v_mul_f32_e32 v115, v183, v115
	v_cvt_pk_bf16_f32 v112, v112, v113
	v_cvt_pk_bf16_f32 v113, v114, v115
	ds_write_b64 v180, v[112:113]
	v_mul_f32_e32 v116, v183, v116
	v_mul_f32_e32 v117, v183, v117
	v_mul_f32_e32 v118, v183, v118
	v_mul_f32_e32 v119, v183, v119
	v_cvt_pk_bf16_f32 v116, v116, v117
	v_cvt_pk_bf16_f32 v117, v118, v119
	ds_write_b64 v180, v[116:117] offset:16
	v_mul_f32_e32 v120, v183, v120
	v_mul_f32_e32 v121, v183, v121
	v_mul_f32_e32 v122, v183, v122
	v_mul_f32_e32 v123, v183, v123
	v_cvt_pk_bf16_f32 v120, v120, v121
	v_cvt_pk_bf16_f32 v121, v122, v123
	ds_write_b64 v180, v[120:121] offset:32
	v_mul_f32_e32 v124, v183, v124
	v_mul_f32_e32 v125, v183, v125
	v_mul_f32_e32 v126, v183, v126
	v_mul_f32_e32 v127, v183, v127
	v_cvt_pk_bf16_f32 v124, v124, v125
	v_cvt_pk_bf16_f32 v125, v126, v127
	ds_write_b64 v180, v[124:125] offset:48
	v_mul_f32_e32 v96, v183, v96
	v_mul_f32_e32 v97, v183, v97
	v_mul_f32_e32 v98, v183, v98
	v_mul_f32_e32 v99, v183, v99
	v_cvt_pk_bf16_f32 v96, v96, v97
	v_cvt_pk_bf16_f32 v97, v98, v99
	ds_write_b64 v180, v[96:97] offset:64
	v_mul_f32_e32 v100, v183, v100
	v_mul_f32_e32 v101, v183, v101
	v_mul_f32_e32 v102, v183, v102
	v_mul_f32_e32 v103, v183, v103
	v_cvt_pk_bf16_f32 v100, v100, v101
	v_cvt_pk_bf16_f32 v101, v102, v103
	ds_write_b64 v180, v[100:101] offset:80
	v_mul_f32_e32 v104, v183, v104
	v_mul_f32_e32 v105, v183, v105
	v_mul_f32_e32 v106, v183, v106
	v_mul_f32_e32 v107, v183, v107
	v_cvt_pk_bf16_f32 v104, v104, v105
	v_cvt_pk_bf16_f32 v105, v106, v107
	ds_write_b64 v180, v[104:105] offset:96
	v_mul_f32_e32 v108, v183, v108
	v_mul_f32_e32 v109, v183, v109
	v_mul_f32_e32 v110, v183, v110
	v_mul_f32_e32 v111, v183, v111
	v_cvt_pk_bf16_f32 v108, v108, v109
	v_cvt_pk_bf16_f32 v109, v110, v111
	ds_write_b64 v180, v[108:109] offset:112
; DI bfr f2bf(float a) { return (bfr)(pack2(a, 0.f) & 0xffffu); }
; DI int crow(int reg, int h) { return (reg & 3) + 8 * (reg >> 2) + 4 * h; }
; template <int lda, class Epi>
; DI void gemm_tile(const bfr* __restrict__ A, const bfr* __restrict__ Bt, int NB, int K, int m0, int n0, char* smem, Epi epi) {
;     ...
; #pragma unroll
;   for (int i = 0; i < 2; ++i)
; #pragma unroll
;     for (int j = 0; j < 4; ++j)
; #pragma unroll
;       for (int q = 0; q < 16; ++q) {
;         int row = m0 + wr * 64 + i * 32 + crow(q, hl);
;         int col = n0 + wc * 128 + j * 32 + r;
;         epi(row, col, acc[i][j][q]);
;       }
; DI void phase_gemm_bf16out(const Params& p, const bfr* A, const bfr* Wt, bfr* C, int N, const float* ss, char* smem) {
;     ...
;     gemm_tile<1024>(A, Wt, N, 1024, mt * 128, nt * 256, smem,
;               [=](int row, int col, float v) {
;                 float inv = rsqrtf(ss[row] * (1.0f / 1024.0f) + EPSF);
;                 C[(size_t)row * N + col] = f2bf(v * inv);
;               });
	v_mul_f32_e32 v80, v183, v80
	v_mul_f32_e32 v81, v183, v81
	v_mul_f32_e32 v82, v183, v82
	v_mul_f32_e32 v83, v183, v83
	v_cvt_pk_bf16_f32 v80, v80, v81
	v_cvt_pk_bf16_f32 v81, v82, v83
	ds_write_b64 v180, v[80:81] offset:128
	v_mul_f32_e32 v84, v183, v84
	v_mul_f32_e32 v85, v183, v85
	v_mul_f32_e32 v86, v183, v86
	v_mul_f32_e32 v87, v183, v87
	v_cvt_pk_bf16_f32 v84, v84, v85
	v_cvt_pk_bf16_f32 v85, v86, v87
	ds_write_b64 v180, v[84:85] offset:144
	v_mul_f32_e32 v88, v183, v88
	v_mul_f32_e32 v89, v183, v89
	v_mul_f32_e32 v90, v183, v90
	v_mul_f32_e32 v91, v183, v91
	v_cvt_pk_bf16_f32 v88, v88, v89
	v_cvt_pk_bf16_f32 v89, v90, v91
	ds_write_b64 v180, v[88:89] offset:160
	v_mul_f32_e32 v92, v183, v92
	v_mul_f32_e32 v93, v183, v93
	v_mul_f32_e32 v94, v183, v94
	v_mul_f32_e32 v95, v183, v95
	v_cvt_pk_bf16_f32 v92, v92, v93
	v_cvt_pk_bf16_f32 v93, v94, v95
	ds_write_b64 v180, v[92:93] offset:176
	v_mul_f32_e32 v64, v183, v64
	v_mul_f32_e32 v65, v183, v65
	v_mul_f32_e32 v66, v183, v66
	v_mul_f32_e32 v67, v183, v67
	v_cvt_pk_bf16_f32 v64, v64, v65
	v_cvt_pk_bf16_f32 v65, v66, v67
	ds_write_b64 v180, v[64:65] offset:192
	v_mul_f32_e32 v68, v183, v68
	v_mul_f32_e32 v69, v183, v69
	v_mul_f32_e32 v70, v183, v70
	v_mul_f32_e32 v71, v183, v71
	v_cvt_pk_bf16_f32 v68, v68, v69
	v_cvt_pk_bf16_f32 v69, v70, v71
	ds_write_b64 v180, v[68:69] offset:208
	v_mul_f32_e32 v72, v183, v72
	v_mul_f32_e32 v73, v183, v73
	v_mul_f32_e32 v74, v183, v74
	v_mul_f32_e32 v75, v183, v75
	v_cvt_pk_bf16_f32 v72, v72, v73
	v_cvt_pk_bf16_f32 v73, v74, v75
	ds_write_b64 v180, v[72:73] offset:224
	v_mul_f32_e32 v76, v183, v76
	v_mul_f32_e32 v77, v183, v77
	v_mul_f32_e32 v78, v183, v78
	v_mul_f32_e32 v79, v183, v79
	v_cvt_pk_bf16_f32 v76, v76, v77
	v_cvt_pk_bf16_f32 v77, v78, v79
	ds_write_b64 v180, v[76:77] offset:240
	s_waitcnt lgkmcnt(0)
	ds_read_b128 v[112:115], v181
	ds_read_b128 v[116:119], v181 offset:1088
	ds_read_b128 v[120:123], v181 offset:2176
	ds_read_b128 v[124:127], v181 offset:3264
	ds_read_b128 v[96:99], v181 offset:4352
	ds_read_b128 v[100:103], v181 offset:5440
	ds_read_b128 v[104:107], v181 offset:6528
	ds_read_b128 v[108:111], v181 offset:7616
	s_add_u32 s66, s64, 0x0
	s_addc_u32 s67, s65, 0
	s_waitcnt lgkmcnt(7)
	global_store_dwordx4 v182, v[112:115], s[66:67]  sc1
	s_add_u32 s66, s64, 0x2000
	s_addc_u32 s67, s65, 0
	s_waitcnt lgkmcnt(6)
	global_store_dwordx4 v182, v[116:119], s[66:67]  sc1
	s_add_u32 s66, s64, 0x4000
	s_addc_u32 s67, s65, 0
	s_waitcnt lgkmcnt(5)
	global_store_dwordx4 v182, v[120:123], s[66:67]  sc1
	s_add_u32 s66, s64, 0x6000
	s_addc_u32 s67, s65, 0
	s_waitcnt lgkmcnt(4)
	global_store_dwordx4 v182, v[124:127], s[66:67]  sc1
	s_add_u32 s66, s64, 0x8000
	s_addc_u32 s67, s65, 0
	s_waitcnt lgkmcnt(3)
	global_store_dwordx4 v182, v[96:99], s[66:67]  sc1
	s_add_u32 s66, s64, 0xa000
	s_addc_u32 s67, s65, 0
	s_waitcnt lgkmcnt(2)
	global_store_dwordx4 v182, v[100:103], s[66:67]  sc1
	s_add_u32 s66, s64, 0xc000
	s_addc_u32 s67, s65, 0
	s_waitcnt lgkmcnt(1)
	global_store_dwordx4 v182, v[104:107], s[66:67]  sc1
	s_add_u32 s66, s64, 0xe000
	s_addc_u32 s67, s65, 0
	s_waitcnt lgkmcnt(0)
; DI bfr f2bf(float a) { return (bfr)(pack2(a, 0.f) & 0xffffu); }
; DI int crow(int reg, int h) { return (reg & 3) + 8 * (reg >> 2) + 4 * h; }
; template <int lda, class Epi>
; DI void gemm_tile(const bfr* __restrict__ A, const bfr* __restrict__ Bt, int NB, int K, int m0, int n0, char* smem, Epi epi) {
;     ...
; #pragma unroll
;   for (int i = 0; i < 2; ++i)
; #pragma unroll
;     for (int j = 0; j < 4; ++j)
; #pragma unroll
;       for (int q = 0; q < 16; ++q) {
;         int row = m0 + wr * 64 + i * 32 + crow(q, hl);
;         int col = n0 + wc * 128 + j * 32 + r;
;         epi(row, col, acc[i][j][q]);
;       }
; DI void phase_gemm_bf16out(const Params& p, const bfr* A, const bfr* Wt, bfr* C, int N, const float* ss, char* smem) {
;     ...
;   for (int t0 = blockIdx.x; t0 < 128 * ntn; t0 += gridDim.x) {
;     const int t = ((gridDim.x & 7) == 0) ? xcd_tile(t0, ntn) : t0;
;     int mt = t / ntn, nt = t % ntn;
;     gemm_tile<1024>(A, Wt, N, 1024, mt * 128, nt * 256, smem,
;               [=](int row, int col, float v) {
;                 float inv = rsqrtf(ss[row] * (1.0f / 1024.0f) + EPSF);
;                 C[(size_t)row * N + col] = f2bf(v * inv);
;               });
	global_store_dwordx4 v182, v[108:111], s[66:67]  sc1
	v_mul_f32_e32 v48, v184, v48
	v_mul_f32_e32 v49, v184, v49
	v_mul_f32_e32 v50, v184, v50
	v_mul_f32_e32 v51, v184, v51
	v_cvt_pk_bf16_f32 v48, v48, v49
	v_cvt_pk_bf16_f32 v49, v50, v51
	ds_write_b64 v180, v[48:49]
	v_mul_f32_e32 v52, v184, v52
	v_mul_f32_e32 v53, v184, v53
	v_mul_f32_e32 v54, v184, v54
	v_mul_f32_e32 v55, v184, v55
	v_cvt_pk_bf16_f32 v52, v52, v53
	v_cvt_pk_bf16_f32 v53, v54, v55
	ds_write_b64 v180, v[52:53] offset:16
	v_mul_f32_e32 v56, v184, v56
	v_mul_f32_e32 v57, v184, v57
	v_mul_f32_e32 v58, v184, v58
	v_mul_f32_e32 v59, v184, v59
	v_cvt_pk_bf16_f32 v56, v56, v57
	v_cvt_pk_bf16_f32 v57, v58, v59
	ds_write_b64 v180, v[56:57] offset:32
	v_mul_f32_e32 v60, v184, v60
	v_mul_f32_e32 v61, v184, v61
	v_mul_f32_e32 v62, v184, v62
	v_mul_f32_e32 v63, v184, v63
	v_cvt_pk_bf16_f32 v60, v60, v61
	v_cvt_pk_bf16_f32 v61, v62, v63
	ds_write_b64 v180, v[60:61] offset:48
	v_mul_f32_e32 v32, v184, v32
	v_mul_f32_e32 v33, v184, v33
	v_mul_f32_e32 v34, v184, v34
	v_mul_f32_e32 v35, v184, v35
	v_cvt_pk_bf16_f32 v32, v32, v33
	v_cvt_pk_bf16_f32 v33, v34, v35
	ds_write_b64 v180, v[32:33] offset:64
	v_mul_f32_e32 v36, v184, v36
	v_mul_f32_e32 v37, v184, v37
	v_mul_f32_e32 v38, v184, v38
	v_mul_f32_e32 v39, v184, v39
	v_cvt_pk_bf16_f32 v36, v36, v37
	v_cvt_pk_bf16_f32 v37, v38, v39
	ds_write_b64 v180, v[36:37] offset:80
	v_mul_f32_e32 v40, v184, v40
	v_mul_f32_e32 v41, v184, v41
	v_mul_f32_e32 v42, v184, v42
	v_mul_f32_e32 v43, v184, v43
	v_cvt_pk_bf16_f32 v40, v40, v41
	v_cvt_pk_bf16_f32 v41, v42, v43
	ds_write_b64 v180, v[40:41] offset:96
	v_mul_f32_e32 v44, v184, v44
	v_mul_f32_e32 v45, v184, v45
	v_mul_f32_e32 v46, v184, v46
	v_mul_f32_e32 v47, v184, v47
	v_cvt_pk_bf16_f32 v44, v44, v45
	v_cvt_pk_bf16_f32 v45, v46, v47
	ds_write_b64 v180, v[44:45] offset:112
	v_mul_f32_e32 v16, v184, v16
	v_mul_f32_e32 v17, v184, v17
	v_mul_f32_e32 v18, v184, v18
	v_mul_f32_e32 v19, v184, v19
	v_cvt_pk_bf16_f32 v16, v16, v17
	v_cvt_pk_bf16_f32 v17, v18, v19
	ds_write_b64 v180, v[16:17] offset:128
	v_mul_f32_e32 v20, v184, v20
	v_mul_f32_e32 v21, v184, v21
	v_mul_f32_e32 v22, v184, v22
	v_mul_f32_e32 v23, v184, v23
	v_cvt_pk_bf16_f32 v20, v20, v21
	v_cvt_pk_bf16_f32 v21, v22, v23
	ds_write_b64 v180, v[20:21] offset:144
	v_mul_f32_e32 v24, v184, v24
	v_mul_f32_e32 v25, v184, v25
	v_mul_f32_e32 v26, v184, v26
	v_mul_f32_e32 v27, v184, v27
	v_cvt_pk_bf16_f32 v24, v24, v25
	v_cvt_pk_bf16_f32 v25, v26, v27
	ds_write_b64 v180, v[24:25] offset:160
	v_mul_f32_e32 v28, v184, v28
	v_mul_f32_e32 v29, v184, v29
	v_mul_f32_e32 v30, v184, v30
	v_mul_f32_e32 v31, v184, v31
	v_cvt_pk_bf16_f32 v28, v28, v29
	v_cvt_pk_bf16_f32 v29, v30, v31
	ds_write_b64 v180, v[28:29] offset:176
	v_mul_f32_e32 v0, v184, v0
	v_mul_f32_e32 v1, v184, v1
	v_mul_f32_e32 v2, v184, v2
	v_mul_f32_e32 v3, v184, v3
	v_cvt_pk_bf16_f32 v0, v0, v1
	v_cvt_pk_bf16_f32 v1, v2, v3
	ds_write_b64 v180, v[0:1] offset:192
	v_mul_f32_e32 v4, v184, v4
	v_mul_f32_e32 v5, v184, v5
	v_mul_f32_e32 v6, v184, v6
	v_mul_f32_e32 v7, v184, v7
	v_cvt_pk_bf16_f32 v4, v4, v5
	v_cvt_pk_bf16_f32 v5, v6, v7
	ds_write_b64 v180, v[4:5] offset:208
	v_mul_f32_e32 v8, v184, v8
	v_mul_f32_e32 v9, v184, v9
	v_mul_f32_e32 v10, v184, v10
	v_mul_f32_e32 v11, v184, v11
	v_cvt_pk_bf16_f32 v8, v8, v9
	v_cvt_pk_bf16_f32 v9, v10, v11
	ds_write_b64 v180, v[8:9] offset:224
	v_mul_f32_e32 v12, v184, v12
	v_mul_f32_e32 v13, v184, v13
	v_mul_f32_e32 v14, v184, v14
	v_mul_f32_e32 v15, v184, v15
	v_cvt_pk_bf16_f32 v12, v12, v13
	v_cvt_pk_bf16_f32 v13, v14, v15
	ds_write_b64 v180, v[12:13] offset:240
	s_waitcnt lgkmcnt(0)
	ds_read_b128 v[48:51], v181
	ds_read_b128 v[52:55], v181 offset:1088
	ds_read_b128 v[56:59], v181 offset:2176
	ds_read_b128 v[60:63], v181 offset:3264
	ds_read_b128 v[32:35], v181 offset:4352
	ds_read_b128 v[36:39], v181 offset:5440
	ds_read_b128 v[40:43], v181 offset:6528
	ds_read_b128 v[44:47], v181 offset:7616
	s_add_u32 s66, s64, 0x10000
	s_addc_u32 s67, s65, 0
	s_waitcnt lgkmcnt(7)
	global_store_dwordx4 v182, v[48:51], s[66:67]  sc1
	s_add_u32 s66, s64, 0x12000
	s_addc_u32 s67, s65, 0
	s_waitcnt lgkmcnt(6)
	global_store_dwordx4 v182, v[52:55], s[66:67]  sc1
	s_add_u32 s66, s64, 0x14000
	s_addc_u32 s67, s65, 0
	s_waitcnt lgkmcnt(5)
	global_store_dwordx4 v182, v[56:59], s[66:67]  sc1
	s_add_u32 s66, s64, 0x16000
	s_addc_u32 s67, s65, 0
	s_waitcnt lgkmcnt(4)
	global_store_dwordx4 v182, v[60:63], s[66:67]  sc1
	s_add_u32 s66, s64, 0x18000
	s_addc_u32 s67, s65, 0
	s_waitcnt lgkmcnt(3)
	global_store_dwordx4 v182, v[32:35], s[66:67]  sc1
	s_add_u32 s66, s64, 0x1a000
	s_addc_u32 s67, s65, 0
	s_waitcnt lgkmcnt(2)
	global_store_dwordx4 v182, v[36:39], s[66:67]  sc1
	s_add_u32 s66, s64, 0x1c000
	s_addc_u32 s67, s65, 0
	s_waitcnt lgkmcnt(1)
	global_store_dwordx4 v182, v[40:43], s[66:67]  sc1
	s_add_u32 s66, s64, 0x1e000
	s_addc_u32 s67, s65, 0
	s_waitcnt lgkmcnt(0)
	global_store_dwordx4 v182, v[44:47], s[66:67]  sc1
	v_readlane_b32 s64, v187, 0
	v_readlane_b32 s65, v187, 1
	v_readlane_b32 s66, v187, 2
	v_readlane_b32 s67, v187, 3
	v_readlane_b32 s68, v187, 4
	v_readlane_b32 s69, v187, 5
	v_readlane_b32 s70, v187, 6
	v_readlane_b32 s71, v187, 7
	v_readlane_b32 s72, v187, 8
	v_readlane_b32 s73, v187, 9
	v_readlane_b32 s74, v187, 10
	v_readlane_b32 s75, v187, 11
	v_readlane_b32 s76, v187, 12
	v_readlane_b32 s77, v187, 13
	v_readlane_b32 s78, v187, 14
	v_readlane_b32 s79, v187, 15
	s_nop 7
	s_add_i32 s28, s28, s34
	s_cmpk_lt_i32 s28, 0x200
	s_cbranch_scc0 .LBB0_936
	s_branch .LBB0_923

; #define MFMA32(a, b, c) __builtin_amdgcn_mfma_f32_32x32x16_bf16((a), (b), (c), 0, 0, 0)
; #define GA_LOAD(pr_) do { _Pragma("unroll") for (int i = 0; i < 4; ++i) ra[i] = *(const u32x4*)(Ab + (i * 32) * lda + (pr_) * 64); } while (0)
; #define GB_LOAD(kt_) do { const bfr* bk_ = Bb + (kt_) * NB * 32; \
;     _Pragma("unroll") for (int i = 0; i < 4; ++i) rb[i] = *(const u32x4*)(bk_ + (i * 64) * 32); } while (0)
; #define G_STORE(kt_) do { bfr* as_ = S0 + ((kt_) & 1) * GSTAGE; bfr* bs_ = as_ + 128 * 40; \
;     if (apar == ((kt_) & 1)) { _Pragma("unroll") for (int i = 0; i < 4; ++i) *(u32x4*)(as_ + asoff + i * 32 * 40) = ra[i]; } \
;     _Pragma("unroll") for (int i = 0; i < 4; ++i) *(u32x4*)(bs_ + bsoff + i * 64 * 40) = rb[i]; } while (0)
; template <int lda>
; DI void gemm_mainloop(const bfr* __restrict__ A, const bfr* __restrict__ Bt, int NB, int K, int m0, int n0, char* smem, f32x16 (&acc)[2][4]) {
;     ...
;   for (int kt = 0; kt < nk; ++kt) {
;     if (kt + 1 < nk) G_STORE(kt + 1);
;     if (kt + 2 < nk) {
;       GB_LOAD(kt + 2);
;       if ((kt & 1) == 0) GA_LOAD((kt >> 1) + 1);
;     }
;     const bfr* As = S0 + (kt & 1) * GSTAGE;
;     const bfr* Bs = As + 128 * 40;
; #pragma unroll
;     for (int ks = 0; ks < 2; ++ks) {
;       bf16x8 af[2], bfg[4];
; #pragma unroll
;       for (int i = 0; i < 2; ++i) af[i] = *(const bf16x8*)(As + (wr * 64 + i * 32 + r) * 40 + ks * 16 + hl * 8);
; #pragma unroll
;       for (int j = 0; j < 4; ++j) bfg[j] = *(const bf16x8*)(Bs + (wc * 128 + j * 32 + r) * 40 + ks * 16 + hl * 8);
; #pragma unroll
;       for (int i = 0; i < 2; ++i)
; #pragma unroll
;         for (int j = 0; j < 4; ++j) acc[i][j] = MFMA32(af[i], bfg[j], acc[i][j]);
;     }
;     __syncthreads();
.Lp10_loop:
	s_waitcnt vmcnt(6) lgkmcnt(0)
	s_barrier
	s_mul_i32 s74, s71, 0x6000
	s_add_u32 s75, s74, 0x2000
	s_cmp_eq_u32 s71, 2
	s_cselect_b32 s75, 0x10000, s75
	v_add_u32_e32 v203, s74, v199
	v_add_u32_e32 v205, s75, v201
	v_add_u32_e32 v204, s74, v200
	v_add_u32_e32 v206, s75, v202
	s_add_u32 s71, s71, 1
	s_cmp_eq_u32 s71, 3
	s_cselect_b32 s71, 0, s71
	ds_read_b128 v[128:131], v203
	ds_read_b128 v[144:147], v205
	ds_read_b128 v[148:151], v205 offset:2048
	ds_read_b128 v[152:155], v205 offset:4096
	ds_read_b128 v[156:159], v205 offset:6144
	ds_read_b128 v[132:135], v203 offset:2048
	v_mfma_f32_32x32x16_bf16 v[112:127], v[160:163], v[136:139], v[112:127]
	s_mul_i32 s74, s70, 0x6000
	s_add_u32 s75, s74, s68
	s_mov_b32 m0, s75
	s_add_u32 s76, s74, 0x2000
	s_cmp_eq_u32 s70, 2
	s_cselect_b32 s76, 0x10000, s76
	global_load_lds_dwordx4 v192, s[64:65]
	v_mfma_f32_32x32x16_bf16 v[96:111], v[164:167], v[136:139], v[96:111]
	s_add_u32 m0, s75, 0x400
	s_add_u32 s76, s76, s69
	global_load_lds_dwordx4 v194, s[64:65]
	v_mfma_f32_32x32x16_bf16 v[80:95], v[168:171], v[136:139], v[80:95]
	s_mov_b32 m0, s76
	s_add_u32 s64, s64, 64
	s_addc_u32 s65, s65, 0
	global_load_lds_dwordx4 v198, s[66:67]
	v_mfma_f32_32x32x16_bf16 v[64:79], v[172:175], v[136:139], v[64:79]
	global_load_lds_dwordx4 v198, s[66:67] offset:1024
	v_mfma_f32_32x32x16_bf16 v[48:63], v[160:163], v[140:143], v[48:63]
	global_load_lds_dwordx4 v198, s[66:67] offset:2048
	v_mfma_f32_32x32x16_bf16 v[32:47], v[164:167], v[140:143], v[32:47]
	global_load_lds_dwordx4 v198, s[66:67] offset:3072
	s_add_u32 s66, s66, 0x10000
	s_addc_u32 s67, s67, 0
	v_mfma_f32_32x32x16_bf16 v[16:31], v[168:171], v[140:143], v[16:31]
	s_add_u32 s70, s70, 1
	s_cmp_eq_u32 s70, 3
	s_cselect_b32 s70, 0, s70
	v_mfma_f32_32x32x16_bf16 v[0:15], v[172:175], v[140:143], v[0:15]
	ds_read_b128 v[136:139], v204
	ds_read_b128 v[160:163], v206
	ds_read_b128 v[164:167], v206 offset:2048
	ds_read_b128 v[168:171], v206 offset:4096
	ds_read_b128 v[172:175], v206 offset:6144
	ds_read_b128 v[140:143], v204 offset:2048
	s_waitcnt lgkmcnt(10)
	v_mfma_f32_32x32x16_bf16 v[112:127], v[144:147], v[128:131], v[112:127]
	s_waitcnt lgkmcnt(9)
	v_mfma_f32_32x32x16_bf16 v[96:111], v[148:151], v[128:131], v[96:111]
	s_waitcnt lgkmcnt(8)
	v_mfma_f32_32x32x16_bf16 v[80:95], v[152:155], v[128:131], v[80:95]
	s_waitcnt lgkmcnt(7)
	v_mfma_f32_32x32x16_bf16 v[64:79], v[156:159], v[128:131], v[64:79]
	s_waitcnt lgkmcnt(6)
	v_mfma_f32_32x32x16_bf16 v[48:63], v[144:147], v[132:135], v[48:63]
	v_mfma_f32_32x32x16_bf16 v[32:47], v[148:151], v[132:135], v[32:47]
	v_mfma_f32_32x32x16_bf16 v[16:31], v[152:155], v[132:135], v[16:31]
	v_mfma_f32_32x32x16_bf16 v[0:15], v[156:159], v[132:135], v[0:15]
	s_add_u32 s72, s72, 1
	s_cmp_lt_u32 s72, 29
	s_cbranch_scc1 .Lp10_loop
	s_waitcnt vmcnt(6) lgkmcnt(0)
	s_barrier
	s_mul_i32 s74, s71, 0x6000
	s_add_u32 s75, s74, 0x2000
	s_cmp_eq_u32 s71, 2
	s_cselect_b32 s75, 0x10000, s75
	v_add_u32_e32 v203, s74, v199
	v_add_u32_e32 v205, s75, v201
	v_add_u32_e32 v204, s74, v200
	v_add_u32_e32 v206, s75, v202
	s_add_u32 s71, s71, 1
	s_cmp_eq_u32 s71, 3
	s_cselect_b32 s71, 0, s71
	ds_read_b128 v[128:131], v203
	ds_read_b128 v[144:147], v205
	ds_read_b128 v[148:151], v205 offset:2048
	ds_read_b128 v[152:155], v205 offset:4096
	ds_read_b128 v[156:159], v205 offset:6144
	ds_read_b128 v[132:135], v203 offset:2048
	v_mfma_f32_32x32x16_bf16 v[112:127], v[160:163], v[136:139], v[112:127]
	v_mfma_f32_32x32x16_bf16 v[96:111], v[164:167], v[136:139], v[96:111]
	v_mfma_f32_32x32x16_bf16 v[80:95], v[168:171], v[136:139], v[80:95]
	v_mfma_f32_32x32x16_bf16 v[64:79], v[172:175], v[136:139], v[64:79]
	v_mfma_f32_32x32x16_bf16 v[48:63], v[160:163], v[140:143], v[48:63]
	v_mfma_f32_32x32x16_bf16 v[32:47], v[164:167], v[140:143], v[32:47]
	v_mfma_f32_32x32x16_bf16 v[16:31], v[168:171], v[140:143], v[16:31]
	v_mfma_f32_32x32x16_bf16 v[0:15], v[172:175], v[140:143], v[0:15]
	ds_read_b128 v[136:139], v204
	ds_read_b128 v[160:163], v206
	ds_read_b128 v[164:167], v206 offset:2048
	ds_read_b128 v[168:171], v206 offset:4096
	ds_read_b128 v[172:175], v206 offset:6144
	ds_read_b128 v[140:143], v204 offset:2048
	s_waitcnt lgkmcnt(10)
	v_mfma_f32_32x32x16_bf16 v[112:127], v[144:147], v[128:131], v[112:127]
	s_waitcnt lgkmcnt(9)
	v_mfma_f32_32x32x16_bf16 v[96:111], v[148:151], v[128:131], v[96:111]
	s_waitcnt lgkmcnt(8)
	v_mfma_f32_32x32x16_bf16 v[80:95], v[152:155], v[128:131], v[80:95]
	s_waitcnt lgkmcnt(7)
	v_mfma_f32_32x32x16_bf16 v[64:79], v[156:159], v[128:131], v[64:79]
	s_waitcnt lgkmcnt(6)
	v_mfma_f32_32x32x16_bf16 v[48:63], v[144:147], v[132:135], v[48:63]
	v_mfma_f32_32x32x16_bf16 v[32:47], v[148:151], v[132:135], v[32:47]
	v_mfma_f32_32x32x16_bf16 v[16:31], v[152:155], v[132:135], v[16:31]
	v_mfma_f32_32x32x16_bf16 v[0:15], v[156:159], v[132:135], v[0:15]
	s_waitcnt vmcnt(0) lgkmcnt(0)
	s_barrier
; #define MFMA32(a, b, c) __builtin_amdgcn_mfma_f32_32x32x16_bf16((a), (b), (c), 0, 0, 0)
; DI int crow(int reg, int h) { return (reg & 3) + 8 * (reg >> 2) + 4 * h; }
; template <int lda>
; DI void gemm_mainloop(const bfr* __restrict__ A, const bfr* __restrict__ Bt, int NB, int K, int m0, int n0, char* smem, f32x16 (&acc)[2][4]) {
;     ...
;     for (int ks = 0; ks < 2; ++ks) {
;       bf16x8 af[2], bfg[4];
; #pragma unroll
;       for (int i = 0; i < 2; ++i) af[i] = *(const bf16x8*)(As + (wr * 64 + i * 32 + r) * 40 + ks * 16 + hl * 8);
; #pragma unroll
;       for (int j = 0; j < 4; ++j) bfg[j] = *(const bf16x8*)(Bs + (wc * 128 + j * 32 + r) * 40 + ks * 16 + hl * 8);
; #pragma unroll
;       for (int i = 0; i < 2; ++i)
; #pragma unroll
;         for (int j = 0; j < 4; ++j) acc[i][j] = MFMA32(af[i], bfg[j], acc[i][j]);
;     }
;     __syncthreads();
; template <bool FIRST, bool HAS_H>
; DI void phase_gemm_resid(const Params& p, const bfr* A, const bfr* Wt, const float* gnext, float* ss, char* smem) {
;     ...
;     int tid2 = threadIdx.x;
;     asm volatile("" : "+v"(tid2));
;     const int lane = tid2 & 63, wid = tid2 >> 6, wr = wid >> 1, wc = wid & 1, r = lane & 31, hl = lane >> 5;
;     const float* xsrc = FIRST ? p.x_prompt : X;
;     const int rbase = m0 + wr * 64 + 4 * hl, cbase = n0 + wc * 128 + r;
; #pragma unroll
;     for (int i = 0; i < 2; ++i) {
; #pragma unroll
;       for (int qh = 0; qh < 2; ++qh) {
;         float rs[8];
; #pragma unroll
;         for (int q = 0; q < 8; ++q) rs[q] = 0.f;
; #pragma unroll
;         for (int jh = 0; jh < 2; ++jh) {
;           float xo[2][8];
; #pragma unroll
;           for (int jj = 0; jj < 2; ++jj)
; #pragma unroll
;             for (int q = 0; q < 8; ++q)
;               xo[jj][q] = xsrc[(rbase + i * 32 + crow(qh * 8 + q, 0)) * 1024 + cbase + (jh * 2 + jj) * 32];
	s_mul_i32 s74, s71, 0x6000
	s_add_u32 s75, s74, 0x2000
	s_cmp_eq_u32 s71, 2
	s_cselect_b32 s75, 0x10000, s75
	v_add_u32_e32 v203, s74, v199
	v_add_u32_e32 v205, s75, v201
	v_add_u32_e32 v204, s74, v200
	v_add_u32_e32 v206, s75, v202
	s_add_u32 s71, s71, 1
	s_cmp_eq_u32 s71, 3
	s_cselect_b32 s71, 0, s71
	ds_read_b128 v[128:131], v203
	ds_read_b128 v[144:147], v205
	ds_read_b128 v[148:151], v205 offset:2048
	ds_read_b128 v[152:155], v205 offset:4096
	ds_read_b128 v[156:159], v205 offset:6144
	ds_read_b128 v[132:135], v203 offset:2048
	v_mfma_f32_32x32x16_bf16 v[112:127], v[160:163], v[136:139], v[112:127]
	v_mfma_f32_32x32x16_bf16 v[96:111], v[164:167], v[136:139], v[96:111]
	v_mfma_f32_32x32x16_bf16 v[80:95], v[168:171], v[136:139], v[80:95]
	v_mfma_f32_32x32x16_bf16 v[64:79], v[172:175], v[136:139], v[64:79]
	v_mfma_f32_32x32x16_bf16 v[48:63], v[160:163], v[140:143], v[48:63]
	v_mfma_f32_32x32x16_bf16 v[32:47], v[164:167], v[140:143], v[32:47]
	v_mfma_f32_32x32x16_bf16 v[16:31], v[168:171], v[140:143], v[16:31]
	v_mfma_f32_32x32x16_bf16 v[0:15], v[172:175], v[140:143], v[0:15]
	ds_read_b128 v[136:139], v204
	ds_read_b128 v[160:163], v206
	ds_read_b128 v[164:167], v206 offset:2048
	ds_read_b128 v[168:171], v206 offset:4096
	ds_read_b128 v[172:175], v206 offset:6144
	ds_read_b128 v[140:143], v204 offset:2048
	s_waitcnt lgkmcnt(10)
	v_mfma_f32_32x32x16_bf16 v[112:127], v[144:147], v[128:131], v[112:127]
	s_waitcnt lgkmcnt(9)
	v_mfma_f32_32x32x16_bf16 v[96:111], v[148:151], v[128:131], v[96:111]
	s_waitcnt lgkmcnt(8)
	v_mfma_f32_32x32x16_bf16 v[80:95], v[152:155], v[128:131], v[80:95]
	s_waitcnt lgkmcnt(7)
	v_mfma_f32_32x32x16_bf16 v[64:79], v[156:159], v[128:131], v[64:79]
	s_waitcnt lgkmcnt(6)
	v_mfma_f32_32x32x16_bf16 v[48:63], v[144:147], v[132:135], v[48:63]
	v_mfma_f32_32x32x16_bf16 v[32:47], v[148:151], v[132:135], v[32:47]
	v_mfma_f32_32x32x16_bf16 v[16:31], v[152:155], v[132:135], v[16:31]
	v_mfma_f32_32x32x16_bf16 v[0:15], v[156:159], v[132:135], v[0:15]
	s_waitcnt lgkmcnt(0)
	v_mfma_f32_32x32x16_bf16 v[112:127], v[160:163], v[136:139], v[112:127]
	v_mfma_f32_32x32x16_bf16 v[96:111], v[164:167], v[136:139], v[96:111]
	v_mfma_f32_32x32x16_bf16 v[80:95], v[168:171], v[136:139], v[80:95]
	v_mfma_f32_32x32x16_bf16 v[64:79], v[172:175], v[136:139], v[64:79]
	v_mfma_f32_32x32x16_bf16 v[48:63], v[160:163], v[140:143], v[48:63]
	v_mfma_f32_32x32x16_bf16 v[32:47], v[164:167], v[140:143], v[32:47]
	v_mfma_f32_32x32x16_bf16 v[16:31], v[168:171], v[140:143], v[16:31]
	v_mfma_f32_32x32x16_bf16 v[0:15], v[172:175], v[140:143], v[0:15]
	s_nop 7
	s_nop 3
	s_load_dwordx2 s[64:65], s[92:93], 0x100
	s_load_dwordx2 s[66:67], s[92:93], 0x100
	s_load_dwordx2 s[68:69], s[92:93], 0x148
	s_load_dwordx2 s[70:71], s[92:93], 0x48
	s_mul_i32 s76, s73, 8704
	s_lshr_b32 s74, s73, 1
	s_lshl_b32 s74, s74, 6
	s_add_u32 s74, s74, s77
	s_and_b32 s75, s73, 1
	s_lshl_b32 s75, s75, 7
	s_add_u32 s75, s75, s78
	v_and_b32_e32 v208, 31, v196
	v_bfe_u32 v209, v196, 5, 1
	v_mul_u32_u24_e32 v210, 272, v208
	v_add_u32_e32 v210, s76, v210
	v_lshl_add_u32 v192, v209, 4, v210
	v_lshl_add_u32 v194, v209, 3, v210
	v_lshlrev_b32_e32 v210, 2, v209
	v_add_lshl_u32 v202, v210, s75, 2
	v_add_lshl_u32 v205, v208, s74, 2
	v_and_b32_e32 v210, 63, v196
	v_xor_b32_e32 v210, 32, v210
	v_lshlrev_b32_e32 v206, 2, v210
	v_bfe_u32 v208, v196, 4, 2
	v_and_b32_e32 v209, 15, v196
	v_mul_u32_u24_e32 v210, 272, v208
	v_lshl_add_u32 v210, v209, 4, v210
	v_add_u32_e32 v198, s76, v210
	v_add_u32_e32 v210, s74, v208
	v_lshlrev_b32_e32 v210, 10, v210
	v_lshl_add_u32 v210, v209, 2, v210
	v_add_lshl_u32 v200, v210, s75, 2
	s_mov_b32 s79, s74
	s_mov_b32 s72, s75
	s_waitcnt lgkmcnt(0)
	s_add_u32 s74, s64, 0x0
	s_addc_u32 s75, s65, 0
	global_load_dwordx4 v[128:131], v200, s[74:75]
	s_add_u32 s74, s64, 0x4000
	s_addc_u32 s75, s65, 0
	global_load_dwordx4 v[132:135], v200, s[74:75]
	s_add_u32 s74, s64, 0x8000
	s_addc_u32 s75, s65, 0
	global_load_dwordx4 v[136:139], v200, s[74:75]
	s_add_u32 s74, s64, 0xc000
	s_addc_u32 s75, s65, 0
	global_load_dwordx4 v[140:143], v200, s[74:75]
	s_add_u32 s74, s64, 0x10000
	s_addc_u32 s75, s65, 0
	global_load_dwordx4 v[144:147], v200, s[74:75]
	s_add_u32 s74, s64, 0x14000
	s_addc_u32 s75, s65, 0
	global_load_dwordx4 v[148:151], v200, s[74:75]
	s_add_u32 s74, s64, 0x18000
	s_addc_u32 s75, s65, 0
	global_load_dwordx4 v[152:155], v200, s[74:75]
	s_add_u32 s74, s64, 0x1c000
	s_addc_u32 s75, s65, 0
	global_load_dwordx4 v[156:159], v200, s[74:75]
	s_mov_b32 s74, s79
	s_mov_b32 s75, s72
	v_bfe_u32 v208, v196, 3, 3
	v_and_b32_e32 v209, 7, v196
	v_mul_u32_u24_e32 v210, 272, v208
	v_lshl_add_u32 v210, v209, 4, v210
	v_add_u32_e32 v199, s76, v210
	v_add_u32_e32 v210, s74, v208
	v_lshlrev_b32_e32 v210, 10, v210
	v_lshl_add_u32 v210, v209, 3, v210
	v_add_lshl_u32 v201, v210, s75, 1
	v_mov_b32_e32 v203, 0
	v_mov_b32_e32 v204, 0
	s_waitcnt lgkmcnt(0)
	s_barrier
; DI bfr f2bf(float a) { return (bfr)(pack2(a, 0.f) & 0xffffu); }
; DI int crow(int reg, int h) { return (reg & 3) + 8 * (reg >> 2) + 4 * h; }
; template <bool FIRST, bool HAS_H>
; DI void phase_gemm_resid(const Params& p, const bfr* A, const bfr* Wt, const float* gnext, float* ss, char* smem) {
;     ...
; #pragma unroll
;     for (int i = 0; i < 2; ++i) {
; #pragma unroll
;       for (int qh = 0; qh < 2; ++qh) {
;         float rs[8];
; #pragma unroll
;         for (int q = 0; q < 8; ++q) rs[q] = 0.f;
; #pragma unroll
;         for (int jh = 0; jh < 2; ++jh) {
;           float xo[2][8];
; #pragma unroll
;           for (int jj = 0; jj < 2; ++jj)
; #pragma unroll
;             for (int q = 0; q < 8; ++q)
;               xo[jj][q] = xsrc[(rbase + i * 32 + crow(qh * 8 + q, 0)) * 1024 + cbase + (jh * 2 + jj) * 32];
; #pragma unroll
;           for (int q = 0; q < 8; ++q) {
;             const int o = (rbase + i * 32 + crow(qh * 8 + q, 0)) * 1024 + cbase;
; #pragma unroll
;             for (int jj = 0; jj < 2; ++jj) {
;               const int j = jh * 2 + jj;
;               const float xn = xo[jj][q] + acc[i][j][qh * 8 + q];
;               X[o + j * 32] = xn;
;               if (HAS_H) Hn[o + j * 32] = f2bf(xn * gnext[cbase + j * 32]);
;               rs[q] += xn * xn;
;             }
;           }
;         }
	s_add_u32 s70, s70, 0x1000
	s_addc_u32 s71, s71, 0
	s_waitcnt vmcnt(7)
	ds_write_b128 v198, v[128:131]
	s_waitcnt vmcnt(6)
	ds_write_b128 v198, v[132:135] offset:1088
	s_waitcnt vmcnt(5)
	ds_write_b128 v198, v[136:139] offset:2176
	s_waitcnt vmcnt(4)
	ds_write_b128 v198, v[140:143] offset:3264
	s_waitcnt vmcnt(3)
	ds_write_b128 v198, v[144:147] offset:4352
	s_waitcnt vmcnt(2)
	ds_write_b128 v198, v[148:151] offset:5440
	s_waitcnt vmcnt(1)
	ds_write_b128 v198, v[152:155] offset:6528
	s_waitcnt vmcnt(0)
	ds_write_b128 v198, v[156:159] offset:7616
	s_add_u32 s74, s64, 0x100
	s_addc_u32 s75, s65, 0
	global_load_dwordx4 v[128:131], v200, s[74:75]
	s_add_u32 s74, s64, 0x4100
	s_addc_u32 s75, s65, 0
	global_load_dwordx4 v[132:135], v200, s[74:75]
	s_add_u32 s74, s64, 0x8100
	s_addc_u32 s75, s65, 0
	global_load_dwordx4 v[136:139], v200, s[74:75]
	s_add_u32 s74, s64, 0xc100
	s_addc_u32 s75, s65, 0
	global_load_dwordx4 v[140:143], v200, s[74:75]
	s_add_u32 s74, s64, 0x10100
	s_addc_u32 s75, s65, 0
	global_load_dwordx4 v[144:147], v200, s[74:75]
	s_add_u32 s74, s64, 0x14100
	s_addc_u32 s75, s65, 0
	global_load_dwordx4 v[148:151], v200, s[74:75]
	s_add_u32 s74, s64, 0x18100
	s_addc_u32 s75, s65, 0
	global_load_dwordx4 v[152:155], v200, s[74:75]
	s_add_u32 s74, s64, 0x1c100
	s_addc_u32 s75, s65, 0
	global_load_dwordx4 v[156:159], v200, s[74:75]
	ds_read_b128 v[160:163], v192
	ds_read_b128 v[164:167], v192 offset:32
	ds_read_b128 v[168:171], v192 offset:64
	ds_read_b128 v[172:175], v192 offset:96
	ds_read_b128 v[176:179], v192 offset:128
	ds_read_b128 v[180:183], v192 offset:160
	ds_read_b128 v[184:187], v192 offset:192
	ds_read_b128 v[188:191], v192 offset:224
	s_waitcnt lgkmcnt(7)
	v_add_f32_e32 v112, v160, v112
	v_add_f32_e32 v113, v161, v113
	v_add_f32_e32 v114, v162, v114
	v_add_f32_e32 v115, v163, v115
	v_fmac_f32_e32 v203, v112, v112
	v_fmac_f32_e32 v203, v113, v113
	v_fmac_f32_e32 v203, v114, v114
	v_fmac_f32_e32 v203, v115, v115
	ds_write_b128 v192, v[112:115]
	s_waitcnt lgkmcnt(7)
	v_add_f32_e32 v116, v164, v116
	v_add_f32_e32 v117, v165, v117
	v_add_f32_e32 v118, v166, v118
	v_add_f32_e32 v119, v167, v119
	v_fmac_f32_e32 v203, v116, v116
	v_fmac_f32_e32 v203, v117, v117
	v_fmac_f32_e32 v203, v118, v118
	v_fmac_f32_e32 v203, v119, v119
	ds_write_b128 v192, v[116:119] offset:32
	s_waitcnt lgkmcnt(7)
	v_add_f32_e32 v120, v168, v120
	v_add_f32_e32 v121, v169, v121
	v_add_f32_e32 v122, v170, v122
	v_add_f32_e32 v123, v171, v123
	v_fmac_f32_e32 v203, v120, v120
	v_fmac_f32_e32 v203, v121, v121
	v_fmac_f32_e32 v203, v122, v122
	v_fmac_f32_e32 v203, v123, v123
	ds_write_b128 v192, v[120:123] offset:64
	s_waitcnt lgkmcnt(7)
	v_add_f32_e32 v124, v172, v124
	v_add_f32_e32 v125, v173, v125
	v_add_f32_e32 v126, v174, v126
	v_add_f32_e32 v127, v175, v127
	v_fmac_f32_e32 v203, v124, v124
	v_fmac_f32_e32 v203, v125, v125
	v_fmac_f32_e32 v203, v126, v126
	v_fmac_f32_e32 v203, v127, v127
	ds_write_b128 v192, v[124:127] offset:96
	s_waitcnt lgkmcnt(7)
	v_add_f32_e32 v96, v176, v96
	v_add_f32_e32 v97, v177, v97
	v_add_f32_e32 v98, v178, v98
	v_add_f32_e32 v99, v179, v99
	v_fmac_f32_e32 v203, v96, v96
	v_fmac_f32_e32 v203, v97, v97
	v_fmac_f32_e32 v203, v98, v98
	v_fmac_f32_e32 v203, v99, v99
	ds_write_b128 v192, v[96:99] offset:128
	s_waitcnt lgkmcnt(7)
	v_add_f32_e32 v100, v180, v100
	v_add_f32_e32 v101, v181, v101
	v_add_f32_e32 v102, v182, v102
	v_add_f32_e32 v103, v183, v103
	v_fmac_f32_e32 v203, v100, v100
	v_fmac_f32_e32 v203, v101, v101
	v_fmac_f32_e32 v203, v102, v102
	v_fmac_f32_e32 v203, v103, v103
	ds_write_b128 v192, v[100:103] offset:160
	s_waitcnt lgkmcnt(7)
	v_add_f32_e32 v104, v184, v104
	v_add_f32_e32 v105, v185, v105
	v_add_f32_e32 v106, v186, v106
	v_add_f32_e32 v107, v187, v107
	v_fmac_f32_e32 v203, v104, v104
	v_fmac_f32_e32 v203, v105, v105
	v_fmac_f32_e32 v203, v106, v106
	v_fmac_f32_e32 v203, v107, v107
	ds_write_b128 v192, v[104:107] offset:192
	s_waitcnt lgkmcnt(7)
	v_add_f32_e32 v108, v188, v108
	v_add_f32_e32 v109, v189, v109
	v_add_f32_e32 v110, v190, v110
	v_add_f32_e32 v111, v191, v111
	v_fmac_f32_e32 v203, v108, v108
	v_fmac_f32_e32 v203, v109, v109
	v_fmac_f32_e32 v203, v110, v110
	v_fmac_f32_e32 v203, v111, v111
	ds_write_b128 v192, v[108:111] offset:224
	ds_read_b128 v[160:163], v198
	ds_read_b128 v[164:167], v198 offset:1088
	ds_read_b128 v[168:171], v198 offset:2176
	ds_read_b128 v[172:175], v198 offset:3264
	ds_read_b128 v[176:179], v198 offset:4352
	ds_read_b128 v[180:183], v198 offset:5440
	ds_read_b128 v[184:187], v198 offset:6528
	ds_read_b128 v[188:191], v198 offset:7616
	s_add_u32 s74, s66, 0x0
	s_addc_u32 s75, s67, 0
	s_waitcnt lgkmcnt(7)
	global_store_dwordx4 v200, v[160:163], s[74:75]  sc1
	s_add_u32 s74, s66, 0x4000
	s_addc_u32 s75, s67, 0
	s_waitcnt lgkmcnt(6)
	global_store_dwordx4 v200, v[164:167], s[74:75]  sc1
	s_add_u32 s74, s66, 0x8000
	s_addc_u32 s75, s67, 0
	s_waitcnt lgkmcnt(5)
	global_store_dwordx4 v200, v[168:171], s[74:75]  sc1
	s_add_u32 s74, s66, 0xc000
	s_addc_u32 s75, s67, 0
	s_waitcnt lgkmcnt(4)
	global_store_dwordx4 v200, v[172:175], s[74:75]  sc1
	s_add_u32 s74, s66, 0x10000
	s_addc_u32 s75, s67, 0
	s_waitcnt lgkmcnt(3)
	global_store_dwordx4 v200, v[176:179], s[74:75]  sc1
	s_add_u32 s74, s66, 0x14000
	s_addc_u32 s75, s67, 0
	s_waitcnt lgkmcnt(2)
	global_store_dwordx4 v200, v[180:183], s[74:75]  sc1
	s_add_u32 s74, s66, 0x18000
	s_addc_u32 s75, s67, 0
	s_waitcnt lgkmcnt(1)
	global_store_dwordx4 v200, v[184:187], s[74:75]  sc1
	s_add_u32 s74, s66, 0x1c000
	s_addc_u32 s75, s67, 0
	s_waitcnt lgkmcnt(0)
; DI bfr f2bf(float a) { return (bfr)(pack2(a, 0.f) & 0xffffu); }
; DI int crow(int reg, int h) { return (reg & 3) + 8 * (reg >> 2) + 4 * h; }
; template <bool FIRST, bool HAS_H>
; DI void phase_gemm_resid(const Params& p, const bfr* A, const bfr* Wt, const float* gnext, float* ss, char* smem) {
;     ...
;               xo[jj][q] = xsrc[(rbase + i * 32 + crow(qh * 8 + q, 0)) * 1024 + cbase + (jh * 2 + jj) * 32];
; #pragma unroll
;           for (int q = 0; q < 8; ++q) {
;             const int o = (rbase + i * 32 + crow(qh * 8 + q, 0)) * 1024 + cbase;
; #pragma unroll
;             for (int jj = 0; jj < 2; ++jj) {
;               const int j = jh * 2 + jj;
;               const float xn = xo[jj][q] + acc[i][j][qh * 8 + q];
;               X[o + j * 32] = xn;
;               if (HAS_H) Hn[o + j * 32] = f2bf(xn * gnext[cbase + j * 32]);
;               rs[q] += xn * xn;
;             }
;           }
;         }
	global_store_dwordx4 v200, v[188:191], s[74:75]  sc1
	global_load_dwordx4 v[160:163], v202, s[70:71]
	global_load_dwordx4 v[164:167], v202, s[70:71] offset:32
	global_load_dwordx4 v[168:171], v202, s[70:71] offset:64
	global_load_dwordx4 v[172:175], v202, s[70:71] offset:96
	global_load_dwordx4 v[176:179], v202, s[70:71] offset:128
	global_load_dwordx4 v[180:183], v202, s[70:71] offset:160
	global_load_dwordx4 v[184:187], v202, s[70:71] offset:192
	global_load_dwordx4 v[188:191], v202, s[70:71] offset:224
	s_waitcnt vmcnt(7)
	v_mul_f32_e32 v112, v160, v112
	v_mul_f32_e32 v113, v161, v113
	v_mul_f32_e32 v114, v162, v114
	v_mul_f32_e32 v115, v163, v115
	v_cvt_pk_bf16_f32 v112, v112, v113
	v_cvt_pk_bf16_f32 v113, v114, v115
	ds_write_b64 v194, v[112:113]
	s_waitcnt vmcnt(6)
	v_mul_f32_e32 v116, v164, v116
	v_mul_f32_e32 v117, v165, v117
	v_mul_f32_e32 v118, v166, v118
	v_mul_f32_e32 v119, v167, v119
	v_cvt_pk_bf16_f32 v116, v116, v117
	v_cvt_pk_bf16_f32 v117, v118, v119
	ds_write_b64 v194, v[116:117] offset:16
	s_waitcnt vmcnt(5)
	v_mul_f32_e32 v120, v168, v120
	v_mul_f32_e32 v121, v169, v121
	v_mul_f32_e32 v122, v170, v122
	v_mul_f32_e32 v123, v171, v123
	v_cvt_pk_bf16_f32 v120, v120, v121
	v_cvt_pk_bf16_f32 v121, v122, v123
	ds_write_b64 v194, v[120:121] offset:32
	s_waitcnt vmcnt(4)
	v_mul_f32_e32 v124, v172, v124
	v_mul_f32_e32 v125, v173, v125
	v_mul_f32_e32 v126, v174, v126
	v_mul_f32_e32 v127, v175, v127
	v_cvt_pk_bf16_f32 v124, v124, v125
	v_cvt_pk_bf16_f32 v125, v126, v127
	ds_write_b64 v194, v[124:125] offset:48
	s_waitcnt vmcnt(3)
	v_mul_f32_e32 v96, v176, v96
	v_mul_f32_e32 v97, v177, v97
	v_mul_f32_e32 v98, v178, v98
	v_mul_f32_e32 v99, v179, v99
	v_cvt_pk_bf16_f32 v96, v96, v97
	v_cvt_pk_bf16_f32 v97, v98, v99
	ds_write_b64 v194, v[96:97] offset:64
	s_waitcnt vmcnt(2)
	v_mul_f32_e32 v100, v180, v100
	v_mul_f32_e32 v101, v181, v101
	v_mul_f32_e32 v102, v182, v102
	v_mul_f32_e32 v103, v183, v103
	v_cvt_pk_bf16_f32 v100, v100, v101
	v_cvt_pk_bf16_f32 v101, v102, v103
	ds_write_b64 v194, v[100:101] offset:80
	s_waitcnt vmcnt(1)
	v_mul_f32_e32 v104, v184, v104
	v_mul_f32_e32 v105, v185, v105
	v_mul_f32_e32 v106, v186, v106
	v_mul_f32_e32 v107, v187, v107
	v_cvt_pk_bf16_f32 v104, v104, v105
	v_cvt_pk_bf16_f32 v105, v106, v107
	ds_write_b64 v194, v[104:105] offset:96
	s_waitcnt vmcnt(0)
	v_mul_f32_e32 v108, v188, v108
	v_mul_f32_e32 v109, v189, v109
	v_mul_f32_e32 v110, v190, v110
	v_mul_f32_e32 v111, v191, v111
	v_cvt_pk_bf16_f32 v108, v108, v109
	v_cvt_pk_bf16_f32 v109, v110, v111
	ds_write_b64 v194, v[108:109] offset:112
	ds_read_b128 v[160:163], v199
	ds_read_b128 v[164:167], v199 offset:2176
	ds_read_b128 v[168:171], v199 offset:4352
	ds_read_b128 v[172:175], v199 offset:6528
	s_add_u32 s74, s68, 0x0
	s_addc_u32 s75, s69, 0
	s_waitcnt lgkmcnt(3)
	global_store_dwordx4 v201, v[160:163], s[74:75]  sc1
	s_add_u32 s74, s68, 0x4000
	s_addc_u32 s75, s69, 0
	s_waitcnt lgkmcnt(2)
	global_store_dwordx4 v201, v[164:167], s[74:75]  sc1
	s_add_u32 s74, s68, 0x8000
	s_addc_u32 s75, s69, 0
	s_waitcnt lgkmcnt(1)
	global_store_dwordx4 v201, v[168:171], s[74:75]  sc1
	s_add_u32 s74, s68, 0xc000
	s_addc_u32 s75, s69, 0
	s_waitcnt lgkmcnt(0)
	global_store_dwordx4 v201, v[172:175], s[74:75]  sc1
	s_waitcnt vmcnt(4)
	ds_write_b128 v198, v[128:131]
	s_waitcnt vmcnt(4)
	ds_write_b128 v198, v[132:135] offset:1088
	s_waitcnt vmcnt(4)
	ds_write_b128 v198, v[136:139] offset:2176
	s_waitcnt vmcnt(4)
	ds_write_b128 v198, v[140:143] offset:3264
	s_waitcnt vmcnt(4)
	ds_write_b128 v198, v[144:147] offset:4352
	s_waitcnt vmcnt(4)
	ds_write_b128 v198, v[148:151] offset:5440
	s_waitcnt vmcnt(4)
	ds_write_b128 v198, v[152:155] offset:6528
	s_waitcnt vmcnt(4)
	ds_write_b128 v198, v[156:159] offset:7616
	s_add_u32 s74, s64, 0x20000
	s_addc_u32 s75, s65, 0
	global_load_dwordx4 v[128:131], v200, s[74:75]
	s_add_u32 s74, s64, 0x24000
	s_addc_u32 s75, s65, 0
	global_load_dwordx4 v[132:135], v200, s[74:75]
	s_add_u32 s74, s64, 0x28000
	s_addc_u32 s75, s65, 0
	global_load_dwordx4 v[136:139], v200, s[74:75]
	s_add_u32 s74, s64, 0x2c000
	s_addc_u32 s75, s65, 0
	global_load_dwordx4 v[140:143], v200, s[74:75]
	s_add_u32 s74, s64, 0x30000
	s_addc_u32 s75, s65, 0
	global_load_dwordx4 v[144:147], v200, s[74:75]
	s_add_u32 s74, s64, 0x34000
	s_addc_u32 s75, s65, 0
	global_load_dwordx4 v[148:151], v200, s[74:75]
	s_add_u32 s74, s64, 0x38000
	s_addc_u32 s75, s65, 0
	global_load_dwordx4 v[152:155], v200, s[74:75]
	s_add_u32 s74, s64, 0x3c000
	s_addc_u32 s75, s65, 0
	global_load_dwordx4 v[156:159], v200, s[74:75]
	ds_read_b128 v[160:163], v192
	ds_read_b128 v[164:167], v192 offset:32
	ds_read_b128 v[168:171], v192 offset:64
	ds_read_b128 v[172:175], v192 offset:96
	ds_read_b128 v[176:179], v192 offset:128
	ds_read_b128 v[180:183], v192 offset:160
	ds_read_b128 v[184:187], v192 offset:192
	ds_read_b128 v[188:191], v192 offset:224
	s_waitcnt lgkmcnt(7)
	v_add_f32_e32 v80, v160, v80
	v_add_f32_e32 v81, v161, v81
	v_add_f32_e32 v82, v162, v82
	v_add_f32_e32 v83, v163, v83
	v_fmac_f32_e32 v203, v80, v80
	v_fmac_f32_e32 v203, v81, v81
	v_fmac_f32_e32 v203, v82, v82
	v_fmac_f32_e32 v203, v83, v83
	ds_write_b128 v192, v[80:83]
	s_waitcnt lgkmcnt(7)
	v_add_f32_e32 v84, v164, v84
	v_add_f32_e32 v85, v165, v85
	v_add_f32_e32 v86, v166, v86
	v_add_f32_e32 v87, v167, v87
	v_fmac_f32_e32 v203, v84, v84
	v_fmac_f32_e32 v203, v85, v85
	v_fmac_f32_e32 v203, v86, v86
	v_fmac_f32_e32 v203, v87, v87
	ds_write_b128 v192, v[84:87] offset:32
	s_waitcnt lgkmcnt(7)
; DI bfr f2bf(float a) { return (bfr)(pack2(a, 0.f) & 0xffffu); }
; DI int crow(int reg, int h) { return (reg & 3) + 8 * (reg >> 2) + 4 * h; }
; template <bool FIRST, bool HAS_H>
; DI void phase_gemm_resid(const Params& p, const bfr* A, const bfr* Wt, const float* gnext, float* ss, char* smem) {
;     ...
;               xo[jj][q] = xsrc[(rbase + i * 32 + crow(qh * 8 + q, 0)) * 1024 + cbase + (jh * 2 + jj) * 32];
; #pragma unroll
;           for (int q = 0; q < 8; ++q) {
;             const int o = (rbase + i * 32 + crow(qh * 8 + q, 0)) * 1024 + cbase;
; #pragma unroll
;             for (int jj = 0; jj < 2; ++jj) {
;               const int j = jh * 2 + jj;
;               const float xn = xo[jj][q] + acc[i][j][qh * 8 + q];
;               X[o + j * 32] = xn;
;               if (HAS_H) Hn[o + j * 32] = f2bf(xn * gnext[cbase + j * 32]);
;               rs[q] += xn * xn;
;             }
;           }
;         }
	v_add_f32_e32 v88, v168, v88
	v_add_f32_e32 v89, v169, v89
	v_add_f32_e32 v90, v170, v90
	v_add_f32_e32 v91, v171, v91
	v_fmac_f32_e32 v203, v88, v88
	v_fmac_f32_e32 v203, v89, v89
	v_fmac_f32_e32 v203, v90, v90
	v_fmac_f32_e32 v203, v91, v91
	ds_write_b128 v192, v[88:91] offset:64
	s_waitcnt lgkmcnt(7)
	v_add_f32_e32 v92, v172, v92
	v_add_f32_e32 v93, v173, v93
	v_add_f32_e32 v94, v174, v94
	v_add_f32_e32 v95, v175, v95
	v_fmac_f32_e32 v203, v92, v92
	v_fmac_f32_e32 v203, v93, v93
	v_fmac_f32_e32 v203, v94, v94
	v_fmac_f32_e32 v203, v95, v95
	ds_write_b128 v192, v[92:95] offset:96
	s_waitcnt lgkmcnt(7)
	v_add_f32_e32 v64, v176, v64
	v_add_f32_e32 v65, v177, v65
	v_add_f32_e32 v66, v178, v66
	v_add_f32_e32 v67, v179, v67
	v_fmac_f32_e32 v203, v64, v64
	v_fmac_f32_e32 v203, v65, v65
	v_fmac_f32_e32 v203, v66, v66
	v_fmac_f32_e32 v203, v67, v67
	ds_write_b128 v192, v[64:67] offset:128
	s_waitcnt lgkmcnt(7)
	v_add_f32_e32 v68, v180, v68
	v_add_f32_e32 v69, v181, v69
	v_add_f32_e32 v70, v182, v70
	v_add_f32_e32 v71, v183, v71
	v_fmac_f32_e32 v203, v68, v68
	v_fmac_f32_e32 v203, v69, v69
	v_fmac_f32_e32 v203, v70, v70
	v_fmac_f32_e32 v203, v71, v71
	ds_write_b128 v192, v[68:71] offset:160
	s_waitcnt lgkmcnt(7)
	v_add_f32_e32 v72, v184, v72
	v_add_f32_e32 v73, v185, v73
	v_add_f32_e32 v74, v186, v74
	v_add_f32_e32 v75, v187, v75
	v_fmac_f32_e32 v203, v72, v72
	v_fmac_f32_e32 v203, v73, v73
	v_fmac_f32_e32 v203, v74, v74
	v_fmac_f32_e32 v203, v75, v75
	ds_write_b128 v192, v[72:75] offset:192
	s_waitcnt lgkmcnt(7)
	v_add_f32_e32 v76, v188, v76
	v_add_f32_e32 v77, v189, v77
	v_add_f32_e32 v78, v190, v78
	v_add_f32_e32 v79, v191, v79
	v_fmac_f32_e32 v203, v76, v76
	v_fmac_f32_e32 v203, v77, v77
	v_fmac_f32_e32 v203, v78, v78
	v_fmac_f32_e32 v203, v79, v79
	ds_write_b128 v192, v[76:79] offset:224
	ds_read_b128 v[160:163], v198
	ds_read_b128 v[164:167], v198 offset:1088
	ds_read_b128 v[168:171], v198 offset:2176
	ds_read_b128 v[172:175], v198 offset:3264
	ds_read_b128 v[176:179], v198 offset:4352
	ds_read_b128 v[180:183], v198 offset:5440
	ds_read_b128 v[184:187], v198 offset:6528
	ds_read_b128 v[188:191], v198 offset:7616
	s_add_u32 s74, s66, 0x100
	s_addc_u32 s75, s67, 0
	s_waitcnt lgkmcnt(7)
	global_store_dwordx4 v200, v[160:163], s[74:75]  sc1
	s_add_u32 s74, s66, 0x4100
	s_addc_u32 s75, s67, 0
	s_waitcnt lgkmcnt(6)
	global_store_dwordx4 v200, v[164:167], s[74:75]  sc1
	s_add_u32 s74, s66, 0x8100
	s_addc_u32 s75, s67, 0
	s_waitcnt lgkmcnt(5)
	global_store_dwordx4 v200, v[168:171], s[74:75]  sc1
	s_add_u32 s74, s66, 0xc100
	s_addc_u32 s75, s67, 0
	s_waitcnt lgkmcnt(4)
	global_store_dwordx4 v200, v[172:175], s[74:75]  sc1
	s_add_u32 s74, s66, 0x10100
	s_addc_u32 s75, s67, 0
	s_waitcnt lgkmcnt(3)
	global_store_dwordx4 v200, v[176:179], s[74:75]  sc1
	s_add_u32 s74, s66, 0x14100
	s_addc_u32 s75, s67, 0
	s_waitcnt lgkmcnt(2)
	global_store_dwordx4 v200, v[180:183], s[74:75]  sc1
	s_add_u32 s74, s66, 0x18100
	s_addc_u32 s75, s67, 0
	s_waitcnt lgkmcnt(1)
	global_store_dwordx4 v200, v[184:187], s[74:75]  sc1
	s_add_u32 s74, s66, 0x1c100
	s_addc_u32 s75, s67, 0
	s_waitcnt lgkmcnt(0)
	global_store_dwordx4 v200, v[188:191], s[74:75]  sc1
	global_load_dwordx4 v[160:163], v202, s[70:71] offset:256
	global_load_dwordx4 v[164:167], v202, s[70:71] offset:288
	global_load_dwordx4 v[168:171], v202, s[70:71] offset:320
	global_load_dwordx4 v[172:175], v202, s[70:71] offset:352
	global_load_dwordx4 v[176:179], v202, s[70:71] offset:384
	global_load_dwordx4 v[180:183], v202, s[70:71] offset:416
	global_load_dwordx4 v[184:187], v202, s[70:71] offset:448
	global_load_dwordx4 v[188:191], v202, s[70:71] offset:480
	s_waitcnt vmcnt(7)
	v_mul_f32_e32 v80, v160, v80
	v_mul_f32_e32 v81, v161, v81
	v_mul_f32_e32 v82, v162, v82
	v_mul_f32_e32 v83, v163, v83
	v_cvt_pk_bf16_f32 v80, v80, v81
	v_cvt_pk_bf16_f32 v81, v82, v83
	ds_write_b64 v194, v[80:81]
	s_waitcnt vmcnt(6)
	v_mul_f32_e32 v84, v164, v84
	v_mul_f32_e32 v85, v165, v85
	v_mul_f32_e32 v86, v166, v86
	v_mul_f32_e32 v87, v167, v87
	v_cvt_pk_bf16_f32 v84, v84, v85
	v_cvt_pk_bf16_f32 v85, v86, v87
	ds_write_b64 v194, v[84:85] offset:16
	s_waitcnt vmcnt(5)
	v_mul_f32_e32 v88, v168, v88
	v_mul_f32_e32 v89, v169, v89
	v_mul_f32_e32 v90, v170, v90
	v_mul_f32_e32 v91, v171, v91
	v_cvt_pk_bf16_f32 v88, v88, v89
	v_cvt_pk_bf16_f32 v89, v90, v91
	ds_write_b64 v194, v[88:89] offset:32
	s_waitcnt vmcnt(4)
	v_mul_f32_e32 v92, v172, v92
	v_mul_f32_e32 v93, v173, v93
	v_mul_f32_e32 v94, v174, v94
	v_mul_f32_e32 v95, v175, v95
	v_cvt_pk_bf16_f32 v92, v92, v93
	v_cvt_pk_bf16_f32 v93, v94, v95
	ds_write_b64 v194, v[92:93] offset:48
	s_waitcnt vmcnt(3)
	v_mul_f32_e32 v64, v176, v64
	v_mul_f32_e32 v65, v177, v65
	v_mul_f32_e32 v66, v178, v66
	v_mul_f32_e32 v67, v179, v67
	v_cvt_pk_bf16_f32 v64, v64, v65
	v_cvt_pk_bf16_f32 v65, v66, v67
	ds_write_b64 v194, v[64:65] offset:64
	s_waitcnt vmcnt(2)
	v_mul_f32_e32 v68, v180, v68
	v_mul_f32_e32 v69, v181, v69
	v_mul_f32_e32 v70, v182, v70
	v_mul_f32_e32 v71, v183, v71
	v_cvt_pk_bf16_f32 v68, v68, v69
	v_cvt_pk_bf16_f32 v69, v70, v71
	ds_write_b64 v194, v[68:69] offset:80
	s_waitcnt vmcnt(1)
	v_mul_f32_e32 v72, v184, v72
	v_mul_f32_e32 v73, v185, v73
	v_mul_f32_e32 v74, v186, v74
	v_mul_f32_e32 v75, v187, v75
	v_cvt_pk_bf16_f32 v72, v72, v73
	v_cvt_pk_bf16_f32 v73, v74, v75
	ds_write_b64 v194, v[72:73] offset:96
	s_waitcnt vmcnt(0)
	v_mul_f32_e32 v76, v188, v76
	v_mul_f32_e32 v77, v189, v77
	v_mul_f32_e32 v78, v190, v78
	v_mul_f32_e32 v79, v191, v79
	v_cvt_pk_bf16_f32 v76, v76, v77
	v_cvt_pk_bf16_f32 v77, v78, v79
	ds_write_b64 v194, v[76:77] offset:112
	ds_read_b128 v[160:163], v199
	ds_read_b128 v[164:167], v199 offset:2176
	ds_read_b128 v[168:171], v199 offset:4352
	ds_read_b128 v[172:175], v199 offset:6528
	s_add_u32 s74, s68, 0x80
	s_addc_u32 s75, s69, 0
	s_waitcnt lgkmcnt(3)
; DI bfr f2bf(float a) { return (bfr)(pack2(a, 0.f) & 0xffffu); }
; DI int crow(int reg, int h) { return (reg & 3) + 8 * (reg >> 2) + 4 * h; }
; template <bool FIRST, bool HAS_H>
; DI void phase_gemm_resid(const Params& p, const bfr* A, const bfr* Wt, const float* gnext, float* ss, char* smem) {
;     ...
;               xo[jj][q] = xsrc[(rbase + i * 32 + crow(qh * 8 + q, 0)) * 1024 + cbase + (jh * 2 + jj) * 32];
; #pragma unroll
;           for (int q = 0; q < 8; ++q) {
;             const int o = (rbase + i * 32 + crow(qh * 8 + q, 0)) * 1024 + cbase;
; #pragma unroll
;             for (int jj = 0; jj < 2; ++jj) {
;               const int j = jh * 2 + jj;
;               const float xn = xo[jj][q] + acc[i][j][qh * 8 + q];
;               X[o + j * 32] = xn;
;               if (HAS_H) Hn[o + j * 32] = f2bf(xn * gnext[cbase + j * 32]);
;               rs[q] += xn * xn;
;             }
;           }
;         }
	global_store_dwordx4 v201, v[160:163], s[74:75]  sc1
	s_add_u32 s74, s68, 0x4080
	s_addc_u32 s75, s69, 0
	s_waitcnt lgkmcnt(2)
	global_store_dwordx4 v201, v[164:167], s[74:75]  sc1
	s_add_u32 s74, s68, 0x8080
	s_addc_u32 s75, s69, 0
	s_waitcnt lgkmcnt(1)
	global_store_dwordx4 v201, v[168:171], s[74:75]  sc1
	s_add_u32 s74, s68, 0xc080
	s_addc_u32 s75, s69, 0
	s_waitcnt lgkmcnt(0)
	global_store_dwordx4 v201, v[172:175], s[74:75]  sc1
	s_waitcnt vmcnt(4)
	ds_write_b128 v198, v[128:131]
	s_waitcnt vmcnt(4)
	ds_write_b128 v198, v[132:135] offset:1088
	s_waitcnt vmcnt(4)
	ds_write_b128 v198, v[136:139] offset:2176
	s_waitcnt vmcnt(4)
	ds_write_b128 v198, v[140:143] offset:3264
	s_waitcnt vmcnt(4)
	ds_write_b128 v198, v[144:147] offset:4352
	s_waitcnt vmcnt(4)
	ds_write_b128 v198, v[148:151] offset:5440
	s_waitcnt vmcnt(4)
	ds_write_b128 v198, v[152:155] offset:6528
	s_waitcnt vmcnt(4)
	ds_write_b128 v198, v[156:159] offset:7616
	s_add_u32 s74, s64, 0x20100
	s_addc_u32 s75, s65, 0
	global_load_dwordx4 v[128:131], v200, s[74:75]
	s_add_u32 s74, s64, 0x24100
	s_addc_u32 s75, s65, 0
	global_load_dwordx4 v[132:135], v200, s[74:75]
	s_add_u32 s74, s64, 0x28100
	s_addc_u32 s75, s65, 0
	global_load_dwordx4 v[136:139], v200, s[74:75]
	s_add_u32 s74, s64, 0x2c100
	s_addc_u32 s75, s65, 0
	global_load_dwordx4 v[140:143], v200, s[74:75]
	s_add_u32 s74, s64, 0x30100
	s_addc_u32 s75, s65, 0
	global_load_dwordx4 v[144:147], v200, s[74:75]
	s_add_u32 s74, s64, 0x34100
	s_addc_u32 s75, s65, 0
	global_load_dwordx4 v[148:151], v200, s[74:75]
	s_add_u32 s74, s64, 0x38100
	s_addc_u32 s75, s65, 0
	global_load_dwordx4 v[152:155], v200, s[74:75]
	s_add_u32 s74, s64, 0x3c100
	s_addc_u32 s75, s65, 0
	global_load_dwordx4 v[156:159], v200, s[74:75]
	ds_read_b128 v[160:163], v192
	ds_read_b128 v[164:167], v192 offset:32
	ds_read_b128 v[168:171], v192 offset:64
	ds_read_b128 v[172:175], v192 offset:96
	ds_read_b128 v[176:179], v192 offset:128
	ds_read_b128 v[180:183], v192 offset:160
	ds_read_b128 v[184:187], v192 offset:192
	ds_read_b128 v[188:191], v192 offset:224
	s_waitcnt lgkmcnt(7)
	v_add_f32_e32 v48, v160, v48
	v_add_f32_e32 v49, v161, v49
	v_add_f32_e32 v50, v162, v50
	v_add_f32_e32 v51, v163, v51
	v_fmac_f32_e32 v204, v48, v48
	v_fmac_f32_e32 v204, v49, v49
	v_fmac_f32_e32 v204, v50, v50
	v_fmac_f32_e32 v204, v51, v51
	ds_write_b128 v192, v[48:51]
	s_waitcnt lgkmcnt(7)
	v_add_f32_e32 v52, v164, v52
	v_add_f32_e32 v53, v165, v53
	v_add_f32_e32 v54, v166, v54
	v_add_f32_e32 v55, v167, v55
	v_fmac_f32_e32 v204, v52, v52
	v_fmac_f32_e32 v204, v53, v53
	v_fmac_f32_e32 v204, v54, v54
	v_fmac_f32_e32 v204, v55, v55
	ds_write_b128 v192, v[52:55] offset:32
	s_waitcnt lgkmcnt(7)
	v_add_f32_e32 v56, v168, v56
	v_add_f32_e32 v57, v169, v57
	v_add_f32_e32 v58, v170, v58
	v_add_f32_e32 v59, v171, v59
	v_fmac_f32_e32 v204, v56, v56
	v_fmac_f32_e32 v204, v57, v57
	v_fmac_f32_e32 v204, v58, v58
	v_fmac_f32_e32 v204, v59, v59
	ds_write_b128 v192, v[56:59] offset:64
	s_waitcnt lgkmcnt(7)
	v_add_f32_e32 v60, v172, v60
	v_add_f32_e32 v61, v173, v61
	v_add_f32_e32 v62, v174, v62
	v_add_f32_e32 v63, v175, v63
	v_fmac_f32_e32 v204, v60, v60
	v_fmac_f32_e32 v204, v61, v61
	v_fmac_f32_e32 v204, v62, v62
	v_fmac_f32_e32 v204, v63, v63
	ds_write_b128 v192, v[60:63] offset:96
	s_waitcnt lgkmcnt(7)
	v_add_f32_e32 v32, v176, v32
	v_add_f32_e32 v33, v177, v33
	v_add_f32_e32 v34, v178, v34
	v_add_f32_e32 v35, v179, v35
	v_fmac_f32_e32 v204, v32, v32
	v_fmac_f32_e32 v204, v33, v33
	v_fmac_f32_e32 v204, v34, v34
	v_fmac_f32_e32 v204, v35, v35
	ds_write_b128 v192, v[32:35] offset:128
	s_waitcnt lgkmcnt(7)
	v_add_f32_e32 v36, v180, v36
	v_add_f32_e32 v37, v181, v37
	v_add_f32_e32 v38, v182, v38
	v_add_f32_e32 v39, v183, v39
	v_fmac_f32_e32 v204, v36, v36
	v_fmac_f32_e32 v204, v37, v37
	v_fmac_f32_e32 v204, v38, v38
	v_fmac_f32_e32 v204, v39, v39
	ds_write_b128 v192, v[36:39] offset:160
	s_waitcnt lgkmcnt(7)
	v_add_f32_e32 v40, v184, v40
	v_add_f32_e32 v41, v185, v41
	v_add_f32_e32 v42, v186, v42
	v_add_f32_e32 v43, v187, v43
	v_fmac_f32_e32 v204, v40, v40
	v_fmac_f32_e32 v204, v41, v41
	v_fmac_f32_e32 v204, v42, v42
	v_fmac_f32_e32 v204, v43, v43
	ds_write_b128 v192, v[40:43] offset:192
	s_waitcnt lgkmcnt(7)
	v_add_f32_e32 v44, v188, v44
	v_add_f32_e32 v45, v189, v45
	v_add_f32_e32 v46, v190, v46
	v_add_f32_e32 v47, v191, v47
	v_fmac_f32_e32 v204, v44, v44
	v_fmac_f32_e32 v204, v45, v45
	v_fmac_f32_e32 v204, v46, v46
	v_fmac_f32_e32 v204, v47, v47
	ds_write_b128 v192, v[44:47] offset:224
	ds_read_b128 v[160:163], v198
	ds_read_b128 v[164:167], v198 offset:1088
	ds_read_b128 v[168:171], v198 offset:2176
	ds_read_b128 v[172:175], v198 offset:3264
	ds_read_b128 v[176:179], v198 offset:4352
	ds_read_b128 v[180:183], v198 offset:5440
	ds_read_b128 v[184:187], v198 offset:6528
	ds_read_b128 v[188:191], v198 offset:7616
	s_add_u32 s74, s66, 0x20000
	s_addc_u32 s75, s67, 0
	s_waitcnt lgkmcnt(7)
	global_store_dwordx4 v200, v[160:163], s[74:75]  sc1
	s_add_u32 s74, s66, 0x24000
	s_addc_u32 s75, s67, 0
	s_waitcnt lgkmcnt(6)
	global_store_dwordx4 v200, v[164:167], s[74:75]  sc1
	s_add_u32 s74, s66, 0x28000
	s_addc_u32 s75, s67, 0
	s_waitcnt lgkmcnt(5)
	global_store_dwordx4 v200, v[168:171], s[74:75]  sc1
	s_add_u32 s74, s66, 0x2c000
	s_addc_u32 s75, s67, 0
	s_waitcnt lgkmcnt(4)
	global_store_dwordx4 v200, v[172:175], s[74:75]  sc1
	s_add_u32 s74, s66, 0x30000
	s_addc_u32 s75, s67, 0
	s_waitcnt lgkmcnt(3)
	global_store_dwordx4 v200, v[176:179], s[74:75]  sc1
	s_add_u32 s74, s66, 0x34000
	s_addc_u32 s75, s67, 0
	s_waitcnt lgkmcnt(2)
	global_store_dwordx4 v200, v[180:183], s[74:75]  sc1
	s_add_u32 s74, s66, 0x38000
	s_addc_u32 s75, s67, 0
	s_waitcnt lgkmcnt(1)
; DI bfr f2bf(float a) { return (bfr)(pack2(a, 0.f) & 0xffffu); }
; DI int crow(int reg, int h) { return (reg & 3) + 8 * (reg >> 2) + 4 * h; }
; template <bool FIRST, bool HAS_H>
; DI void phase_gemm_resid(const Params& p, const bfr* A, const bfr* Wt, const float* gnext, float* ss, char* smem) {
;     ...
;               xo[jj][q] = xsrc[(rbase + i * 32 + crow(qh * 8 + q, 0)) * 1024 + cbase + (jh * 2 + jj) * 32];
; #pragma unroll
;           for (int q = 0; q < 8; ++q) {
;             const int o = (rbase + i * 32 + crow(qh * 8 + q, 0)) * 1024 + cbase;
; #pragma unroll
;             for (int jj = 0; jj < 2; ++jj) {
;               const int j = jh * 2 + jj;
;               const float xn = xo[jj][q] + acc[i][j][qh * 8 + q];
;               X[o + j * 32] = xn;
;               if (HAS_H) Hn[o + j * 32] = f2bf(xn * gnext[cbase + j * 32]);
;               rs[q] += xn * xn;
;             }
;           }
;         }
	global_store_dwordx4 v200, v[184:187], s[74:75]  sc1
	s_add_u32 s74, s66, 0x3c000
	s_addc_u32 s75, s67, 0
	s_waitcnt lgkmcnt(0)
	global_store_dwordx4 v200, v[188:191], s[74:75]  sc1
	global_load_dwordx4 v[160:163], v202, s[70:71]
	global_load_dwordx4 v[164:167], v202, s[70:71] offset:32
	global_load_dwordx4 v[168:171], v202, s[70:71] offset:64
	global_load_dwordx4 v[172:175], v202, s[70:71] offset:96
	global_load_dwordx4 v[176:179], v202, s[70:71] offset:128
	global_load_dwordx4 v[180:183], v202, s[70:71] offset:160
	global_load_dwordx4 v[184:187], v202, s[70:71] offset:192
	global_load_dwordx4 v[188:191], v202, s[70:71] offset:224
	s_waitcnt vmcnt(7)
	v_mul_f32_e32 v48, v160, v48
	v_mul_f32_e32 v49, v161, v49
	v_mul_f32_e32 v50, v162, v50
	v_mul_f32_e32 v51, v163, v51
	v_cvt_pk_bf16_f32 v48, v48, v49
	v_cvt_pk_bf16_f32 v49, v50, v51
	ds_write_b64 v194, v[48:49]
	s_waitcnt vmcnt(6)
	v_mul_f32_e32 v52, v164, v52
	v_mul_f32_e32 v53, v165, v53
	v_mul_f32_e32 v54, v166, v54
	v_mul_f32_e32 v55, v167, v55
	v_cvt_pk_bf16_f32 v52, v52, v53
	v_cvt_pk_bf16_f32 v53, v54, v55
	ds_write_b64 v194, v[52:53] offset:16
	s_waitcnt vmcnt(5)
	v_mul_f32_e32 v56, v168, v56
	v_mul_f32_e32 v57, v169, v57
	v_mul_f32_e32 v58, v170, v58
	v_mul_f32_e32 v59, v171, v59
	v_cvt_pk_bf16_f32 v56, v56, v57
	v_cvt_pk_bf16_f32 v57, v58, v59
	ds_write_b64 v194, v[56:57] offset:32
	s_waitcnt vmcnt(4)
	v_mul_f32_e32 v60, v172, v60
	v_mul_f32_e32 v61, v173, v61
	v_mul_f32_e32 v62, v174, v62
	v_mul_f32_e32 v63, v175, v63
	v_cvt_pk_bf16_f32 v60, v60, v61
	v_cvt_pk_bf16_f32 v61, v62, v63
	ds_write_b64 v194, v[60:61] offset:48
	s_waitcnt vmcnt(3)
	v_mul_f32_e32 v32, v176, v32
	v_mul_f32_e32 v33, v177, v33
	v_mul_f32_e32 v34, v178, v34
	v_mul_f32_e32 v35, v179, v35
	v_cvt_pk_bf16_f32 v32, v32, v33
	v_cvt_pk_bf16_f32 v33, v34, v35
	ds_write_b64 v194, v[32:33] offset:64
	s_waitcnt vmcnt(2)
	v_mul_f32_e32 v36, v180, v36
	v_mul_f32_e32 v37, v181, v37
	v_mul_f32_e32 v38, v182, v38
	v_mul_f32_e32 v39, v183, v39
	v_cvt_pk_bf16_f32 v36, v36, v37
	v_cvt_pk_bf16_f32 v37, v38, v39
	ds_write_b64 v194, v[36:37] offset:80
	s_waitcnt vmcnt(1)
	v_mul_f32_e32 v40, v184, v40
	v_mul_f32_e32 v41, v185, v41
	v_mul_f32_e32 v42, v186, v42
	v_mul_f32_e32 v43, v187, v43
	v_cvt_pk_bf16_f32 v40, v40, v41
	v_cvt_pk_bf16_f32 v41, v42, v43
	ds_write_b64 v194, v[40:41] offset:96
	s_waitcnt vmcnt(0)
	v_mul_f32_e32 v44, v188, v44
	v_mul_f32_e32 v45, v189, v45
	v_mul_f32_e32 v46, v190, v46
	v_mul_f32_e32 v47, v191, v47
	v_cvt_pk_bf16_f32 v44, v44, v45
	v_cvt_pk_bf16_f32 v45, v46, v47
	ds_write_b64 v194, v[44:45] offset:112
	ds_read_b128 v[160:163], v199
	ds_read_b128 v[164:167], v199 offset:2176
	ds_read_b128 v[168:171], v199 offset:4352
	ds_read_b128 v[172:175], v199 offset:6528
	s_add_u32 s74, s68, 0x10000
	s_addc_u32 s75, s69, 0
	s_waitcnt lgkmcnt(3)
	global_store_dwordx4 v201, v[160:163], s[74:75]  sc1
	s_add_u32 s74, s68, 0x14000
	s_addc_u32 s75, s69, 0
	s_waitcnt lgkmcnt(2)
	global_store_dwordx4 v201, v[164:167], s[74:75]  sc1
	s_add_u32 s74, s68, 0x18000
	s_addc_u32 s75, s69, 0
	s_waitcnt lgkmcnt(1)
	global_store_dwordx4 v201, v[168:171], s[74:75]  sc1
	s_add_u32 s74, s68, 0x1c000
	s_addc_u32 s75, s69, 0
	s_waitcnt lgkmcnt(0)
	global_store_dwordx4 v201, v[172:175], s[74:75]  sc1
	s_waitcnt vmcnt(4)
	ds_write_b128 v198, v[128:131]
	s_waitcnt vmcnt(4)
	ds_write_b128 v198, v[132:135] offset:1088
	s_waitcnt vmcnt(4)
	ds_write_b128 v198, v[136:139] offset:2176
	s_waitcnt vmcnt(4)
	ds_write_b128 v198, v[140:143] offset:3264
	s_waitcnt vmcnt(4)
	ds_write_b128 v198, v[144:147] offset:4352
	s_waitcnt vmcnt(4)
	ds_write_b128 v198, v[148:151] offset:5440
	s_waitcnt vmcnt(4)
	ds_write_b128 v198, v[152:155] offset:6528
	s_waitcnt vmcnt(4)
	ds_write_b128 v198, v[156:159] offset:7616
	ds_read_b128 v[160:163], v192
	ds_read_b128 v[164:167], v192 offset:32
	ds_read_b128 v[168:171], v192 offset:64
	ds_read_b128 v[172:175], v192 offset:96
	ds_read_b128 v[176:179], v192 offset:128
	ds_read_b128 v[180:183], v192 offset:160
	ds_read_b128 v[184:187], v192 offset:192
	ds_read_b128 v[188:191], v192 offset:224
	s_waitcnt lgkmcnt(7)
	v_add_f32_e32 v16, v160, v16
	v_add_f32_e32 v17, v161, v17
	v_add_f32_e32 v18, v162, v18
	v_add_f32_e32 v19, v163, v19
	v_fmac_f32_e32 v204, v16, v16
	v_fmac_f32_e32 v204, v17, v17
	v_fmac_f32_e32 v204, v18, v18
	v_fmac_f32_e32 v204, v19, v19
	ds_write_b128 v192, v[16:19]
	s_waitcnt lgkmcnt(7)
	v_add_f32_e32 v20, v164, v20
	v_add_f32_e32 v21, v165, v21
	v_add_f32_e32 v22, v166, v22
	v_add_f32_e32 v23, v167, v23
	v_fmac_f32_e32 v204, v20, v20
	v_fmac_f32_e32 v204, v21, v21
	v_fmac_f32_e32 v204, v22, v22
	v_fmac_f32_e32 v204, v23, v23
	ds_write_b128 v192, v[20:23] offset:32
	s_waitcnt lgkmcnt(7)
	v_add_f32_e32 v24, v168, v24
	v_add_f32_e32 v25, v169, v25
	v_add_f32_e32 v26, v170, v26
	v_add_f32_e32 v27, v171, v27
	v_fmac_f32_e32 v204, v24, v24
	v_fmac_f32_e32 v204, v25, v25
	v_fmac_f32_e32 v204, v26, v26
	v_fmac_f32_e32 v204, v27, v27
	ds_write_b128 v192, v[24:27] offset:64
	s_waitcnt lgkmcnt(7)
	v_add_f32_e32 v28, v172, v28
	v_add_f32_e32 v29, v173, v29
	v_add_f32_e32 v30, v174, v30
	v_add_f32_e32 v31, v175, v31
	v_fmac_f32_e32 v204, v28, v28
	v_fmac_f32_e32 v204, v29, v29
	v_fmac_f32_e32 v204, v30, v30
	v_fmac_f32_e32 v204, v31, v31
	ds_write_b128 v192, v[28:31] offset:96
	s_waitcnt lgkmcnt(7)
	v_add_f32_e32 v0, v176, v0
	v_add_f32_e32 v1, v177, v1
	v_add_f32_e32 v2, v178, v2
	v_add_f32_e32 v3, v179, v3
	v_fmac_f32_e32 v204, v0, v0
	v_fmac_f32_e32 v204, v1, v1
	v_fmac_f32_e32 v204, v2, v2
	v_fmac_f32_e32 v204, v3, v3
	ds_write_b128 v192, v[0:3] offset:128
	s_waitcnt lgkmcnt(7)
; DI bfr f2bf(float a) { return (bfr)(pack2(a, 0.f) & 0xffffu); }
; DI int crow(int reg, int h) { return (reg & 3) + 8 * (reg >> 2) + 4 * h; }
; template <bool FIRST, bool HAS_H>
; DI void phase_gemm_resid(const Params& p, const bfr* A, const bfr* Wt, const float* gnext, float* ss, char* smem) {
;     ...
;           for (int q = 0; q < 8; ++q) {
;             const int o = (rbase + i * 32 + crow(qh * 8 + q, 0)) * 1024 + cbase;
; #pragma unroll
;             for (int jj = 0; jj < 2; ++jj) {
;               const int j = jh * 2 + jj;
;               const float xn = xo[jj][q] + acc[i][j][qh * 8 + q];
;               X[o + j * 32] = xn;
;               if (HAS_H) Hn[o + j * 32] = f2bf(xn * gnext[cbase + j * 32]);
;               rs[q] += xn * xn;
;             }
;           }
;         }
; #pragma unroll
;         for (int q = 0; q < 8; ++q) rs[q] = half32_sum_hi(rs[q]);
;         if (r == 31) {
; #pragma unroll
;           for (int q = 0; q < 8; ++q) unsafeAtomicAdd(ss + rbase + i * 32 + crow(qh * 8 + q, 0), rs[q]);
;         }
	v_add_f32_e32 v4, v180, v4
	v_add_f32_e32 v5, v181, v5
	v_add_f32_e32 v6, v182, v6
	v_add_f32_e32 v7, v183, v7
	v_fmac_f32_e32 v204, v4, v4
	v_fmac_f32_e32 v204, v5, v5
	v_fmac_f32_e32 v204, v6, v6
	v_fmac_f32_e32 v204, v7, v7
	ds_write_b128 v192, v[4:7] offset:160
	s_waitcnt lgkmcnt(7)
	v_add_f32_e32 v8, v184, v8
	v_add_f32_e32 v9, v185, v9
	v_add_f32_e32 v10, v186, v10
	v_add_f32_e32 v11, v187, v11
	v_fmac_f32_e32 v204, v8, v8
	v_fmac_f32_e32 v204, v9, v9
	v_fmac_f32_e32 v204, v10, v10
	v_fmac_f32_e32 v204, v11, v11
	ds_write_b128 v192, v[8:11] offset:192
	s_waitcnt lgkmcnt(7)
	v_add_f32_e32 v12, v188, v12
	v_add_f32_e32 v13, v189, v13
	v_add_f32_e32 v14, v190, v14
	v_add_f32_e32 v15, v191, v15
	v_fmac_f32_e32 v204, v12, v12
	v_fmac_f32_e32 v204, v13, v13
	v_fmac_f32_e32 v204, v14, v14
	v_fmac_f32_e32 v204, v15, v15
	ds_write_b128 v192, v[12:15] offset:224
	ds_read_b128 v[160:163], v198
	ds_read_b128 v[164:167], v198 offset:1088
	ds_read_b128 v[168:171], v198 offset:2176
	ds_read_b128 v[172:175], v198 offset:3264
	ds_read_b128 v[176:179], v198 offset:4352
	ds_read_b128 v[180:183], v198 offset:5440
	ds_read_b128 v[184:187], v198 offset:6528
	ds_read_b128 v[188:191], v198 offset:7616
	s_add_u32 s74, s66, 0x20100
	s_addc_u32 s75, s67, 0
	s_waitcnt lgkmcnt(7)
	global_store_dwordx4 v200, v[160:163], s[74:75]  sc1
	s_add_u32 s74, s66, 0x24100
	s_addc_u32 s75, s67, 0
	s_waitcnt lgkmcnt(6)
	global_store_dwordx4 v200, v[164:167], s[74:75]  sc1
	s_add_u32 s74, s66, 0x28100
	s_addc_u32 s75, s67, 0
	s_waitcnt lgkmcnt(5)
	global_store_dwordx4 v200, v[168:171], s[74:75]  sc1
	s_add_u32 s74, s66, 0x2c100
	s_addc_u32 s75, s67, 0
	s_waitcnt lgkmcnt(4)
	global_store_dwordx4 v200, v[172:175], s[74:75]  sc1
	s_add_u32 s74, s66, 0x30100
	s_addc_u32 s75, s67, 0
	s_waitcnt lgkmcnt(3)
	global_store_dwordx4 v200, v[176:179], s[74:75]  sc1
	s_add_u32 s74, s66, 0x34100
	s_addc_u32 s75, s67, 0
	s_waitcnt lgkmcnt(2)
	global_store_dwordx4 v200, v[180:183], s[74:75]  sc1
	s_add_u32 s74, s66, 0x38100
	s_addc_u32 s75, s67, 0
	s_waitcnt lgkmcnt(1)
	global_store_dwordx4 v200, v[184:187], s[74:75]  sc1
	s_add_u32 s74, s66, 0x3c100
	s_addc_u32 s75, s67, 0
	s_waitcnt lgkmcnt(0)
	global_store_dwordx4 v200, v[188:191], s[74:75]  sc1
	global_load_dwordx4 v[160:163], v202, s[70:71] offset:256
	global_load_dwordx4 v[164:167], v202, s[70:71] offset:288
	global_load_dwordx4 v[168:171], v202, s[70:71] offset:320
	global_load_dwordx4 v[172:175], v202, s[70:71] offset:352
	global_load_dwordx4 v[176:179], v202, s[70:71] offset:384
	global_load_dwordx4 v[180:183], v202, s[70:71] offset:416
	global_load_dwordx4 v[184:187], v202, s[70:71] offset:448
	global_load_dwordx4 v[188:191], v202, s[70:71] offset:480
	s_waitcnt vmcnt(7)
	v_mul_f32_e32 v16, v160, v16
	v_mul_f32_e32 v17, v161, v17
	v_mul_f32_e32 v18, v162, v18
	v_mul_f32_e32 v19, v163, v19
	v_cvt_pk_bf16_f32 v16, v16, v17
	v_cvt_pk_bf16_f32 v17, v18, v19
	ds_write_b64 v194, v[16:17]
	s_waitcnt vmcnt(6)
	v_mul_f32_e32 v20, v164, v20
	v_mul_f32_e32 v21, v165, v21
	v_mul_f32_e32 v22, v166, v22
	v_mul_f32_e32 v23, v167, v23
	v_cvt_pk_bf16_f32 v20, v20, v21
	v_cvt_pk_bf16_f32 v21, v22, v23
	ds_write_b64 v194, v[20:21] offset:16
	s_waitcnt vmcnt(5)
	v_mul_f32_e32 v24, v168, v24
	v_mul_f32_e32 v25, v169, v25
	v_mul_f32_e32 v26, v170, v26
	v_mul_f32_e32 v27, v171, v27
	v_cvt_pk_bf16_f32 v24, v24, v25
	v_cvt_pk_bf16_f32 v25, v26, v27
	ds_write_b64 v194, v[24:25] offset:32
	s_waitcnt vmcnt(4)
	v_mul_f32_e32 v28, v172, v28
	v_mul_f32_e32 v29, v173, v29
	v_mul_f32_e32 v30, v174, v30
	v_mul_f32_e32 v31, v175, v31
	v_cvt_pk_bf16_f32 v28, v28, v29
	v_cvt_pk_bf16_f32 v29, v30, v31
	ds_write_b64 v194, v[28:29] offset:48
	s_waitcnt vmcnt(3)
	v_mul_f32_e32 v0, v176, v0
	v_mul_f32_e32 v1, v177, v1
	v_mul_f32_e32 v2, v178, v2
	v_mul_f32_e32 v3, v179, v3
	v_cvt_pk_bf16_f32 v0, v0, v1
	v_cvt_pk_bf16_f32 v1, v2, v3
	ds_write_b64 v194, v[0:1] offset:64
	s_waitcnt vmcnt(2)
	v_mul_f32_e32 v4, v180, v4
	v_mul_f32_e32 v5, v181, v5
	v_mul_f32_e32 v6, v182, v6
	v_mul_f32_e32 v7, v183, v7
	v_cvt_pk_bf16_f32 v4, v4, v5
	v_cvt_pk_bf16_f32 v5, v6, v7
	ds_write_b64 v194, v[4:5] offset:80
	s_waitcnt vmcnt(1)
	v_mul_f32_e32 v8, v184, v8
	v_mul_f32_e32 v9, v185, v9
	v_mul_f32_e32 v10, v186, v10
	v_mul_f32_e32 v11, v187, v11
	v_cvt_pk_bf16_f32 v8, v8, v9
	v_cvt_pk_bf16_f32 v9, v10, v11
	ds_write_b64 v194, v[8:9] offset:96
	s_waitcnt vmcnt(0)
	v_mul_f32_e32 v12, v188, v12
	v_mul_f32_e32 v13, v189, v13
	v_mul_f32_e32 v14, v190, v14
	v_mul_f32_e32 v15, v191, v15
	v_cvt_pk_bf16_f32 v12, v12, v13
	v_cvt_pk_bf16_f32 v13, v14, v15
	ds_write_b64 v194, v[12:13] offset:112
	ds_read_b128 v[160:163], v199
	ds_read_b128 v[164:167], v199 offset:2176
	ds_read_b128 v[168:171], v199 offset:4352
	ds_read_b128 v[172:175], v199 offset:6528
	s_add_u32 s74, s68, 0x10080
	s_addc_u32 s75, s69, 0
	s_waitcnt lgkmcnt(3)
	global_store_dwordx4 v201, v[160:163], s[74:75]  sc1
	s_add_u32 s74, s68, 0x14080
	s_addc_u32 s75, s69, 0
	s_waitcnt lgkmcnt(2)
	global_store_dwordx4 v201, v[164:167], s[74:75]  sc1
	s_add_u32 s74, s68, 0x18080
	s_addc_u32 s75, s69, 0
	s_waitcnt lgkmcnt(1)
	global_store_dwordx4 v201, v[168:171], s[74:75]  sc1
	s_add_u32 s74, s68, 0x1c080
	s_addc_u32 s75, s69, 0
	s_waitcnt lgkmcnt(0)
	global_store_dwordx4 v201, v[172:175], s[74:75]  sc1
	s_load_dwordx2 s[64:65], s[92:93], 0x140
	ds_bpermute_b32 v208, v206, v203
	ds_bpermute_b32 v209, v206, v204
	s_waitcnt lgkmcnt(0)
	s_add_u32 s64, s64, 0x10200
	s_addc_u32 s65, s65, 0
	v_add_f32_e32 v208, v208, v203
	v_add_f32_e32 v209, v209, v204
	s_mov_b32 exec_hi, 0
	s_nop 1
	global_atomic_add_f32 v205, v208, s[64:65]
	global_atomic_add_f32 v205, v209, s[64:65] offset:128
	s_mov_b64 exec, -1
	v_readlane_b32 s64, v207, 0
	v_readlane_b32 s65, v207, 1
	v_readlane_b32 s66, v207, 2
	v_readlane_b32 s67, v207, 3
	v_readlane_b32 s68, v207, 4
	v_readlane_b32 s69, v207, 5
	v_readlane_b32 s70, v207, 6
	v_readlane_b32 s71, v207, 7
	v_readlane_b32 s72, v207, 8
	v_readlane_b32 s73, v207, 9
	v_readlane_b32 s74, v207, 10
	v_readlane_b32 s75, v207, 11
	v_readlane_b32 s76, v207, 12
	v_readlane_b32 s77, v207, 13
	v_readlane_b32 s78, v207, 14
	v_readlane_b32 s79, v207, 15
	s_nop 7
	s_branch .LBB0_1096

; #define MFMA32(a, b, c) __builtin_amdgcn_mfma_f32_32x32x16_bf16((a), (b), (c), 0, 0, 0)
; #define GA_LOAD(pr_) do { _Pragma("unroll") for (int i = 0; i < 4; ++i) ra[i] = *(const u32x4*)(Ab + (i * 32) * lda + (pr_) * 64); } while (0)
; #define GB_LOAD(kt_) do { const bfr* bk_ = Bb + (kt_) * NB * 32; \
;     _Pragma("unroll") for (int i = 0; i < 4; ++i) rb[i] = *(const u32x4*)(bk_ + (i * 64) * 32); } while (0)
; #define G_STORE(kt_) do { bfr* as_ = S0 + ((kt_) & 1) * GSTAGE; bfr* bs_ = as_ + 128 * 40; \
;     if (apar == ((kt_) & 1)) { _Pragma("unroll") for (int i = 0; i < 4; ++i) *(u32x4*)(as_ + asoff + i * 32 * 40) = ra[i]; } \
;     _Pragma("unroll") for (int i = 0; i < 4; ++i) *(u32x4*)(bs_ + bsoff + i * 64 * 40) = rb[i]; } while (0)
; template <int lda>
; DI void gemm_mainloop(const bfr* __restrict__ A, const bfr* __restrict__ Bt, int NB, int K, int m0, int n0, char* smem, f32x16 (&acc)[2][4]) {
;     ...
;   for (int kt = 0; kt < nk; ++kt) {
;     if (kt + 1 < nk) G_STORE(kt + 1);
;     if (kt + 2 < nk) {
;       GB_LOAD(kt + 2);
;       if ((kt & 1) == 0) GA_LOAD((kt >> 1) + 1);
;     }
;     const bfr* As = S0 + (kt & 1) * GSTAGE;
;     const bfr* Bs = As + 128 * 40;
; #pragma unroll
;     for (int ks = 0; ks < 2; ++ks) {
;       bf16x8 af[2], bfg[4];
; #pragma unroll
;       for (int i = 0; i < 2; ++i) af[i] = *(const bf16x8*)(As + (wr * 64 + i * 32 + r) * 40 + ks * 16 + hl * 8);
; #pragma unroll
;       for (int j = 0; j < 4; ++j) bfg[j] = *(const bf16x8*)(Bs + (wc * 128 + j * 32 + r) * 40 + ks * 16 + hl * 8);
; #pragma unroll
;       for (int i = 0; i < 2; ++i)
; #pragma unroll
;         for (int j = 0; j < 4; ++j) acc[i][j] = MFMA32(af[i], bfg[j], acc[i][j]);
;     }
;     __syncthreads();
.Lp12_loop:
	s_waitcnt vmcnt(6) lgkmcnt(0)
	s_barrier
	s_mul_i32 s74, s71, 0x6000
	s_add_u32 s75, s74, 0x2000
	s_cmp_eq_u32 s71, 2
	s_cselect_b32 s75, 0x10000, s75
	v_add_u32_e32 v183, s74, v179
	v_add_u32_e32 v185, s75, v181
	v_add_u32_e32 v184, s74, v180
	v_add_u32_e32 v186, s75, v182
	s_add_u32 s71, s71, 1
	s_cmp_eq_u32 s71, 3
	s_cselect_b32 s71, 0, s71
	ds_read_b128 v[128:131], v183
	ds_read_b128 v[144:147], v185
	ds_read_b128 v[148:151], v185 offset:2048
	ds_read_b128 v[152:155], v185 offset:4096
	ds_read_b128 v[156:159], v185 offset:6144
	ds_read_b128 v[132:135], v183 offset:2048
	v_mfma_f32_32x32x16_bf16 v[112:127], v[160:163], v[136:139], v[112:127]
	s_mul_i32 s74, s70, 0x6000
	s_add_u32 s75, s74, s68
	s_mov_b32 m0, s75
	s_add_u32 s76, s74, 0x2000
	s_cmp_eq_u32 s70, 2
	s_cselect_b32 s76, 0x10000, s76
	global_load_lds_dwordx4 v176, s[64:65]
	v_mfma_f32_32x32x16_bf16 v[96:111], v[164:167], v[136:139], v[96:111]
	s_add_u32 m0, s75, 0x400
	s_add_u32 s76, s76, s69
	global_load_lds_dwordx4 v177, s[64:65]
	v_mfma_f32_32x32x16_bf16 v[80:95], v[168:171], v[136:139], v[80:95]
	s_mov_b32 m0, s76
	s_add_u32 s64, s64, 64
	s_addc_u32 s65, s65, 0
	global_load_lds_dwordx4 v178, s[66:67]
	v_mfma_f32_32x32x16_bf16 v[64:79], v[172:175], v[136:139], v[64:79]
	global_load_lds_dwordx4 v178, s[66:67] offset:1024
	v_mfma_f32_32x32x16_bf16 v[48:63], v[160:163], v[140:143], v[48:63]
	global_load_lds_dwordx4 v178, s[66:67] offset:2048
	v_mfma_f32_32x32x16_bf16 v[32:47], v[164:167], v[140:143], v[32:47]
	global_load_lds_dwordx4 v178, s[66:67] offset:3072
	s_add_u32 s66, s66, 0x20000
	s_addc_u32 s67, s67, 0
	v_mfma_f32_32x32x16_bf16 v[16:31], v[168:171], v[140:143], v[16:31]
	s_add_u32 s70, s70, 1
	s_cmp_eq_u32 s70, 3
	s_cselect_b32 s70, 0, s70
	v_mfma_f32_32x32x16_bf16 v[0:15], v[172:175], v[140:143], v[0:15]
	ds_read_b128 v[136:139], v184
	ds_read_b128 v[160:163], v186
	ds_read_b128 v[164:167], v186 offset:2048
	ds_read_b128 v[168:171], v186 offset:4096
	ds_read_b128 v[172:175], v186 offset:6144
	ds_read_b128 v[140:143], v184 offset:2048
	s_waitcnt lgkmcnt(10)
	v_mfma_f32_32x32x16_bf16 v[112:127], v[144:147], v[128:131], v[112:127]
	s_waitcnt lgkmcnt(9)
	v_mfma_f32_32x32x16_bf16 v[96:111], v[148:151], v[128:131], v[96:111]
	s_waitcnt lgkmcnt(8)
	v_mfma_f32_32x32x16_bf16 v[80:95], v[152:155], v[128:131], v[80:95]
	s_waitcnt lgkmcnt(7)
	v_mfma_f32_32x32x16_bf16 v[64:79], v[156:159], v[128:131], v[64:79]
	s_waitcnt lgkmcnt(6)
	v_mfma_f32_32x32x16_bf16 v[48:63], v[144:147], v[132:135], v[48:63]
	v_mfma_f32_32x32x16_bf16 v[32:47], v[148:151], v[132:135], v[32:47]
	v_mfma_f32_32x32x16_bf16 v[16:31], v[152:155], v[132:135], v[16:31]
	v_mfma_f32_32x32x16_bf16 v[0:15], v[156:159], v[132:135], v[0:15]
	s_add_u32 s72, s72, 1
	s_cmp_lt_u32 s72, 29
	s_cbranch_scc1 .Lp12_loop
	s_waitcnt vmcnt(6) lgkmcnt(0)
	s_barrier
	s_mul_i32 s74, s71, 0x6000
	s_add_u32 s75, s74, 0x2000
	s_cmp_eq_u32 s71, 2
	s_cselect_b32 s75, 0x10000, s75
	v_add_u32_e32 v183, s74, v179
	v_add_u32_e32 v185, s75, v181
	v_add_u32_e32 v184, s74, v180
	v_add_u32_e32 v186, s75, v182
	s_add_u32 s71, s71, 1
	s_cmp_eq_u32 s71, 3
	s_cselect_b32 s71, 0, s71
	ds_read_b128 v[128:131], v183
	ds_read_b128 v[144:147], v185
	ds_read_b128 v[148:151], v185 offset:2048
	ds_read_b128 v[152:155], v185 offset:4096
	ds_read_b128 v[156:159], v185 offset:6144
	ds_read_b128 v[132:135], v183 offset:2048
	v_mfma_f32_32x32x16_bf16 v[112:127], v[160:163], v[136:139], v[112:127]
	v_mfma_f32_32x32x16_bf16 v[96:111], v[164:167], v[136:139], v[96:111]
	v_mfma_f32_32x32x16_bf16 v[80:95], v[168:171], v[136:139], v[80:95]
	v_mfma_f32_32x32x16_bf16 v[64:79], v[172:175], v[136:139], v[64:79]
	v_mfma_f32_32x32x16_bf16 v[48:63], v[160:163], v[140:143], v[48:63]
	v_mfma_f32_32x32x16_bf16 v[32:47], v[164:167], v[140:143], v[32:47]
	v_mfma_f32_32x32x16_bf16 v[16:31], v[168:171], v[140:143], v[16:31]
	v_mfma_f32_32x32x16_bf16 v[0:15], v[172:175], v[140:143], v[0:15]
	ds_read_b128 v[136:139], v184
	ds_read_b128 v[160:163], v186
	ds_read_b128 v[164:167], v186 offset:2048
	ds_read_b128 v[168:171], v186 offset:4096
	ds_read_b128 v[172:175], v186 offset:6144
	ds_read_b128 v[140:143], v184 offset:2048
	s_waitcnt lgkmcnt(10)
	v_mfma_f32_32x32x16_bf16 v[112:127], v[144:147], v[128:131], v[112:127]
	s_waitcnt lgkmcnt(9)
	v_mfma_f32_32x32x16_bf16 v[96:111], v[148:151], v[128:131], v[96:111]
	s_waitcnt lgkmcnt(8)
	v_mfma_f32_32x32x16_bf16 v[80:95], v[152:155], v[128:131], v[80:95]
	s_waitcnt lgkmcnt(7)
	v_mfma_f32_32x32x16_bf16 v[64:79], v[156:159], v[128:131], v[64:79]
	s_waitcnt lgkmcnt(6)
	v_mfma_f32_32x32x16_bf16 v[48:63], v[144:147], v[132:135], v[48:63]
	v_mfma_f32_32x32x16_bf16 v[32:47], v[148:151], v[132:135], v[32:47]
	v_mfma_f32_32x32x16_bf16 v[16:31], v[152:155], v[132:135], v[16:31]
	v_mfma_f32_32x32x16_bf16 v[0:15], v[156:159], v[132:135], v[0:15]
	s_waitcnt vmcnt(0) lgkmcnt(0)
	s_barrier
; #define MFMA32(a, b, c) __builtin_amdgcn_mfma_f32_32x32x16_bf16((a), (b), (c), 0, 0, 0)
; DI bfr f2bf(float a) { return (bfr)(pack2(a, 0.f) & 0xffffu); }
; template <int lda>
; DI void gemm_mainloop(const bfr* __restrict__ A, const bfr* __restrict__ Bt, int NB, int K, int m0, int n0, char* smem, f32x16 (&acc)[2][4]) {
;     ...
; #pragma unroll
;     for (int ks = 0; ks < 2; ++ks) {
;       bf16x8 af[2], bfg[4];
; #pragma unroll
;       for (int i = 0; i < 2; ++i) af[i] = *(const bf16x8*)(As + (wr * 64 + i * 32 + r) * 40 + ks * 16 + hl * 8);
; #pragma unroll
;       for (int j = 0; j < 4; ++j) bfg[j] = *(const bf16x8*)(Bs + (wc * 128 + j * 32 + r) * 40 + ks * 16 + hl * 8);
; #pragma unroll
;       for (int i = 0; i < 2; ++i)
; #pragma unroll
;         for (int j = 0; j < 4; ++j) acc[i][j] = MFMA32(af[i], bfg[j], acc[i][j]);
;     }
;     __syncthreads();
; DI void phase_gemm_bf16out(const Params& p, const bfr* A, const bfr* Wt, bfr* C, int N, const float* ss, char* smem) {
;     ...
;   for (int t0 = blockIdx.x; t0 < 128 * ntn; t0 += gridDim.x) {
;     const int t = ((gridDim.x & 7) == 0) ? xcd_tile(t0, ntn) : t0;
;     int mt = t / ntn, nt = t % ntn;
;     gemm_tile<1024>(A, Wt, N, 1024, mt * 128, nt * 256, smem,
;               [=](int row, int col, float v) {
;                 float inv = rsqrtf(ss[row] * (1.0f / 1024.0f) + EPSF);
;                 C[(size_t)row * N + col] = f2bf(v * inv);
;               });
	s_mul_i32 s74, s71, 0x6000
	s_add_u32 s75, s74, 0x2000
	s_cmp_eq_u32 s71, 2
	s_cselect_b32 s75, 0x10000, s75
	v_add_u32_e32 v183, s74, v179
	v_add_u32_e32 v185, s75, v181
	v_add_u32_e32 v184, s74, v180
	v_add_u32_e32 v186, s75, v182
	s_add_u32 s71, s71, 1
	s_cmp_eq_u32 s71, 3
	s_cselect_b32 s71, 0, s71
	ds_read_b128 v[128:131], v183
	ds_read_b128 v[144:147], v185
	ds_read_b128 v[148:151], v185 offset:2048
	ds_read_b128 v[152:155], v185 offset:4096
	ds_read_b128 v[156:159], v185 offset:6144
	ds_read_b128 v[132:135], v183 offset:2048
	v_mfma_f32_32x32x16_bf16 v[112:127], v[160:163], v[136:139], v[112:127]
	v_mfma_f32_32x32x16_bf16 v[96:111], v[164:167], v[136:139], v[96:111]
	v_mfma_f32_32x32x16_bf16 v[80:95], v[168:171], v[136:139], v[80:95]
	v_mfma_f32_32x32x16_bf16 v[64:79], v[172:175], v[136:139], v[64:79]
	v_mfma_f32_32x32x16_bf16 v[48:63], v[160:163], v[140:143], v[48:63]
	v_mfma_f32_32x32x16_bf16 v[32:47], v[164:167], v[140:143], v[32:47]
	v_mfma_f32_32x32x16_bf16 v[16:31], v[168:171], v[140:143], v[16:31]
	v_mfma_f32_32x32x16_bf16 v[0:15], v[172:175], v[140:143], v[0:15]
	ds_read_b128 v[136:139], v184
	ds_read_b128 v[160:163], v186
	ds_read_b128 v[164:167], v186 offset:2048
	ds_read_b128 v[168:171], v186 offset:4096
	ds_read_b128 v[172:175], v186 offset:6144
	ds_read_b128 v[140:143], v184 offset:2048
	s_waitcnt lgkmcnt(10)
	v_mfma_f32_32x32x16_bf16 v[112:127], v[144:147], v[128:131], v[112:127]
	s_waitcnt lgkmcnt(9)
	v_mfma_f32_32x32x16_bf16 v[96:111], v[148:151], v[128:131], v[96:111]
	s_waitcnt lgkmcnt(8)
	v_mfma_f32_32x32x16_bf16 v[80:95], v[152:155], v[128:131], v[80:95]
	s_waitcnt lgkmcnt(7)
	v_mfma_f32_32x32x16_bf16 v[64:79], v[156:159], v[128:131], v[64:79]
	s_waitcnt lgkmcnt(6)
	v_mfma_f32_32x32x16_bf16 v[48:63], v[144:147], v[132:135], v[48:63]
	v_mfma_f32_32x32x16_bf16 v[32:47], v[148:151], v[132:135], v[32:47]
	v_mfma_f32_32x32x16_bf16 v[16:31], v[152:155], v[132:135], v[16:31]
	v_mfma_f32_32x32x16_bf16 v[0:15], v[156:159], v[132:135], v[0:15]
	s_waitcnt lgkmcnt(0)
	v_mfma_f32_32x32x16_bf16 v[112:127], v[160:163], v[136:139], v[112:127]
	v_mfma_f32_32x32x16_bf16 v[96:111], v[164:167], v[136:139], v[96:111]
	v_mfma_f32_32x32x16_bf16 v[80:95], v[168:171], v[136:139], v[80:95]
	v_mfma_f32_32x32x16_bf16 v[64:79], v[172:175], v[136:139], v[64:79]
	v_mfma_f32_32x32x16_bf16 v[48:63], v[160:163], v[140:143], v[48:63]
	v_mfma_f32_32x32x16_bf16 v[32:47], v[164:167], v[140:143], v[32:47]
	v_mfma_f32_32x32x16_bf16 v[16:31], v[168:171], v[140:143], v[16:31]
	v_mfma_f32_32x32x16_bf16 v[0:15], v[172:175], v[140:143], v[0:15]
	s_nop 7
	s_nop 3
	s_barrier
	s_load_dwordx2 s[64:65], s[92:93], 0x150
	s_load_dwordx2 s[66:67], s[92:93], 0x140
	v_and_b32_e32 v176, 31, v196
	v_bfe_u32 v177, v196, 5, 1
	s_lshr_b32 s74, s73, 1
	s_lshl_b32 s74, s74, 6
	s_add_u32 s74, s74, s77
	v_add_u32_e32 v178, s74, v176
	s_mul_i32 s76, s73, 8704
	v_mul_u32_u24_e32 v180, 272, v176
	v_lshl_add_u32 v180, v177, 3, v180
	v_add_u32_e32 v180, s76, v180
	v_bfe_u32 v185, v196, 4, 2
	v_and_b32_e32 v186, 15, v196
	v_mul_u32_u24_e32 v181, 272, v185
	v_lshl_add_u32 v181, v186, 4, v181
	v_add_u32_e32 v181, s76, v181
	s_and_b32 s75, s73, 1
	s_lshl_b32 s75, s75, 7
	s_add_u32 s75, s75, s78
	v_add_u32_e32 v179, s74, v185
	v_mul_u32_u24_e32 v179, 0x800, v179
	v_lshl_add_u32 v179, v186, 3, v179
	v_add_lshl_u32 v182, v179, s75, 1
	s_waitcnt lgkmcnt(0)
	s_add_u32 s66, s66, 0x10200
	s_addc_u32 s67, s67, 0
	v_lshlrev_b32_e32 v179, 2, v178
	global_load_dword v183, v179, s[66:67]
	global_load_dword v184, v179, s[66:67] offset:128
	s_waitcnt vmcnt(0)
	v_mul_f32_e32 v183, 0x3a800000, v183
	v_mul_f32_e32 v184, 0x3a800000, v184
	v_add_f32_e32 v183, 0x358637bd, v183
	v_add_f32_e32 v184, 0x358637bd, v184
	v_rsq_f32_e32 v183, v183
	v_rsq_f32_e32 v184, v184
	s_nop 1
	v_mul_f32_e32 v112, v183, v112
	v_mul_f32_e32 v113, v183, v113
	v_mul_f32_e32 v114, v183, v114
	v_mul_f32_e32 v115, v183, v115
	v_cvt_pk_bf16_f32 v112, v112, v113
	v_cvt_pk_bf16_f32 v113, v114, v115
	ds_write_b64 v180, v[112:113]
	v_mul_f32_e32 v116, v183, v116
	v_mul_f32_e32 v117, v183, v117
	v_mul_f32_e32 v118, v183, v118
	v_mul_f32_e32 v119, v183, v119
	v_cvt_pk_bf16_f32 v116, v116, v117
	v_cvt_pk_bf16_f32 v117, v118, v119
	ds_write_b64 v180, v[116:117] offset:16
	v_mul_f32_e32 v120, v183, v120
	v_mul_f32_e32 v121, v183, v121
	v_mul_f32_e32 v122, v183, v122
	v_mul_f32_e32 v123, v183, v123
	v_cvt_pk_bf16_f32 v120, v120, v121
	v_cvt_pk_bf16_f32 v121, v122, v123
	ds_write_b64 v180, v[120:121] offset:32
	v_mul_f32_e32 v124, v183, v124
	v_mul_f32_e32 v125, v183, v125
	v_mul_f32_e32 v126, v183, v126
	v_mul_f32_e32 v127, v183, v127
	v_cvt_pk_bf16_f32 v124, v124, v125
	v_cvt_pk_bf16_f32 v125, v126, v127
	ds_write_b64 v180, v[124:125] offset:48
	v_mul_f32_e32 v96, v183, v96
	v_mul_f32_e32 v97, v183, v97
	v_mul_f32_e32 v98, v183, v98
	v_mul_f32_e32 v99, v183, v99
	v_cvt_pk_bf16_f32 v96, v96, v97
	v_cvt_pk_bf16_f32 v97, v98, v99
	ds_write_b64 v180, v[96:97] offset:64
	v_mul_f32_e32 v100, v183, v100
	v_mul_f32_e32 v101, v183, v101
	v_mul_f32_e32 v102, v183, v102
	v_mul_f32_e32 v103, v183, v103
	v_cvt_pk_bf16_f32 v100, v100, v101
	v_cvt_pk_bf16_f32 v101, v102, v103
	ds_write_b64 v180, v[100:101] offset:80
	v_mul_f32_e32 v104, v183, v104
	v_mul_f32_e32 v105, v183, v105
	v_mul_f32_e32 v106, v183, v106
	v_mul_f32_e32 v107, v183, v107
	v_cvt_pk_bf16_f32 v104, v104, v105
	v_cvt_pk_bf16_f32 v105, v106, v107
	ds_write_b64 v180, v[104:105] offset:96
	v_mul_f32_e32 v108, v183, v108
	v_mul_f32_e32 v109, v183, v109
	v_mul_f32_e32 v110, v183, v110
	v_mul_f32_e32 v111, v183, v111
	v_cvt_pk_bf16_f32 v108, v108, v109
	v_cvt_pk_bf16_f32 v109, v110, v111
; DI bfr f2bf(float a) { return (bfr)(pack2(a, 0.f) & 0xffffu); }
; DI void phase_gemm_bf16out(const Params& p, const bfr* A, const bfr* Wt, bfr* C, int N, const float* ss, char* smem) {
;     ...
;     gemm_tile<1024>(A, Wt, N, 1024, mt * 128, nt * 256, smem,
;               [=](int row, int col, float v) {
;                 float inv = rsqrtf(ss[row] * (1.0f / 1024.0f) + EPSF);
;                 C[(size_t)row * N + col] = f2bf(v * inv);
;               });
	ds_write_b64 v180, v[108:109] offset:112
	v_mul_f32_e32 v80, v183, v80
	v_mul_f32_e32 v81, v183, v81
	v_mul_f32_e32 v82, v183, v82
	v_mul_f32_e32 v83, v183, v83
	v_cvt_pk_bf16_f32 v80, v80, v81
	v_cvt_pk_bf16_f32 v81, v82, v83
	ds_write_b64 v180, v[80:81] offset:128
	v_mul_f32_e32 v84, v183, v84
	v_mul_f32_e32 v85, v183, v85
	v_mul_f32_e32 v86, v183, v86
	v_mul_f32_e32 v87, v183, v87
	v_cvt_pk_bf16_f32 v84, v84, v85
	v_cvt_pk_bf16_f32 v85, v86, v87
	ds_write_b64 v180, v[84:85] offset:144
	v_mul_f32_e32 v88, v183, v88
	v_mul_f32_e32 v89, v183, v89
	v_mul_f32_e32 v90, v183, v90
	v_mul_f32_e32 v91, v183, v91
	v_cvt_pk_bf16_f32 v88, v88, v89
	v_cvt_pk_bf16_f32 v89, v90, v91
	ds_write_b64 v180, v[88:89] offset:160
	v_mul_f32_e32 v92, v183, v92
	v_mul_f32_e32 v93, v183, v93
	v_mul_f32_e32 v94, v183, v94
	v_mul_f32_e32 v95, v183, v95
	v_cvt_pk_bf16_f32 v92, v92, v93
	v_cvt_pk_bf16_f32 v93, v94, v95
	ds_write_b64 v180, v[92:93] offset:176
	v_mul_f32_e32 v64, v183, v64
	v_mul_f32_e32 v65, v183, v65
	v_mul_f32_e32 v66, v183, v66
	v_mul_f32_e32 v67, v183, v67
	v_cvt_pk_bf16_f32 v64, v64, v65
	v_cvt_pk_bf16_f32 v65, v66, v67
	ds_write_b64 v180, v[64:65] offset:192
	v_mul_f32_e32 v68, v183, v68
	v_mul_f32_e32 v69, v183, v69
	v_mul_f32_e32 v70, v183, v70
	v_mul_f32_e32 v71, v183, v71
	v_cvt_pk_bf16_f32 v68, v68, v69
	v_cvt_pk_bf16_f32 v69, v70, v71
	ds_write_b64 v180, v[68:69] offset:208
	v_mul_f32_e32 v72, v183, v72
	v_mul_f32_e32 v73, v183, v73
	v_mul_f32_e32 v74, v183, v74
	v_mul_f32_e32 v75, v183, v75
	v_cvt_pk_bf16_f32 v72, v72, v73
	v_cvt_pk_bf16_f32 v73, v74, v75
	ds_write_b64 v180, v[72:73] offset:224
	v_mul_f32_e32 v76, v183, v76
	v_mul_f32_e32 v77, v183, v77
	v_mul_f32_e32 v78, v183, v78
	v_mul_f32_e32 v79, v183, v79
	v_cvt_pk_bf16_f32 v76, v76, v77
	v_cvt_pk_bf16_f32 v77, v78, v79
	ds_write_b64 v180, v[76:77] offset:240
	s_waitcnt lgkmcnt(0)
	ds_read_b128 v[112:115], v181
	ds_read_b128 v[116:119], v181 offset:1088
	ds_read_b128 v[120:123], v181 offset:2176
	ds_read_b128 v[124:127], v181 offset:3264
	ds_read_b128 v[96:99], v181 offset:4352
	ds_read_b128 v[100:103], v181 offset:5440
	ds_read_b128 v[104:107], v181 offset:6528
	ds_read_b128 v[108:111], v181 offset:7616
	s_add_u32 s66, s64, 0x0
	s_addc_u32 s67, s65, 0
	s_waitcnt lgkmcnt(7)
	global_store_dwordx4 v182, v[112:115], s[66:67]  sc1
	s_add_u32 s66, s64, 0x4000
	s_addc_u32 s67, s65, 0
	s_waitcnt lgkmcnt(6)
	global_store_dwordx4 v182, v[116:119], s[66:67]  sc1
	s_add_u32 s66, s64, 0x8000
	s_addc_u32 s67, s65, 0
	s_waitcnt lgkmcnt(5)
	global_store_dwordx4 v182, v[120:123], s[66:67]  sc1
	s_add_u32 s66, s64, 0xc000
	s_addc_u32 s67, s65, 0
	s_waitcnt lgkmcnt(4)
	global_store_dwordx4 v182, v[124:127], s[66:67]  sc1
	s_add_u32 s66, s64, 0x10000
	s_addc_u32 s67, s65, 0
	s_waitcnt lgkmcnt(3)
	global_store_dwordx4 v182, v[96:99], s[66:67]  sc1
	s_add_u32 s66, s64, 0x14000
	s_addc_u32 s67, s65, 0
	s_waitcnt lgkmcnt(2)
	global_store_dwordx4 v182, v[100:103], s[66:67]  sc1
	s_add_u32 s66, s64, 0x18000
	s_addc_u32 s67, s65, 0
	s_waitcnt lgkmcnt(1)
	global_store_dwordx4 v182, v[104:107], s[66:67]  sc1
	s_add_u32 s66, s64, 0x1c000
	s_addc_u32 s67, s65, 0
	s_waitcnt lgkmcnt(0)
; DI bfr f2bf(float a) { return (bfr)(pack2(a, 0.f) & 0xffffu); }
; DI void phase_gemm_bf16out(const Params& p, const bfr* A, const bfr* Wt, bfr* C, int N, const float* ss, char* smem) {
;     ...
;   for (int t0 = blockIdx.x; t0 < 128 * ntn; t0 += gridDim.x) {
;     const int t = ((gridDim.x & 7) == 0) ? xcd_tile(t0, ntn) : t0;
;     ...
;     gemm_tile<1024>(A, Wt, N, 1024, mt * 128, nt * 256, smem,
;               [=](int row, int col, float v) {
;                 float inv = rsqrtf(ss[row] * (1.0f / 1024.0f) + EPSF);
;                 C[(size_t)row * N + col] = f2bf(v * inv);
;               });
	global_store_dwordx4 v182, v[108:111], s[66:67]  sc1
	v_mul_f32_e32 v48, v184, v48
	v_mul_f32_e32 v49, v184, v49
	v_mul_f32_e32 v50, v184, v50
	v_mul_f32_e32 v51, v184, v51
	v_cvt_pk_bf16_f32 v48, v48, v49
	v_cvt_pk_bf16_f32 v49, v50, v51
	ds_write_b64 v180, v[48:49]
	v_mul_f32_e32 v52, v184, v52
	v_mul_f32_e32 v53, v184, v53
	v_mul_f32_e32 v54, v184, v54
	v_mul_f32_e32 v55, v184, v55
	v_cvt_pk_bf16_f32 v52, v52, v53
	v_cvt_pk_bf16_f32 v53, v54, v55
	ds_write_b64 v180, v[52:53] offset:16
	v_mul_f32_e32 v56, v184, v56
	v_mul_f32_e32 v57, v184, v57
	v_mul_f32_e32 v58, v184, v58
	v_mul_f32_e32 v59, v184, v59
	v_cvt_pk_bf16_f32 v56, v56, v57
	v_cvt_pk_bf16_f32 v57, v58, v59
	ds_write_b64 v180, v[56:57] offset:32
	v_mul_f32_e32 v60, v184, v60
	v_mul_f32_e32 v61, v184, v61
	v_mul_f32_e32 v62, v184, v62
	v_mul_f32_e32 v63, v184, v63
	v_cvt_pk_bf16_f32 v60, v60, v61
	v_cvt_pk_bf16_f32 v61, v62, v63
	ds_write_b64 v180, v[60:61] offset:48
	v_mul_f32_e32 v32, v184, v32
	v_mul_f32_e32 v33, v184, v33
	v_mul_f32_e32 v34, v184, v34
	v_mul_f32_e32 v35, v184, v35
	v_cvt_pk_bf16_f32 v32, v32, v33
	v_cvt_pk_bf16_f32 v33, v34, v35
	ds_write_b64 v180, v[32:33] offset:64
	v_mul_f32_e32 v36, v184, v36
	v_mul_f32_e32 v37, v184, v37
	v_mul_f32_e32 v38, v184, v38
	v_mul_f32_e32 v39, v184, v39
	v_cvt_pk_bf16_f32 v36, v36, v37
	v_cvt_pk_bf16_f32 v37, v38, v39
	ds_write_b64 v180, v[36:37] offset:80
	v_mul_f32_e32 v40, v184, v40
	v_mul_f32_e32 v41, v184, v41
	v_mul_f32_e32 v42, v184, v42
	v_mul_f32_e32 v43, v184, v43
	v_cvt_pk_bf16_f32 v40, v40, v41
	v_cvt_pk_bf16_f32 v41, v42, v43
	ds_write_b64 v180, v[40:41] offset:96
	v_mul_f32_e32 v44, v184, v44
	v_mul_f32_e32 v45, v184, v45
	v_mul_f32_e32 v46, v184, v46
	v_mul_f32_e32 v47, v184, v47
	v_cvt_pk_bf16_f32 v44, v44, v45
	v_cvt_pk_bf16_f32 v45, v46, v47
	ds_write_b64 v180, v[44:45] offset:112
	v_mul_f32_e32 v16, v184, v16
	v_mul_f32_e32 v17, v184, v17
	v_mul_f32_e32 v18, v184, v18
	v_mul_f32_e32 v19, v184, v19
	v_cvt_pk_bf16_f32 v16, v16, v17
	v_cvt_pk_bf16_f32 v17, v18, v19
	ds_write_b64 v180, v[16:17] offset:128
	v_mul_f32_e32 v20, v184, v20
	v_mul_f32_e32 v21, v184, v21
	v_mul_f32_e32 v22, v184, v22
	v_mul_f32_e32 v23, v184, v23
	v_cvt_pk_bf16_f32 v20, v20, v21
	v_cvt_pk_bf16_f32 v21, v22, v23
	ds_write_b64 v180, v[20:21] offset:144
	v_mul_f32_e32 v24, v184, v24
	v_mul_f32_e32 v25, v184, v25
	v_mul_f32_e32 v26, v184, v26
	v_mul_f32_e32 v27, v184, v27
	v_cvt_pk_bf16_f32 v24, v24, v25
	v_cvt_pk_bf16_f32 v25, v26, v27
	ds_write_b64 v180, v[24:25] offset:160
	v_mul_f32_e32 v28, v184, v28
	v_mul_f32_e32 v29, v184, v29
	v_mul_f32_e32 v30, v184, v30
	v_mul_f32_e32 v31, v184, v31
	v_cvt_pk_bf16_f32 v28, v28, v29
	v_cvt_pk_bf16_f32 v29, v30, v31
	ds_write_b64 v180, v[28:29] offset:176
	v_mul_f32_e32 v0, v184, v0
	v_mul_f32_e32 v1, v184, v1
	v_mul_f32_e32 v2, v184, v2
	v_mul_f32_e32 v3, v184, v3
	v_cvt_pk_bf16_f32 v0, v0, v1
	v_cvt_pk_bf16_f32 v1, v2, v3
	ds_write_b64 v180, v[0:1] offset:192
	v_mul_f32_e32 v4, v184, v4
	v_mul_f32_e32 v5, v184, v5
	v_mul_f32_e32 v6, v184, v6
	v_mul_f32_e32 v7, v184, v7
	v_cvt_pk_bf16_f32 v4, v4, v5
	v_cvt_pk_bf16_f32 v5, v6, v7
	ds_write_b64 v180, v[4:5] offset:208
	v_mul_f32_e32 v8, v184, v8
	v_mul_f32_e32 v9, v184, v9
	v_mul_f32_e32 v10, v184, v10
	v_mul_f32_e32 v11, v184, v11
	v_cvt_pk_bf16_f32 v8, v8, v9
	v_cvt_pk_bf16_f32 v9, v10, v11
	ds_write_b64 v180, v[8:9] offset:224
	v_mul_f32_e32 v12, v184, v12
	v_mul_f32_e32 v13, v184, v13
	v_mul_f32_e32 v14, v184, v14
	v_mul_f32_e32 v15, v184, v15
	v_cvt_pk_bf16_f32 v12, v12, v13
	v_cvt_pk_bf16_f32 v13, v14, v15
	ds_write_b64 v180, v[12:13] offset:240
	s_waitcnt lgkmcnt(0)
	ds_read_b128 v[48:51], v181
	ds_read_b128 v[52:55], v181 offset:1088
	ds_read_b128 v[56:59], v181 offset:2176
	ds_read_b128 v[60:63], v181 offset:3264
	ds_read_b128 v[32:35], v181 offset:4352
	ds_read_b128 v[36:39], v181 offset:5440
	ds_read_b128 v[40:43], v181 offset:6528
	ds_read_b128 v[44:47], v181 offset:7616
	s_add_u32 s66, s64, 0x20000
	s_addc_u32 s67, s65, 0
	s_waitcnt lgkmcnt(7)
	global_store_dwordx4 v182, v[48:51], s[66:67]  sc1
	s_add_u32 s66, s64, 0x24000
	s_addc_u32 s67, s65, 0
	s_waitcnt lgkmcnt(6)
	global_store_dwordx4 v182, v[52:55], s[66:67]  sc1
	s_add_u32 s66, s64, 0x28000
	s_addc_u32 s67, s65, 0
	s_waitcnt lgkmcnt(5)
	global_store_dwordx4 v182, v[56:59], s[66:67]  sc1
	s_add_u32 s66, s64, 0x2c000
	s_addc_u32 s67, s65, 0
	s_waitcnt lgkmcnt(4)
	global_store_dwordx4 v182, v[60:63], s[66:67]  sc1
	s_add_u32 s66, s64, 0x30000
	s_addc_u32 s67, s65, 0
	s_waitcnt lgkmcnt(3)
	global_store_dwordx4 v182, v[32:35], s[66:67]  sc1
	s_add_u32 s66, s64, 0x34000
	s_addc_u32 s67, s65, 0
	s_waitcnt lgkmcnt(2)
	global_store_dwordx4 v182, v[36:39], s[66:67]  sc1
	s_add_u32 s66, s64, 0x38000
	s_addc_u32 s67, s65, 0
	s_waitcnt lgkmcnt(1)
	global_store_dwordx4 v182, v[40:43], s[66:67]  sc1
	s_add_u32 s66, s64, 0x3c000
	s_addc_u32 s67, s65, 0
	s_waitcnt lgkmcnt(0)
	global_store_dwordx4 v182, v[44:47], s[66:67]  sc1
	v_readlane_b32 s64, v187, 0
	v_readlane_b32 s65, v187, 1
	v_readlane_b32 s66, v187, 2
	v_readlane_b32 s67, v187, 3
	v_readlane_b32 s68, v187, 4
	v_readlane_b32 s69, v187, 5
	v_readlane_b32 s70, v187, 6
	v_readlane_b32 s71, v187, 7
	v_readlane_b32 s72, v187, 8
	v_readlane_b32 s73, v187, 9
	v_readlane_b32 s74, v187, 10
	v_readlane_b32 s75, v187, 11
	v_readlane_b32 s76, v187, 12
	v_readlane_b32 s77, v187, 13
	v_readlane_b32 s78, v187, 14
	v_readlane_b32 s79, v187, 15
	s_nop 7
	s_add_i32 s28, s28, s34
	s_cmpk_lt_i32 s28, 0x400
	s_cbranch_scc0 .LBB0_1192
	s_branch .LBB0_1179

; #define MFMA32(a, b, c) __builtin_amdgcn_mfma_f32_32x32x16_bf16((a), (b), (c), 0, 0, 0)
; #define GA_LOAD(pr_) do { _Pragma("unroll") for (int i = 0; i < 4; ++i) ra[i] = *(const u32x4*)(Ab + (i * 32) * lda + (pr_) * 64); } while (0)
; #define GB_LOAD(kt_) do { const bfr* bk_ = Bb + (kt_) * NB * 32; \
;     _Pragma("unroll") for (int i = 0; i < 4; ++i) rb[i] = *(const u32x4*)(bk_ + (i * 64) * 32); } while (0)
; #define G_STORE(kt_) do { bfr* as_ = S0 + ((kt_) & 1) * GSTAGE; bfr* bs_ = as_ + 128 * 40; \
;     if (apar == ((kt_) & 1)) { _Pragma("unroll") for (int i = 0; i < 4; ++i) *(u32x4*)(as_ + asoff + i * 32 * 40) = ra[i]; } \
;     _Pragma("unroll") for (int i = 0; i < 4; ++i) *(u32x4*)(bs_ + bsoff + i * 64 * 40) = rb[i]; } while (0)
; template <int lda>
; DI void gemm_mainloop(const bfr* __restrict__ A, const bfr* __restrict__ Bt, int NB, int K, int m0, int n0, char* smem, f32x16 (&acc)[2][4]) {
;     ...
;   for (int kt = 0; kt < nk; ++kt) {
;     if (kt + 1 < nk) G_STORE(kt + 1);
;     if (kt + 2 < nk) {
;       GB_LOAD(kt + 2);
;       if ((kt & 1) == 0) GA_LOAD((kt >> 1) + 1);
;     }
;     const bfr* As = S0 + (kt & 1) * GSTAGE;
;     const bfr* Bs = As + 128 * 40;
; #pragma unroll
;     for (int ks = 0; ks < 2; ++ks) {
;       bf16x8 af[2], bfg[4];
; #pragma unroll
;       for (int i = 0; i < 2; ++i) af[i] = *(const bf16x8*)(As + (wr * 64 + i * 32 + r) * 40 + ks * 16 + hl * 8);
; #pragma unroll
;       for (int j = 0; j < 4; ++j) bfg[j] = *(const bf16x8*)(Bs + (wc * 128 + j * 32 + r) * 40 + ks * 16 + hl * 8);
; #pragma unroll
;       for (int i = 0; i < 2; ++i)
; #pragma unroll
;         for (int j = 0; j < 4; ++j) acc[i][j] = MFMA32(af[i], bfg[j], acc[i][j]);
;     }
;     __syncthreads();
;   }
.Lp14_loop:
	s_waitcnt vmcnt(6) lgkmcnt(0)
	s_barrier
	s_mul_i32 s74, s71, 0x6000
	s_add_u32 s75, s74, 0x2000
	s_cmp_eq_u32 s71, 2
	s_cselect_b32 s75, 0x10000, s75
	v_add_u32_e32 v184, s74, v180
	v_add_u32_e32 v186, s75, v182
	v_add_u32_e32 v185, s74, v181
	v_add_u32_e32 v187, s75, v183
	s_add_u32 s71, s71, 1
	s_cmp_eq_u32 s71, 3
	s_cselect_b32 s71, 0, s71
	ds_read_b128 v[128:131], v184
	ds_read_b128 v[144:147], v186
	ds_read_b128 v[148:151], v186 offset:2048
	ds_read_b128 v[152:155], v186 offset:4096
	ds_read_b128 v[156:159], v186 offset:6144
	ds_read_b128 v[132:135], v184 offset:2048
	v_mfma_f32_32x32x16_bf16 v[112:127], v[164:167], v[136:139], v[112:127]
	s_mul_i32 s74, s70, 0x6000
	s_add_u32 s75, s74, s68
	s_mov_b32 m0, s75
	s_add_u32 s76, s74, 0x2000
	s_cmp_eq_u32 s70, 2
	s_cselect_b32 s76, 0x10000, s76
	global_load_lds_dwordx4 v160, s[64:65]
	v_mfma_f32_32x32x16_bf16 v[96:111], v[168:171], v[136:139], v[96:111]
	s_add_u32 m0, s75, 0x400
	s_add_u32 s76, s76, s69
	global_load_lds_dwordx4 v162, s[64:65]
	v_mfma_f32_32x32x16_bf16 v[80:95], v[172:175], v[136:139], v[80:95]
	s_mov_b32 m0, s76
	s_add_u32 s64, s64, 64
	s_addc_u32 s65, s65, 0
	global_load_lds_dwordx4 v163, s[66:67]
	v_mfma_f32_32x32x16_bf16 v[64:79], v[176:179], v[136:139], v[64:79]
	global_load_lds_dwordx4 v163, s[66:67] offset:1024
	v_mfma_f32_32x32x16_bf16 v[48:63], v[164:167], v[140:143], v[48:63]
	global_load_lds_dwordx4 v163, s[66:67] offset:2048
	v_mfma_f32_32x32x16_bf16 v[32:47], v[168:171], v[140:143], v[32:47]
	global_load_lds_dwordx4 v163, s[66:67] offset:3072
	s_add_u32 s66, s66, 0x4000
	s_addc_u32 s67, s67, 0
	v_mfma_f32_32x32x16_bf16 v[16:31], v[172:175], v[140:143], v[16:31]
	s_add_u32 s70, s70, 1
	s_cmp_eq_u32 s70, 3
	s_cselect_b32 s70, 0, s70
	v_mfma_f32_32x32x16_bf16 v[0:15], v[176:179], v[140:143], v[0:15]
	ds_read_b128 v[136:139], v185
	ds_read_b128 v[164:167], v187
	ds_read_b128 v[168:171], v187 offset:2048
	ds_read_b128 v[172:175], v187 offset:4096
	ds_read_b128 v[176:179], v187 offset:6144
	ds_read_b128 v[140:143], v185 offset:2048
	s_waitcnt lgkmcnt(10)
	v_mfma_f32_32x32x16_bf16 v[112:127], v[144:147], v[128:131], v[112:127]
	s_waitcnt lgkmcnt(9)
	v_mfma_f32_32x32x16_bf16 v[96:111], v[148:151], v[128:131], v[96:111]
	s_waitcnt lgkmcnt(8)
	v_mfma_f32_32x32x16_bf16 v[80:95], v[152:155], v[128:131], v[80:95]
	s_waitcnt lgkmcnt(7)
	v_mfma_f32_32x32x16_bf16 v[64:79], v[156:159], v[128:131], v[64:79]
	s_waitcnt lgkmcnt(6)
	v_mfma_f32_32x32x16_bf16 v[48:63], v[144:147], v[132:135], v[48:63]
	v_mfma_f32_32x32x16_bf16 v[32:47], v[148:151], v[132:135], v[32:47]
	v_mfma_f32_32x32x16_bf16 v[16:31], v[152:155], v[132:135], v[16:31]
	v_mfma_f32_32x32x16_bf16 v[0:15], v[156:159], v[132:135], v[0:15]
	s_add_u32 s72, s72, 1
	s_cmp_lt_u32 s72, 5
	s_cbranch_scc1 .Lp14_loop
	s_waitcnt vmcnt(6) lgkmcnt(0)
	s_barrier
	s_mul_i32 s74, s71, 0x6000
	s_add_u32 s75, s74, 0x2000
	s_cmp_eq_u32 s71, 2
	s_cselect_b32 s75, 0x10000, s75
	v_add_u32_e32 v184, s74, v180
	v_add_u32_e32 v186, s75, v182
	v_add_u32_e32 v185, s74, v181
	v_add_u32_e32 v187, s75, v183
	s_add_u32 s71, s71, 1
	s_cmp_eq_u32 s71, 3
	s_cselect_b32 s71, 0, s71
	ds_read_b128 v[128:131], v184
	ds_read_b128 v[144:147], v186
	ds_read_b128 v[148:151], v186 offset:2048
	ds_read_b128 v[152:155], v186 offset:4096
	ds_read_b128 v[156:159], v186 offset:6144
	ds_read_b128 v[132:135], v184 offset:2048
	v_mfma_f32_32x32x16_bf16 v[112:127], v[164:167], v[136:139], v[112:127]
	v_mfma_f32_32x32x16_bf16 v[96:111], v[168:171], v[136:139], v[96:111]
	v_mfma_f32_32x32x16_bf16 v[80:95], v[172:175], v[136:139], v[80:95]
	v_mfma_f32_32x32x16_bf16 v[64:79], v[176:179], v[136:139], v[64:79]
	v_mfma_f32_32x32x16_bf16 v[48:63], v[164:167], v[140:143], v[48:63]
	v_mfma_f32_32x32x16_bf16 v[32:47], v[168:171], v[140:143], v[32:47]
	v_mfma_f32_32x32x16_bf16 v[16:31], v[172:175], v[140:143], v[16:31]
	v_mfma_f32_32x32x16_bf16 v[0:15], v[176:179], v[140:143], v[0:15]
	ds_read_b128 v[136:139], v185
	ds_read_b128 v[164:167], v187
	ds_read_b128 v[168:171], v187 offset:2048
	ds_read_b128 v[172:175], v187 offset:4096
	ds_read_b128 v[176:179], v187 offset:6144
	ds_read_b128 v[140:143], v185 offset:2048
	s_waitcnt lgkmcnt(10)
	v_mfma_f32_32x32x16_bf16 v[112:127], v[144:147], v[128:131], v[112:127]
	s_waitcnt lgkmcnt(9)
	v_mfma_f32_32x32x16_bf16 v[96:111], v[148:151], v[128:131], v[96:111]
	s_waitcnt lgkmcnt(8)
	v_mfma_f32_32x32x16_bf16 v[80:95], v[152:155], v[128:131], v[80:95]
	s_waitcnt lgkmcnt(7)
	v_mfma_f32_32x32x16_bf16 v[64:79], v[156:159], v[128:131], v[64:79]
	s_waitcnt lgkmcnt(6)
	v_mfma_f32_32x32x16_bf16 v[48:63], v[144:147], v[132:135], v[48:63]
	v_mfma_f32_32x32x16_bf16 v[32:47], v[148:151], v[132:135], v[32:47]
	v_mfma_f32_32x32x16_bf16 v[16:31], v[152:155], v[132:135], v[16:31]
	v_mfma_f32_32x32x16_bf16 v[0:15], v[156:159], v[132:135], v[0:15]
	s_waitcnt vmcnt(0) lgkmcnt(0)
	s_barrier
; #define MFMA32(a, b, c) __builtin_amdgcn_mfma_f32_32x32x16_bf16((a), (b), (c), 0, 0, 0)
; DI bfr f2bf(float a) { return (bfr)(pack2(a, 0.f) & 0xffffu); }
; DI float bf2f(bfr u) { return __uint_as_float(((unsigned)u) << 16); }
; DI float siluf_(float x) { return x / (1.0f + __expf(-x)); }
; template <int lda>
; DI void gemm_mainloop(const bfr* __restrict__ A, const bfr* __restrict__ Bt, int NB, int K, int m0, int n0, char* smem, f32x16 (&acc)[2][4]) {
;     ...
; #pragma unroll
;     for (int ks = 0; ks < 2; ++ks) {
;       bf16x8 af[2], bfg[4];
; #pragma unroll
;       for (int i = 0; i < 2; ++i) af[i] = *(const bf16x8*)(As + (wr * 64 + i * 32 + r) * 40 + ks * 16 + hl * 8);
; #pragma unroll
;       for (int j = 0; j < 4; ++j) bfg[j] = *(const bf16x8*)(Bs + (wc * 128 + j * 32 + r) * 40 + ks * 16 + hl * 8);
; #pragma unroll
;       for (int i = 0; i < 2; ++i)
; #pragma unroll
;         for (int j = 0; j < 4; ++j) acc[i][j] = MFMA32(af[i], bfg[j], acc[i][j]);
;     }
;     __syncthreads();
; DI void phase_gemm_pool(const Params& p, char* smem) {
;     ...
;     gemm_tile<1024>(p.MIX + g * 256, p.WtPool + (size_t)g * 65536, 256, 256, mt * 128, nt * 256, smem,
;               [=](int row, int col, float v) {
;                 float gate = bf2f(P2[(size_t)row * 2048 + 1024 + g * 256 + col]);
;                 float z = (v + bp[col]) * sc[col] * siluf_(gate);
;                 Z[(size_t)row * 1024 + g * 256 + col] = f2bf(z);
;               });
	s_mul_i32 s74, s71, 0x6000
	s_add_u32 s75, s74, 0x2000
	s_cmp_eq_u32 s71, 2
	s_cselect_b32 s75, 0x10000, s75
	v_add_u32_e32 v184, s74, v180
	v_add_u32_e32 v186, s75, v182
	v_add_u32_e32 v185, s74, v181
	v_add_u32_e32 v187, s75, v183
	s_add_u32 s71, s71, 1
	s_cmp_eq_u32 s71, 3
	s_cselect_b32 s71, 0, s71
	ds_read_b128 v[128:131], v184
	ds_read_b128 v[144:147], v186
	ds_read_b128 v[148:151], v186 offset:2048
	ds_read_b128 v[152:155], v186 offset:4096
	ds_read_b128 v[156:159], v186 offset:6144
	ds_read_b128 v[132:135], v184 offset:2048
	v_mfma_f32_32x32x16_bf16 v[112:127], v[164:167], v[136:139], v[112:127]
	v_mfma_f32_32x32x16_bf16 v[96:111], v[168:171], v[136:139], v[96:111]
	v_mfma_f32_32x32x16_bf16 v[80:95], v[172:175], v[136:139], v[80:95]
	v_mfma_f32_32x32x16_bf16 v[64:79], v[176:179], v[136:139], v[64:79]
	v_mfma_f32_32x32x16_bf16 v[48:63], v[164:167], v[140:143], v[48:63]
	v_mfma_f32_32x32x16_bf16 v[32:47], v[168:171], v[140:143], v[32:47]
	v_mfma_f32_32x32x16_bf16 v[16:31], v[172:175], v[140:143], v[16:31]
	v_mfma_f32_32x32x16_bf16 v[0:15], v[176:179], v[140:143], v[0:15]
	ds_read_b128 v[136:139], v185
	ds_read_b128 v[164:167], v187
	ds_read_b128 v[168:171], v187 offset:2048
	ds_read_b128 v[172:175], v187 offset:4096
	ds_read_b128 v[176:179], v187 offset:6144
	ds_read_b128 v[140:143], v185 offset:2048
	s_waitcnt lgkmcnt(10)
	v_mfma_f32_32x32x16_bf16 v[112:127], v[144:147], v[128:131], v[112:127]
	s_waitcnt lgkmcnt(9)
	v_mfma_f32_32x32x16_bf16 v[96:111], v[148:151], v[128:131], v[96:111]
	s_waitcnt lgkmcnt(8)
	v_mfma_f32_32x32x16_bf16 v[80:95], v[152:155], v[128:131], v[80:95]
	s_waitcnt lgkmcnt(7)
	v_mfma_f32_32x32x16_bf16 v[64:79], v[156:159], v[128:131], v[64:79]
	s_waitcnt lgkmcnt(6)
	v_mfma_f32_32x32x16_bf16 v[48:63], v[144:147], v[132:135], v[48:63]
	v_mfma_f32_32x32x16_bf16 v[32:47], v[148:151], v[132:135], v[32:47]
	v_mfma_f32_32x32x16_bf16 v[16:31], v[152:155], v[132:135], v[16:31]
	v_mfma_f32_32x32x16_bf16 v[0:15], v[156:159], v[132:135], v[0:15]
	s_waitcnt lgkmcnt(0)
	v_mfma_f32_32x32x16_bf16 v[112:127], v[164:167], v[136:139], v[112:127]
	v_mfma_f32_32x32x16_bf16 v[96:111], v[168:171], v[136:139], v[96:111]
	v_mfma_f32_32x32x16_bf16 v[80:95], v[172:175], v[136:139], v[80:95]
	v_mfma_f32_32x32x16_bf16 v[64:79], v[176:179], v[136:139], v[64:79]
	v_mfma_f32_32x32x16_bf16 v[48:63], v[164:167], v[140:143], v[48:63]
	v_mfma_f32_32x32x16_bf16 v[32:47], v[168:171], v[140:143], v[32:47]
	v_mfma_f32_32x32x16_bf16 v[16:31], v[172:175], v[140:143], v[16:31]
	v_mfma_f32_32x32x16_bf16 v[0:15], v[176:179], v[140:143], v[0:15]
	s_nop 7
	s_nop 3
	s_load_dwordx2 s[64:65], s[92:93], 0x150
	s_load_dwordx2 s[66:67], s[92:93], 0x168
	s_load_dwordx4 s[68:71], s[92:93], 0xc0
	s_mul_i32 s76, s73, 8704
	s_lshr_b32 s74, s73, 1
	s_lshl_b32 s74, s74, 6
	s_add_u32 s74, s74, s77
	s_and_b32 s75, s73, 1
	s_lshl_b32 s75, s75, 7
	s_add_u32 s75, s75, s78
	v_and_b32_e32 v189, 31, v196
	v_bfe_u32 v190, v196, 5, 1
	v_mul_u32_u24_e32 v191, 272, v189
	v_add_u32_e32 v191, s76, v191
	v_lshl_add_u32 v160, v190, 3, v191
	v_lshlrev_b32_e32 v191, 2, v190
	v_add_lshl_u32 v181, v191, s75, 2
	v_bfe_u32 v189, v196, 4, 2
	v_and_b32_e32 v190, 15, v196
	v_mul_u32_u24_e32 v191, 272, v189
	v_lshl_add_u32 v191, v190, 4, v191
	v_add_u32_e32 v162, s76, v191
	v_add_u32_e32 v191, s74, v189
	v_lshlrev_b32_e32 v192, 3, v190
	v_add_u32_e32 v192, s75, v192
	v_lshl_add_u32 v189, v191, 10, v192
	v_lshlrev_b32_e32 v180, 1, v189
	v_add_u32_e32 v192, 0x400, v192
	v_lshl_add_u32 v189, v191, 11, v192
	v_lshlrev_b32_e32 v163, 1, v189
	s_waitcnt lgkmcnt(0)
	s_barrier
	s_add_u32 s74, s64, 0x0
	s_addc_u32 s75, s65, 0
	global_load_dwordx4 v[128:131], v163, s[74:75]
	s_add_u32 s74, s64, 0x4000
	s_addc_u32 s75, s65, 0
	global_load_dwordx4 v[132:135], v163, s[74:75]
	s_add_u32 s74, s64, 0x8000
	s_addc_u32 s75, s65, 0
	global_load_dwordx4 v[136:139], v163, s[74:75]
	s_add_u32 s74, s64, 0xc000
	s_addc_u32 s75, s65, 0
	global_load_dwordx4 v[140:143], v163, s[74:75]
	s_add_u32 s74, s64, 0x10000
	s_addc_u32 s75, s65, 0
	global_load_dwordx4 v[144:147], v163, s[74:75]
	s_add_u32 s74, s64, 0x14000
	s_addc_u32 s75, s65, 0
	global_load_dwordx4 v[148:151], v163, s[74:75]
	s_add_u32 s74, s64, 0x18000
	s_addc_u32 s75, s65, 0
	global_load_dwordx4 v[152:155], v163, s[74:75]
	s_add_u32 s74, s64, 0x1c000
	s_addc_u32 s75, s65, 0
	global_load_dwordx4 v[156:159], v163, s[74:75]
	s_waitcnt vmcnt(7)
	ds_write_b128 v162, v[128:131]
	s_waitcnt vmcnt(6)
	ds_write_b128 v162, v[132:135] offset:1088
	s_waitcnt vmcnt(5)
	ds_write_b128 v162, v[136:139] offset:2176
	s_waitcnt vmcnt(4)
	ds_write_b128 v162, v[140:143] offset:3264
	s_waitcnt vmcnt(3)
	ds_write_b128 v162, v[144:147] offset:4352
	s_waitcnt vmcnt(2)
	ds_write_b128 v162, v[148:151] offset:5440
	s_waitcnt vmcnt(1)
	ds_write_b128 v162, v[152:155] offset:6528
	s_waitcnt vmcnt(0)
	ds_write_b128 v162, v[156:159] offset:7616
	global_load_dwordx4 v[128:131], v181, s[68:69]
	global_load_dwordx4 v[132:135], v181, s[68:69] offset:32
	global_load_dwordx4 v[136:139], v181, s[68:69] offset:64
	global_load_dwordx4 v[140:143], v181, s[68:69] offset:96
	global_load_dwordx4 v[144:147], v181, s[70:71]
	global_load_dwordx4 v[148:151], v181, s[70:71] offset:32
	global_load_dwordx4 v[152:155], v181, s[70:71] offset:64
	global_load_dwordx4 v[156:159], v181, s[70:71] offset:96
	ds_read_b64 v[164:165], v160
	s_waitcnt vmcnt(3) lgkmcnt(0)
; DI bfr f2bf(float a) { return (bfr)(pack2(a, 0.f) & 0xffffu); }
; DI float bf2f(bfr u) { return __uint_as_float(((unsigned)u) << 16); }
; DI float siluf_(float x) { return x / (1.0f + __expf(-x)); }
; DI void phase_gemm_pool(const Params& p, char* smem) {
;     ...
;               [=](int row, int col, float v) {
;                 float gate = bf2f(P2[(size_t)row * 2048 + 1024 + g * 256 + col]);
;                 float z = (v + bp[col]) * sc[col] * siluf_(gate);
;                 Z[(size_t)row * 1024 + g * 256 + col] = f2bf(z);
;               });
	v_lshlrev_b32_e32 v182, 16, v164
	v_and_b32_e32 v183, 0xffff0000, v164
	v_lshlrev_b32_e32 v184, 16, v165
	v_and_b32_e32 v185, 0xffff0000, v165
	v_add_f32_e32 v112, v128, v112
	v_mul_f32_e32 v112, v144, v112
	v_add_f32_e32 v113, v129, v113
	v_mul_f32_e32 v113, v145, v113
	v_add_f32_e32 v114, v130, v114
	v_mul_f32_e32 v114, v146, v114
	v_add_f32_e32 v115, v131, v115
	v_mul_f32_e32 v115, v147, v115
	v_mul_f32_e32 v189, 0xbfb8aa3b, v182
	v_mul_f32_e32 v190, 0xbfb8aa3b, v183
	v_mul_f32_e32 v191, 0xbfb8aa3b, v184
	v_mul_f32_e32 v192, 0xbfb8aa3b, v185
	v_exp_f32_e32 v189, v189
	v_exp_f32_e32 v190, v190
	v_exp_f32_e32 v191, v191
	v_exp_f32_e32 v192, v192
	s_nop 0
	v_add_f32_e32 v189, 1.0, v189
	v_add_f32_e32 v190, 1.0, v190
	v_add_f32_e32 v191, 1.0, v191
	v_add_f32_e32 v192, 1.0, v192
	v_rcp_f32_e32 v166, v189
	v_rcp_f32_e32 v167, v190
	s_nop 0
	v_fma_f32 v189, -v189, v166, 2.0
	v_fma_f32 v190, -v190, v167, 2.0
	v_mul_f32_e32 v166, v166, v189
	v_mul_f32_e32 v167, v167, v190
	v_mul_f32_e32 v182, v182, v166
	v_mul_f32_e32 v183, v183, v167
	v_rcp_f32_e32 v166, v191
	v_rcp_f32_e32 v167, v192
	s_nop 0
	v_fma_f32 v191, -v191, v166, 2.0
	v_fma_f32 v192, -v192, v167, 2.0
	v_mul_f32_e32 v166, v166, v191
	v_mul_f32_e32 v167, v167, v192
	v_mul_f32_e32 v184, v184, v166
	v_mul_f32_e32 v185, v185, v167
	v_mul_f32_e32 v112, v182, v112
	v_mul_f32_e32 v113, v183, v113
	v_mul_f32_e32 v114, v184, v114
	v_mul_f32_e32 v115, v185, v115
	v_cvt_pk_bf16_f32 v112, v112, v113
	v_cvt_pk_bf16_f32 v113, v114, v115
	ds_write_b64 v160, v[112:113]
	ds_read_b64 v[164:165], v160 offset:16
	s_waitcnt vmcnt(2) lgkmcnt(0)
	v_lshlrev_b32_e32 v182, 16, v164
	v_and_b32_e32 v183, 0xffff0000, v164
	v_lshlrev_b32_e32 v184, 16, v165
	v_and_b32_e32 v185, 0xffff0000, v165
	v_add_f32_e32 v116, v132, v116
	v_mul_f32_e32 v116, v148, v116
	v_add_f32_e32 v117, v133, v117
	v_mul_f32_e32 v117, v149, v117
	v_add_f32_e32 v118, v134, v118
	v_mul_f32_e32 v118, v150, v118
	v_add_f32_e32 v119, v135, v119
	v_mul_f32_e32 v119, v151, v119
	v_mul_f32_e32 v189, 0xbfb8aa3b, v182
	v_mul_f32_e32 v190, 0xbfb8aa3b, v183
	v_mul_f32_e32 v191, 0xbfb8aa3b, v184
	v_mul_f32_e32 v192, 0xbfb8aa3b, v185
	v_exp_f32_e32 v189, v189
	v_exp_f32_e32 v190, v190
	v_exp_f32_e32 v191, v191
	v_exp_f32_e32 v192, v192
	s_nop 0
	v_add_f32_e32 v189, 1.0, v189
	v_add_f32_e32 v190, 1.0, v190
	v_add_f32_e32 v191, 1.0, v191
	v_add_f32_e32 v192, 1.0, v192
	v_rcp_f32_e32 v166, v189
	v_rcp_f32_e32 v167, v190
	s_nop 0
	v_fma_f32 v189, -v189, v166, 2.0
	v_fma_f32 v190, -v190, v167, 2.0
	v_mul_f32_e32 v166, v166, v189
	v_mul_f32_e32 v167, v167, v190
	v_mul_f32_e32 v182, v182, v166
	v_mul_f32_e32 v183, v183, v167
	v_rcp_f32_e32 v166, v191
	v_rcp_f32_e32 v167, v192
	s_nop 0
	v_fma_f32 v191, -v191, v166, 2.0
	v_fma_f32 v192, -v192, v167, 2.0
	v_mul_f32_e32 v166, v166, v191
	v_mul_f32_e32 v167, v167, v192
	v_mul_f32_e32 v184, v184, v166
	v_mul_f32_e32 v185, v185, v167
	v_mul_f32_e32 v116, v182, v116
	v_mul_f32_e32 v117, v183, v117
	v_mul_f32_e32 v118, v184, v118
	v_mul_f32_e32 v119, v185, v119
	v_cvt_pk_bf16_f32 v116, v116, v117
	v_cvt_pk_bf16_f32 v117, v118, v119
	ds_write_b64 v160, v[116:117] offset:16
	ds_read_b64 v[164:165], v160 offset:32
	s_waitcnt vmcnt(1) lgkmcnt(0)
	v_lshlrev_b32_e32 v182, 16, v164
	v_and_b32_e32 v183, 0xffff0000, v164
	v_lshlrev_b32_e32 v184, 16, v165
	v_and_b32_e32 v185, 0xffff0000, v165
	v_add_f32_e32 v120, v136, v120
	v_mul_f32_e32 v120, v152, v120
	v_add_f32_e32 v121, v137, v121
	v_mul_f32_e32 v121, v153, v121
	v_add_f32_e32 v122, v138, v122
	v_mul_f32_e32 v122, v154, v122
	v_add_f32_e32 v123, v139, v123
	v_mul_f32_e32 v123, v155, v123
	v_mul_f32_e32 v189, 0xbfb8aa3b, v182
	v_mul_f32_e32 v190, 0xbfb8aa3b, v183
	v_mul_f32_e32 v191, 0xbfb8aa3b, v184
	v_mul_f32_e32 v192, 0xbfb8aa3b, v185
	v_exp_f32_e32 v189, v189
	v_exp_f32_e32 v190, v190
	v_exp_f32_e32 v191, v191
	v_exp_f32_e32 v192, v192
	s_nop 0
	v_add_f32_e32 v189, 1.0, v189
	v_add_f32_e32 v190, 1.0, v190
	v_add_f32_e32 v191, 1.0, v191
	v_add_f32_e32 v192, 1.0, v192
	v_rcp_f32_e32 v166, v189
	v_rcp_f32_e32 v167, v190
	s_nop 0
	v_fma_f32 v189, -v189, v166, 2.0
	v_fma_f32 v190, -v190, v167, 2.0
	v_mul_f32_e32 v166, v166, v189
	v_mul_f32_e32 v167, v167, v190
	v_mul_f32_e32 v182, v182, v166
	v_mul_f32_e32 v183, v183, v167
	v_rcp_f32_e32 v166, v191
	v_rcp_f32_e32 v167, v192
	s_nop 0
	v_fma_f32 v191, -v191, v166, 2.0
	v_fma_f32 v192, -v192, v167, 2.0
	v_mul_f32_e32 v166, v166, v191
	v_mul_f32_e32 v167, v167, v192
	v_mul_f32_e32 v184, v184, v166
	v_mul_f32_e32 v185, v185, v167
	v_mul_f32_e32 v120, v182, v120
	v_mul_f32_e32 v121, v183, v121
	v_mul_f32_e32 v122, v184, v122
	v_mul_f32_e32 v123, v185, v123
	v_cvt_pk_bf16_f32 v120, v120, v121
	v_cvt_pk_bf16_f32 v121, v122, v123
	ds_write_b64 v160, v[120:121] offset:32
	ds_read_b64 v[164:165], v160 offset:48
	s_waitcnt vmcnt(0) lgkmcnt(0)
; DI bfr f2bf(float a) { return (bfr)(pack2(a, 0.f) & 0xffffu); }
; DI float bf2f(bfr u) { return __uint_as_float(((unsigned)u) << 16); }
; DI float siluf_(float x) { return x / (1.0f + __expf(-x)); }
; DI void phase_gemm_pool(const Params& p, char* smem) {
;     ...
;               [=](int row, int col, float v) {
;                 float gate = bf2f(P2[(size_t)row * 2048 + 1024 + g * 256 + col]);
;                 float z = (v + bp[col]) * sc[col] * siluf_(gate);
;                 Z[(size_t)row * 1024 + g * 256 + col] = f2bf(z);
;               });
	v_lshlrev_b32_e32 v182, 16, v164
	v_and_b32_e32 v183, 0xffff0000, v164
	v_lshlrev_b32_e32 v184, 16, v165
	v_and_b32_e32 v185, 0xffff0000, v165
	v_add_f32_e32 v124, v140, v124
	v_mul_f32_e32 v124, v156, v124
	v_add_f32_e32 v125, v141, v125
	v_mul_f32_e32 v125, v157, v125
	v_add_f32_e32 v126, v142, v126
	v_mul_f32_e32 v126, v158, v126
	v_add_f32_e32 v127, v143, v127
	v_mul_f32_e32 v127, v159, v127
	v_mul_f32_e32 v189, 0xbfb8aa3b, v182
	v_mul_f32_e32 v190, 0xbfb8aa3b, v183
	v_mul_f32_e32 v191, 0xbfb8aa3b, v184
	v_mul_f32_e32 v192, 0xbfb8aa3b, v185
	v_exp_f32_e32 v189, v189
	v_exp_f32_e32 v190, v190
	v_exp_f32_e32 v191, v191
	v_exp_f32_e32 v192, v192
	s_nop 0
	v_add_f32_e32 v189, 1.0, v189
	v_add_f32_e32 v190, 1.0, v190
	v_add_f32_e32 v191, 1.0, v191
	v_add_f32_e32 v192, 1.0, v192
	v_rcp_f32_e32 v166, v189
	v_rcp_f32_e32 v167, v190
	s_nop 0
	v_fma_f32 v189, -v189, v166, 2.0
	v_fma_f32 v190, -v190, v167, 2.0
	v_mul_f32_e32 v166, v166, v189
	v_mul_f32_e32 v167, v167, v190
	v_mul_f32_e32 v182, v182, v166
	v_mul_f32_e32 v183, v183, v167
	v_rcp_f32_e32 v166, v191
	v_rcp_f32_e32 v167, v192
	s_nop 0
	v_fma_f32 v191, -v191, v166, 2.0
	v_fma_f32 v192, -v192, v167, 2.0
	v_mul_f32_e32 v166, v166, v191
	v_mul_f32_e32 v167, v167, v192
	v_mul_f32_e32 v184, v184, v166
	v_mul_f32_e32 v185, v185, v167
	v_mul_f32_e32 v124, v182, v124
	v_mul_f32_e32 v125, v183, v125
	v_mul_f32_e32 v126, v184, v126
	v_mul_f32_e32 v127, v185, v127
	v_cvt_pk_bf16_f32 v124, v124, v125
	v_cvt_pk_bf16_f32 v125, v126, v127
	ds_write_b64 v160, v[124:125] offset:48
	global_load_dwordx4 v[128:131], v181, s[68:69] offset:128
	global_load_dwordx4 v[132:135], v181, s[68:69] offset:160
	global_load_dwordx4 v[136:139], v181, s[68:69] offset:192
	global_load_dwordx4 v[140:143], v181, s[68:69] offset:224
	global_load_dwordx4 v[144:147], v181, s[70:71] offset:128
	global_load_dwordx4 v[148:151], v181, s[70:71] offset:160
	global_load_dwordx4 v[152:155], v181, s[70:71] offset:192
	global_load_dwordx4 v[156:159], v181, s[70:71] offset:224
	ds_read_b64 v[164:165], v160 offset:64
	s_waitcnt vmcnt(3) lgkmcnt(0)
	v_lshlrev_b32_e32 v182, 16, v164
	v_and_b32_e32 v183, 0xffff0000, v164
	v_lshlrev_b32_e32 v184, 16, v165
	v_and_b32_e32 v185, 0xffff0000, v165
	v_add_f32_e32 v96, v128, v96
	v_mul_f32_e32 v96, v144, v96
	v_add_f32_e32 v97, v129, v97
	v_mul_f32_e32 v97, v145, v97
	v_add_f32_e32 v98, v130, v98
	v_mul_f32_e32 v98, v146, v98
	v_add_f32_e32 v99, v131, v99
	v_mul_f32_e32 v99, v147, v99
	v_mul_f32_e32 v189, 0xbfb8aa3b, v182
	v_mul_f32_e32 v190, 0xbfb8aa3b, v183
	v_mul_f32_e32 v191, 0xbfb8aa3b, v184
	v_mul_f32_e32 v192, 0xbfb8aa3b, v185
	v_exp_f32_e32 v189, v189
	v_exp_f32_e32 v190, v190
	v_exp_f32_e32 v191, v191
	v_exp_f32_e32 v192, v192
	s_nop 0
	v_add_f32_e32 v189, 1.0, v189
	v_add_f32_e32 v190, 1.0, v190
	v_add_f32_e32 v191, 1.0, v191
	v_add_f32_e32 v192, 1.0, v192
	v_rcp_f32_e32 v166, v189
	v_rcp_f32_e32 v167, v190
	s_nop 0
	v_fma_f32 v189, -v189, v166, 2.0
	v_fma_f32 v190, -v190, v167, 2.0
	v_mul_f32_e32 v166, v166, v189
	v_mul_f32_e32 v167, v167, v190
	v_mul_f32_e32 v182, v182, v166
	v_mul_f32_e32 v183, v183, v167
	v_rcp_f32_e32 v166, v191
	v_rcp_f32_e32 v167, v192
	s_nop 0
	v_fma_f32 v191, -v191, v166, 2.0
	v_fma_f32 v192, -v192, v167, 2.0
	v_mul_f32_e32 v166, v166, v191
	v_mul_f32_e32 v167, v167, v192
	v_mul_f32_e32 v184, v184, v166
	v_mul_f32_e32 v185, v185, v167
	v_mul_f32_e32 v96, v182, v96
	v_mul_f32_e32 v97, v183, v97
	v_mul_f32_e32 v98, v184, v98
	v_mul_f32_e32 v99, v185, v99
	v_cvt_pk_bf16_f32 v96, v96, v97
	v_cvt_pk_bf16_f32 v97, v98, v99
	ds_write_b64 v160, v[96:97] offset:64
	ds_read_b64 v[164:165], v160 offset:80
	s_waitcnt vmcnt(2) lgkmcnt(0)
	v_lshlrev_b32_e32 v182, 16, v164
	v_and_b32_e32 v183, 0xffff0000, v164
	v_lshlrev_b32_e32 v184, 16, v165
	v_and_b32_e32 v185, 0xffff0000, v165
	v_add_f32_e32 v100, v132, v100
	v_mul_f32_e32 v100, v148, v100
	v_add_f32_e32 v101, v133, v101
	v_mul_f32_e32 v101, v149, v101
	v_add_f32_e32 v102, v134, v102
	v_mul_f32_e32 v102, v150, v102
	v_add_f32_e32 v103, v135, v103
	v_mul_f32_e32 v103, v151, v103
	v_mul_f32_e32 v189, 0xbfb8aa3b, v182
	v_mul_f32_e32 v190, 0xbfb8aa3b, v183
	v_mul_f32_e32 v191, 0xbfb8aa3b, v184
	v_mul_f32_e32 v192, 0xbfb8aa3b, v185
	v_exp_f32_e32 v189, v189
	v_exp_f32_e32 v190, v190
	v_exp_f32_e32 v191, v191
	v_exp_f32_e32 v192, v192
	s_nop 0
	v_add_f32_e32 v189, 1.0, v189
	v_add_f32_e32 v190, 1.0, v190
	v_add_f32_e32 v191, 1.0, v191
	v_add_f32_e32 v192, 1.0, v192
	v_rcp_f32_e32 v166, v189
	v_rcp_f32_e32 v167, v190
	s_nop 0
	v_fma_f32 v189, -v189, v166, 2.0
	v_fma_f32 v190, -v190, v167, 2.0
	v_mul_f32_e32 v166, v166, v189
	v_mul_f32_e32 v167, v167, v190
	v_mul_f32_e32 v182, v182, v166
	v_mul_f32_e32 v183, v183, v167
	v_rcp_f32_e32 v166, v191
	v_rcp_f32_e32 v167, v192
	s_nop 0
	v_fma_f32 v191, -v191, v166, 2.0
	v_fma_f32 v192, -v192, v167, 2.0
	v_mul_f32_e32 v166, v166, v191
	v_mul_f32_e32 v167, v167, v192
	v_mul_f32_e32 v184, v184, v166
	v_mul_f32_e32 v185, v185, v167
	v_mul_f32_e32 v100, v182, v100
	v_mul_f32_e32 v101, v183, v101
	v_mul_f32_e32 v102, v184, v102
	v_mul_f32_e32 v103, v185, v103
	v_cvt_pk_bf16_f32 v100, v100, v101
	v_cvt_pk_bf16_f32 v101, v102, v103
	ds_write_b64 v160, v[100:101] offset:80
	ds_read_b64 v[164:165], v160 offset:96
	s_waitcnt vmcnt(1) lgkmcnt(0)
; DI bfr f2bf(float a) { return (bfr)(pack2(a, 0.f) & 0xffffu); }
; DI float bf2f(bfr u) { return __uint_as_float(((unsigned)u) << 16); }
; DI float siluf_(float x) { return x / (1.0f + __expf(-x)); }
; DI void phase_gemm_pool(const Params& p, char* smem) {
;     ...
;               [=](int row, int col, float v) {
;                 float gate = bf2f(P2[(size_t)row * 2048 + 1024 + g * 256 + col]);
;                 float z = (v + bp[col]) * sc[col] * siluf_(gate);
;                 Z[(size_t)row * 1024 + g * 256 + col] = f2bf(z);
;               });
	v_lshlrev_b32_e32 v182, 16, v164
	v_and_b32_e32 v183, 0xffff0000, v164
	v_lshlrev_b32_e32 v184, 16, v165
	v_and_b32_e32 v185, 0xffff0000, v165
	v_add_f32_e32 v104, v136, v104
	v_mul_f32_e32 v104, v152, v104
	v_add_f32_e32 v105, v137, v105
	v_mul_f32_e32 v105, v153, v105
	v_add_f32_e32 v106, v138, v106
	v_mul_f32_e32 v106, v154, v106
	v_add_f32_e32 v107, v139, v107
	v_mul_f32_e32 v107, v155, v107
	v_mul_f32_e32 v189, 0xbfb8aa3b, v182
	v_mul_f32_e32 v190, 0xbfb8aa3b, v183
	v_mul_f32_e32 v191, 0xbfb8aa3b, v184
	v_mul_f32_e32 v192, 0xbfb8aa3b, v185
	v_exp_f32_e32 v189, v189
	v_exp_f32_e32 v190, v190
	v_exp_f32_e32 v191, v191
	v_exp_f32_e32 v192, v192
	s_nop 0
	v_add_f32_e32 v189, 1.0, v189
	v_add_f32_e32 v190, 1.0, v190
	v_add_f32_e32 v191, 1.0, v191
	v_add_f32_e32 v192, 1.0, v192
	v_rcp_f32_e32 v166, v189
	v_rcp_f32_e32 v167, v190
	s_nop 0
	v_fma_f32 v189, -v189, v166, 2.0
	v_fma_f32 v190, -v190, v167, 2.0
	v_mul_f32_e32 v166, v166, v189
	v_mul_f32_e32 v167, v167, v190
	v_mul_f32_e32 v182, v182, v166
	v_mul_f32_e32 v183, v183, v167
	v_rcp_f32_e32 v166, v191
	v_rcp_f32_e32 v167, v192
	s_nop 0
	v_fma_f32 v191, -v191, v166, 2.0
	v_fma_f32 v192, -v192, v167, 2.0
	v_mul_f32_e32 v166, v166, v191
	v_mul_f32_e32 v167, v167, v192
	v_mul_f32_e32 v184, v184, v166
	v_mul_f32_e32 v185, v185, v167
	v_mul_f32_e32 v104, v182, v104
	v_mul_f32_e32 v105, v183, v105
	v_mul_f32_e32 v106, v184, v106
	v_mul_f32_e32 v107, v185, v107
	v_cvt_pk_bf16_f32 v104, v104, v105
	v_cvt_pk_bf16_f32 v105, v106, v107
	ds_write_b64 v160, v[104:105] offset:96
	ds_read_b64 v[164:165], v160 offset:112
	s_waitcnt vmcnt(0) lgkmcnt(0)
	v_lshlrev_b32_e32 v182, 16, v164
	v_and_b32_e32 v183, 0xffff0000, v164
	v_lshlrev_b32_e32 v184, 16, v165
	v_and_b32_e32 v185, 0xffff0000, v165
	v_add_f32_e32 v108, v140, v108
	v_mul_f32_e32 v108, v156, v108
	v_add_f32_e32 v109, v141, v109
	v_mul_f32_e32 v109, v157, v109
	v_add_f32_e32 v110, v142, v110
	v_mul_f32_e32 v110, v158, v110
	v_add_f32_e32 v111, v143, v111
	v_mul_f32_e32 v111, v159, v111
	v_mul_f32_e32 v189, 0xbfb8aa3b, v182
	v_mul_f32_e32 v190, 0xbfb8aa3b, v183
	v_mul_f32_e32 v191, 0xbfb8aa3b, v184
	v_mul_f32_e32 v192, 0xbfb8aa3b, v185
	v_exp_f32_e32 v189, v189
	v_exp_f32_e32 v190, v190
	v_exp_f32_e32 v191, v191
	v_exp_f32_e32 v192, v192
	s_nop 0
	v_add_f32_e32 v189, 1.0, v189
	v_add_f32_e32 v190, 1.0, v190
	v_add_f32_e32 v191, 1.0, v191
	v_add_f32_e32 v192, 1.0, v192
	v_rcp_f32_e32 v166, v189
	v_rcp_f32_e32 v167, v190
	s_nop 0
	v_fma_f32 v189, -v189, v166, 2.0
	v_fma_f32 v190, -v190, v167, 2.0
	v_mul_f32_e32 v166, v166, v189
	v_mul_f32_e32 v167, v167, v190
	v_mul_f32_e32 v182, v182, v166
	v_mul_f32_e32 v183, v183, v167
	v_rcp_f32_e32 v166, v191
	v_rcp_f32_e32 v167, v192
	s_nop 0
	v_fma_f32 v191, -v191, v166, 2.0
	v_fma_f32 v192, -v192, v167, 2.0
	v_mul_f32_e32 v166, v166, v191
	v_mul_f32_e32 v167, v167, v192
	v_mul_f32_e32 v184, v184, v166
	v_mul_f32_e32 v185, v185, v167
	v_mul_f32_e32 v108, v182, v108
	v_mul_f32_e32 v109, v183, v109
	v_mul_f32_e32 v110, v184, v110
	v_mul_f32_e32 v111, v185, v111
	v_cvt_pk_bf16_f32 v108, v108, v109
	v_cvt_pk_bf16_f32 v109, v110, v111
	ds_write_b64 v160, v[108:109] offset:112
	global_load_dwordx4 v[128:131], v181, s[68:69] offset:256
	global_load_dwordx4 v[132:135], v181, s[68:69] offset:288
	global_load_dwordx4 v[136:139], v181, s[68:69] offset:320
	global_load_dwordx4 v[140:143], v181, s[68:69] offset:352
	global_load_dwordx4 v[144:147], v181, s[70:71] offset:256
	global_load_dwordx4 v[148:151], v181, s[70:71] offset:288
	global_load_dwordx4 v[152:155], v181, s[70:71] offset:320
	global_load_dwordx4 v[156:159], v181, s[70:71] offset:352
	ds_read_b64 v[164:165], v160 offset:128
	s_waitcnt vmcnt(3) lgkmcnt(0)
	v_lshlrev_b32_e32 v182, 16, v164
	v_and_b32_e32 v183, 0xffff0000, v164
	v_lshlrev_b32_e32 v184, 16, v165
	v_and_b32_e32 v185, 0xffff0000, v165
	v_add_f32_e32 v80, v128, v80
	v_mul_f32_e32 v80, v144, v80
	v_add_f32_e32 v81, v129, v81
	v_mul_f32_e32 v81, v145, v81
	v_add_f32_e32 v82, v130, v82
	v_mul_f32_e32 v82, v146, v82
	v_add_f32_e32 v83, v131, v83
	v_mul_f32_e32 v83, v147, v83
	v_mul_f32_e32 v189, 0xbfb8aa3b, v182
	v_mul_f32_e32 v190, 0xbfb8aa3b, v183
	v_mul_f32_e32 v191, 0xbfb8aa3b, v184
	v_mul_f32_e32 v192, 0xbfb8aa3b, v185
	v_exp_f32_e32 v189, v189
	v_exp_f32_e32 v190, v190
	v_exp_f32_e32 v191, v191
	v_exp_f32_e32 v192, v192
	s_nop 0
	v_add_f32_e32 v189, 1.0, v189
	v_add_f32_e32 v190, 1.0, v190
	v_add_f32_e32 v191, 1.0, v191
	v_add_f32_e32 v192, 1.0, v192
	v_rcp_f32_e32 v166, v189
	v_rcp_f32_e32 v167, v190
	s_nop 0
	v_fma_f32 v189, -v189, v166, 2.0
	v_fma_f32 v190, -v190, v167, 2.0
	v_mul_f32_e32 v166, v166, v189
	v_mul_f32_e32 v167, v167, v190
	v_mul_f32_e32 v182, v182, v166
	v_mul_f32_e32 v183, v183, v167
	v_rcp_f32_e32 v166, v191
	v_rcp_f32_e32 v167, v192
	s_nop 0
	v_fma_f32 v191, -v191, v166, 2.0
	v_fma_f32 v192, -v192, v167, 2.0
	v_mul_f32_e32 v166, v166, v191
	v_mul_f32_e32 v167, v167, v192
	v_mul_f32_e32 v184, v184, v166
	v_mul_f32_e32 v185, v185, v167
	v_mul_f32_e32 v80, v182, v80
	v_mul_f32_e32 v81, v183, v81
	v_mul_f32_e32 v82, v184, v82
	v_mul_f32_e32 v83, v185, v83
	v_cvt_pk_bf16_f32 v80, v80, v81
	v_cvt_pk_bf16_f32 v81, v82, v83
	ds_write_b64 v160, v[80:81] offset:128
	ds_read_b64 v[164:165], v160 offset:144
	s_waitcnt vmcnt(2) lgkmcnt(0)
; DI bfr f2bf(float a) { return (bfr)(pack2(a, 0.f) & 0xffffu); }
; DI float bf2f(bfr u) { return __uint_as_float(((unsigned)u) << 16); }
; DI float siluf_(float x) { return x / (1.0f + __expf(-x)); }
; DI void phase_gemm_pool(const Params& p, char* smem) {
;     ...
;               [=](int row, int col, float v) {
;                 float gate = bf2f(P2[(size_t)row * 2048 + 1024 + g * 256 + col]);
;                 float z = (v + bp[col]) * sc[col] * siluf_(gate);
;                 Z[(size_t)row * 1024 + g * 256 + col] = f2bf(z);
;               });
	v_lshlrev_b32_e32 v182, 16, v164
	v_and_b32_e32 v183, 0xffff0000, v164
	v_lshlrev_b32_e32 v184, 16, v165
	v_and_b32_e32 v185, 0xffff0000, v165
	v_add_f32_e32 v84, v132, v84
	v_mul_f32_e32 v84, v148, v84
	v_add_f32_e32 v85, v133, v85
	v_mul_f32_e32 v85, v149, v85
	v_add_f32_e32 v86, v134, v86
	v_mul_f32_e32 v86, v150, v86
	v_add_f32_e32 v87, v135, v87
	v_mul_f32_e32 v87, v151, v87
	v_mul_f32_e32 v189, 0xbfb8aa3b, v182
	v_mul_f32_e32 v190, 0xbfb8aa3b, v183
	v_mul_f32_e32 v191, 0xbfb8aa3b, v184
	v_mul_f32_e32 v192, 0xbfb8aa3b, v185
	v_exp_f32_e32 v189, v189
	v_exp_f32_e32 v190, v190
	v_exp_f32_e32 v191, v191
	v_exp_f32_e32 v192, v192
	s_nop 0
	v_add_f32_e32 v189, 1.0, v189
	v_add_f32_e32 v190, 1.0, v190
	v_add_f32_e32 v191, 1.0, v191
	v_add_f32_e32 v192, 1.0, v192
	v_rcp_f32_e32 v166, v189
	v_rcp_f32_e32 v167, v190
	s_nop 0
	v_fma_f32 v189, -v189, v166, 2.0
	v_fma_f32 v190, -v190, v167, 2.0
	v_mul_f32_e32 v166, v166, v189
	v_mul_f32_e32 v167, v167, v190
	v_mul_f32_e32 v182, v182, v166
	v_mul_f32_e32 v183, v183, v167
	v_rcp_f32_e32 v166, v191
	v_rcp_f32_e32 v167, v192
	s_nop 0
	v_fma_f32 v191, -v191, v166, 2.0
	v_fma_f32 v192, -v192, v167, 2.0
	v_mul_f32_e32 v166, v166, v191
	v_mul_f32_e32 v167, v167, v192
	v_mul_f32_e32 v184, v184, v166
	v_mul_f32_e32 v185, v185, v167
	v_mul_f32_e32 v84, v182, v84
	v_mul_f32_e32 v85, v183, v85
	v_mul_f32_e32 v86, v184, v86
	v_mul_f32_e32 v87, v185, v87
	v_cvt_pk_bf16_f32 v84, v84, v85
	v_cvt_pk_bf16_f32 v85, v86, v87
	ds_write_b64 v160, v[84:85] offset:144
	ds_read_b64 v[164:165], v160 offset:160
	s_waitcnt vmcnt(1) lgkmcnt(0)
	v_lshlrev_b32_e32 v182, 16, v164
	v_and_b32_e32 v183, 0xffff0000, v164
	v_lshlrev_b32_e32 v184, 16, v165
	v_and_b32_e32 v185, 0xffff0000, v165
	v_add_f32_e32 v88, v136, v88
	v_mul_f32_e32 v88, v152, v88
	v_add_f32_e32 v89, v137, v89
	v_mul_f32_e32 v89, v153, v89
	v_add_f32_e32 v90, v138, v90
	v_mul_f32_e32 v90, v154, v90
	v_add_f32_e32 v91, v139, v91
	v_mul_f32_e32 v91, v155, v91
	v_mul_f32_e32 v189, 0xbfb8aa3b, v182
	v_mul_f32_e32 v190, 0xbfb8aa3b, v183
	v_mul_f32_e32 v191, 0xbfb8aa3b, v184
	v_mul_f32_e32 v192, 0xbfb8aa3b, v185
	v_exp_f32_e32 v189, v189
	v_exp_f32_e32 v190, v190
	v_exp_f32_e32 v191, v191
	v_exp_f32_e32 v192, v192
	s_nop 0
	v_add_f32_e32 v189, 1.0, v189
	v_add_f32_e32 v190, 1.0, v190
	v_add_f32_e32 v191, 1.0, v191
	v_add_f32_e32 v192, 1.0, v192
	v_rcp_f32_e32 v166, v189
	v_rcp_f32_e32 v167, v190
	s_nop 0
	v_fma_f32 v189, -v189, v166, 2.0
	v_fma_f32 v190, -v190, v167, 2.0
	v_mul_f32_e32 v166, v166, v189
	v_mul_f32_e32 v167, v167, v190
	v_mul_f32_e32 v182, v182, v166
	v_mul_f32_e32 v183, v183, v167
	v_rcp_f32_e32 v166, v191
	v_rcp_f32_e32 v167, v192
	s_nop 0
	v_fma_f32 v191, -v191, v166, 2.0
	v_fma_f32 v192, -v192, v167, 2.0
	v_mul_f32_e32 v166, v166, v191
	v_mul_f32_e32 v167, v167, v192
	v_mul_f32_e32 v184, v184, v166
	v_mul_f32_e32 v185, v185, v167
	v_mul_f32_e32 v88, v182, v88
	v_mul_f32_e32 v89, v183, v89
	v_mul_f32_e32 v90, v184, v90
	v_mul_f32_e32 v91, v185, v91
	v_cvt_pk_bf16_f32 v88, v88, v89
	v_cvt_pk_bf16_f32 v89, v90, v91
	ds_write_b64 v160, v[88:89] offset:160
	ds_read_b64 v[164:165], v160 offset:176
	s_waitcnt vmcnt(0) lgkmcnt(0)
	v_lshlrev_b32_e32 v182, 16, v164
	v_and_b32_e32 v183, 0xffff0000, v164
	v_lshlrev_b32_e32 v184, 16, v165
	v_and_b32_e32 v185, 0xffff0000, v165
	v_add_f32_e32 v92, v140, v92
	v_mul_f32_e32 v92, v156, v92
	v_add_f32_e32 v93, v141, v93
	v_mul_f32_e32 v93, v157, v93
	v_add_f32_e32 v94, v142, v94
	v_mul_f32_e32 v94, v158, v94
	v_add_f32_e32 v95, v143, v95
	v_mul_f32_e32 v95, v159, v95
	v_mul_f32_e32 v189, 0xbfb8aa3b, v182
	v_mul_f32_e32 v190, 0xbfb8aa3b, v183
	v_mul_f32_e32 v191, 0xbfb8aa3b, v184
	v_mul_f32_e32 v192, 0xbfb8aa3b, v185
	v_exp_f32_e32 v189, v189
	v_exp_f32_e32 v190, v190
	v_exp_f32_e32 v191, v191
	v_exp_f32_e32 v192, v192
	s_nop 0
	v_add_f32_e32 v189, 1.0, v189
	v_add_f32_e32 v190, 1.0, v190
	v_add_f32_e32 v191, 1.0, v191
	v_add_f32_e32 v192, 1.0, v192
	v_rcp_f32_e32 v166, v189
	v_rcp_f32_e32 v167, v190
	s_nop 0
	v_fma_f32 v189, -v189, v166, 2.0
	v_fma_f32 v190, -v190, v167, 2.0
	v_mul_f32_e32 v166, v166, v189
	v_mul_f32_e32 v167, v167, v190
	v_mul_f32_e32 v182, v182, v166
	v_mul_f32_e32 v183, v183, v167
	v_rcp_f32_e32 v166, v191
	v_rcp_f32_e32 v167, v192
	s_nop 0
	v_fma_f32 v191, -v191, v166, 2.0
	v_fma_f32 v192, -v192, v167, 2.0
	v_mul_f32_e32 v166, v166, v191
	v_mul_f32_e32 v167, v167, v192
	v_mul_f32_e32 v184, v184, v166
	v_mul_f32_e32 v185, v185, v167
	v_mul_f32_e32 v92, v182, v92
	v_mul_f32_e32 v93, v183, v93
	v_mul_f32_e32 v94, v184, v94
	v_mul_f32_e32 v95, v185, v95
	v_cvt_pk_bf16_f32 v92, v92, v93
	v_cvt_pk_bf16_f32 v93, v94, v95
	ds_write_b64 v160, v[92:93] offset:176
	global_load_dwordx4 v[128:131], v181, s[68:69] offset:384
	global_load_dwordx4 v[132:135], v181, s[68:69] offset:416
	global_load_dwordx4 v[136:139], v181, s[68:69] offset:448
	global_load_dwordx4 v[140:143], v181, s[68:69] offset:480
	global_load_dwordx4 v[144:147], v181, s[70:71] offset:384
	global_load_dwordx4 v[148:151], v181, s[70:71] offset:416
	global_load_dwordx4 v[152:155], v181, s[70:71] offset:448
	global_load_dwordx4 v[156:159], v181, s[70:71] offset:480
	ds_read_b64 v[164:165], v160 offset:192
	s_waitcnt vmcnt(3) lgkmcnt(0)
; DI bfr f2bf(float a) { return (bfr)(pack2(a, 0.f) & 0xffffu); }
; DI float bf2f(bfr u) { return __uint_as_float(((unsigned)u) << 16); }
; DI float siluf_(float x) { return x / (1.0f + __expf(-x)); }
; DI void phase_gemm_pool(const Params& p, char* smem) {
;     ...
;               [=](int row, int col, float v) {
;                 float gate = bf2f(P2[(size_t)row * 2048 + 1024 + g * 256 + col]);
;                 float z = (v + bp[col]) * sc[col] * siluf_(gate);
;                 Z[(size_t)row * 1024 + g * 256 + col] = f2bf(z);
;               });
	v_lshlrev_b32_e32 v182, 16, v164
	v_and_b32_e32 v183, 0xffff0000, v164
	v_lshlrev_b32_e32 v184, 16, v165
	v_and_b32_e32 v185, 0xffff0000, v165
	v_add_f32_e32 v64, v128, v64
	v_mul_f32_e32 v64, v144, v64
	v_add_f32_e32 v65, v129, v65
	v_mul_f32_e32 v65, v145, v65
	v_add_f32_e32 v66, v130, v66
	v_mul_f32_e32 v66, v146, v66
	v_add_f32_e32 v67, v131, v67
	v_mul_f32_e32 v67, v147, v67
	v_mul_f32_e32 v189, 0xbfb8aa3b, v182
	v_mul_f32_e32 v190, 0xbfb8aa3b, v183
	v_mul_f32_e32 v191, 0xbfb8aa3b, v184
	v_mul_f32_e32 v192, 0xbfb8aa3b, v185
	v_exp_f32_e32 v189, v189
	v_exp_f32_e32 v190, v190
	v_exp_f32_e32 v191, v191
	v_exp_f32_e32 v192, v192
	s_nop 0
	v_add_f32_e32 v189, 1.0, v189
	v_add_f32_e32 v190, 1.0, v190
	v_add_f32_e32 v191, 1.0, v191
	v_add_f32_e32 v192, 1.0, v192
	v_rcp_f32_e32 v166, v189
	v_rcp_f32_e32 v167, v190
	s_nop 0
	v_fma_f32 v189, -v189, v166, 2.0
	v_fma_f32 v190, -v190, v167, 2.0
	v_mul_f32_e32 v166, v166, v189
	v_mul_f32_e32 v167, v167, v190
	v_mul_f32_e32 v182, v182, v166
	v_mul_f32_e32 v183, v183, v167
	v_rcp_f32_e32 v166, v191
	v_rcp_f32_e32 v167, v192
	s_nop 0
	v_fma_f32 v191, -v191, v166, 2.0
	v_fma_f32 v192, -v192, v167, 2.0
	v_mul_f32_e32 v166, v166, v191
	v_mul_f32_e32 v167, v167, v192
	v_mul_f32_e32 v184, v184, v166
	v_mul_f32_e32 v185, v185, v167
	v_mul_f32_e32 v64, v182, v64
	v_mul_f32_e32 v65, v183, v65
	v_mul_f32_e32 v66, v184, v66
	v_mul_f32_e32 v67, v185, v67
	v_cvt_pk_bf16_f32 v64, v64, v65
	v_cvt_pk_bf16_f32 v65, v66, v67
	ds_write_b64 v160, v[64:65] offset:192
	ds_read_b64 v[164:165], v160 offset:208
	s_waitcnt vmcnt(2) lgkmcnt(0)
	v_lshlrev_b32_e32 v182, 16, v164
	v_and_b32_e32 v183, 0xffff0000, v164
	v_lshlrev_b32_e32 v184, 16, v165
	v_and_b32_e32 v185, 0xffff0000, v165
	v_add_f32_e32 v68, v132, v68
	v_mul_f32_e32 v68, v148, v68
	v_add_f32_e32 v69, v133, v69
	v_mul_f32_e32 v69, v149, v69
	v_add_f32_e32 v70, v134, v70
	v_mul_f32_e32 v70, v150, v70
	v_add_f32_e32 v71, v135, v71
	v_mul_f32_e32 v71, v151, v71
	v_mul_f32_e32 v189, 0xbfb8aa3b, v182
	v_mul_f32_e32 v190, 0xbfb8aa3b, v183
	v_mul_f32_e32 v191, 0xbfb8aa3b, v184
	v_mul_f32_e32 v192, 0xbfb8aa3b, v185
	v_exp_f32_e32 v189, v189
	v_exp_f32_e32 v190, v190
	v_exp_f32_e32 v191, v191
	v_exp_f32_e32 v192, v192
	s_nop 0
	v_add_f32_e32 v189, 1.0, v189
	v_add_f32_e32 v190, 1.0, v190
	v_add_f32_e32 v191, 1.0, v191
	v_add_f32_e32 v192, 1.0, v192
	v_rcp_f32_e32 v166, v189
	v_rcp_f32_e32 v167, v190
	s_nop 0
	v_fma_f32 v189, -v189, v166, 2.0
	v_fma_f32 v190, -v190, v167, 2.0
	v_mul_f32_e32 v166, v166, v189
	v_mul_f32_e32 v167, v167, v190
	v_mul_f32_e32 v182, v182, v166
	v_mul_f32_e32 v183, v183, v167
	v_rcp_f32_e32 v166, v191
	v_rcp_f32_e32 v167, v192
	s_nop 0
	v_fma_f32 v191, -v191, v166, 2.0
	v_fma_f32 v192, -v192, v167, 2.0
	v_mul_f32_e32 v166, v166, v191
	v_mul_f32_e32 v167, v167, v192
	v_mul_f32_e32 v184, v184, v166
	v_mul_f32_e32 v185, v185, v167
	v_mul_f32_e32 v68, v182, v68
	v_mul_f32_e32 v69, v183, v69
	v_mul_f32_e32 v70, v184, v70
	v_mul_f32_e32 v71, v185, v71
	v_cvt_pk_bf16_f32 v68, v68, v69
	v_cvt_pk_bf16_f32 v69, v70, v71
	ds_write_b64 v160, v[68:69] offset:208
	ds_read_b64 v[164:165], v160 offset:224
	s_waitcnt vmcnt(1) lgkmcnt(0)
	v_lshlrev_b32_e32 v182, 16, v164
	v_and_b32_e32 v183, 0xffff0000, v164
	v_lshlrev_b32_e32 v184, 16, v165
	v_and_b32_e32 v185, 0xffff0000, v165
	v_add_f32_e32 v72, v136, v72
	v_mul_f32_e32 v72, v152, v72
	v_add_f32_e32 v73, v137, v73
	v_mul_f32_e32 v73, v153, v73
	v_add_f32_e32 v74, v138, v74
	v_mul_f32_e32 v74, v154, v74
	v_add_f32_e32 v75, v139, v75
	v_mul_f32_e32 v75, v155, v75
	v_mul_f32_e32 v189, 0xbfb8aa3b, v182
	v_mul_f32_e32 v190, 0xbfb8aa3b, v183
	v_mul_f32_e32 v191, 0xbfb8aa3b, v184
	v_mul_f32_e32 v192, 0xbfb8aa3b, v185
	v_exp_f32_e32 v189, v189
	v_exp_f32_e32 v190, v190
	v_exp_f32_e32 v191, v191
	v_exp_f32_e32 v192, v192
	s_nop 0
	v_add_f32_e32 v189, 1.0, v189
	v_add_f32_e32 v190, 1.0, v190
	v_add_f32_e32 v191, 1.0, v191
	v_add_f32_e32 v192, 1.0, v192
	v_rcp_f32_e32 v166, v189
	v_rcp_f32_e32 v167, v190
	s_nop 0
	v_fma_f32 v189, -v189, v166, 2.0
	v_fma_f32 v190, -v190, v167, 2.0
	v_mul_f32_e32 v166, v166, v189
	v_mul_f32_e32 v167, v167, v190
	v_mul_f32_e32 v182, v182, v166
	v_mul_f32_e32 v183, v183, v167
	v_rcp_f32_e32 v166, v191
	v_rcp_f32_e32 v167, v192
	s_nop 0
	v_fma_f32 v191, -v191, v166, 2.0
	v_fma_f32 v192, -v192, v167, 2.0
	v_mul_f32_e32 v166, v166, v191
	v_mul_f32_e32 v167, v167, v192
	v_mul_f32_e32 v184, v184, v166
	v_mul_f32_e32 v185, v185, v167
	v_mul_f32_e32 v72, v182, v72
	v_mul_f32_e32 v73, v183, v73
	v_mul_f32_e32 v74, v184, v74
	v_mul_f32_e32 v75, v185, v75
	v_cvt_pk_bf16_f32 v72, v72, v73
	v_cvt_pk_bf16_f32 v73, v74, v75
	ds_write_b64 v160, v[72:73] offset:224
	ds_read_b64 v[164:165], v160 offset:240
	s_waitcnt vmcnt(0) lgkmcnt(0)
	v_lshlrev_b32_e32 v182, 16, v164
	v_and_b32_e32 v183, 0xffff0000, v164
	v_lshlrev_b32_e32 v184, 16, v165
	v_and_b32_e32 v185, 0xffff0000, v165
	v_add_f32_e32 v76, v140, v76
	v_mul_f32_e32 v76, v156, v76
	v_add_f32_e32 v77, v141, v77
	v_mul_f32_e32 v77, v157, v77
	v_add_f32_e32 v78, v142, v78
	v_mul_f32_e32 v78, v158, v78
	v_add_f32_e32 v79, v143, v79
	v_mul_f32_e32 v79, v159, v79
	v_mul_f32_e32 v189, 0xbfb8aa3b, v182
	v_mul_f32_e32 v190, 0xbfb8aa3b, v183
	v_mul_f32_e32 v191, 0xbfb8aa3b, v184
	v_mul_f32_e32 v192, 0xbfb8aa3b, v185
	v_exp_f32_e32 v189, v189
	v_exp_f32_e32 v190, v190
	v_exp_f32_e32 v191, v191
	v_exp_f32_e32 v192, v192
	s_nop 0
	v_add_f32_e32 v189, 1.0, v189
	v_add_f32_e32 v190, 1.0, v190
	v_add_f32_e32 v191, 1.0, v191
	v_add_f32_e32 v192, 1.0, v192
	v_rcp_f32_e32 v166, v189
	v_rcp_f32_e32 v167, v190
	s_nop 0
	v_fma_f32 v189, -v189, v166, 2.0
	v_fma_f32 v190, -v190, v167, 2.0
	v_mul_f32_e32 v166, v166, v189
	v_mul_f32_e32 v167, v167, v190
	v_mul_f32_e32 v182, v182, v166
	v_mul_f32_e32 v183, v183, v167
	v_rcp_f32_e32 v166, v191
	v_rcp_f32_e32 v167, v192
	s_nop 0
	v_fma_f32 v191, -v191, v166, 2.0
	v_fma_f32 v192, -v192, v167, 2.0
	v_mul_f32_e32 v166, v166, v191
	v_mul_f32_e32 v167, v167, v192
	v_mul_f32_e32 v184, v184, v166
	v_mul_f32_e32 v185, v185, v167
	v_mul_f32_e32 v76, v182, v76
	v_mul_f32_e32 v77, v183, v77
	v_mul_f32_e32 v78, v184, v78
	v_mul_f32_e32 v79, v185, v79
	v_cvt_pk_bf16_f32 v76, v76, v77
	v_cvt_pk_bf16_f32 v77, v78, v79
	ds_write_b64 v160, v[76:77] offset:240
	s_waitcnt lgkmcnt(0)
; DI bfr f2bf(float a) { return (bfr)(pack2(a, 0.f) & 0xffffu); }
; DI float bf2f(bfr u) { return __uint_as_float(((unsigned)u) << 16); }
; DI float siluf_(float x) { return x / (1.0f + __expf(-x)); }
; DI void phase_gemm_pool(const Params& p, char* smem) {
;     ...
;     gemm_tile<1024>(p.MIX + g * 256, p.WtPool + (size_t)g * 65536, 256, 256, mt * 128, nt * 256, smem,
;               [=](int row, int col, float v) {
;                 float gate = bf2f(P2[(size_t)row * 2048 + 1024 + g * 256 + col]);
;                 float z = (v + bp[col]) * sc[col] * siluf_(gate);
;                 Z[(size_t)row * 1024 + g * 256 + col] = f2bf(z);
;               });
	ds_read_b128 v[128:131], v162
	ds_read_b128 v[132:135], v162 offset:1088
	ds_read_b128 v[136:139], v162 offset:2176
	ds_read_b128 v[140:143], v162 offset:3264
	ds_read_b128 v[144:147], v162 offset:4352
	ds_read_b128 v[148:151], v162 offset:5440
	ds_read_b128 v[152:155], v162 offset:6528
	ds_read_b128 v[156:159], v162 offset:7616
	s_add_u32 s74, s66, 0x0
	s_addc_u32 s75, s67, 0
	s_waitcnt lgkmcnt(7)
	global_store_dwordx4 v180, v[128:131], s[74:75]  sc1
	s_add_u32 s74, s66, 0x2000
	s_addc_u32 s75, s67, 0
	s_waitcnt lgkmcnt(6)
	global_store_dwordx4 v180, v[132:135], s[74:75]  sc1
	s_add_u32 s74, s66, 0x4000
	s_addc_u32 s75, s67, 0
	s_waitcnt lgkmcnt(5)
	global_store_dwordx4 v180, v[136:139], s[74:75]  sc1
	s_add_u32 s74, s66, 0x6000
	s_addc_u32 s75, s67, 0
	s_waitcnt lgkmcnt(4)
	global_store_dwordx4 v180, v[140:143], s[74:75]  sc1
	s_add_u32 s74, s66, 0x8000
	s_addc_u32 s75, s67, 0
	s_waitcnt lgkmcnt(3)
	global_store_dwordx4 v180, v[144:147], s[74:75]  sc1
	s_add_u32 s74, s66, 0xa000
	s_addc_u32 s75, s67, 0
	s_waitcnt lgkmcnt(2)
	global_store_dwordx4 v180, v[148:151], s[74:75]  sc1
	s_add_u32 s74, s66, 0xc000
	s_addc_u32 s75, s67, 0
	s_waitcnt lgkmcnt(1)
	global_store_dwordx4 v180, v[152:155], s[74:75]  sc1
	s_add_u32 s74, s66, 0xe000
	s_addc_u32 s75, s67, 0
	s_waitcnt lgkmcnt(0)
	global_store_dwordx4 v180, v[156:159], s[74:75]  sc1
	s_add_u32 s74, s64, 0x20000
	s_addc_u32 s75, s65, 0
	global_load_dwordx4 v[128:131], v163, s[74:75]
	s_add_u32 s74, s64, 0x24000
	s_addc_u32 s75, s65, 0
	global_load_dwordx4 v[132:135], v163, s[74:75]
	s_add_u32 s74, s64, 0x28000
	s_addc_u32 s75, s65, 0
	global_load_dwordx4 v[136:139], v163, s[74:75]
	s_add_u32 s74, s64, 0x2c000
	s_addc_u32 s75, s65, 0
	global_load_dwordx4 v[140:143], v163, s[74:75]
	s_add_u32 s74, s64, 0x30000
	s_addc_u32 s75, s65, 0
	global_load_dwordx4 v[144:147], v163, s[74:75]
	s_add_u32 s74, s64, 0x34000
	s_addc_u32 s75, s65, 0
	global_load_dwordx4 v[148:151], v163, s[74:75]
	s_add_u32 s74, s64, 0x38000
	s_addc_u32 s75, s65, 0
	global_load_dwordx4 v[152:155], v163, s[74:75]
	s_add_u32 s74, s64, 0x3c000
	s_addc_u32 s75, s65, 0
	global_load_dwordx4 v[156:159], v163, s[74:75]
	s_waitcnt vmcnt(7)
	ds_write_b128 v162, v[128:131]
	s_waitcnt vmcnt(6)
	ds_write_b128 v162, v[132:135] offset:1088
	s_waitcnt vmcnt(5)
	ds_write_b128 v162, v[136:139] offset:2176
	s_waitcnt vmcnt(4)
	ds_write_b128 v162, v[140:143] offset:3264
	s_waitcnt vmcnt(3)
	ds_write_b128 v162, v[144:147] offset:4352
	s_waitcnt vmcnt(2)
	ds_write_b128 v162, v[148:151] offset:5440
	s_waitcnt vmcnt(1)
	ds_write_b128 v162, v[152:155] offset:6528
	s_waitcnt vmcnt(0)
	ds_write_b128 v162, v[156:159] offset:7616
	global_load_dwordx4 v[128:131], v181, s[68:69]
	global_load_dwordx4 v[132:135], v181, s[68:69] offset:32
	global_load_dwordx4 v[136:139], v181, s[68:69] offset:64
	global_load_dwordx4 v[140:143], v181, s[68:69] offset:96
	global_load_dwordx4 v[144:147], v181, s[70:71]
	global_load_dwordx4 v[148:151], v181, s[70:71] offset:32
	global_load_dwordx4 v[152:155], v181, s[70:71] offset:64
	global_load_dwordx4 v[156:159], v181, s[70:71] offset:96
	ds_read_b64 v[164:165], v160
	s_waitcnt vmcnt(3) lgkmcnt(0)
	v_lshlrev_b32_e32 v182, 16, v164
	v_and_b32_e32 v183, 0xffff0000, v164
	v_lshlrev_b32_e32 v184, 16, v165
	v_and_b32_e32 v185, 0xffff0000, v165
	v_add_f32_e32 v48, v128, v48
	v_mul_f32_e32 v48, v144, v48
	v_add_f32_e32 v49, v129, v49
	v_mul_f32_e32 v49, v145, v49
	v_add_f32_e32 v50, v130, v50
	v_mul_f32_e32 v50, v146, v50
	v_add_f32_e32 v51, v131, v51
	v_mul_f32_e32 v51, v147, v51
	v_mul_f32_e32 v189, 0xbfb8aa3b, v182
	v_mul_f32_e32 v190, 0xbfb8aa3b, v183
	v_mul_f32_e32 v191, 0xbfb8aa3b, v184
	v_mul_f32_e32 v192, 0xbfb8aa3b, v185
	v_exp_f32_e32 v189, v189
	v_exp_f32_e32 v190, v190
	v_exp_f32_e32 v191, v191
	v_exp_f32_e32 v192, v192
	s_nop 0
	v_add_f32_e32 v189, 1.0, v189
	v_add_f32_e32 v190, 1.0, v190
	v_add_f32_e32 v191, 1.0, v191
	v_add_f32_e32 v192, 1.0, v192
	v_rcp_f32_e32 v166, v189
	v_rcp_f32_e32 v167, v190
	s_nop 0
	v_fma_f32 v189, -v189, v166, 2.0
	v_fma_f32 v190, -v190, v167, 2.0
	v_mul_f32_e32 v166, v166, v189
	v_mul_f32_e32 v167, v167, v190
	v_mul_f32_e32 v182, v182, v166
	v_mul_f32_e32 v183, v183, v167
	v_rcp_f32_e32 v166, v191
	v_rcp_f32_e32 v167, v192
	s_nop 0
	v_fma_f32 v191, -v191, v166, 2.0
	v_fma_f32 v192, -v192, v167, 2.0
	v_mul_f32_e32 v166, v166, v191
	v_mul_f32_e32 v167, v167, v192
	v_mul_f32_e32 v184, v184, v166
	v_mul_f32_e32 v185, v185, v167
	v_mul_f32_e32 v48, v182, v48
	v_mul_f32_e32 v49, v183, v49
	v_mul_f32_e32 v50, v184, v50
	v_mul_f32_e32 v51, v185, v51
	v_cvt_pk_bf16_f32 v48, v48, v49
	v_cvt_pk_bf16_f32 v49, v50, v51
	ds_write_b64 v160, v[48:49]
	ds_read_b64 v[164:165], v160 offset:16
	s_waitcnt vmcnt(2) lgkmcnt(0)
	v_lshlrev_b32_e32 v182, 16, v164
	v_and_b32_e32 v183, 0xffff0000, v164
	v_lshlrev_b32_e32 v184, 16, v165
	v_and_b32_e32 v185, 0xffff0000, v165
	v_add_f32_e32 v52, v132, v52
	v_mul_f32_e32 v52, v148, v52
	v_add_f32_e32 v53, v133, v53
	v_mul_f32_e32 v53, v149, v53
	v_add_f32_e32 v54, v134, v54
	v_mul_f32_e32 v54, v150, v54
	v_add_f32_e32 v55, v135, v55
	v_mul_f32_e32 v55, v151, v55
	v_mul_f32_e32 v189, 0xbfb8aa3b, v182
	v_mul_f32_e32 v190, 0xbfb8aa3b, v183
	v_mul_f32_e32 v191, 0xbfb8aa3b, v184
	v_mul_f32_e32 v192, 0xbfb8aa3b, v185
	v_exp_f32_e32 v189, v189
	v_exp_f32_e32 v190, v190
	v_exp_f32_e32 v191, v191
	v_exp_f32_e32 v192, v192
	s_nop 0
	v_add_f32_e32 v189, 1.0, v189
	v_add_f32_e32 v190, 1.0, v190
	v_add_f32_e32 v191, 1.0, v191
	v_add_f32_e32 v192, 1.0, v192
	v_rcp_f32_e32 v166, v189
	v_rcp_f32_e32 v167, v190
	s_nop 0
	v_fma_f32 v189, -v189, v166, 2.0
	v_fma_f32 v190, -v190, v167, 2.0
	v_mul_f32_e32 v166, v166, v189
	v_mul_f32_e32 v167, v167, v190
	v_mul_f32_e32 v182, v182, v166
	v_mul_f32_e32 v183, v183, v167
	v_rcp_f32_e32 v166, v191
	v_rcp_f32_e32 v167, v192
	s_nop 0
	v_fma_f32 v191, -v191, v166, 2.0
	v_fma_f32 v192, -v192, v167, 2.0
	v_mul_f32_e32 v166, v166, v191
	v_mul_f32_e32 v167, v167, v192
	v_mul_f32_e32 v184, v184, v166
	v_mul_f32_e32 v185, v185, v167
	v_mul_f32_e32 v52, v182, v52
	v_mul_f32_e32 v53, v183, v53
	v_mul_f32_e32 v54, v184, v54
	v_mul_f32_e32 v55, v185, v55
	v_cvt_pk_bf16_f32 v52, v52, v53
	v_cvt_pk_bf16_f32 v53, v54, v55
	ds_write_b64 v160, v[52:53] offset:16
	ds_read_b64 v[164:165], v160 offset:32
	s_waitcnt vmcnt(1) lgkmcnt(0)
; DI bfr f2bf(float a) { return (bfr)(pack2(a, 0.f) & 0xffffu); }
; DI float bf2f(bfr u) { return __uint_as_float(((unsigned)u) << 16); }
; DI float siluf_(float x) { return x / (1.0f + __expf(-x)); }
; DI void phase_gemm_pool(const Params& p, char* smem) {
;     ...
;               [=](int row, int col, float v) {
;                 float gate = bf2f(P2[(size_t)row * 2048 + 1024 + g * 256 + col]);
;                 float z = (v + bp[col]) * sc[col] * siluf_(gate);
;                 Z[(size_t)row * 1024 + g * 256 + col] = f2bf(z);
;               });
	v_lshlrev_b32_e32 v182, 16, v164
	v_and_b32_e32 v183, 0xffff0000, v164
	v_lshlrev_b32_e32 v184, 16, v165
	v_and_b32_e32 v185, 0xffff0000, v165
	v_add_f32_e32 v56, v136, v56
	v_mul_f32_e32 v56, v152, v56
	v_add_f32_e32 v57, v137, v57
	v_mul_f32_e32 v57, v153, v57
	v_add_f32_e32 v58, v138, v58
	v_mul_f32_e32 v58, v154, v58
	v_add_f32_e32 v59, v139, v59
	v_mul_f32_e32 v59, v155, v59
	v_mul_f32_e32 v189, 0xbfb8aa3b, v182
	v_mul_f32_e32 v190, 0xbfb8aa3b, v183
	v_mul_f32_e32 v191, 0xbfb8aa3b, v184
	v_mul_f32_e32 v192, 0xbfb8aa3b, v185
	v_exp_f32_e32 v189, v189
	v_exp_f32_e32 v190, v190
	v_exp_f32_e32 v191, v191
	v_exp_f32_e32 v192, v192
	s_nop 0
	v_add_f32_e32 v189, 1.0, v189
	v_add_f32_e32 v190, 1.0, v190
	v_add_f32_e32 v191, 1.0, v191
	v_add_f32_e32 v192, 1.0, v192
	v_rcp_f32_e32 v166, v189
	v_rcp_f32_e32 v167, v190
	s_nop 0
	v_fma_f32 v189, -v189, v166, 2.0
	v_fma_f32 v190, -v190, v167, 2.0
	v_mul_f32_e32 v166, v166, v189
	v_mul_f32_e32 v167, v167, v190
	v_mul_f32_e32 v182, v182, v166
	v_mul_f32_e32 v183, v183, v167
	v_rcp_f32_e32 v166, v191
	v_rcp_f32_e32 v167, v192
	s_nop 0
	v_fma_f32 v191, -v191, v166, 2.0
	v_fma_f32 v192, -v192, v167, 2.0
	v_mul_f32_e32 v166, v166, v191
	v_mul_f32_e32 v167, v167, v192
	v_mul_f32_e32 v184, v184, v166
	v_mul_f32_e32 v185, v185, v167
	v_mul_f32_e32 v56, v182, v56
	v_mul_f32_e32 v57, v183, v57
	v_mul_f32_e32 v58, v184, v58
	v_mul_f32_e32 v59, v185, v59
	v_cvt_pk_bf16_f32 v56, v56, v57
	v_cvt_pk_bf16_f32 v57, v58, v59
	ds_write_b64 v160, v[56:57] offset:32
	ds_read_b64 v[164:165], v160 offset:48
	s_waitcnt vmcnt(0) lgkmcnt(0)
	v_lshlrev_b32_e32 v182, 16, v164
	v_and_b32_e32 v183, 0xffff0000, v164
	v_lshlrev_b32_e32 v184, 16, v165
	v_and_b32_e32 v185, 0xffff0000, v165
	v_add_f32_e32 v60, v140, v60
	v_mul_f32_e32 v60, v156, v60
	v_add_f32_e32 v61, v141, v61
	v_mul_f32_e32 v61, v157, v61
	v_add_f32_e32 v62, v142, v62
	v_mul_f32_e32 v62, v158, v62
	v_add_f32_e32 v63, v143, v63
	v_mul_f32_e32 v63, v159, v63
	v_mul_f32_e32 v189, 0xbfb8aa3b, v182
	v_mul_f32_e32 v190, 0xbfb8aa3b, v183
	v_mul_f32_e32 v191, 0xbfb8aa3b, v184
	v_mul_f32_e32 v192, 0xbfb8aa3b, v185
	v_exp_f32_e32 v189, v189
	v_exp_f32_e32 v190, v190
	v_exp_f32_e32 v191, v191
	v_exp_f32_e32 v192, v192
	s_nop 0
	v_add_f32_e32 v189, 1.0, v189
	v_add_f32_e32 v190, 1.0, v190
	v_add_f32_e32 v191, 1.0, v191
	v_add_f32_e32 v192, 1.0, v192
	v_rcp_f32_e32 v166, v189
	v_rcp_f32_e32 v167, v190
	s_nop 0
	v_fma_f32 v189, -v189, v166, 2.0
	v_fma_f32 v190, -v190, v167, 2.0
	v_mul_f32_e32 v166, v166, v189
	v_mul_f32_e32 v167, v167, v190
	v_mul_f32_e32 v182, v182, v166
	v_mul_f32_e32 v183, v183, v167
	v_rcp_f32_e32 v166, v191
	v_rcp_f32_e32 v167, v192
	s_nop 0
	v_fma_f32 v191, -v191, v166, 2.0
	v_fma_f32 v192, -v192, v167, 2.0
	v_mul_f32_e32 v166, v166, v191
	v_mul_f32_e32 v167, v167, v192
	v_mul_f32_e32 v184, v184, v166
	v_mul_f32_e32 v185, v185, v167
	v_mul_f32_e32 v60, v182, v60
	v_mul_f32_e32 v61, v183, v61
	v_mul_f32_e32 v62, v184, v62
	v_mul_f32_e32 v63, v185, v63
	v_cvt_pk_bf16_f32 v60, v60, v61
	v_cvt_pk_bf16_f32 v61, v62, v63
	ds_write_b64 v160, v[60:61] offset:48
	global_load_dwordx4 v[128:131], v181, s[68:69] offset:128
	global_load_dwordx4 v[132:135], v181, s[68:69] offset:160
	global_load_dwordx4 v[136:139], v181, s[68:69] offset:192
	global_load_dwordx4 v[140:143], v181, s[68:69] offset:224
	global_load_dwordx4 v[144:147], v181, s[70:71] offset:128
	global_load_dwordx4 v[148:151], v181, s[70:71] offset:160
	global_load_dwordx4 v[152:155], v181, s[70:71] offset:192
	global_load_dwordx4 v[156:159], v181, s[70:71] offset:224
	ds_read_b64 v[164:165], v160 offset:64
	s_waitcnt vmcnt(3) lgkmcnt(0)
	v_lshlrev_b32_e32 v182, 16, v164
	v_and_b32_e32 v183, 0xffff0000, v164
	v_lshlrev_b32_e32 v184, 16, v165
	v_and_b32_e32 v185, 0xffff0000, v165
	v_add_f32_e32 v32, v128, v32
	v_mul_f32_e32 v32, v144, v32
	v_add_f32_e32 v33, v129, v33
	v_mul_f32_e32 v33, v145, v33
	v_add_f32_e32 v34, v130, v34
	v_mul_f32_e32 v34, v146, v34
	v_add_f32_e32 v35, v131, v35
	v_mul_f32_e32 v35, v147, v35
	v_mul_f32_e32 v189, 0xbfb8aa3b, v182
	v_mul_f32_e32 v190, 0xbfb8aa3b, v183
	v_mul_f32_e32 v191, 0xbfb8aa3b, v184
	v_mul_f32_e32 v192, 0xbfb8aa3b, v185
	v_exp_f32_e32 v189, v189
	v_exp_f32_e32 v190, v190
	v_exp_f32_e32 v191, v191
	v_exp_f32_e32 v192, v192
	s_nop 0
	v_add_f32_e32 v189, 1.0, v189
	v_add_f32_e32 v190, 1.0, v190
	v_add_f32_e32 v191, 1.0, v191
	v_add_f32_e32 v192, 1.0, v192
	v_rcp_f32_e32 v166, v189
	v_rcp_f32_e32 v167, v190
	s_nop 0
	v_fma_f32 v189, -v189, v166, 2.0
	v_fma_f32 v190, -v190, v167, 2.0
	v_mul_f32_e32 v166, v166, v189
	v_mul_f32_e32 v167, v167, v190
	v_mul_f32_e32 v182, v182, v166
	v_mul_f32_e32 v183, v183, v167
	v_rcp_f32_e32 v166, v191
	v_rcp_f32_e32 v167, v192
	s_nop 0
	v_fma_f32 v191, -v191, v166, 2.0
	v_fma_f32 v192, -v192, v167, 2.0
	v_mul_f32_e32 v166, v166, v191
	v_mul_f32_e32 v167, v167, v192
	v_mul_f32_e32 v184, v184, v166
	v_mul_f32_e32 v185, v185, v167
	v_mul_f32_e32 v32, v182, v32
	v_mul_f32_e32 v33, v183, v33
	v_mul_f32_e32 v34, v184, v34
	v_mul_f32_e32 v35, v185, v35
	v_cvt_pk_bf16_f32 v32, v32, v33
	v_cvt_pk_bf16_f32 v33, v34, v35
	ds_write_b64 v160, v[32:33] offset:64
	ds_read_b64 v[164:165], v160 offset:80
	s_waitcnt vmcnt(2) lgkmcnt(0)
; DI bfr f2bf(float a) { return (bfr)(pack2(a, 0.f) & 0xffffu); }
; DI float bf2f(bfr u) { return __uint_as_float(((unsigned)u) << 16); }
; DI float siluf_(float x) { return x / (1.0f + __expf(-x)); }
; DI void phase_gemm_pool(const Params& p, char* smem) {
;     ...
;               [=](int row, int col, float v) {
;                 float gate = bf2f(P2[(size_t)row * 2048 + 1024 + g * 256 + col]);
;                 float z = (v + bp[col]) * sc[col] * siluf_(gate);
;                 Z[(size_t)row * 1024 + g * 256 + col] = f2bf(z);
;               });
	v_lshlrev_b32_e32 v182, 16, v164
	v_and_b32_e32 v183, 0xffff0000, v164
	v_lshlrev_b32_e32 v184, 16, v165
	v_and_b32_e32 v185, 0xffff0000, v165
	v_add_f32_e32 v36, v132, v36
	v_mul_f32_e32 v36, v148, v36
	v_add_f32_e32 v37, v133, v37
	v_mul_f32_e32 v37, v149, v37
	v_add_f32_e32 v38, v134, v38
	v_mul_f32_e32 v38, v150, v38
	v_add_f32_e32 v39, v135, v39
	v_mul_f32_e32 v39, v151, v39
	v_mul_f32_e32 v189, 0xbfb8aa3b, v182
	v_mul_f32_e32 v190, 0xbfb8aa3b, v183
	v_mul_f32_e32 v191, 0xbfb8aa3b, v184
	v_mul_f32_e32 v192, 0xbfb8aa3b, v185
	v_exp_f32_e32 v189, v189
	v_exp_f32_e32 v190, v190
	v_exp_f32_e32 v191, v191
	v_exp_f32_e32 v192, v192
	s_nop 0
	v_add_f32_e32 v189, 1.0, v189
	v_add_f32_e32 v190, 1.0, v190
	v_add_f32_e32 v191, 1.0, v191
	v_add_f32_e32 v192, 1.0, v192
	v_rcp_f32_e32 v166, v189
	v_rcp_f32_e32 v167, v190
	s_nop 0
	v_fma_f32 v189, -v189, v166, 2.0
	v_fma_f32 v190, -v190, v167, 2.0
	v_mul_f32_e32 v166, v166, v189
	v_mul_f32_e32 v167, v167, v190
	v_mul_f32_e32 v182, v182, v166
	v_mul_f32_e32 v183, v183, v167
	v_rcp_f32_e32 v166, v191
	v_rcp_f32_e32 v167, v192
	s_nop 0
	v_fma_f32 v191, -v191, v166, 2.0
	v_fma_f32 v192, -v192, v167, 2.0
	v_mul_f32_e32 v166, v166, v191
	v_mul_f32_e32 v167, v167, v192
	v_mul_f32_e32 v184, v184, v166
	v_mul_f32_e32 v185, v185, v167
	v_mul_f32_e32 v36, v182, v36
	v_mul_f32_e32 v37, v183, v37
	v_mul_f32_e32 v38, v184, v38
	v_mul_f32_e32 v39, v185, v39
	v_cvt_pk_bf16_f32 v36, v36, v37
	v_cvt_pk_bf16_f32 v37, v38, v39
	ds_write_b64 v160, v[36:37] offset:80
	ds_read_b64 v[164:165], v160 offset:96
	s_waitcnt vmcnt(1) lgkmcnt(0)
	v_lshlrev_b32_e32 v182, 16, v164
	v_and_b32_e32 v183, 0xffff0000, v164
	v_lshlrev_b32_e32 v184, 16, v165
	v_and_b32_e32 v185, 0xffff0000, v165
	v_add_f32_e32 v40, v136, v40
	v_mul_f32_e32 v40, v152, v40
	v_add_f32_e32 v41, v137, v41
	v_mul_f32_e32 v41, v153, v41
	v_add_f32_e32 v42, v138, v42
	v_mul_f32_e32 v42, v154, v42
	v_add_f32_e32 v43, v139, v43
	v_mul_f32_e32 v43, v155, v43
	v_mul_f32_e32 v189, 0xbfb8aa3b, v182
	v_mul_f32_e32 v190, 0xbfb8aa3b, v183
	v_mul_f32_e32 v191, 0xbfb8aa3b, v184
	v_mul_f32_e32 v192, 0xbfb8aa3b, v185
	v_exp_f32_e32 v189, v189
	v_exp_f32_e32 v190, v190
	v_exp_f32_e32 v191, v191
	v_exp_f32_e32 v192, v192
	s_nop 0
	v_add_f32_e32 v189, 1.0, v189
	v_add_f32_e32 v190, 1.0, v190
	v_add_f32_e32 v191, 1.0, v191
	v_add_f32_e32 v192, 1.0, v192
	v_rcp_f32_e32 v166, v189
	v_rcp_f32_e32 v167, v190
	s_nop 0
	v_fma_f32 v189, -v189, v166, 2.0
	v_fma_f32 v190, -v190, v167, 2.0
	v_mul_f32_e32 v166, v166, v189
	v_mul_f32_e32 v167, v167, v190
	v_mul_f32_e32 v182, v182, v166
	v_mul_f32_e32 v183, v183, v167
	v_rcp_f32_e32 v166, v191
	v_rcp_f32_e32 v167, v192
	s_nop 0
	v_fma_f32 v191, -v191, v166, 2.0
	v_fma_f32 v192, -v192, v167, 2.0
	v_mul_f32_e32 v166, v166, v191
	v_mul_f32_e32 v167, v167, v192
	v_mul_f32_e32 v184, v184, v166
	v_mul_f32_e32 v185, v185, v167
	v_mul_f32_e32 v40, v182, v40
	v_mul_f32_e32 v41, v183, v41
	v_mul_f32_e32 v42, v184, v42
	v_mul_f32_e32 v43, v185, v43
	v_cvt_pk_bf16_f32 v40, v40, v41
	v_cvt_pk_bf16_f32 v41, v42, v43
	ds_write_b64 v160, v[40:41] offset:96
	ds_read_b64 v[164:165], v160 offset:112
	s_waitcnt vmcnt(0) lgkmcnt(0)
	v_lshlrev_b32_e32 v182, 16, v164
	v_and_b32_e32 v183, 0xffff0000, v164
	v_lshlrev_b32_e32 v184, 16, v165
	v_and_b32_e32 v185, 0xffff0000, v165
	v_add_f32_e32 v44, v140, v44
	v_mul_f32_e32 v44, v156, v44
	v_add_f32_e32 v45, v141, v45
	v_mul_f32_e32 v45, v157, v45
	v_add_f32_e32 v46, v142, v46
	v_mul_f32_e32 v46, v158, v46
	v_add_f32_e32 v47, v143, v47
	v_mul_f32_e32 v47, v159, v47
	v_mul_f32_e32 v189, 0xbfb8aa3b, v182
	v_mul_f32_e32 v190, 0xbfb8aa3b, v183
	v_mul_f32_e32 v191, 0xbfb8aa3b, v184
	v_mul_f32_e32 v192, 0xbfb8aa3b, v185
	v_exp_f32_e32 v189, v189
	v_exp_f32_e32 v190, v190
	v_exp_f32_e32 v191, v191
	v_exp_f32_e32 v192, v192
	s_nop 0
	v_add_f32_e32 v189, 1.0, v189
	v_add_f32_e32 v190, 1.0, v190
	v_add_f32_e32 v191, 1.0, v191
	v_add_f32_e32 v192, 1.0, v192
	v_rcp_f32_e32 v166, v189
	v_rcp_f32_e32 v167, v190
	s_nop 0
	v_fma_f32 v189, -v189, v166, 2.0
	v_fma_f32 v190, -v190, v167, 2.0
	v_mul_f32_e32 v166, v166, v189
	v_mul_f32_e32 v167, v167, v190
	v_mul_f32_e32 v182, v182, v166
	v_mul_f32_e32 v183, v183, v167
	v_rcp_f32_e32 v166, v191
	v_rcp_f32_e32 v167, v192
	s_nop 0
	v_fma_f32 v191, -v191, v166, 2.0
	v_fma_f32 v192, -v192, v167, 2.0
	v_mul_f32_e32 v166, v166, v191
	v_mul_f32_e32 v167, v167, v192
	v_mul_f32_e32 v184, v184, v166
	v_mul_f32_e32 v185, v185, v167
	v_mul_f32_e32 v44, v182, v44
	v_mul_f32_e32 v45, v183, v45
	v_mul_f32_e32 v46, v184, v46
	v_mul_f32_e32 v47, v185, v47
	v_cvt_pk_bf16_f32 v44, v44, v45
	v_cvt_pk_bf16_f32 v45, v46, v47
	ds_write_b64 v160, v[44:45] offset:112
	global_load_dwordx4 v[128:131], v181, s[68:69] offset:256
	global_load_dwordx4 v[132:135], v181, s[68:69] offset:288
	global_load_dwordx4 v[136:139], v181, s[68:69] offset:320
	global_load_dwordx4 v[140:143], v181, s[68:69] offset:352
	global_load_dwordx4 v[144:147], v181, s[70:71] offset:256
	global_load_dwordx4 v[148:151], v181, s[70:71] offset:288
	global_load_dwordx4 v[152:155], v181, s[70:71] offset:320
	global_load_dwordx4 v[156:159], v181, s[70:71] offset:352
	ds_read_b64 v[164:165], v160 offset:128
	s_waitcnt vmcnt(3) lgkmcnt(0)
; DI bfr f2bf(float a) { return (bfr)(pack2(a, 0.f) & 0xffffu); }
; DI float bf2f(bfr u) { return __uint_as_float(((unsigned)u) << 16); }
; DI float siluf_(float x) { return x / (1.0f + __expf(-x)); }
; DI void phase_gemm_pool(const Params& p, char* smem) {
;     ...
;               [=](int row, int col, float v) {
;                 float gate = bf2f(P2[(size_t)row * 2048 + 1024 + g * 256 + col]);
;                 float z = (v + bp[col]) * sc[col] * siluf_(gate);
;                 Z[(size_t)row * 1024 + g * 256 + col] = f2bf(z);
;               });
	v_lshlrev_b32_e32 v182, 16, v164
	v_and_b32_e32 v183, 0xffff0000, v164
	v_lshlrev_b32_e32 v184, 16, v165
	v_and_b32_e32 v185, 0xffff0000, v165
	v_add_f32_e32 v16, v128, v16
	v_mul_f32_e32 v16, v144, v16
	v_add_f32_e32 v17, v129, v17
	v_mul_f32_e32 v17, v145, v17
	v_add_f32_e32 v18, v130, v18
	v_mul_f32_e32 v18, v146, v18
	v_add_f32_e32 v19, v131, v19
	v_mul_f32_e32 v19, v147, v19
	v_mul_f32_e32 v189, 0xbfb8aa3b, v182
	v_mul_f32_e32 v190, 0xbfb8aa3b, v183
	v_mul_f32_e32 v191, 0xbfb8aa3b, v184
	v_mul_f32_e32 v192, 0xbfb8aa3b, v185
	v_exp_f32_e32 v189, v189
	v_exp_f32_e32 v190, v190
	v_exp_f32_e32 v191, v191
	v_exp_f32_e32 v192, v192
	s_nop 0
	v_add_f32_e32 v189, 1.0, v189
	v_add_f32_e32 v190, 1.0, v190
	v_add_f32_e32 v191, 1.0, v191
	v_add_f32_e32 v192, 1.0, v192
	v_rcp_f32_e32 v166, v189
	v_rcp_f32_e32 v167, v190
	s_nop 0
	v_fma_f32 v189, -v189, v166, 2.0
	v_fma_f32 v190, -v190, v167, 2.0
	v_mul_f32_e32 v166, v166, v189
	v_mul_f32_e32 v167, v167, v190
	v_mul_f32_e32 v182, v182, v166
	v_mul_f32_e32 v183, v183, v167
	v_rcp_f32_e32 v166, v191
	v_rcp_f32_e32 v167, v192
	s_nop 0
	v_fma_f32 v191, -v191, v166, 2.0
	v_fma_f32 v192, -v192, v167, 2.0
	v_mul_f32_e32 v166, v166, v191
	v_mul_f32_e32 v167, v167, v192
	v_mul_f32_e32 v184, v184, v166
	v_mul_f32_e32 v185, v185, v167
	v_mul_f32_e32 v16, v182, v16
	v_mul_f32_e32 v17, v183, v17
	v_mul_f32_e32 v18, v184, v18
	v_mul_f32_e32 v19, v185, v19
	v_cvt_pk_bf16_f32 v16, v16, v17
	v_cvt_pk_bf16_f32 v17, v18, v19
	ds_write_b64 v160, v[16:17] offset:128
	ds_read_b64 v[164:165], v160 offset:144
	s_waitcnt vmcnt(2) lgkmcnt(0)
	v_lshlrev_b32_e32 v182, 16, v164
	v_and_b32_e32 v183, 0xffff0000, v164
	v_lshlrev_b32_e32 v184, 16, v165
	v_and_b32_e32 v185, 0xffff0000, v165
	v_add_f32_e32 v20, v132, v20
	v_mul_f32_e32 v20, v148, v20
	v_add_f32_e32 v21, v133, v21
	v_mul_f32_e32 v21, v149, v21
	v_add_f32_e32 v22, v134, v22
	v_mul_f32_e32 v22, v150, v22
	v_add_f32_e32 v23, v135, v23
	v_mul_f32_e32 v23, v151, v23
	v_mul_f32_e32 v189, 0xbfb8aa3b, v182
	v_mul_f32_e32 v190, 0xbfb8aa3b, v183
	v_mul_f32_e32 v191, 0xbfb8aa3b, v184
	v_mul_f32_e32 v192, 0xbfb8aa3b, v185
	v_exp_f32_e32 v189, v189
	v_exp_f32_e32 v190, v190
	v_exp_f32_e32 v191, v191
	v_exp_f32_e32 v192, v192
	s_nop 0
	v_add_f32_e32 v189, 1.0, v189
	v_add_f32_e32 v190, 1.0, v190
	v_add_f32_e32 v191, 1.0, v191
	v_add_f32_e32 v192, 1.0, v192
	v_rcp_f32_e32 v166, v189
	v_rcp_f32_e32 v167, v190
	s_nop 0
	v_fma_f32 v189, -v189, v166, 2.0
	v_fma_f32 v190, -v190, v167, 2.0
	v_mul_f32_e32 v166, v166, v189
	v_mul_f32_e32 v167, v167, v190
	v_mul_f32_e32 v182, v182, v166
	v_mul_f32_e32 v183, v183, v167
	v_rcp_f32_e32 v166, v191
	v_rcp_f32_e32 v167, v192
	s_nop 0
	v_fma_f32 v191, -v191, v166, 2.0
	v_fma_f32 v192, -v192, v167, 2.0
	v_mul_f32_e32 v166, v166, v191
	v_mul_f32_e32 v167, v167, v192
	v_mul_f32_e32 v184, v184, v166
	v_mul_f32_e32 v185, v185, v167
	v_mul_f32_e32 v20, v182, v20
	v_mul_f32_e32 v21, v183, v21
	v_mul_f32_e32 v22, v184, v22
	v_mul_f32_e32 v23, v185, v23
	v_cvt_pk_bf16_f32 v20, v20, v21
	v_cvt_pk_bf16_f32 v21, v22, v23
	ds_write_b64 v160, v[20:21] offset:144
	ds_read_b64 v[164:165], v160 offset:160
	s_waitcnt vmcnt(1) lgkmcnt(0)
	v_lshlrev_b32_e32 v182, 16, v164
	v_and_b32_e32 v183, 0xffff0000, v164
	v_lshlrev_b32_e32 v184, 16, v165
	v_and_b32_e32 v185, 0xffff0000, v165
	v_add_f32_e32 v24, v136, v24
	v_mul_f32_e32 v24, v152, v24
	v_add_f32_e32 v25, v137, v25
	v_mul_f32_e32 v25, v153, v25
	v_add_f32_e32 v26, v138, v26
	v_mul_f32_e32 v26, v154, v26
	v_add_f32_e32 v27, v139, v27
	v_mul_f32_e32 v27, v155, v27
	v_mul_f32_e32 v189, 0xbfb8aa3b, v182
	v_mul_f32_e32 v190, 0xbfb8aa3b, v183
	v_mul_f32_e32 v191, 0xbfb8aa3b, v184
	v_mul_f32_e32 v192, 0xbfb8aa3b, v185
	v_exp_f32_e32 v189, v189
	v_exp_f32_e32 v190, v190
	v_exp_f32_e32 v191, v191
	v_exp_f32_e32 v192, v192
	s_nop 0
	v_add_f32_e32 v189, 1.0, v189
	v_add_f32_e32 v190, 1.0, v190
	v_add_f32_e32 v191, 1.0, v191
	v_add_f32_e32 v192, 1.0, v192
	v_rcp_f32_e32 v166, v189
	v_rcp_f32_e32 v167, v190
	s_nop 0
	v_fma_f32 v189, -v189, v166, 2.0
	v_fma_f32 v190, -v190, v167, 2.0
	v_mul_f32_e32 v166, v166, v189
	v_mul_f32_e32 v167, v167, v190
	v_mul_f32_e32 v182, v182, v166
	v_mul_f32_e32 v183, v183, v167
	v_rcp_f32_e32 v166, v191
	v_rcp_f32_e32 v167, v192
	s_nop 0
	v_fma_f32 v191, -v191, v166, 2.0
	v_fma_f32 v192, -v192, v167, 2.0
	v_mul_f32_e32 v166, v166, v191
	v_mul_f32_e32 v167, v167, v192
	v_mul_f32_e32 v184, v184, v166
	v_mul_f32_e32 v185, v185, v167
	v_mul_f32_e32 v24, v182, v24
	v_mul_f32_e32 v25, v183, v25
	v_mul_f32_e32 v26, v184, v26
	v_mul_f32_e32 v27, v185, v27
	v_cvt_pk_bf16_f32 v24, v24, v25
	v_cvt_pk_bf16_f32 v25, v26, v27
	ds_write_b64 v160, v[24:25] offset:160
	ds_read_b64 v[164:165], v160 offset:176
	s_waitcnt vmcnt(0) lgkmcnt(0)
; DI bfr f2bf(float a) { return (bfr)(pack2(a, 0.f) & 0xffffu); }
; DI float bf2f(bfr u) { return __uint_as_float(((unsigned)u) << 16); }
; DI float siluf_(float x) { return x / (1.0f + __expf(-x)); }
; DI void phase_gemm_pool(const Params& p, char* smem) {
;     ...
;               [=](int row, int col, float v) {
;                 float gate = bf2f(P2[(size_t)row * 2048 + 1024 + g * 256 + col]);
;                 float z = (v + bp[col]) * sc[col] * siluf_(gate);
;                 Z[(size_t)row * 1024 + g * 256 + col] = f2bf(z);
;               });
	v_lshlrev_b32_e32 v182, 16, v164
	v_and_b32_e32 v183, 0xffff0000, v164
	v_lshlrev_b32_e32 v184, 16, v165
	v_and_b32_e32 v185, 0xffff0000, v165
	v_add_f32_e32 v28, v140, v28
	v_mul_f32_e32 v28, v156, v28
	v_add_f32_e32 v29, v141, v29
	v_mul_f32_e32 v29, v157, v29
	v_add_f32_e32 v30, v142, v30
	v_mul_f32_e32 v30, v158, v30
	v_add_f32_e32 v31, v143, v31
	v_mul_f32_e32 v31, v159, v31
	v_mul_f32_e32 v189, 0xbfb8aa3b, v182
	v_mul_f32_e32 v190, 0xbfb8aa3b, v183
	v_mul_f32_e32 v191, 0xbfb8aa3b, v184
	v_mul_f32_e32 v192, 0xbfb8aa3b, v185
	v_exp_f32_e32 v189, v189
	v_exp_f32_e32 v190, v190
	v_exp_f32_e32 v191, v191
	v_exp_f32_e32 v192, v192
	s_nop 0
	v_add_f32_e32 v189, 1.0, v189
	v_add_f32_e32 v190, 1.0, v190
	v_add_f32_e32 v191, 1.0, v191
	v_add_f32_e32 v192, 1.0, v192
	v_rcp_f32_e32 v166, v189
	v_rcp_f32_e32 v167, v190
	s_nop 0
	v_fma_f32 v189, -v189, v166, 2.0
	v_fma_f32 v190, -v190, v167, 2.0
	v_mul_f32_e32 v166, v166, v189
	v_mul_f32_e32 v167, v167, v190
	v_mul_f32_e32 v182, v182, v166
	v_mul_f32_e32 v183, v183, v167
	v_rcp_f32_e32 v166, v191
	v_rcp_f32_e32 v167, v192
	s_nop 0
	v_fma_f32 v191, -v191, v166, 2.0
	v_fma_f32 v192, -v192, v167, 2.0
	v_mul_f32_e32 v166, v166, v191
	v_mul_f32_e32 v167, v167, v192
	v_mul_f32_e32 v184, v184, v166
	v_mul_f32_e32 v185, v185, v167
	v_mul_f32_e32 v28, v182, v28
	v_mul_f32_e32 v29, v183, v29
	v_mul_f32_e32 v30, v184, v30
	v_mul_f32_e32 v31, v185, v31
	v_cvt_pk_bf16_f32 v28, v28, v29
	v_cvt_pk_bf16_f32 v29, v30, v31
	ds_write_b64 v160, v[28:29] offset:176
	global_load_dwordx4 v[128:131], v181, s[68:69] offset:384
	global_load_dwordx4 v[132:135], v181, s[68:69] offset:416
	global_load_dwordx4 v[136:139], v181, s[68:69] offset:448
	global_load_dwordx4 v[140:143], v181, s[68:69] offset:480
	global_load_dwordx4 v[144:147], v181, s[70:71] offset:384
	global_load_dwordx4 v[148:151], v181, s[70:71] offset:416
	global_load_dwordx4 v[152:155], v181, s[70:71] offset:448
	global_load_dwordx4 v[156:159], v181, s[70:71] offset:480
	ds_read_b64 v[164:165], v160 offset:192
	s_waitcnt vmcnt(3) lgkmcnt(0)
	v_lshlrev_b32_e32 v182, 16, v164
	v_and_b32_e32 v183, 0xffff0000, v164
	v_lshlrev_b32_e32 v184, 16, v165
	v_and_b32_e32 v185, 0xffff0000, v165
	v_add_f32_e32 v0, v128, v0
	v_mul_f32_e32 v0, v144, v0
	v_add_f32_e32 v1, v129, v1
	v_mul_f32_e32 v1, v145, v1
	v_add_f32_e32 v2, v130, v2
	v_mul_f32_e32 v2, v146, v2
	v_add_f32_e32 v3, v131, v3
	v_mul_f32_e32 v3, v147, v3
	v_mul_f32_e32 v189, 0xbfb8aa3b, v182
	v_mul_f32_e32 v190, 0xbfb8aa3b, v183
	v_mul_f32_e32 v191, 0xbfb8aa3b, v184
	v_mul_f32_e32 v192, 0xbfb8aa3b, v185
	v_exp_f32_e32 v189, v189
	v_exp_f32_e32 v190, v190
	v_exp_f32_e32 v191, v191
	v_exp_f32_e32 v192, v192
	s_nop 0
	v_add_f32_e32 v189, 1.0, v189
	v_add_f32_e32 v190, 1.0, v190
	v_add_f32_e32 v191, 1.0, v191
	v_add_f32_e32 v192, 1.0, v192
	v_rcp_f32_e32 v166, v189
	v_rcp_f32_e32 v167, v190
	s_nop 0
	v_fma_f32 v189, -v189, v166, 2.0
	v_fma_f32 v190, -v190, v167, 2.0
	v_mul_f32_e32 v166, v166, v189
	v_mul_f32_e32 v167, v167, v190
	v_mul_f32_e32 v182, v182, v166
	v_mul_f32_e32 v183, v183, v167
	v_rcp_f32_e32 v166, v191
	v_rcp_f32_e32 v167, v192
	s_nop 0
	v_fma_f32 v191, -v191, v166, 2.0
	v_fma_f32 v192, -v192, v167, 2.0
	v_mul_f32_e32 v166, v166, v191
	v_mul_f32_e32 v167, v167, v192
	v_mul_f32_e32 v184, v184, v166
	v_mul_f32_e32 v185, v185, v167
	v_mul_f32_e32 v0, v182, v0
	v_mul_f32_e32 v1, v183, v1
	v_mul_f32_e32 v2, v184, v2
	v_mul_f32_e32 v3, v185, v3
	v_cvt_pk_bf16_f32 v0, v0, v1
	v_cvt_pk_bf16_f32 v1, v2, v3
	ds_write_b64 v160, v[0:1] offset:192
	ds_read_b64 v[164:165], v160 offset:208
	s_waitcnt vmcnt(2) lgkmcnt(0)
	v_lshlrev_b32_e32 v182, 16, v164
	v_and_b32_e32 v183, 0xffff0000, v164
	v_lshlrev_b32_e32 v184, 16, v165
	v_and_b32_e32 v185, 0xffff0000, v165
	v_add_f32_e32 v4, v132, v4
	v_mul_f32_e32 v4, v148, v4
	v_add_f32_e32 v5, v133, v5
	v_mul_f32_e32 v5, v149, v5
	v_add_f32_e32 v6, v134, v6
	v_mul_f32_e32 v6, v150, v6
	v_add_f32_e32 v7, v135, v7
	v_mul_f32_e32 v7, v151, v7
	v_mul_f32_e32 v189, 0xbfb8aa3b, v182
	v_mul_f32_e32 v190, 0xbfb8aa3b, v183
	v_mul_f32_e32 v191, 0xbfb8aa3b, v184
	v_mul_f32_e32 v192, 0xbfb8aa3b, v185
	v_exp_f32_e32 v189, v189
	v_exp_f32_e32 v190, v190
	v_exp_f32_e32 v191, v191
	v_exp_f32_e32 v192, v192
	s_nop 0
	v_add_f32_e32 v189, 1.0, v189
	v_add_f32_e32 v190, 1.0, v190
	v_add_f32_e32 v191, 1.0, v191
	v_add_f32_e32 v192, 1.0, v192
	v_rcp_f32_e32 v166, v189
	v_rcp_f32_e32 v167, v190
	s_nop 0
	v_fma_f32 v189, -v189, v166, 2.0
	v_fma_f32 v190, -v190, v167, 2.0
	v_mul_f32_e32 v166, v166, v189
	v_mul_f32_e32 v167, v167, v190
	v_mul_f32_e32 v182, v182, v166
	v_mul_f32_e32 v183, v183, v167
	v_rcp_f32_e32 v166, v191
	v_rcp_f32_e32 v167, v192
	s_nop 0
	v_fma_f32 v191, -v191, v166, 2.0
	v_fma_f32 v192, -v192, v167, 2.0
	v_mul_f32_e32 v166, v166, v191
	v_mul_f32_e32 v167, v167, v192
	v_mul_f32_e32 v184, v184, v166
	v_mul_f32_e32 v185, v185, v167
	v_mul_f32_e32 v4, v182, v4
	v_mul_f32_e32 v5, v183, v5
	v_mul_f32_e32 v6, v184, v6
	v_mul_f32_e32 v7, v185, v7
	v_cvt_pk_bf16_f32 v4, v4, v5
	v_cvt_pk_bf16_f32 v5, v6, v7
	ds_write_b64 v160, v[4:5] offset:208
	ds_read_b64 v[164:165], v160 offset:224
	s_waitcnt vmcnt(1) lgkmcnt(0)
; DI bfr f2bf(float a) { return (bfr)(pack2(a, 0.f) & 0xffffu); }
; DI float bf2f(bfr u) { return __uint_as_float(((unsigned)u) << 16); }
; DI float siluf_(float x) { return x / (1.0f + __expf(-x)); }
; DI void phase_gemm_pool(const Params& p, char* smem) {
;     ...
;   for (int t0 = blockIdx.x; t0 < 128 * 4; t0 += gridDim.x) {
;     const int t = ((gridDim.x & 7) == 0) ? xcd_tile(t0, 4) : t0;
;     ...
;     gemm_tile<1024>(p.MIX + g * 256, p.WtPool + (size_t)g * 65536, 256, 256, mt * 128, nt * 256, smem,
;               [=](int row, int col, float v) {
;                 float gate = bf2f(P2[(size_t)row * 2048 + 1024 + g * 256 + col]);
;                 float z = (v + bp[col]) * sc[col] * siluf_(gate);
;                 Z[(size_t)row * 1024 + g * 256 + col] = f2bf(z);
;               });
	v_lshlrev_b32_e32 v182, 16, v164
	v_and_b32_e32 v183, 0xffff0000, v164
	v_lshlrev_b32_e32 v184, 16, v165
	v_and_b32_e32 v185, 0xffff0000, v165
	v_add_f32_e32 v8, v136, v8
	v_mul_f32_e32 v8, v152, v8
	v_add_f32_e32 v9, v137, v9
	v_mul_f32_e32 v9, v153, v9
	v_add_f32_e32 v10, v138, v10
	v_mul_f32_e32 v10, v154, v10
	v_add_f32_e32 v11, v139, v11
	v_mul_f32_e32 v11, v155, v11
	v_mul_f32_e32 v189, 0xbfb8aa3b, v182
	v_mul_f32_e32 v190, 0xbfb8aa3b, v183
	v_mul_f32_e32 v191, 0xbfb8aa3b, v184
	v_mul_f32_e32 v192, 0xbfb8aa3b, v185
	v_exp_f32_e32 v189, v189
	v_exp_f32_e32 v190, v190
	v_exp_f32_e32 v191, v191
	v_exp_f32_e32 v192, v192
	s_nop 0
	v_add_f32_e32 v189, 1.0, v189
	v_add_f32_e32 v190, 1.0, v190
	v_add_f32_e32 v191, 1.0, v191
	v_add_f32_e32 v192, 1.0, v192
	v_rcp_f32_e32 v166, v189
	v_rcp_f32_e32 v167, v190
	s_nop 0
	v_fma_f32 v189, -v189, v166, 2.0
	v_fma_f32 v190, -v190, v167, 2.0
	v_mul_f32_e32 v166, v166, v189
	v_mul_f32_e32 v167, v167, v190
	v_mul_f32_e32 v182, v182, v166
	v_mul_f32_e32 v183, v183, v167
	v_rcp_f32_e32 v166, v191
	v_rcp_f32_e32 v167, v192
	s_nop 0
	v_fma_f32 v191, -v191, v166, 2.0
	v_fma_f32 v192, -v192, v167, 2.0
	v_mul_f32_e32 v166, v166, v191
	v_mul_f32_e32 v167, v167, v192
	v_mul_f32_e32 v184, v184, v166
	v_mul_f32_e32 v185, v185, v167
	v_mul_f32_e32 v8, v182, v8
	v_mul_f32_e32 v9, v183, v9
	v_mul_f32_e32 v10, v184, v10
	v_mul_f32_e32 v11, v185, v11
	v_cvt_pk_bf16_f32 v8, v8, v9
	v_cvt_pk_bf16_f32 v9, v10, v11
	ds_write_b64 v160, v[8:9] offset:224
	ds_read_b64 v[164:165], v160 offset:240
	s_waitcnt vmcnt(0) lgkmcnt(0)
	v_lshlrev_b32_e32 v182, 16, v164
	v_and_b32_e32 v183, 0xffff0000, v164
	v_lshlrev_b32_e32 v184, 16, v165
	v_and_b32_e32 v185, 0xffff0000, v165
	v_add_f32_e32 v12, v140, v12
	v_mul_f32_e32 v12, v156, v12
	v_add_f32_e32 v13, v141, v13
	v_mul_f32_e32 v13, v157, v13
	v_add_f32_e32 v14, v142, v14
	v_mul_f32_e32 v14, v158, v14
	v_add_f32_e32 v15, v143, v15
	v_mul_f32_e32 v15, v159, v15
	v_mul_f32_e32 v189, 0xbfb8aa3b, v182
	v_mul_f32_e32 v190, 0xbfb8aa3b, v183
	v_mul_f32_e32 v191, 0xbfb8aa3b, v184
	v_mul_f32_e32 v192, 0xbfb8aa3b, v185
	v_exp_f32_e32 v189, v189
	v_exp_f32_e32 v190, v190
	v_exp_f32_e32 v191, v191
	v_exp_f32_e32 v192, v192
	s_nop 0
	v_add_f32_e32 v189, 1.0, v189
	v_add_f32_e32 v190, 1.0, v190
	v_add_f32_e32 v191, 1.0, v191
	v_add_f32_e32 v192, 1.0, v192
	v_rcp_f32_e32 v166, v189
	v_rcp_f32_e32 v167, v190
	s_nop 0
	v_fma_f32 v189, -v189, v166, 2.0
	v_fma_f32 v190, -v190, v167, 2.0
	v_mul_f32_e32 v166, v166, v189
	v_mul_f32_e32 v167, v167, v190
	v_mul_f32_e32 v182, v182, v166
	v_mul_f32_e32 v183, v183, v167
	v_rcp_f32_e32 v166, v191
	v_rcp_f32_e32 v167, v192
	s_nop 0
	v_fma_f32 v191, -v191, v166, 2.0
	v_fma_f32 v192, -v192, v167, 2.0
	v_mul_f32_e32 v166, v166, v191
	v_mul_f32_e32 v167, v167, v192
	v_mul_f32_e32 v184, v184, v166
	v_mul_f32_e32 v185, v185, v167
	v_mul_f32_e32 v12, v182, v12
	v_mul_f32_e32 v13, v183, v13
	v_mul_f32_e32 v14, v184, v14
	v_mul_f32_e32 v15, v185, v15
	v_cvt_pk_bf16_f32 v12, v12, v13
	v_cvt_pk_bf16_f32 v13, v14, v15
	ds_write_b64 v160, v[12:13] offset:240
	s_waitcnt lgkmcnt(0)
	ds_read_b128 v[128:131], v162
	ds_read_b128 v[132:135], v162 offset:1088
	ds_read_b128 v[136:139], v162 offset:2176
	ds_read_b128 v[140:143], v162 offset:3264
	ds_read_b128 v[144:147], v162 offset:4352
	ds_read_b128 v[148:151], v162 offset:5440
	ds_read_b128 v[152:155], v162 offset:6528
	ds_read_b128 v[156:159], v162 offset:7616
	s_add_u32 s74, s66, 0x10000
	s_addc_u32 s75, s67, 0
	s_waitcnt lgkmcnt(7)
	global_store_dwordx4 v180, v[128:131], s[74:75]  sc1
	s_add_u32 s74, s66, 0x12000
	s_addc_u32 s75, s67, 0
	s_waitcnt lgkmcnt(6)
	global_store_dwordx4 v180, v[132:135], s[74:75]  sc1
	s_add_u32 s74, s66, 0x14000
	s_addc_u32 s75, s67, 0
	s_waitcnt lgkmcnt(5)
	global_store_dwordx4 v180, v[136:139], s[74:75]  sc1
	s_add_u32 s74, s66, 0x16000
	s_addc_u32 s75, s67, 0
	s_waitcnt lgkmcnt(4)
	global_store_dwordx4 v180, v[140:143], s[74:75]  sc1
	s_add_u32 s74, s66, 0x18000
	s_addc_u32 s75, s67, 0
	s_waitcnt lgkmcnt(3)
	global_store_dwordx4 v180, v[144:147], s[74:75]  sc1
	s_add_u32 s74, s66, 0x1a000
	s_addc_u32 s75, s67, 0
	s_waitcnt lgkmcnt(2)
	global_store_dwordx4 v180, v[148:151], s[74:75]  sc1
	s_add_u32 s74, s66, 0x1c000
	s_addc_u32 s75, s67, 0
	s_waitcnt lgkmcnt(1)
	global_store_dwordx4 v180, v[152:155], s[74:75]  sc1
	s_add_u32 s74, s66, 0x1e000
	s_addc_u32 s75, s67, 0
	s_waitcnt lgkmcnt(0)
	global_store_dwordx4 v180, v[156:159], s[74:75]  sc1
	v_readlane_b32 s64, v188, 0
	v_readlane_b32 s65, v188, 1
	v_readlane_b32 s66, v188, 2
	v_readlane_b32 s67, v188, 3
	v_readlane_b32 s68, v188, 4
	v_readlane_b32 s69, v188, 5
	v_readlane_b32 s70, v188, 6
	v_readlane_b32 s71, v188, 7
	v_readlane_b32 s72, v188, 8
	v_readlane_b32 s73, v188, 9
	v_readlane_b32 s74, v188, 10
	v_readlane_b32 s75, v188, 11
	v_readlane_b32 s76, v188, 12
	v_readlane_b32 s77, v188, 13
	v_readlane_b32 s78, v188, 14
	v_readlane_b32 s79, v188, 15
	s_nop 7
	s_lshl_b32 s6, s22, 2
	s_add_u32 s4, s12, s6
	s_addc_u32 s5, s13, 0
	s_add_u32 s6, s14, s6
	s_addc_u32 s7, s15, 0
	s_lshl_b32 s10, s22, 1
	s_add_u32 s22, s16, s10
	s_addc_u32 s23, s17, 0
	s_add_i32 s37, s37, s24
	s_add_i32 s25, s25, s26
	s_cmpk_lt_i32 s37, 0x200
	s_cbranch_scc0 .LBB0_1395
	s_branch .LBB0_1377

; #define MFMA32(a, b, c) __builtin_amdgcn_mfma_f32_32x32x16_bf16((a), (b), (c), 0, 0, 0)
; #define GA_LOAD(pr_) do { _Pragma("unroll") for (int i = 0; i < 4; ++i) ra[i] = *(const u32x4*)(Ab + (i * 32) * lda + (pr_) * 64); } while (0)
; #define GB_LOAD(kt_) do { const bfr* bk_ = Bb + (kt_) * NB * 32; \
;     _Pragma("unroll") for (int i = 0; i < 4; ++i) rb[i] = *(const u32x4*)(bk_ + (i * 64) * 32); } while (0)
; #define G_STORE(kt_) do { bfr* as_ = S0 + ((kt_) & 1) * GSTAGE; bfr* bs_ = as_ + 128 * 40; \
;     if (apar == ((kt_) & 1)) { _Pragma("unroll") for (int i = 0; i < 4; ++i) *(u32x4*)(as_ + asoff + i * 32 * 40) = ra[i]; } \
;     _Pragma("unroll") for (int i = 0; i < 4; ++i) *(u32x4*)(bs_ + bsoff + i * 64 * 40) = rb[i]; } while (0)
; template <int lda>
; DI void gemm_mainloop(const bfr* __restrict__ A, const bfr* __restrict__ Bt, int NB, int K, int m0, int n0, char* smem, f32x16 (&acc)[2][4]) {
;     ...
;   for (int kt = 0; kt < nk; ++kt) {
;     if (kt + 1 < nk) G_STORE(kt + 1);
;     if (kt + 2 < nk) {
;       GB_LOAD(kt + 2);
;       if ((kt & 1) == 0) GA_LOAD((kt >> 1) + 1);
;     }
;     const bfr* As = S0 + (kt & 1) * GSTAGE;
;     const bfr* Bs = As + 128 * 40;
; #pragma unroll
;     for (int ks = 0; ks < 2; ++ks) {
;       bf16x8 af[2], bfg[4];
; #pragma unroll
;       for (int i = 0; i < 2; ++i) af[i] = *(const bf16x8*)(As + (wr * 64 + i * 32 + r) * 40 + ks * 16 + hl * 8);
; #pragma unroll
;       for (int j = 0; j < 4; ++j) bfg[j] = *(const bf16x8*)(Bs + (wc * 128 + j * 32 + r) * 40 + ks * 16 + hl * 8);
; #pragma unroll
;       for (int i = 0; i < 2; ++i)
; #pragma unroll
;         for (int j = 0; j < 4; ++j) acc[i][j] = MFMA32(af[i], bfg[j], acc[i][j]);
;     }
;     __syncthreads();
;   }
.Lp15_loop:
	s_waitcnt vmcnt(6) lgkmcnt(0)
	s_barrier
	s_mul_i32 s74, s71, 0x6000
	s_add_u32 s75, s74, 0x2000
	s_cmp_eq_u32 s71, 2
	s_cselect_b32 s75, 0x10000, s75
	v_add_u32_e32 v205, s74, v201
	v_add_u32_e32 v207, s75, v203
	v_add_u32_e32 v206, s74, v202
	v_add_u32_e32 v208, s75, v204
	s_add_u32 s71, s71, 1
	s_cmp_eq_u32 s71, 3
	s_cselect_b32 s71, 0, s71
	ds_read_b128 v[128:131], v205
	ds_read_b128 v[144:147], v207
	ds_read_b128 v[148:151], v207 offset:2048
	ds_read_b128 v[152:155], v207 offset:4096
	ds_read_b128 v[156:159], v207 offset:6144
	ds_read_b128 v[132:135], v205 offset:2048
	v_mfma_f32_32x32x16_bf16 v[112:127], v[160:163], v[136:139], v[112:127]
	s_mul_i32 s74, s70, 0x6000
	s_add_u32 s75, s74, s68
	s_mov_b32 m0, s75
	s_add_u32 s76, s74, 0x2000
	s_cmp_eq_u32 s70, 2
	s_cselect_b32 s76, 0x10000, s76
	global_load_lds_dwordx4 v192, s[64:65]
	v_mfma_f32_32x32x16_bf16 v[96:111], v[164:167], v[136:139], v[96:111]
	s_add_u32 m0, s75, 0x400
	s_add_u32 s76, s76, s69
	global_load_lds_dwordx4 v194, s[64:65]
	v_mfma_f32_32x32x16_bf16 v[80:95], v[168:171], v[136:139], v[80:95]
	s_mov_b32 m0, s76
	s_add_u32 s64, s64, 64
	s_addc_u32 s65, s65, 0
	global_load_lds_dwordx4 v200, s[66:67]
	v_mfma_f32_32x32x16_bf16 v[64:79], v[172:175], v[136:139], v[64:79]
	global_load_lds_dwordx4 v200, s[66:67] offset:1024
	v_mfma_f32_32x32x16_bf16 v[48:63], v[160:163], v[140:143], v[48:63]
	global_load_lds_dwordx4 v200, s[66:67] offset:2048
	v_mfma_f32_32x32x16_bf16 v[32:47], v[164:167], v[140:143], v[32:47]
	global_load_lds_dwordx4 v200, s[66:67] offset:3072
	s_add_u32 s66, s66, 0x10000
	s_addc_u32 s67, s67, 0
	v_mfma_f32_32x32x16_bf16 v[16:31], v[168:171], v[140:143], v[16:31]
	s_add_u32 s70, s70, 1
	s_cmp_eq_u32 s70, 3
	s_cselect_b32 s70, 0, s70
	v_mfma_f32_32x32x16_bf16 v[0:15], v[172:175], v[140:143], v[0:15]
	ds_read_b128 v[136:139], v206
	ds_read_b128 v[160:163], v208
	ds_read_b128 v[164:167], v208 offset:2048
	ds_read_b128 v[168:171], v208 offset:4096
	ds_read_b128 v[172:175], v208 offset:6144
	ds_read_b128 v[140:143], v206 offset:2048
	s_waitcnt lgkmcnt(10)
	v_mfma_f32_32x32x16_bf16 v[112:127], v[144:147], v[128:131], v[112:127]
	s_waitcnt lgkmcnt(9)
	v_mfma_f32_32x32x16_bf16 v[96:111], v[148:151], v[128:131], v[96:111]
	s_waitcnt lgkmcnt(8)
	v_mfma_f32_32x32x16_bf16 v[80:95], v[152:155], v[128:131], v[80:95]
	s_waitcnt lgkmcnt(7)
	v_mfma_f32_32x32x16_bf16 v[64:79], v[156:159], v[128:131], v[64:79]
	s_waitcnt lgkmcnt(6)
	v_mfma_f32_32x32x16_bf16 v[48:63], v[144:147], v[132:135], v[48:63]
	v_mfma_f32_32x32x16_bf16 v[32:47], v[148:151], v[132:135], v[32:47]
	v_mfma_f32_32x32x16_bf16 v[16:31], v[152:155], v[132:135], v[16:31]
	v_mfma_f32_32x32x16_bf16 v[0:15], v[156:159], v[132:135], v[0:15]
	s_add_u32 s72, s72, 1
	s_cmp_lt_u32 s72, 29
	s_cbranch_scc1 .Lp15_loop
	s_waitcnt vmcnt(6) lgkmcnt(0)
	s_barrier
	s_mul_i32 s74, s71, 0x6000
	s_add_u32 s75, s74, 0x2000
	s_cmp_eq_u32 s71, 2
	s_cselect_b32 s75, 0x10000, s75
	v_add_u32_e32 v205, s74, v201
	v_add_u32_e32 v207, s75, v203
	v_add_u32_e32 v206, s74, v202
	v_add_u32_e32 v208, s75, v204
	s_add_u32 s71, s71, 1
	s_cmp_eq_u32 s71, 3
	s_cselect_b32 s71, 0, s71
	ds_read_b128 v[128:131], v205
	ds_read_b128 v[144:147], v207
	ds_read_b128 v[148:151], v207 offset:2048
	ds_read_b128 v[152:155], v207 offset:4096
	ds_read_b128 v[156:159], v207 offset:6144
	ds_read_b128 v[132:135], v205 offset:2048
	v_mfma_f32_32x32x16_bf16 v[112:127], v[160:163], v[136:139], v[112:127]
	v_mfma_f32_32x32x16_bf16 v[96:111], v[164:167], v[136:139], v[96:111]
	v_mfma_f32_32x32x16_bf16 v[80:95], v[168:171], v[136:139], v[80:95]
	v_mfma_f32_32x32x16_bf16 v[64:79], v[172:175], v[136:139], v[64:79]
	v_mfma_f32_32x32x16_bf16 v[48:63], v[160:163], v[140:143], v[48:63]
	v_mfma_f32_32x32x16_bf16 v[32:47], v[164:167], v[140:143], v[32:47]
	v_mfma_f32_32x32x16_bf16 v[16:31], v[168:171], v[140:143], v[16:31]
	v_mfma_f32_32x32x16_bf16 v[0:15], v[172:175], v[140:143], v[0:15]
	ds_read_b128 v[136:139], v206
	ds_read_b128 v[160:163], v208
	ds_read_b128 v[164:167], v208 offset:2048
	ds_read_b128 v[168:171], v208 offset:4096
	ds_read_b128 v[172:175], v208 offset:6144
	ds_read_b128 v[140:143], v206 offset:2048
	s_waitcnt lgkmcnt(10)
	v_mfma_f32_32x32x16_bf16 v[112:127], v[144:147], v[128:131], v[112:127]
	s_waitcnt lgkmcnt(9)
	v_mfma_f32_32x32x16_bf16 v[96:111], v[148:151], v[128:131], v[96:111]
	s_waitcnt lgkmcnt(8)
	v_mfma_f32_32x32x16_bf16 v[80:95], v[152:155], v[128:131], v[80:95]
	s_waitcnt lgkmcnt(7)
	v_mfma_f32_32x32x16_bf16 v[64:79], v[156:159], v[128:131], v[64:79]
	s_waitcnt lgkmcnt(6)
	v_mfma_f32_32x32x16_bf16 v[48:63], v[144:147], v[132:135], v[48:63]
	v_mfma_f32_32x32x16_bf16 v[32:47], v[148:151], v[132:135], v[32:47]
	v_mfma_f32_32x32x16_bf16 v[16:31], v[152:155], v[132:135], v[16:31]
	v_mfma_f32_32x32x16_bf16 v[0:15], v[156:159], v[132:135], v[0:15]
	s_waitcnt vmcnt(0) lgkmcnt(0)
	s_barrier
; #define MFMA32(a, b, c) __builtin_amdgcn_mfma_f32_32x32x16_bf16((a), (b), (c), 0, 0, 0)
; DI int crow(int reg, int h) { return (reg & 3) + 8 * (reg >> 2) + 4 * h; }
; template <int lda>
; DI void gemm_mainloop(const bfr* __restrict__ A, const bfr* __restrict__ Bt, int NB, int K, int m0, int n0, char* smem, f32x16 (&acc)[2][4]) {
;     ...
; #pragma unroll
;     for (int ks = 0; ks < 2; ++ks) {
;       bf16x8 af[2], bfg[4];
; #pragma unroll
;       for (int i = 0; i < 2; ++i) af[i] = *(const bf16x8*)(As + (wr * 64 + i * 32 + r) * 40 + ks * 16 + hl * 8);
; #pragma unroll
;       for (int j = 0; j < 4; ++j) bfg[j] = *(const bf16x8*)(Bs + (wc * 128 + j * 32 + r) * 40 + ks * 16 + hl * 8);
; #pragma unroll
;       for (int i = 0; i < 2; ++i)
; #pragma unroll
;         for (int j = 0; j < 4; ++j) acc[i][j] = MFMA32(af[i], bfg[j], acc[i][j]);
;     }
;     __syncthreads();
; template <bool FIRST, bool HAS_H>
; DI void phase_gemm_resid(const Params& p, const bfr* A, const bfr* Wt, const float* gnext, float* ss, char* smem) {
;     ...
;     int tid2 = threadIdx.x;
;     asm volatile("" : "+v"(tid2));
;     const int lane = tid2 & 63, wid = tid2 >> 6, wr = wid >> 1, wc = wid & 1, r = lane & 31, hl = lane >> 5;
;     const float* xsrc = FIRST ? p.x_prompt : X;
;     const int rbase = m0 + wr * 64 + 4 * hl, cbase = n0 + wc * 128 + r;
; #pragma unroll
;     for (int i = 0; i < 2; ++i) {
; #pragma unroll
;       for (int qh = 0; qh < 2; ++qh) {
;         float rs[8];
; #pragma unroll
;         for (int q = 0; q < 8; ++q) rs[q] = 0.f;
; #pragma unroll
;         for (int jh = 0; jh < 2; ++jh) {
;           float xo[2][8];
; #pragma unroll
;           for (int jj = 0; jj < 2; ++jj)
; #pragma unroll
;             for (int q = 0; q < 8; ++q)
;               xo[jj][q] = xsrc[(rbase + i * 32 + crow(qh * 8 + q, 0)) * 1024 + cbase + (jh * 2 + jj) * 32];
	s_mul_i32 s74, s71, 0x6000
	s_add_u32 s75, s74, 0x2000
	s_cmp_eq_u32 s71, 2
	s_cselect_b32 s75, 0x10000, s75
	v_add_u32_e32 v205, s74, v201
	v_add_u32_e32 v207, s75, v203
	v_add_u32_e32 v206, s74, v202
	v_add_u32_e32 v208, s75, v204
	s_add_u32 s71, s71, 1
	s_cmp_eq_u32 s71, 3
	s_cselect_b32 s71, 0, s71
	ds_read_b128 v[128:131], v205
	ds_read_b128 v[144:147], v207
	ds_read_b128 v[148:151], v207 offset:2048
	ds_read_b128 v[152:155], v207 offset:4096
	ds_read_b128 v[156:159], v207 offset:6144
	ds_read_b128 v[132:135], v205 offset:2048
	v_mfma_f32_32x32x16_bf16 v[112:127], v[160:163], v[136:139], v[112:127]
	v_mfma_f32_32x32x16_bf16 v[96:111], v[164:167], v[136:139], v[96:111]
	v_mfma_f32_32x32x16_bf16 v[80:95], v[168:171], v[136:139], v[80:95]
	v_mfma_f32_32x32x16_bf16 v[64:79], v[172:175], v[136:139], v[64:79]
	v_mfma_f32_32x32x16_bf16 v[48:63], v[160:163], v[140:143], v[48:63]
	v_mfma_f32_32x32x16_bf16 v[32:47], v[164:167], v[140:143], v[32:47]
	v_mfma_f32_32x32x16_bf16 v[16:31], v[168:171], v[140:143], v[16:31]
	v_mfma_f32_32x32x16_bf16 v[0:15], v[172:175], v[140:143], v[0:15]
	ds_read_b128 v[136:139], v206
	ds_read_b128 v[160:163], v208
	ds_read_b128 v[164:167], v208 offset:2048
	ds_read_b128 v[168:171], v208 offset:4096
	ds_read_b128 v[172:175], v208 offset:6144
	ds_read_b128 v[140:143], v206 offset:2048
	s_waitcnt lgkmcnt(10)
	v_mfma_f32_32x32x16_bf16 v[112:127], v[144:147], v[128:131], v[112:127]
	s_waitcnt lgkmcnt(9)
	v_mfma_f32_32x32x16_bf16 v[96:111], v[148:151], v[128:131], v[96:111]
	s_waitcnt lgkmcnt(8)
	v_mfma_f32_32x32x16_bf16 v[80:95], v[152:155], v[128:131], v[80:95]
	s_waitcnt lgkmcnt(7)
	v_mfma_f32_32x32x16_bf16 v[64:79], v[156:159], v[128:131], v[64:79]
	s_waitcnt lgkmcnt(6)
	v_mfma_f32_32x32x16_bf16 v[48:63], v[144:147], v[132:135], v[48:63]
	v_mfma_f32_32x32x16_bf16 v[32:47], v[148:151], v[132:135], v[32:47]
	v_mfma_f32_32x32x16_bf16 v[16:31], v[152:155], v[132:135], v[16:31]
	v_mfma_f32_32x32x16_bf16 v[0:15], v[156:159], v[132:135], v[0:15]
	s_waitcnt lgkmcnt(0)
	v_mfma_f32_32x32x16_bf16 v[112:127], v[160:163], v[136:139], v[112:127]
	v_mfma_f32_32x32x16_bf16 v[96:111], v[164:167], v[136:139], v[96:111]
	v_mfma_f32_32x32x16_bf16 v[80:95], v[168:171], v[136:139], v[80:95]
	v_mfma_f32_32x32x16_bf16 v[64:79], v[172:175], v[136:139], v[64:79]
	v_mfma_f32_32x32x16_bf16 v[48:63], v[160:163], v[140:143], v[48:63]
	v_mfma_f32_32x32x16_bf16 v[32:47], v[164:167], v[140:143], v[32:47]
	v_mfma_f32_32x32x16_bf16 v[16:31], v[168:171], v[140:143], v[16:31]
	v_mfma_f32_32x32x16_bf16 v[0:15], v[172:175], v[140:143], v[0:15]
	s_nop 7
	s_nop 3
	s_load_dwordx2 s[64:65], s[92:93], 0x100
	s_load_dwordx2 s[66:67], s[92:93], 0x100
	s_load_dwordx2 s[68:69], s[92:93], 0x148
	s_load_dwordx2 s[70:71], s[92:93], 0x50
	s_mul_i32 s76, s73, 8704
	s_lshr_b32 s74, s73, 1
	s_lshl_b32 s74, s74, 6
	s_add_u32 s74, s74, s77
	s_and_b32 s75, s73, 1
	s_lshl_b32 s75, s75, 7
	s_add_u32 s75, s75, s78
	v_and_b32_e32 v210, 31, v196
	v_bfe_u32 v211, v196, 5, 1
	v_mul_u32_u24_e32 v216, 272, v210
	v_add_u32_e32 v216, s76, v216
	v_lshl_add_u32 v192, v211, 4, v216
	v_lshl_add_u32 v194, v211, 3, v216
	v_lshlrev_b32_e32 v216, 2, v211
	v_add_lshl_u32 v204, v216, s75, 2
	v_add_lshl_u32 v207, v210, s74, 2
	v_and_b32_e32 v216, 63, v196
	v_xor_b32_e32 v216, 32, v216
	v_lshlrev_b32_e32 v208, 2, v216
	v_bfe_u32 v210, v196, 4, 2
	v_and_b32_e32 v211, 15, v196
	v_mul_u32_u24_e32 v216, 272, v210
	v_lshl_add_u32 v216, v211, 4, v216
	v_add_u32_e32 v200, s76, v216
	v_add_u32_e32 v216, s74, v210
	v_lshlrev_b32_e32 v216, 10, v216
	v_lshl_add_u32 v216, v211, 2, v216
	v_add_lshl_u32 v202, v216, s75, 2
	s_mov_b32 s79, s74
	s_mov_b32 s72, s75
	s_waitcnt lgkmcnt(0)
	s_add_u32 s74, s64, 0x0
	s_addc_u32 s75, s65, 0
	global_load_dwordx4 v[128:131], v202, s[74:75]
	s_add_u32 s74, s64, 0x4000
	s_addc_u32 s75, s65, 0
	global_load_dwordx4 v[132:135], v202, s[74:75]
	s_add_u32 s74, s64, 0x8000
	s_addc_u32 s75, s65, 0
	global_load_dwordx4 v[136:139], v202, s[74:75]
	s_add_u32 s74, s64, 0xc000
	s_addc_u32 s75, s65, 0
	global_load_dwordx4 v[140:143], v202, s[74:75]
	s_add_u32 s74, s64, 0x10000
	s_addc_u32 s75, s65, 0
	global_load_dwordx4 v[144:147], v202, s[74:75]
	s_add_u32 s74, s64, 0x14000
	s_addc_u32 s75, s65, 0
	global_load_dwordx4 v[148:151], v202, s[74:75]
	s_add_u32 s74, s64, 0x18000
	s_addc_u32 s75, s65, 0
	global_load_dwordx4 v[152:155], v202, s[74:75]
	s_add_u32 s74, s64, 0x1c000
	s_addc_u32 s75, s65, 0
	global_load_dwordx4 v[156:159], v202, s[74:75]
	s_mov_b32 s74, s79
	s_mov_b32 s75, s72
	v_bfe_u32 v210, v196, 3, 3
	v_and_b32_e32 v211, 7, v196
	v_mul_u32_u24_e32 v216, 272, v210
	v_lshl_add_u32 v216, v211, 4, v216
	v_add_u32_e32 v201, s76, v216
	v_add_u32_e32 v216, s74, v210
	v_lshlrev_b32_e32 v216, 10, v216
	v_lshl_add_u32 v216, v211, 3, v216
	v_add_lshl_u32 v203, v216, s75, 1
	v_mov_b32_e32 v205, 0
	v_mov_b32_e32 v206, 0
	s_waitcnt lgkmcnt(0)
	s_barrier
; DI bfr f2bf(float a) { return (bfr)(pack2(a, 0.f) & 0xffffu); }
; DI int crow(int reg, int h) { return (reg & 3) + 8 * (reg >> 2) + 4 * h; }
; template <bool FIRST, bool HAS_H>
; DI void phase_gemm_resid(const Params& p, const bfr* A, const bfr* Wt, const float* gnext, float* ss, char* smem) {
;     ...
; #pragma unroll
;     for (int i = 0; i < 2; ++i) {
; #pragma unroll
;       for (int qh = 0; qh < 2; ++qh) {
;         float rs[8];
; #pragma unroll
;         for (int q = 0; q < 8; ++q) rs[q] = 0.f;
; #pragma unroll
;         for (int jh = 0; jh < 2; ++jh) {
;           float xo[2][8];
; #pragma unroll
;           for (int jj = 0; jj < 2; ++jj)
; #pragma unroll
;             for (int q = 0; q < 8; ++q)
;               xo[jj][q] = xsrc[(rbase + i * 32 + crow(qh * 8 + q, 0)) * 1024 + cbase + (jh * 2 + jj) * 32];
; #pragma unroll
;           for (int q = 0; q < 8; ++q) {
;             const int o = (rbase + i * 32 + crow(qh * 8 + q, 0)) * 1024 + cbase;
; #pragma unroll
;             for (int jj = 0; jj < 2; ++jj) {
;               const int j = jh * 2 + jj;
;               const float xn = xo[jj][q] + acc[i][j][qh * 8 + q];
;               X[o + j * 32] = xn;
;               if (HAS_H) Hn[o + j * 32] = f2bf(xn * gnext[cbase + j * 32]);
;               rs[q] += xn * xn;
;             }
;           }
;         }
	s_add_u32 s70, s70, 0x1000
	s_addc_u32 s71, s71, 0
	s_waitcnt vmcnt(7)
	ds_write_b128 v200, v[128:131]
	s_waitcnt vmcnt(6)
	ds_write_b128 v200, v[132:135] offset:1088
	s_waitcnt vmcnt(5)
	ds_write_b128 v200, v[136:139] offset:2176
	s_waitcnt vmcnt(4)
	ds_write_b128 v200, v[140:143] offset:3264
	s_waitcnt vmcnt(3)
	ds_write_b128 v200, v[144:147] offset:4352
	s_waitcnt vmcnt(2)
	ds_write_b128 v200, v[148:151] offset:5440
	s_waitcnt vmcnt(1)
	ds_write_b128 v200, v[152:155] offset:6528
	s_waitcnt vmcnt(0)
	ds_write_b128 v200, v[156:159] offset:7616
	s_add_u32 s74, s64, 0x100
	s_addc_u32 s75, s65, 0
	global_load_dwordx4 v[128:131], v202, s[74:75]
	s_add_u32 s74, s64, 0x4100
	s_addc_u32 s75, s65, 0
	global_load_dwordx4 v[132:135], v202, s[74:75]
	s_add_u32 s74, s64, 0x8100
	s_addc_u32 s75, s65, 0
	global_load_dwordx4 v[136:139], v202, s[74:75]
	s_add_u32 s74, s64, 0xc100
	s_addc_u32 s75, s65, 0
	global_load_dwordx4 v[140:143], v202, s[74:75]
	s_add_u32 s74, s64, 0x10100
	s_addc_u32 s75, s65, 0
	global_load_dwordx4 v[144:147], v202, s[74:75]
	s_add_u32 s74, s64, 0x14100
	s_addc_u32 s75, s65, 0
	global_load_dwordx4 v[148:151], v202, s[74:75]
	s_add_u32 s74, s64, 0x18100
	s_addc_u32 s75, s65, 0
	global_load_dwordx4 v[152:155], v202, s[74:75]
	s_add_u32 s74, s64, 0x1c100
	s_addc_u32 s75, s65, 0
	global_load_dwordx4 v[156:159], v202, s[74:75]
	ds_read_b128 v[160:163], v192
	ds_read_b128 v[164:167], v192 offset:32
	ds_read_b128 v[168:171], v192 offset:64
	ds_read_b128 v[172:175], v192 offset:96
	ds_read_b128 v[176:179], v192 offset:128
	ds_read_b128 v[180:183], v192 offset:160
	ds_read_b128 v[184:187], v192 offset:192
	ds_read_b128 v[188:191], v192 offset:224
	s_waitcnt lgkmcnt(7)
	v_add_f32_e32 v112, v160, v112
	v_add_f32_e32 v113, v161, v113
	v_add_f32_e32 v114, v162, v114
	v_add_f32_e32 v115, v163, v115
	v_fmac_f32_e32 v205, v112, v112
	v_fmac_f32_e32 v205, v113, v113
	v_fmac_f32_e32 v205, v114, v114
	v_fmac_f32_e32 v205, v115, v115
	ds_write_b128 v192, v[112:115]
	s_waitcnt lgkmcnt(7)
	v_add_f32_e32 v116, v164, v116
	v_add_f32_e32 v117, v165, v117
	v_add_f32_e32 v118, v166, v118
	v_add_f32_e32 v119, v167, v119
	v_fmac_f32_e32 v205, v116, v116
	v_fmac_f32_e32 v205, v117, v117
	v_fmac_f32_e32 v205, v118, v118
	v_fmac_f32_e32 v205, v119, v119
	ds_write_b128 v192, v[116:119] offset:32
	s_waitcnt lgkmcnt(7)
	v_add_f32_e32 v120, v168, v120
	v_add_f32_e32 v121, v169, v121
	v_add_f32_e32 v122, v170, v122
	v_add_f32_e32 v123, v171, v123
	v_fmac_f32_e32 v205, v120, v120
	v_fmac_f32_e32 v205, v121, v121
	v_fmac_f32_e32 v205, v122, v122
	v_fmac_f32_e32 v205, v123, v123
	ds_write_b128 v192, v[120:123] offset:64
	s_waitcnt lgkmcnt(7)
	v_add_f32_e32 v124, v172, v124
	v_add_f32_e32 v125, v173, v125
	v_add_f32_e32 v126, v174, v126
	v_add_f32_e32 v127, v175, v127
	v_fmac_f32_e32 v205, v124, v124
	v_fmac_f32_e32 v205, v125, v125
	v_fmac_f32_e32 v205, v126, v126
	v_fmac_f32_e32 v205, v127, v127
	ds_write_b128 v192, v[124:127] offset:96
	s_waitcnt lgkmcnt(7)
	v_add_f32_e32 v96, v176, v96
	v_add_f32_e32 v97, v177, v97
	v_add_f32_e32 v98, v178, v98
	v_add_f32_e32 v99, v179, v99
	v_fmac_f32_e32 v205, v96, v96
	v_fmac_f32_e32 v205, v97, v97
	v_fmac_f32_e32 v205, v98, v98
	v_fmac_f32_e32 v205, v99, v99
	ds_write_b128 v192, v[96:99] offset:128
	s_waitcnt lgkmcnt(7)
	v_add_f32_e32 v100, v180, v100
	v_add_f32_e32 v101, v181, v101
	v_add_f32_e32 v102, v182, v102
	v_add_f32_e32 v103, v183, v103
	v_fmac_f32_e32 v205, v100, v100
	v_fmac_f32_e32 v205, v101, v101
	v_fmac_f32_e32 v205, v102, v102
	v_fmac_f32_e32 v205, v103, v103
	ds_write_b128 v192, v[100:103] offset:160
	s_waitcnt lgkmcnt(7)
	v_add_f32_e32 v104, v184, v104
	v_add_f32_e32 v105, v185, v105
	v_add_f32_e32 v106, v186, v106
	v_add_f32_e32 v107, v187, v107
	v_fmac_f32_e32 v205, v104, v104
	v_fmac_f32_e32 v205, v105, v105
	v_fmac_f32_e32 v205, v106, v106
	v_fmac_f32_e32 v205, v107, v107
	ds_write_b128 v192, v[104:107] offset:192
	s_waitcnt lgkmcnt(7)
	v_add_f32_e32 v108, v188, v108
	v_add_f32_e32 v109, v189, v109
	v_add_f32_e32 v110, v190, v110
	v_add_f32_e32 v111, v191, v111
	v_fmac_f32_e32 v205, v108, v108
	v_fmac_f32_e32 v205, v109, v109
	v_fmac_f32_e32 v205, v110, v110
	v_fmac_f32_e32 v205, v111, v111
	ds_write_b128 v192, v[108:111] offset:224
	ds_read_b128 v[160:163], v200
	ds_read_b128 v[164:167], v200 offset:1088
	ds_read_b128 v[168:171], v200 offset:2176
	ds_read_b128 v[172:175], v200 offset:3264
	ds_read_b128 v[176:179], v200 offset:4352
	ds_read_b128 v[180:183], v200 offset:5440
	ds_read_b128 v[184:187], v200 offset:6528
	ds_read_b128 v[188:191], v200 offset:7616
	s_add_u32 s74, s66, 0x0
	s_addc_u32 s75, s67, 0
	s_waitcnt lgkmcnt(7)
	global_store_dwordx4 v202, v[160:163], s[74:75]  sc1
	s_add_u32 s74, s66, 0x4000
	s_addc_u32 s75, s67, 0
	s_waitcnt lgkmcnt(6)
	global_store_dwordx4 v202, v[164:167], s[74:75]  sc1
	s_add_u32 s74, s66, 0x8000
	s_addc_u32 s75, s67, 0
	s_waitcnt lgkmcnt(5)
	global_store_dwordx4 v202, v[168:171], s[74:75]  sc1
	s_add_u32 s74, s66, 0xc000
	s_addc_u32 s75, s67, 0
	s_waitcnt lgkmcnt(4)
	global_store_dwordx4 v202, v[172:175], s[74:75]  sc1
	s_add_u32 s74, s66, 0x10000
	s_addc_u32 s75, s67, 0
	s_waitcnt lgkmcnt(3)
	global_store_dwordx4 v202, v[176:179], s[74:75]  sc1
	s_add_u32 s74, s66, 0x14000
	s_addc_u32 s75, s67, 0
	s_waitcnt lgkmcnt(2)
	global_store_dwordx4 v202, v[180:183], s[74:75]  sc1
	s_add_u32 s74, s66, 0x18000
	s_addc_u32 s75, s67, 0
	s_waitcnt lgkmcnt(1)
	global_store_dwordx4 v202, v[184:187], s[74:75]  sc1
	s_add_u32 s74, s66, 0x1c000
	s_addc_u32 s75, s67, 0
	s_waitcnt lgkmcnt(0)
; DI bfr f2bf(float a) { return (bfr)(pack2(a, 0.f) & 0xffffu); }
; DI int crow(int reg, int h) { return (reg & 3) + 8 * (reg >> 2) + 4 * h; }
; template <bool FIRST, bool HAS_H>
; DI void phase_gemm_resid(const Params& p, const bfr* A, const bfr* Wt, const float* gnext, float* ss, char* smem) {
;     ...
; #pragma unroll
;     for (int i = 0; i < 2; ++i) {
; #pragma unroll
;       for (int qh = 0; qh < 2; ++qh) {
;         float rs[8];
; #pragma unroll
;         for (int q = 0; q < 8; ++q) rs[q] = 0.f;
; #pragma unroll
;         for (int jh = 0; jh < 2; ++jh) {
;           float xo[2][8];
; #pragma unroll
;           for (int jj = 0; jj < 2; ++jj)
; #pragma unroll
;             for (int q = 0; q < 8; ++q)
;               xo[jj][q] = xsrc[(rbase + i * 32 + crow(qh * 8 + q, 0)) * 1024 + cbase + (jh * 2 + jj) * 32];
; #pragma unroll
;           for (int q = 0; q < 8; ++q) {
;             const int o = (rbase + i * 32 + crow(qh * 8 + q, 0)) * 1024 + cbase;
; #pragma unroll
;             for (int jj = 0; jj < 2; ++jj) {
;               const int j = jh * 2 + jj;
;               const float xn = xo[jj][q] + acc[i][j][qh * 8 + q];
;               X[o + j * 32] = xn;
;               if (HAS_H) Hn[o + j * 32] = f2bf(xn * gnext[cbase + j * 32]);
;               rs[q] += xn * xn;
;             }
;           }
;         }
	global_store_dwordx4 v202, v[188:191], s[74:75]  sc1
	global_load_dwordx4 v[160:163], v204, s[70:71]
	global_load_dwordx4 v[164:167], v204, s[70:71] offset:32
	global_load_dwordx4 v[168:171], v204, s[70:71] offset:64
	global_load_dwordx4 v[172:175], v204, s[70:71] offset:96
	global_load_dwordx4 v[176:179], v204, s[70:71] offset:128
	global_load_dwordx4 v[180:183], v204, s[70:71] offset:160
	global_load_dwordx4 v[184:187], v204, s[70:71] offset:192
	global_load_dwordx4 v[188:191], v204, s[70:71] offset:224
	s_waitcnt vmcnt(7)
	v_mul_f32_e32 v112, v160, v112
	v_mul_f32_e32 v113, v161, v113
	v_mul_f32_e32 v114, v162, v114
	v_mul_f32_e32 v115, v163, v115
	v_cvt_pk_bf16_f32 v112, v112, v113
	v_cvt_pk_bf16_f32 v113, v114, v115
	ds_write_b64 v194, v[112:113]
	s_waitcnt vmcnt(6)
	v_mul_f32_e32 v116, v164, v116
	v_mul_f32_e32 v117, v165, v117
	v_mul_f32_e32 v118, v166, v118
	v_mul_f32_e32 v119, v167, v119
	v_cvt_pk_bf16_f32 v116, v116, v117
	v_cvt_pk_bf16_f32 v117, v118, v119
	ds_write_b64 v194, v[116:117] offset:16
	s_waitcnt vmcnt(5)
	v_mul_f32_e32 v120, v168, v120
	v_mul_f32_e32 v121, v169, v121
	v_mul_f32_e32 v122, v170, v122
	v_mul_f32_e32 v123, v171, v123
	v_cvt_pk_bf16_f32 v120, v120, v121
	v_cvt_pk_bf16_f32 v121, v122, v123
	ds_write_b64 v194, v[120:121] offset:32
	s_waitcnt vmcnt(4)
	v_mul_f32_e32 v124, v172, v124
	v_mul_f32_e32 v125, v173, v125
	v_mul_f32_e32 v126, v174, v126
	v_mul_f32_e32 v127, v175, v127
	v_cvt_pk_bf16_f32 v124, v124, v125
	v_cvt_pk_bf16_f32 v125, v126, v127
	ds_write_b64 v194, v[124:125] offset:48
	s_waitcnt vmcnt(3)
	v_mul_f32_e32 v96, v176, v96
	v_mul_f32_e32 v97, v177, v97
	v_mul_f32_e32 v98, v178, v98
	v_mul_f32_e32 v99, v179, v99
	v_cvt_pk_bf16_f32 v96, v96, v97
	v_cvt_pk_bf16_f32 v97, v98, v99
	ds_write_b64 v194, v[96:97] offset:64
	s_waitcnt vmcnt(2)
	v_mul_f32_e32 v100, v180, v100
	v_mul_f32_e32 v101, v181, v101
	v_mul_f32_e32 v102, v182, v102
	v_mul_f32_e32 v103, v183, v103
	v_cvt_pk_bf16_f32 v100, v100, v101
	v_cvt_pk_bf16_f32 v101, v102, v103
	ds_write_b64 v194, v[100:101] offset:80
	s_waitcnt vmcnt(1)
	v_mul_f32_e32 v104, v184, v104
	v_mul_f32_e32 v105, v185, v105
	v_mul_f32_e32 v106, v186, v106
	v_mul_f32_e32 v107, v187, v107
	v_cvt_pk_bf16_f32 v104, v104, v105
	v_cvt_pk_bf16_f32 v105, v106, v107
	ds_write_b64 v194, v[104:105] offset:96
	s_waitcnt vmcnt(0)
	v_mul_f32_e32 v108, v188, v108
	v_mul_f32_e32 v109, v189, v109
	v_mul_f32_e32 v110, v190, v110
	v_mul_f32_e32 v111, v191, v111
	v_cvt_pk_bf16_f32 v108, v108, v109
	v_cvt_pk_bf16_f32 v109, v110, v111
	ds_write_b64 v194, v[108:109] offset:112
	ds_read_b128 v[160:163], v201
	ds_read_b128 v[164:167], v201 offset:2176
	ds_read_b128 v[168:171], v201 offset:4352
	ds_read_b128 v[172:175], v201 offset:6528
	s_add_u32 s74, s68, 0x0
	s_addc_u32 s75, s69, 0
	s_waitcnt lgkmcnt(3)
	global_store_dwordx4 v203, v[160:163], s[74:75]  sc1
	s_add_u32 s74, s68, 0x4000
	s_addc_u32 s75, s69, 0
	s_waitcnt lgkmcnt(2)
	global_store_dwordx4 v203, v[164:167], s[74:75]  sc1
	s_add_u32 s74, s68, 0x8000
	s_addc_u32 s75, s69, 0
	s_waitcnt lgkmcnt(1)
	global_store_dwordx4 v203, v[168:171], s[74:75]  sc1
	s_add_u32 s74, s68, 0xc000
	s_addc_u32 s75, s69, 0
	s_waitcnt lgkmcnt(0)
	global_store_dwordx4 v203, v[172:175], s[74:75]  sc1
	s_waitcnt vmcnt(4)
	ds_write_b128 v200, v[128:131]
	s_waitcnt vmcnt(4)
	ds_write_b128 v200, v[132:135] offset:1088
	s_waitcnt vmcnt(4)
	ds_write_b128 v200, v[136:139] offset:2176
	s_waitcnt vmcnt(4)
	ds_write_b128 v200, v[140:143] offset:3264
	s_waitcnt vmcnt(4)
	ds_write_b128 v200, v[144:147] offset:4352
	s_waitcnt vmcnt(4)
	ds_write_b128 v200, v[148:151] offset:5440
	s_waitcnt vmcnt(4)
	ds_write_b128 v200, v[152:155] offset:6528
	s_waitcnt vmcnt(4)
	ds_write_b128 v200, v[156:159] offset:7616
	s_add_u32 s74, s64, 0x20000
	s_addc_u32 s75, s65, 0
	global_load_dwordx4 v[128:131], v202, s[74:75]
	s_add_u32 s74, s64, 0x24000
	s_addc_u32 s75, s65, 0
	global_load_dwordx4 v[132:135], v202, s[74:75]
	s_add_u32 s74, s64, 0x28000
	s_addc_u32 s75, s65, 0
	global_load_dwordx4 v[136:139], v202, s[74:75]
	s_add_u32 s74, s64, 0x2c000
	s_addc_u32 s75, s65, 0
	global_load_dwordx4 v[140:143], v202, s[74:75]
	s_add_u32 s74, s64, 0x30000
	s_addc_u32 s75, s65, 0
	global_load_dwordx4 v[144:147], v202, s[74:75]
	s_add_u32 s74, s64, 0x34000
	s_addc_u32 s75, s65, 0
	global_load_dwordx4 v[148:151], v202, s[74:75]
	s_add_u32 s74, s64, 0x38000
	s_addc_u32 s75, s65, 0
	global_load_dwordx4 v[152:155], v202, s[74:75]
	s_add_u32 s74, s64, 0x3c000
	s_addc_u32 s75, s65, 0
	global_load_dwordx4 v[156:159], v202, s[74:75]
	ds_read_b128 v[160:163], v192
	ds_read_b128 v[164:167], v192 offset:32
	ds_read_b128 v[168:171], v192 offset:64
	ds_read_b128 v[172:175], v192 offset:96
	ds_read_b128 v[176:179], v192 offset:128
	ds_read_b128 v[180:183], v192 offset:160
	ds_read_b128 v[184:187], v192 offset:192
	ds_read_b128 v[188:191], v192 offset:224
	s_waitcnt lgkmcnt(7)
	v_add_f32_e32 v80, v160, v80
	v_add_f32_e32 v81, v161, v81
	v_add_f32_e32 v82, v162, v82
	v_add_f32_e32 v83, v163, v83
	v_fmac_f32_e32 v205, v80, v80
	v_fmac_f32_e32 v205, v81, v81
	v_fmac_f32_e32 v205, v82, v82
	v_fmac_f32_e32 v205, v83, v83
	ds_write_b128 v192, v[80:83]
	s_waitcnt lgkmcnt(7)
	v_add_f32_e32 v84, v164, v84
	v_add_f32_e32 v85, v165, v85
	v_add_f32_e32 v86, v166, v86
	v_add_f32_e32 v87, v167, v87
	v_fmac_f32_e32 v205, v84, v84
	v_fmac_f32_e32 v205, v85, v85
	v_fmac_f32_e32 v205, v86, v86
	v_fmac_f32_e32 v205, v87, v87
	ds_write_b128 v192, v[84:87] offset:32
	s_waitcnt lgkmcnt(7)
; DI bfr f2bf(float a) { return (bfr)(pack2(a, 0.f) & 0xffffu); }
; DI int crow(int reg, int h) { return (reg & 3) + 8 * (reg >> 2) + 4 * h; }
; template <bool FIRST, bool HAS_H>
; DI void phase_gemm_resid(const Params& p, const bfr* A, const bfr* Wt, const float* gnext, float* ss, char* smem) {
;     ...
; #pragma unroll
;     for (int i = 0; i < 2; ++i) {
; #pragma unroll
;       for (int qh = 0; qh < 2; ++qh) {
;         float rs[8];
; #pragma unroll
;         for (int q = 0; q < 8; ++q) rs[q] = 0.f;
; #pragma unroll
;         for (int jh = 0; jh < 2; ++jh) {
;           float xo[2][8];
; #pragma unroll
;           for (int jj = 0; jj < 2; ++jj)
; #pragma unroll
;             for (int q = 0; q < 8; ++q)
;               xo[jj][q] = xsrc[(rbase + i * 32 + crow(qh * 8 + q, 0)) * 1024 + cbase + (jh * 2 + jj) * 32];
; #pragma unroll
;           for (int q = 0; q < 8; ++q) {
;             const int o = (rbase + i * 32 + crow(qh * 8 + q, 0)) * 1024 + cbase;
; #pragma unroll
;             for (int jj = 0; jj < 2; ++jj) {
;               const int j = jh * 2 + jj;
;               const float xn = xo[jj][q] + acc[i][j][qh * 8 + q];
;               X[o + j * 32] = xn;
;               if (HAS_H) Hn[o + j * 32] = f2bf(xn * gnext[cbase + j * 32]);
;               rs[q] += xn * xn;
;             }
;           }
;         }
	v_add_f32_e32 v88, v168, v88
	v_add_f32_e32 v89, v169, v89
	v_add_f32_e32 v90, v170, v90
	v_add_f32_e32 v91, v171, v91
	v_fmac_f32_e32 v205, v88, v88
	v_fmac_f32_e32 v205, v89, v89
	v_fmac_f32_e32 v205, v90, v90
	v_fmac_f32_e32 v205, v91, v91
	ds_write_b128 v192, v[88:91] offset:64
	s_waitcnt lgkmcnt(7)
	v_add_f32_e32 v92, v172, v92
	v_add_f32_e32 v93, v173, v93
	v_add_f32_e32 v94, v174, v94
	v_add_f32_e32 v95, v175, v95
	v_fmac_f32_e32 v205, v92, v92
	v_fmac_f32_e32 v205, v93, v93
	v_fmac_f32_e32 v205, v94, v94
	v_fmac_f32_e32 v205, v95, v95
	ds_write_b128 v192, v[92:95] offset:96
	s_waitcnt lgkmcnt(7)
	v_add_f32_e32 v64, v176, v64
	v_add_f32_e32 v65, v177, v65
	v_add_f32_e32 v66, v178, v66
	v_add_f32_e32 v67, v179, v67
	v_fmac_f32_e32 v205, v64, v64
	v_fmac_f32_e32 v205, v65, v65
	v_fmac_f32_e32 v205, v66, v66
	v_fmac_f32_e32 v205, v67, v67
	ds_write_b128 v192, v[64:67] offset:128
	s_waitcnt lgkmcnt(7)
	v_add_f32_e32 v68, v180, v68
	v_add_f32_e32 v69, v181, v69
	v_add_f32_e32 v70, v182, v70
	v_add_f32_e32 v71, v183, v71
	v_fmac_f32_e32 v205, v68, v68
	v_fmac_f32_e32 v205, v69, v69
	v_fmac_f32_e32 v205, v70, v70
	v_fmac_f32_e32 v205, v71, v71
	ds_write_b128 v192, v[68:71] offset:160
	s_waitcnt lgkmcnt(7)
	v_add_f32_e32 v72, v184, v72
	v_add_f32_e32 v73, v185, v73
	v_add_f32_e32 v74, v186, v74
	v_add_f32_e32 v75, v187, v75
	v_fmac_f32_e32 v205, v72, v72
	v_fmac_f32_e32 v205, v73, v73
	v_fmac_f32_e32 v205, v74, v74
	v_fmac_f32_e32 v205, v75, v75
	ds_write_b128 v192, v[72:75] offset:192
	s_waitcnt lgkmcnt(7)
	v_add_f32_e32 v76, v188, v76
	v_add_f32_e32 v77, v189, v77
	v_add_f32_e32 v78, v190, v78
	v_add_f32_e32 v79, v191, v79
	v_fmac_f32_e32 v205, v76, v76
	v_fmac_f32_e32 v205, v77, v77
	v_fmac_f32_e32 v205, v78, v78
	v_fmac_f32_e32 v205, v79, v79
	ds_write_b128 v192, v[76:79] offset:224
	ds_read_b128 v[160:163], v200
	ds_read_b128 v[164:167], v200 offset:1088
	ds_read_b128 v[168:171], v200 offset:2176
	ds_read_b128 v[172:175], v200 offset:3264
	ds_read_b128 v[176:179], v200 offset:4352
	ds_read_b128 v[180:183], v200 offset:5440
	ds_read_b128 v[184:187], v200 offset:6528
	ds_read_b128 v[188:191], v200 offset:7616
	s_add_u32 s74, s66, 0x100
	s_addc_u32 s75, s67, 0
	s_waitcnt lgkmcnt(7)
	global_store_dwordx4 v202, v[160:163], s[74:75]  sc1
	s_add_u32 s74, s66, 0x4100
	s_addc_u32 s75, s67, 0
	s_waitcnt lgkmcnt(6)
	global_store_dwordx4 v202, v[164:167], s[74:75]  sc1
	s_add_u32 s74, s66, 0x8100
	s_addc_u32 s75, s67, 0
	s_waitcnt lgkmcnt(5)
	global_store_dwordx4 v202, v[168:171], s[74:75]  sc1
	s_add_u32 s74, s66, 0xc100
	s_addc_u32 s75, s67, 0
	s_waitcnt lgkmcnt(4)
	global_store_dwordx4 v202, v[172:175], s[74:75]  sc1
	s_add_u32 s74, s66, 0x10100
	s_addc_u32 s75, s67, 0
	s_waitcnt lgkmcnt(3)
	global_store_dwordx4 v202, v[176:179], s[74:75]  sc1
	s_add_u32 s74, s66, 0x14100
	s_addc_u32 s75, s67, 0
	s_waitcnt lgkmcnt(2)
	global_store_dwordx4 v202, v[180:183], s[74:75]  sc1
	s_add_u32 s74, s66, 0x18100
	s_addc_u32 s75, s67, 0
	s_waitcnt lgkmcnt(1)
	global_store_dwordx4 v202, v[184:187], s[74:75]  sc1
	s_add_u32 s74, s66, 0x1c100
	s_addc_u32 s75, s67, 0
	s_waitcnt lgkmcnt(0)
	global_store_dwordx4 v202, v[188:191], s[74:75]  sc1
	global_load_dwordx4 v[160:163], v204, s[70:71] offset:256
	global_load_dwordx4 v[164:167], v204, s[70:71] offset:288
	global_load_dwordx4 v[168:171], v204, s[70:71] offset:320
	global_load_dwordx4 v[172:175], v204, s[70:71] offset:352
	global_load_dwordx4 v[176:179], v204, s[70:71] offset:384
	global_load_dwordx4 v[180:183], v204, s[70:71] offset:416
	global_load_dwordx4 v[184:187], v204, s[70:71] offset:448
	global_load_dwordx4 v[188:191], v204, s[70:71] offset:480
	s_waitcnt vmcnt(7)
	v_mul_f32_e32 v80, v160, v80
	v_mul_f32_e32 v81, v161, v81
	v_mul_f32_e32 v82, v162, v82
	v_mul_f32_e32 v83, v163, v83
	v_cvt_pk_bf16_f32 v80, v80, v81
	v_cvt_pk_bf16_f32 v81, v82, v83
	ds_write_b64 v194, v[80:81]
	s_waitcnt vmcnt(6)
	v_mul_f32_e32 v84, v164, v84
	v_mul_f32_e32 v85, v165, v85
	v_mul_f32_e32 v86, v166, v86
	v_mul_f32_e32 v87, v167, v87
	v_cvt_pk_bf16_f32 v84, v84, v85
	v_cvt_pk_bf16_f32 v85, v86, v87
	ds_write_b64 v194, v[84:85] offset:16
	s_waitcnt vmcnt(5)
	v_mul_f32_e32 v88, v168, v88
	v_mul_f32_e32 v89, v169, v89
	v_mul_f32_e32 v90, v170, v90
	v_mul_f32_e32 v91, v171, v91
	v_cvt_pk_bf16_f32 v88, v88, v89
	v_cvt_pk_bf16_f32 v89, v90, v91
	ds_write_b64 v194, v[88:89] offset:32
	s_waitcnt vmcnt(4)
	v_mul_f32_e32 v92, v172, v92
	v_mul_f32_e32 v93, v173, v93
	v_mul_f32_e32 v94, v174, v94
	v_mul_f32_e32 v95, v175, v95
	v_cvt_pk_bf16_f32 v92, v92, v93
	v_cvt_pk_bf16_f32 v93, v94, v95
	ds_write_b64 v194, v[92:93] offset:48
	s_waitcnt vmcnt(3)
	v_mul_f32_e32 v64, v176, v64
	v_mul_f32_e32 v65, v177, v65
	v_mul_f32_e32 v66, v178, v66
	v_mul_f32_e32 v67, v179, v67
	v_cvt_pk_bf16_f32 v64, v64, v65
	v_cvt_pk_bf16_f32 v65, v66, v67
	ds_write_b64 v194, v[64:65] offset:64
	s_waitcnt vmcnt(2)
	v_mul_f32_e32 v68, v180, v68
	v_mul_f32_e32 v69, v181, v69
	v_mul_f32_e32 v70, v182, v70
	v_mul_f32_e32 v71, v183, v71
	v_cvt_pk_bf16_f32 v68, v68, v69
	v_cvt_pk_bf16_f32 v69, v70, v71
	ds_write_b64 v194, v[68:69] offset:80
	s_waitcnt vmcnt(1)
	v_mul_f32_e32 v72, v184, v72
	v_mul_f32_e32 v73, v185, v73
	v_mul_f32_e32 v74, v186, v74
	v_mul_f32_e32 v75, v187, v75
	v_cvt_pk_bf16_f32 v72, v72, v73
	v_cvt_pk_bf16_f32 v73, v74, v75
	ds_write_b64 v194, v[72:73] offset:96
	s_waitcnt vmcnt(0)
	v_mul_f32_e32 v76, v188, v76
	v_mul_f32_e32 v77, v189, v77
	v_mul_f32_e32 v78, v190, v78
	v_mul_f32_e32 v79, v191, v79
	v_cvt_pk_bf16_f32 v76, v76, v77
	v_cvt_pk_bf16_f32 v77, v78, v79
	ds_write_b64 v194, v[76:77] offset:112
	ds_read_b128 v[160:163], v201
	ds_read_b128 v[164:167], v201 offset:2176
	ds_read_b128 v[168:171], v201 offset:4352
	ds_read_b128 v[172:175], v201 offset:6528
	s_add_u32 s74, s68, 0x80
	s_addc_u32 s75, s69, 0
	s_waitcnt lgkmcnt(3)
; DI bfr f2bf(float a) { return (bfr)(pack2(a, 0.f) & 0xffffu); }
; DI int crow(int reg, int h) { return (reg & 3) + 8 * (reg >> 2) + 4 * h; }
; template <bool FIRST, bool HAS_H>
; DI void phase_gemm_resid(const Params& p, const bfr* A, const bfr* Wt, const float* gnext, float* ss, char* smem) {
;     ...
; #pragma unroll
;     for (int i = 0; i < 2; ++i) {
; #pragma unroll
;       for (int qh = 0; qh < 2; ++qh) {
;         float rs[8];
; #pragma unroll
;         for (int q = 0; q < 8; ++q) rs[q] = 0.f;
; #pragma unroll
;         for (int jh = 0; jh < 2; ++jh) {
;           float xo[2][8];
; #pragma unroll
;           for (int jj = 0; jj < 2; ++jj)
; #pragma unroll
;             for (int q = 0; q < 8; ++q)
;               xo[jj][q] = xsrc[(rbase + i * 32 + crow(qh * 8 + q, 0)) * 1024 + cbase + (jh * 2 + jj) * 32];
; #pragma unroll
;           for (int q = 0; q < 8; ++q) {
;             const int o = (rbase + i * 32 + crow(qh * 8 + q, 0)) * 1024 + cbase;
; #pragma unroll
;             for (int jj = 0; jj < 2; ++jj) {
;               const int j = jh * 2 + jj;
;               const float xn = xo[jj][q] + acc[i][j][qh * 8 + q];
;               X[o + j * 32] = xn;
;               if (HAS_H) Hn[o + j * 32] = f2bf(xn * gnext[cbase + j * 32]);
;               rs[q] += xn * xn;
;             }
;           }
;         }
	global_store_dwordx4 v203, v[160:163], s[74:75]  sc1
	s_add_u32 s74, s68, 0x4080
	s_addc_u32 s75, s69, 0
	s_waitcnt lgkmcnt(2)
	global_store_dwordx4 v203, v[164:167], s[74:75]  sc1
	s_add_u32 s74, s68, 0x8080
	s_addc_u32 s75, s69, 0
	s_waitcnt lgkmcnt(1)
	global_store_dwordx4 v203, v[168:171], s[74:75]  sc1
	s_add_u32 s74, s68, 0xc080
	s_addc_u32 s75, s69, 0
	s_waitcnt lgkmcnt(0)
	global_store_dwordx4 v203, v[172:175], s[74:75]  sc1
	s_waitcnt vmcnt(4)
	ds_write_b128 v200, v[128:131]
	s_waitcnt vmcnt(4)
	ds_write_b128 v200, v[132:135] offset:1088
	s_waitcnt vmcnt(4)
	ds_write_b128 v200, v[136:139] offset:2176
	s_waitcnt vmcnt(4)
	ds_write_b128 v200, v[140:143] offset:3264
	s_waitcnt vmcnt(4)
	ds_write_b128 v200, v[144:147] offset:4352
	s_waitcnt vmcnt(4)
	ds_write_b128 v200, v[148:151] offset:5440
	s_waitcnt vmcnt(4)
	ds_write_b128 v200, v[152:155] offset:6528
	s_waitcnt vmcnt(4)
	ds_write_b128 v200, v[156:159] offset:7616
	s_add_u32 s74, s64, 0x20100
	s_addc_u32 s75, s65, 0
	global_load_dwordx4 v[128:131], v202, s[74:75]
	s_add_u32 s74, s64, 0x24100
	s_addc_u32 s75, s65, 0
	global_load_dwordx4 v[132:135], v202, s[74:75]
	s_add_u32 s74, s64, 0x28100
	s_addc_u32 s75, s65, 0
	global_load_dwordx4 v[136:139], v202, s[74:75]
	s_add_u32 s74, s64, 0x2c100
	s_addc_u32 s75, s65, 0
	global_load_dwordx4 v[140:143], v202, s[74:75]
	s_add_u32 s74, s64, 0x30100
	s_addc_u32 s75, s65, 0
	global_load_dwordx4 v[144:147], v202, s[74:75]
	s_add_u32 s74, s64, 0x34100
	s_addc_u32 s75, s65, 0
	global_load_dwordx4 v[148:151], v202, s[74:75]
	s_add_u32 s74, s64, 0x38100
	s_addc_u32 s75, s65, 0
	global_load_dwordx4 v[152:155], v202, s[74:75]
	s_add_u32 s74, s64, 0x3c100
	s_addc_u32 s75, s65, 0
	global_load_dwordx4 v[156:159], v202, s[74:75]
	ds_read_b128 v[160:163], v192
	ds_read_b128 v[164:167], v192 offset:32
	ds_read_b128 v[168:171], v192 offset:64
	ds_read_b128 v[172:175], v192 offset:96
	ds_read_b128 v[176:179], v192 offset:128
	ds_read_b128 v[180:183], v192 offset:160
	ds_read_b128 v[184:187], v192 offset:192
	ds_read_b128 v[188:191], v192 offset:224
	s_waitcnt lgkmcnt(7)
	v_add_f32_e32 v48, v160, v48
	v_add_f32_e32 v49, v161, v49
	v_add_f32_e32 v50, v162, v50
	v_add_f32_e32 v51, v163, v51
	v_fmac_f32_e32 v206, v48, v48
	v_fmac_f32_e32 v206, v49, v49
	v_fmac_f32_e32 v206, v50, v50
	v_fmac_f32_e32 v206, v51, v51
	ds_write_b128 v192, v[48:51]
	s_waitcnt lgkmcnt(7)
	v_add_f32_e32 v52, v164, v52
	v_add_f32_e32 v53, v165, v53
	v_add_f32_e32 v54, v166, v54
	v_add_f32_e32 v55, v167, v55
	v_fmac_f32_e32 v206, v52, v52
	v_fmac_f32_e32 v206, v53, v53
	v_fmac_f32_e32 v206, v54, v54
	v_fmac_f32_e32 v206, v55, v55
	ds_write_b128 v192, v[52:55] offset:32
	s_waitcnt lgkmcnt(7)
	v_add_f32_e32 v56, v168, v56
	v_add_f32_e32 v57, v169, v57
	v_add_f32_e32 v58, v170, v58
	v_add_f32_e32 v59, v171, v59
	v_fmac_f32_e32 v206, v56, v56
	v_fmac_f32_e32 v206, v57, v57
	v_fmac_f32_e32 v206, v58, v58
	v_fmac_f32_e32 v206, v59, v59
	ds_write_b128 v192, v[56:59] offset:64
	s_waitcnt lgkmcnt(7)
	v_add_f32_e32 v60, v172, v60
	v_add_f32_e32 v61, v173, v61
	v_add_f32_e32 v62, v174, v62
	v_add_f32_e32 v63, v175, v63
	v_fmac_f32_e32 v206, v60, v60
	v_fmac_f32_e32 v206, v61, v61
	v_fmac_f32_e32 v206, v62, v62
	v_fmac_f32_e32 v206, v63, v63
	ds_write_b128 v192, v[60:63] offset:96
	s_waitcnt lgkmcnt(7)
	v_add_f32_e32 v32, v176, v32
	v_add_f32_e32 v33, v177, v33
	v_add_f32_e32 v34, v178, v34
	v_add_f32_e32 v35, v179, v35
	v_fmac_f32_e32 v206, v32, v32
	v_fmac_f32_e32 v206, v33, v33
	v_fmac_f32_e32 v206, v34, v34
	v_fmac_f32_e32 v206, v35, v35
	ds_write_b128 v192, v[32:35] offset:128
	s_waitcnt lgkmcnt(7)
	v_add_f32_e32 v36, v180, v36
	v_add_f32_e32 v37, v181, v37
	v_add_f32_e32 v38, v182, v38
	v_add_f32_e32 v39, v183, v39
	v_fmac_f32_e32 v206, v36, v36
	v_fmac_f32_e32 v206, v37, v37
	v_fmac_f32_e32 v206, v38, v38
	v_fmac_f32_e32 v206, v39, v39
	ds_write_b128 v192, v[36:39] offset:160
	s_waitcnt lgkmcnt(7)
	v_add_f32_e32 v40, v184, v40
	v_add_f32_e32 v41, v185, v41
	v_add_f32_e32 v42, v186, v42
	v_add_f32_e32 v43, v187, v43
	v_fmac_f32_e32 v206, v40, v40
	v_fmac_f32_e32 v206, v41, v41
	v_fmac_f32_e32 v206, v42, v42
	v_fmac_f32_e32 v206, v43, v43
	ds_write_b128 v192, v[40:43] offset:192
	s_waitcnt lgkmcnt(7)
	v_add_f32_e32 v44, v188, v44
	v_add_f32_e32 v45, v189, v45
	v_add_f32_e32 v46, v190, v46
	v_add_f32_e32 v47, v191, v47
	v_fmac_f32_e32 v206, v44, v44
	v_fmac_f32_e32 v206, v45, v45
	v_fmac_f32_e32 v206, v46, v46
	v_fmac_f32_e32 v206, v47, v47
	ds_write_b128 v192, v[44:47] offset:224
	ds_read_b128 v[160:163], v200
	ds_read_b128 v[164:167], v200 offset:1088
	ds_read_b128 v[168:171], v200 offset:2176
	ds_read_b128 v[172:175], v200 offset:3264
	ds_read_b128 v[176:179], v200 offset:4352
	ds_read_b128 v[180:183], v200 offset:5440
	ds_read_b128 v[184:187], v200 offset:6528
	ds_read_b128 v[188:191], v200 offset:7616
	s_add_u32 s74, s66, 0x20000
	s_addc_u32 s75, s67, 0
	s_waitcnt lgkmcnt(7)
	global_store_dwordx4 v202, v[160:163], s[74:75]  sc1
	s_add_u32 s74, s66, 0x24000
	s_addc_u32 s75, s67, 0
	s_waitcnt lgkmcnt(6)
	global_store_dwordx4 v202, v[164:167], s[74:75]  sc1
	s_add_u32 s74, s66, 0x28000
	s_addc_u32 s75, s67, 0
	s_waitcnt lgkmcnt(5)
	global_store_dwordx4 v202, v[168:171], s[74:75]  sc1
	s_add_u32 s74, s66, 0x2c000
	s_addc_u32 s75, s67, 0
	s_waitcnt lgkmcnt(4)
	global_store_dwordx4 v202, v[172:175], s[74:75]  sc1
	s_add_u32 s74, s66, 0x30000
	s_addc_u32 s75, s67, 0
	s_waitcnt lgkmcnt(3)
	global_store_dwordx4 v202, v[176:179], s[74:75]  sc1
	s_add_u32 s74, s66, 0x34000
	s_addc_u32 s75, s67, 0
	s_waitcnt lgkmcnt(2)
	global_store_dwordx4 v202, v[180:183], s[74:75]  sc1
	s_add_u32 s74, s66, 0x38000
	s_addc_u32 s75, s67, 0
	s_waitcnt lgkmcnt(1)
; DI bfr f2bf(float a) { return (bfr)(pack2(a, 0.f) & 0xffffu); }
; DI int crow(int reg, int h) { return (reg & 3) + 8 * (reg >> 2) + 4 * h; }
; template <bool FIRST, bool HAS_H>
; DI void phase_gemm_resid(const Params& p, const bfr* A, const bfr* Wt, const float* gnext, float* ss, char* smem) {
;     ...
; #pragma unroll
;     for (int i = 0; i < 2; ++i) {
; #pragma unroll
;       for (int qh = 0; qh < 2; ++qh) {
;         float rs[8];
; #pragma unroll
;         for (int q = 0; q < 8; ++q) rs[q] = 0.f;
; #pragma unroll
;         for (int jh = 0; jh < 2; ++jh) {
;           float xo[2][8];
; #pragma unroll
;           for (int jj = 0; jj < 2; ++jj)
; #pragma unroll
;             for (int q = 0; q < 8; ++q)
;               xo[jj][q] = xsrc[(rbase + i * 32 + crow(qh * 8 + q, 0)) * 1024 + cbase + (jh * 2 + jj) * 32];
; #pragma unroll
;           for (int q = 0; q < 8; ++q) {
;             const int o = (rbase + i * 32 + crow(qh * 8 + q, 0)) * 1024 + cbase;
; #pragma unroll
;             for (int jj = 0; jj < 2; ++jj) {
;               const int j = jh * 2 + jj;
;               const float xn = xo[jj][q] + acc[i][j][qh * 8 + q];
;               X[o + j * 32] = xn;
;               if (HAS_H) Hn[o + j * 32] = f2bf(xn * gnext[cbase + j * 32]);
;               rs[q] += xn * xn;
;             }
;           }
;         }
	global_store_dwordx4 v202, v[184:187], s[74:75]  sc1
	s_add_u32 s74, s66, 0x3c000
	s_addc_u32 s75, s67, 0
	s_waitcnt lgkmcnt(0)
	global_store_dwordx4 v202, v[188:191], s[74:75]  sc1
	global_load_dwordx4 v[160:163], v204, s[70:71]
	global_load_dwordx4 v[164:167], v204, s[70:71] offset:32
	global_load_dwordx4 v[168:171], v204, s[70:71] offset:64
	global_load_dwordx4 v[172:175], v204, s[70:71] offset:96
	global_load_dwordx4 v[176:179], v204, s[70:71] offset:128
	global_load_dwordx4 v[180:183], v204, s[70:71] offset:160
	global_load_dwordx4 v[184:187], v204, s[70:71] offset:192
	global_load_dwordx4 v[188:191], v204, s[70:71] offset:224
	s_waitcnt vmcnt(7)
	v_mul_f32_e32 v48, v160, v48
	v_mul_f32_e32 v49, v161, v49
	v_mul_f32_e32 v50, v162, v50
	v_mul_f32_e32 v51, v163, v51
	v_cvt_pk_bf16_f32 v48, v48, v49
	v_cvt_pk_bf16_f32 v49, v50, v51
	ds_write_b64 v194, v[48:49]
	s_waitcnt vmcnt(6)
	v_mul_f32_e32 v52, v164, v52
	v_mul_f32_e32 v53, v165, v53
	v_mul_f32_e32 v54, v166, v54
	v_mul_f32_e32 v55, v167, v55
	v_cvt_pk_bf16_f32 v52, v52, v53
	v_cvt_pk_bf16_f32 v53, v54, v55
	ds_write_b64 v194, v[52:53] offset:16
	s_waitcnt vmcnt(5)
	v_mul_f32_e32 v56, v168, v56
	v_mul_f32_e32 v57, v169, v57
	v_mul_f32_e32 v58, v170, v58
	v_mul_f32_e32 v59, v171, v59
	v_cvt_pk_bf16_f32 v56, v56, v57
	v_cvt_pk_bf16_f32 v57, v58, v59
	ds_write_b64 v194, v[56:57] offset:32
	s_waitcnt vmcnt(4)
	v_mul_f32_e32 v60, v172, v60
	v_mul_f32_e32 v61, v173, v61
	v_mul_f32_e32 v62, v174, v62
	v_mul_f32_e32 v63, v175, v63
	v_cvt_pk_bf16_f32 v60, v60, v61
	v_cvt_pk_bf16_f32 v61, v62, v63
	ds_write_b64 v194, v[60:61] offset:48
	s_waitcnt vmcnt(3)
	v_mul_f32_e32 v32, v176, v32
	v_mul_f32_e32 v33, v177, v33
	v_mul_f32_e32 v34, v178, v34
	v_mul_f32_e32 v35, v179, v35
	v_cvt_pk_bf16_f32 v32, v32, v33
	v_cvt_pk_bf16_f32 v33, v34, v35
	ds_write_b64 v194, v[32:33] offset:64
	s_waitcnt vmcnt(2)
	v_mul_f32_e32 v36, v180, v36
	v_mul_f32_e32 v37, v181, v37
	v_mul_f32_e32 v38, v182, v38
	v_mul_f32_e32 v39, v183, v39
	v_cvt_pk_bf16_f32 v36, v36, v37
	v_cvt_pk_bf16_f32 v37, v38, v39
	ds_write_b64 v194, v[36:37] offset:80
	s_waitcnt vmcnt(1)
	v_mul_f32_e32 v40, v184, v40
	v_mul_f32_e32 v41, v185, v41
	v_mul_f32_e32 v42, v186, v42
	v_mul_f32_e32 v43, v187, v43
	v_cvt_pk_bf16_f32 v40, v40, v41
	v_cvt_pk_bf16_f32 v41, v42, v43
	ds_write_b64 v194, v[40:41] offset:96
	s_waitcnt vmcnt(0)
	v_mul_f32_e32 v44, v188, v44
	v_mul_f32_e32 v45, v189, v45
	v_mul_f32_e32 v46, v190, v46
	v_mul_f32_e32 v47, v191, v47
	v_cvt_pk_bf16_f32 v44, v44, v45
	v_cvt_pk_bf16_f32 v45, v46, v47
	ds_write_b64 v194, v[44:45] offset:112
	ds_read_b128 v[160:163], v201
	ds_read_b128 v[164:167], v201 offset:2176
	ds_read_b128 v[168:171], v201 offset:4352
	ds_read_b128 v[172:175], v201 offset:6528
	s_add_u32 s74, s68, 0x10000
	s_addc_u32 s75, s69, 0
	s_waitcnt lgkmcnt(3)
	global_store_dwordx4 v203, v[160:163], s[74:75]  sc1
	s_add_u32 s74, s68, 0x14000
	s_addc_u32 s75, s69, 0
	s_waitcnt lgkmcnt(2)
	global_store_dwordx4 v203, v[164:167], s[74:75]  sc1
	s_add_u32 s74, s68, 0x18000
	s_addc_u32 s75, s69, 0
	s_waitcnt lgkmcnt(1)
	global_store_dwordx4 v203, v[168:171], s[74:75]  sc1
	s_add_u32 s74, s68, 0x1c000
	s_addc_u32 s75, s69, 0
	s_waitcnt lgkmcnt(0)
	global_store_dwordx4 v203, v[172:175], s[74:75]  sc1
	s_waitcnt vmcnt(4)
	ds_write_b128 v200, v[128:131]
	s_waitcnt vmcnt(4)
	ds_write_b128 v200, v[132:135] offset:1088
	s_waitcnt vmcnt(4)
	ds_write_b128 v200, v[136:139] offset:2176
	s_waitcnt vmcnt(4)
	ds_write_b128 v200, v[140:143] offset:3264
	s_waitcnt vmcnt(4)
	ds_write_b128 v200, v[144:147] offset:4352
	s_waitcnt vmcnt(4)
	ds_write_b128 v200, v[148:151] offset:5440
	s_waitcnt vmcnt(4)
	ds_write_b128 v200, v[152:155] offset:6528
	s_waitcnt vmcnt(4)
	ds_write_b128 v200, v[156:159] offset:7616
	ds_read_b128 v[160:163], v192
	ds_read_b128 v[164:167], v192 offset:32
	ds_read_b128 v[168:171], v192 offset:64
	ds_read_b128 v[172:175], v192 offset:96
	ds_read_b128 v[176:179], v192 offset:128
	ds_read_b128 v[180:183], v192 offset:160
	ds_read_b128 v[184:187], v192 offset:192
	ds_read_b128 v[188:191], v192 offset:224
	s_waitcnt lgkmcnt(7)
	v_add_f32_e32 v16, v160, v16
	v_add_f32_e32 v17, v161, v17
	v_add_f32_e32 v18, v162, v18
	v_add_f32_e32 v19, v163, v19
	v_fmac_f32_e32 v206, v16, v16
	v_fmac_f32_e32 v206, v17, v17
	v_fmac_f32_e32 v206, v18, v18
	v_fmac_f32_e32 v206, v19, v19
	ds_write_b128 v192, v[16:19]
	s_waitcnt lgkmcnt(7)
	v_add_f32_e32 v20, v164, v20
	v_add_f32_e32 v21, v165, v21
	v_add_f32_e32 v22, v166, v22
	v_add_f32_e32 v23, v167, v23
	v_fmac_f32_e32 v206, v20, v20
	v_fmac_f32_e32 v206, v21, v21
	v_fmac_f32_e32 v206, v22, v22
	v_fmac_f32_e32 v206, v23, v23
	ds_write_b128 v192, v[20:23] offset:32
	s_waitcnt lgkmcnt(7)
	v_add_f32_e32 v24, v168, v24
	v_add_f32_e32 v25, v169, v25
	v_add_f32_e32 v26, v170, v26
	v_add_f32_e32 v27, v171, v27
	v_fmac_f32_e32 v206, v24, v24
	v_fmac_f32_e32 v206, v25, v25
	v_fmac_f32_e32 v206, v26, v26
	v_fmac_f32_e32 v206, v27, v27
	ds_write_b128 v192, v[24:27] offset:64
	s_waitcnt lgkmcnt(7)
	v_add_f32_e32 v28, v172, v28
	v_add_f32_e32 v29, v173, v29
	v_add_f32_e32 v30, v174, v30
	v_add_f32_e32 v31, v175, v31
	v_fmac_f32_e32 v206, v28, v28
	v_fmac_f32_e32 v206, v29, v29
	v_fmac_f32_e32 v206, v30, v30
	v_fmac_f32_e32 v206, v31, v31
	ds_write_b128 v192, v[28:31] offset:96
	s_waitcnt lgkmcnt(7)
	v_add_f32_e32 v0, v176, v0
	v_add_f32_e32 v1, v177, v1
	v_add_f32_e32 v2, v178, v2
	v_add_f32_e32 v3, v179, v3
	v_fmac_f32_e32 v206, v0, v0
	v_fmac_f32_e32 v206, v1, v1
	v_fmac_f32_e32 v206, v2, v2
	v_fmac_f32_e32 v206, v3, v3
	ds_write_b128 v192, v[0:3] offset:128
	s_waitcnt lgkmcnt(7)
; DI bfr f2bf(float a) { return (bfr)(pack2(a, 0.f) & 0xffffu); }
; DI int crow(int reg, int h) { return (reg & 3) + 8 * (reg >> 2) + 4 * h; }
; template <bool FIRST, bool HAS_H>
; DI void phase_gemm_resid(const Params& p, const bfr* A, const bfr* Wt, const float* gnext, float* ss, char* smem) {
;     ...
; #pragma unroll
;     for (int i = 0; i < 2; ++i) {
; #pragma unroll
;       for (int qh = 0; qh < 2; ++qh) {
;         float rs[8];
; #pragma unroll
;         for (int q = 0; q < 8; ++q) rs[q] = 0.f;
; #pragma unroll
;         for (int jh = 0; jh < 2; ++jh) {
;           float xo[2][8];
; #pragma unroll
;           for (int jj = 0; jj < 2; ++jj)
; #pragma unroll
;             for (int q = 0; q < 8; ++q)
;               xo[jj][q] = xsrc[(rbase + i * 32 + crow(qh * 8 + q, 0)) * 1024 + cbase + (jh * 2 + jj) * 32];
; #pragma unroll
;           for (int q = 0; q < 8; ++q) {
;             const int o = (rbase + i * 32 + crow(qh * 8 + q, 0)) * 1024 + cbase;
; #pragma unroll
;             for (int jj = 0; jj < 2; ++jj) {
;               const int j = jh * 2 + jj;
;               const float xn = xo[jj][q] + acc[i][j][qh * 8 + q];
;               X[o + j * 32] = xn;
;               if (HAS_H) Hn[o + j * 32] = f2bf(xn * gnext[cbase + j * 32]);
;               rs[q] += xn * xn;
;             }
;           }
;         }
; #pragma unroll
;         for (int q = 0; q < 8; ++q) rs[q] = half32_sum_hi(rs[q]);
;         if (r == 31) {
; #pragma unroll
;           for (int q = 0; q < 8; ++q) unsafeAtomicAdd(ss + rbase + i * 32 + crow(qh * 8 + q, 0), rs[q]);
;         }
	v_add_f32_e32 v4, v180, v4
	v_add_f32_e32 v5, v181, v5
	v_add_f32_e32 v6, v182, v6
	v_add_f32_e32 v7, v183, v7
	v_fmac_f32_e32 v206, v4, v4
	v_fmac_f32_e32 v206, v5, v5
	v_fmac_f32_e32 v206, v6, v6
	v_fmac_f32_e32 v206, v7, v7
	ds_write_b128 v192, v[4:7] offset:160
	s_waitcnt lgkmcnt(7)
	v_add_f32_e32 v8, v184, v8
	v_add_f32_e32 v9, v185, v9
	v_add_f32_e32 v10, v186, v10
	v_add_f32_e32 v11, v187, v11
	v_fmac_f32_e32 v206, v8, v8
	v_fmac_f32_e32 v206, v9, v9
	v_fmac_f32_e32 v206, v10, v10
	v_fmac_f32_e32 v206, v11, v11
	ds_write_b128 v192, v[8:11] offset:192
	s_waitcnt lgkmcnt(7)
	v_add_f32_e32 v12, v188, v12
	v_add_f32_e32 v13, v189, v13
	v_add_f32_e32 v14, v190, v14
	v_add_f32_e32 v15, v191, v15
	v_fmac_f32_e32 v206, v12, v12
	v_fmac_f32_e32 v206, v13, v13
	v_fmac_f32_e32 v206, v14, v14
	v_fmac_f32_e32 v206, v15, v15
	ds_write_b128 v192, v[12:15] offset:224
	ds_read_b128 v[160:163], v200
	ds_read_b128 v[164:167], v200 offset:1088
	ds_read_b128 v[168:171], v200 offset:2176
	ds_read_b128 v[172:175], v200 offset:3264
	ds_read_b128 v[176:179], v200 offset:4352
	ds_read_b128 v[180:183], v200 offset:5440
	ds_read_b128 v[184:187], v200 offset:6528
	ds_read_b128 v[188:191], v200 offset:7616
	s_add_u32 s74, s66, 0x20100
	s_addc_u32 s75, s67, 0
	s_waitcnt lgkmcnt(7)
	global_store_dwordx4 v202, v[160:163], s[74:75]  sc1
	s_add_u32 s74, s66, 0x24100
	s_addc_u32 s75, s67, 0
	s_waitcnt lgkmcnt(6)
	global_store_dwordx4 v202, v[164:167], s[74:75]  sc1
	s_add_u32 s74, s66, 0x28100
	s_addc_u32 s75, s67, 0
	s_waitcnt lgkmcnt(5)
	global_store_dwordx4 v202, v[168:171], s[74:75]  sc1
	s_add_u32 s74, s66, 0x2c100
	s_addc_u32 s75, s67, 0
	s_waitcnt lgkmcnt(4)
	global_store_dwordx4 v202, v[172:175], s[74:75]  sc1
	s_add_u32 s74, s66, 0x30100
	s_addc_u32 s75, s67, 0
	s_waitcnt lgkmcnt(3)
	global_store_dwordx4 v202, v[176:179], s[74:75]  sc1
	s_add_u32 s74, s66, 0x34100
	s_addc_u32 s75, s67, 0
	s_waitcnt lgkmcnt(2)
	global_store_dwordx4 v202, v[180:183], s[74:75]  sc1
	s_add_u32 s74, s66, 0x38100
	s_addc_u32 s75, s67, 0
	s_waitcnt lgkmcnt(1)
	global_store_dwordx4 v202, v[184:187], s[74:75]  sc1
	s_add_u32 s74, s66, 0x3c100
	s_addc_u32 s75, s67, 0
	s_waitcnt lgkmcnt(0)
	global_store_dwordx4 v202, v[188:191], s[74:75]  sc1
	global_load_dwordx4 v[160:163], v204, s[70:71] offset:256
	global_load_dwordx4 v[164:167], v204, s[70:71] offset:288
	global_load_dwordx4 v[168:171], v204, s[70:71] offset:320
	global_load_dwordx4 v[172:175], v204, s[70:71] offset:352
	global_load_dwordx4 v[176:179], v204, s[70:71] offset:384
	global_load_dwordx4 v[180:183], v204, s[70:71] offset:416
	global_load_dwordx4 v[184:187], v204, s[70:71] offset:448
	global_load_dwordx4 v[188:191], v204, s[70:71] offset:480
	s_waitcnt vmcnt(7)
	v_mul_f32_e32 v16, v160, v16
	v_mul_f32_e32 v17, v161, v17
	v_mul_f32_e32 v18, v162, v18
	v_mul_f32_e32 v19, v163, v19
	v_cvt_pk_bf16_f32 v16, v16, v17
	v_cvt_pk_bf16_f32 v17, v18, v19
	ds_write_b64 v194, v[16:17]
	s_waitcnt vmcnt(6)
	v_mul_f32_e32 v20, v164, v20
	v_mul_f32_e32 v21, v165, v21
	v_mul_f32_e32 v22, v166, v22
	v_mul_f32_e32 v23, v167, v23
	v_cvt_pk_bf16_f32 v20, v20, v21
	v_cvt_pk_bf16_f32 v21, v22, v23
	ds_write_b64 v194, v[20:21] offset:16
	s_waitcnt vmcnt(5)
	v_mul_f32_e32 v24, v168, v24
	v_mul_f32_e32 v25, v169, v25
	v_mul_f32_e32 v26, v170, v26
	v_mul_f32_e32 v27, v171, v27
	v_cvt_pk_bf16_f32 v24, v24, v25
	v_cvt_pk_bf16_f32 v25, v26, v27
	ds_write_b64 v194, v[24:25] offset:32
	s_waitcnt vmcnt(4)
	v_mul_f32_e32 v28, v172, v28
	v_mul_f32_e32 v29, v173, v29
	v_mul_f32_e32 v30, v174, v30
	v_mul_f32_e32 v31, v175, v31
	v_cvt_pk_bf16_f32 v28, v28, v29
	v_cvt_pk_bf16_f32 v29, v30, v31
	ds_write_b64 v194, v[28:29] offset:48
	s_waitcnt vmcnt(3)
	v_mul_f32_e32 v0, v176, v0
	v_mul_f32_e32 v1, v177, v1
	v_mul_f32_e32 v2, v178, v2
	v_mul_f32_e32 v3, v179, v3
	v_cvt_pk_bf16_f32 v0, v0, v1
	v_cvt_pk_bf16_f32 v1, v2, v3
	ds_write_b64 v194, v[0:1] offset:64
	s_waitcnt vmcnt(2)
	v_mul_f32_e32 v4, v180, v4
	v_mul_f32_e32 v5, v181, v5
	v_mul_f32_e32 v6, v182, v6
	v_mul_f32_e32 v7, v183, v7
	v_cvt_pk_bf16_f32 v4, v4, v5
	v_cvt_pk_bf16_f32 v5, v6, v7
	ds_write_b64 v194, v[4:5] offset:80
	s_waitcnt vmcnt(1)
	v_mul_f32_e32 v8, v184, v8
	v_mul_f32_e32 v9, v185, v9
	v_mul_f32_e32 v10, v186, v10
	v_mul_f32_e32 v11, v187, v11
	v_cvt_pk_bf16_f32 v8, v8, v9
	v_cvt_pk_bf16_f32 v9, v10, v11
	ds_write_b64 v194, v[8:9] offset:96
	s_waitcnt vmcnt(0)
	v_mul_f32_e32 v12, v188, v12
	v_mul_f32_e32 v13, v189, v13
	v_mul_f32_e32 v14, v190, v14
	v_mul_f32_e32 v15, v191, v15
	v_cvt_pk_bf16_f32 v12, v12, v13
	v_cvt_pk_bf16_f32 v13, v14, v15
	ds_write_b64 v194, v[12:13] offset:112
	ds_read_b128 v[160:163], v201
	ds_read_b128 v[164:167], v201 offset:2176
	ds_read_b128 v[168:171], v201 offset:4352
	ds_read_b128 v[172:175], v201 offset:6528
	s_add_u32 s74, s68, 0x10080
	s_addc_u32 s75, s69, 0
	s_waitcnt lgkmcnt(3)
	global_store_dwordx4 v203, v[160:163], s[74:75]  sc1
	s_add_u32 s74, s68, 0x14080
	s_addc_u32 s75, s69, 0
	s_waitcnt lgkmcnt(2)
	global_store_dwordx4 v203, v[164:167], s[74:75]  sc1
	s_add_u32 s74, s68, 0x18080
	s_addc_u32 s75, s69, 0
	s_waitcnt lgkmcnt(1)
	global_store_dwordx4 v203, v[168:171], s[74:75]  sc1
	s_add_u32 s74, s68, 0x1c080
	s_addc_u32 s75, s69, 0
	s_waitcnt lgkmcnt(0)
	global_store_dwordx4 v203, v[172:175], s[74:75]  sc1
	s_load_dwordx2 s[64:65], s[92:93], 0x140
	ds_bpermute_b32 v210, v208, v205
	ds_bpermute_b32 v211, v208, v206
	s_waitcnt lgkmcnt(0)
	s_add_u32 s64, s64, 0x20400
	s_addc_u32 s65, s65, 0
	v_add_f32_e32 v210, v210, v205
	v_add_f32_e32 v211, v211, v206
	s_mov_b32 exec_hi, 0
	s_nop 1
	global_atomic_add_f32 v207, v210, s[64:65]
	global_atomic_add_f32 v207, v211, s[64:65] offset:128
	s_mov_b64 exec, -1
	v_readlane_b32 s64, v209, 0
	v_readlane_b32 s65, v209, 1
	v_readlane_b32 s66, v209, 2
	v_readlane_b32 s67, v209, 3
	v_readlane_b32 s68, v209, 4
	v_readlane_b32 s69, v209, 5
	v_readlane_b32 s70, v209, 6
	v_readlane_b32 s71, v209, 7
	v_readlane_b32 s72, v209, 8
	v_readlane_b32 s73, v209, 9
	v_readlane_b32 s74, v209, 10
	v_readlane_b32 s75, v209, 11
	v_readlane_b32 s76, v209, 12
	v_readlane_b32 s77, v209, 13
	v_readlane_b32 s78, v209, 14
	v_readlane_b32 s79, v209, 15
	s_nop 7
	s_branch .LBB0_1463

; #define MFMA32(a, b, c) __builtin_amdgcn_mfma_f32_32x32x16_bf16((a), (b), (c), 0, 0, 0)
; #define GA_LOAD(pr_) do { _Pragma("unroll") for (int i = 0; i < 4; ++i) ra[i] = *(const u32x4*)(Ab + (i * 32) * lda + (pr_) * 64); } while (0)
; #define GB_LOAD(kt_) do { const bfr* bk_ = Bb + (kt_) * NB * 32; \
;     _Pragma("unroll") for (int i = 0; i < 4; ++i) rb[i] = *(const u32x4*)(bk_ + (i * 64) * 32); } while (0)
; #define G_STORE(kt_) do { bfr* as_ = S0 + ((kt_) & 1) * GSTAGE; bfr* bs_ = as_ + 128 * 40; \
;     if (apar == ((kt_) & 1)) { _Pragma("unroll") for (int i = 0; i < 4; ++i) *(u32x4*)(as_ + asoff + i * 32 * 40) = ra[i]; } \
;     _Pragma("unroll") for (int i = 0; i < 4; ++i) *(u32x4*)(bs_ + bsoff + i * 64 * 40) = rb[i]; } while (0)
; template <int lda>
; DI void gemm_mainloop(const bfr* __restrict__ A, const bfr* __restrict__ Bt, int NB, int K, int m0, int n0, char* smem, f32x16 (&acc)[2][4]) {
;     ...
;   for (int kt = 0; kt < nk; ++kt) {
;     if (kt + 1 < nk) G_STORE(kt + 1);
;     if (kt + 2 < nk) {
;       GB_LOAD(kt + 2);
;       if ((kt & 1) == 0) GA_LOAD((kt >> 1) + 1);
;     }
;     const bfr* As = S0 + (kt & 1) * GSTAGE;
;     const bfr* Bs = As + 128 * 40;
; #pragma unroll
;     for (int ks = 0; ks < 2; ++ks) {
;       bf16x8 af[2], bfg[4];
; #pragma unroll
;       for (int i = 0; i < 2; ++i) af[i] = *(const bf16x8*)(As + (wr * 64 + i * 32 + r) * 40 + ks * 16 + hl * 8);
; #pragma unroll
;       for (int j = 0; j < 4; ++j) bfg[j] = *(const bf16x8*)(Bs + (wc * 128 + j * 32 + r) * 40 + ks * 16 + hl * 8);
; #pragma unroll
;       for (int i = 0; i < 2; ++i)
; #pragma unroll
;         for (int j = 0; j < 4; ++j) acc[i][j] = MFMA32(af[i], bfg[j], acc[i][j]);
;     }
;     __syncthreads();
;   }
.Lp17_loop:
	s_waitcnt vmcnt(6) lgkmcnt(0)
	s_barrier
	s_mul_i32 s74, s71, 0x6000
	s_add_u32 s75, s74, 0x2000
	s_cmp_eq_u32 s71, 2
	s_cselect_b32 s75, 0x10000, s75
	v_add_u32_e32 v183, s74, v179
	v_add_u32_e32 v185, s75, v181
	v_add_u32_e32 v184, s74, v180
	v_add_u32_e32 v186, s75, v182
	s_add_u32 s71, s71, 1
	s_cmp_eq_u32 s71, 3
	s_cselect_b32 s71, 0, s71
	ds_read_b128 v[128:131], v183
	ds_read_b128 v[144:147], v185
	ds_read_b128 v[148:151], v185 offset:2048
	ds_read_b128 v[152:155], v185 offset:4096
	ds_read_b128 v[156:159], v185 offset:6144
	ds_read_b128 v[132:135], v183 offset:2048
	v_mfma_f32_32x32x16_bf16 v[112:127], v[160:163], v[136:139], v[112:127]
	s_mul_i32 s74, s70, 0x6000
	s_add_u32 s75, s74, s68
	s_mov_b32 m0, s75
	s_add_u32 s76, s74, 0x2000
	s_cmp_eq_u32 s70, 2
	s_cselect_b32 s76, 0x10000, s76
	global_load_lds_dwordx4 v176, s[64:65]
	v_mfma_f32_32x32x16_bf16 v[96:111], v[164:167], v[136:139], v[96:111]
	s_add_u32 m0, s75, 0x400
	s_add_u32 s76, s76, s69
	global_load_lds_dwordx4 v177, s[64:65]
	v_mfma_f32_32x32x16_bf16 v[80:95], v[168:171], v[136:139], v[80:95]
	s_mov_b32 m0, s76
	s_add_u32 s64, s64, 64
	s_addc_u32 s65, s65, 0
	global_load_lds_dwordx4 v178, s[66:67]
	v_mfma_f32_32x32x16_bf16 v[64:79], v[172:175], v[136:139], v[64:79]
	global_load_lds_dwordx4 v178, s[66:67] offset:1024
	v_mfma_f32_32x32x16_bf16 v[48:63], v[160:163], v[140:143], v[48:63]
	global_load_lds_dwordx4 v178, s[66:67] offset:2048
	v_mfma_f32_32x32x16_bf16 v[32:47], v[164:167], v[140:143], v[32:47]
	global_load_lds_dwordx4 v178, s[66:67] offset:3072
	s_add_u32 s66, s66, 0x10000
	s_addc_u32 s67, s67, 0
	v_mfma_f32_32x32x16_bf16 v[16:31], v[168:171], v[140:143], v[16:31]
	s_add_u32 s70, s70, 1
	s_cmp_eq_u32 s70, 3
	s_cselect_b32 s70, 0, s70
	v_mfma_f32_32x32x16_bf16 v[0:15], v[172:175], v[140:143], v[0:15]
	ds_read_b128 v[136:139], v184
	ds_read_b128 v[160:163], v186
	ds_read_b128 v[164:167], v186 offset:2048
	ds_read_b128 v[168:171], v186 offset:4096
	ds_read_b128 v[172:175], v186 offset:6144
	ds_read_b128 v[140:143], v184 offset:2048
	s_waitcnt lgkmcnt(10)
	v_mfma_f32_32x32x16_bf16 v[112:127], v[144:147], v[128:131], v[112:127]
	s_waitcnt lgkmcnt(9)
	v_mfma_f32_32x32x16_bf16 v[96:111], v[148:151], v[128:131], v[96:111]
	s_waitcnt lgkmcnt(8)
	v_mfma_f32_32x32x16_bf16 v[80:95], v[152:155], v[128:131], v[80:95]
	s_waitcnt lgkmcnt(7)
	v_mfma_f32_32x32x16_bf16 v[64:79], v[156:159], v[128:131], v[64:79]
	s_waitcnt lgkmcnt(6)
	v_mfma_f32_32x32x16_bf16 v[48:63], v[144:147], v[132:135], v[48:63]
	v_mfma_f32_32x32x16_bf16 v[32:47], v[148:151], v[132:135], v[32:47]
	v_mfma_f32_32x32x16_bf16 v[16:31], v[152:155], v[132:135], v[16:31]
	v_mfma_f32_32x32x16_bf16 v[0:15], v[156:159], v[132:135], v[0:15]
	s_add_u32 s72, s72, 1
	s_cmp_lt_u32 s72, 29
	s_cbranch_scc1 .Lp17_loop
	s_waitcnt vmcnt(6) lgkmcnt(0)
	s_barrier
	s_mul_i32 s74, s71, 0x6000
	s_add_u32 s75, s74, 0x2000
	s_cmp_eq_u32 s71, 2
	s_cselect_b32 s75, 0x10000, s75
	v_add_u32_e32 v183, s74, v179
	v_add_u32_e32 v185, s75, v181
	v_add_u32_e32 v184, s74, v180
	v_add_u32_e32 v186, s75, v182
	s_add_u32 s71, s71, 1
	s_cmp_eq_u32 s71, 3
	s_cselect_b32 s71, 0, s71
	ds_read_b128 v[128:131], v183
	ds_read_b128 v[144:147], v185
	ds_read_b128 v[148:151], v185 offset:2048
	ds_read_b128 v[152:155], v185 offset:4096
	ds_read_b128 v[156:159], v185 offset:6144
	ds_read_b128 v[132:135], v183 offset:2048
	v_mfma_f32_32x32x16_bf16 v[112:127], v[160:163], v[136:139], v[112:127]
	v_mfma_f32_32x32x16_bf16 v[96:111], v[164:167], v[136:139], v[96:111]
	v_mfma_f32_32x32x16_bf16 v[80:95], v[168:171], v[136:139], v[80:95]
	v_mfma_f32_32x32x16_bf16 v[64:79], v[172:175], v[136:139], v[64:79]
	v_mfma_f32_32x32x16_bf16 v[48:63], v[160:163], v[140:143], v[48:63]
	v_mfma_f32_32x32x16_bf16 v[32:47], v[164:167], v[140:143], v[32:47]
	v_mfma_f32_32x32x16_bf16 v[16:31], v[168:171], v[140:143], v[16:31]
	v_mfma_f32_32x32x16_bf16 v[0:15], v[172:175], v[140:143], v[0:15]
	ds_read_b128 v[136:139], v184
	ds_read_b128 v[160:163], v186
	ds_read_b128 v[164:167], v186 offset:2048
	ds_read_b128 v[168:171], v186 offset:4096
	ds_read_b128 v[172:175], v186 offset:6144
	ds_read_b128 v[140:143], v184 offset:2048
	s_waitcnt lgkmcnt(10)
	v_mfma_f32_32x32x16_bf16 v[112:127], v[144:147], v[128:131], v[112:127]
	s_waitcnt lgkmcnt(9)
	v_mfma_f32_32x32x16_bf16 v[96:111], v[148:151], v[128:131], v[96:111]
	s_waitcnt lgkmcnt(8)
	v_mfma_f32_32x32x16_bf16 v[80:95], v[152:155], v[128:131], v[80:95]
	s_waitcnt lgkmcnt(7)
	v_mfma_f32_32x32x16_bf16 v[64:79], v[156:159], v[128:131], v[64:79]
	s_waitcnt lgkmcnt(6)
	v_mfma_f32_32x32x16_bf16 v[48:63], v[144:147], v[132:135], v[48:63]
	v_mfma_f32_32x32x16_bf16 v[32:47], v[148:151], v[132:135], v[32:47]
	v_mfma_f32_32x32x16_bf16 v[16:31], v[152:155], v[132:135], v[16:31]
	v_mfma_f32_32x32x16_bf16 v[0:15], v[156:159], v[132:135], v[0:15]
	s_waitcnt vmcnt(0) lgkmcnt(0)
	s_barrier
; #define MFMA32(a, b, c) __builtin_amdgcn_mfma_f32_32x32x16_bf16((a), (b), (c), 0, 0, 0)
; DI bfr f2bf(float a) { return (bfr)(pack2(a, 0.f) & 0xffffu); }
; template <int lda>
; DI void gemm_mainloop(const bfr* __restrict__ A, const bfr* __restrict__ Bt, int NB, int K, int m0, int n0, char* smem, f32x16 (&acc)[2][4]) {
;     ...
; #pragma unroll
;     for (int ks = 0; ks < 2; ++ks) {
;       bf16x8 af[2], bfg[4];
; #pragma unroll
;       for (int i = 0; i < 2; ++i) af[i] = *(const bf16x8*)(As + (wr * 64 + i * 32 + r) * 40 + ks * 16 + hl * 8);
; #pragma unroll
;       for (int j = 0; j < 4; ++j) bfg[j] = *(const bf16x8*)(Bs + (wc * 128 + j * 32 + r) * 40 + ks * 16 + hl * 8);
; #pragma unroll
;       for (int i = 0; i < 2; ++i)
; #pragma unroll
;         for (int j = 0; j < 4; ++j) acc[i][j] = MFMA32(af[i], bfg[j], acc[i][j]);
;     }
;     __syncthreads();
; DI void phase_gemm_bf16out(const Params& p, const bfr* A, const bfr* Wt, bfr* C, int N, const float* ss, char* smem) {
;     ...
;   for (int t0 = blockIdx.x; t0 < 128 * ntn; t0 += gridDim.x) {
;     const int t = ((gridDim.x & 7) == 0) ? xcd_tile(t0, ntn) : t0;
;     int mt = t / ntn, nt = t % ntn;
;     gemm_tile<1024>(A, Wt, N, 1024, mt * 128, nt * 256, smem,
;               [=](int row, int col, float v) {
;                 float inv = rsqrtf(ss[row] * (1.0f / 1024.0f) + EPSF);
;                 C[(size_t)row * N + col] = f2bf(v * inv);
;               });
	s_mul_i32 s74, s71, 0x6000
	s_add_u32 s75, s74, 0x2000
	s_cmp_eq_u32 s71, 2
	s_cselect_b32 s75, 0x10000, s75
	v_add_u32_e32 v183, s74, v179
	v_add_u32_e32 v185, s75, v181
	v_add_u32_e32 v184, s74, v180
	v_add_u32_e32 v186, s75, v182
	s_add_u32 s71, s71, 1
	s_cmp_eq_u32 s71, 3
	s_cselect_b32 s71, 0, s71
	ds_read_b128 v[128:131], v183
	ds_read_b128 v[144:147], v185
	ds_read_b128 v[148:151], v185 offset:2048
	ds_read_b128 v[152:155], v185 offset:4096
	ds_read_b128 v[156:159], v185 offset:6144
	ds_read_b128 v[132:135], v183 offset:2048
	v_mfma_f32_32x32x16_bf16 v[112:127], v[160:163], v[136:139], v[112:127]
	v_mfma_f32_32x32x16_bf16 v[96:111], v[164:167], v[136:139], v[96:111]
	v_mfma_f32_32x32x16_bf16 v[80:95], v[168:171], v[136:139], v[80:95]
	v_mfma_f32_32x32x16_bf16 v[64:79], v[172:175], v[136:139], v[64:79]
	v_mfma_f32_32x32x16_bf16 v[48:63], v[160:163], v[140:143], v[48:63]
	v_mfma_f32_32x32x16_bf16 v[32:47], v[164:167], v[140:143], v[32:47]
	v_mfma_f32_32x32x16_bf16 v[16:31], v[168:171], v[140:143], v[16:31]
	v_mfma_f32_32x32x16_bf16 v[0:15], v[172:175], v[140:143], v[0:15]
	ds_read_b128 v[136:139], v184
	ds_read_b128 v[160:163], v186
	ds_read_b128 v[164:167], v186 offset:2048
	ds_read_b128 v[168:171], v186 offset:4096
	ds_read_b128 v[172:175], v186 offset:6144
	ds_read_b128 v[140:143], v184 offset:2048
	s_waitcnt lgkmcnt(10)
	v_mfma_f32_32x32x16_bf16 v[112:127], v[144:147], v[128:131], v[112:127]
	s_waitcnt lgkmcnt(9)
	v_mfma_f32_32x32x16_bf16 v[96:111], v[148:151], v[128:131], v[96:111]
	s_waitcnt lgkmcnt(8)
	v_mfma_f32_32x32x16_bf16 v[80:95], v[152:155], v[128:131], v[80:95]
	s_waitcnt lgkmcnt(7)
	v_mfma_f32_32x32x16_bf16 v[64:79], v[156:159], v[128:131], v[64:79]
	s_waitcnt lgkmcnt(6)
	v_mfma_f32_32x32x16_bf16 v[48:63], v[144:147], v[132:135], v[48:63]
	v_mfma_f32_32x32x16_bf16 v[32:47], v[148:151], v[132:135], v[32:47]
	v_mfma_f32_32x32x16_bf16 v[16:31], v[152:155], v[132:135], v[16:31]
	v_mfma_f32_32x32x16_bf16 v[0:15], v[156:159], v[132:135], v[0:15]
	s_waitcnt lgkmcnt(0)
	v_mfma_f32_32x32x16_bf16 v[112:127], v[160:163], v[136:139], v[112:127]
	v_mfma_f32_32x32x16_bf16 v[96:111], v[164:167], v[136:139], v[96:111]
	v_mfma_f32_32x32x16_bf16 v[80:95], v[168:171], v[136:139], v[80:95]
	v_mfma_f32_32x32x16_bf16 v[64:79], v[172:175], v[136:139], v[64:79]
	v_mfma_f32_32x32x16_bf16 v[48:63], v[160:163], v[140:143], v[48:63]
	v_mfma_f32_32x32x16_bf16 v[32:47], v[164:167], v[140:143], v[32:47]
	v_mfma_f32_32x32x16_bf16 v[16:31], v[168:171], v[140:143], v[16:31]
	v_mfma_f32_32x32x16_bf16 v[0:15], v[172:175], v[140:143], v[0:15]
	s_nop 7
	s_nop 3
	s_barrier
	s_load_dwordx2 s[64:65], s[92:93], 0x160
	s_load_dwordx2 s[66:67], s[92:93], 0x140
	v_and_b32_e32 v176, 31, v196
	v_bfe_u32 v177, v196, 5, 1
	s_lshr_b32 s74, s73, 1
	s_lshl_b32 s74, s74, 6
	s_add_u32 s74, s74, s77
	v_add_u32_e32 v178, s74, v176
	s_mul_i32 s76, s73, 8704
	v_mul_u32_u24_e32 v180, 272, v176
	v_lshl_add_u32 v180, v177, 3, v180
	v_add_u32_e32 v180, s76, v180
	v_bfe_u32 v185, v196, 4, 2
	v_and_b32_e32 v186, 15, v196
	v_mul_u32_u24_e32 v181, 272, v185
	v_lshl_add_u32 v181, v186, 4, v181
	v_add_u32_e32 v181, s76, v181
	s_and_b32 s75, s73, 1
	s_lshl_b32 s75, s75, 7
	s_add_u32 s75, s75, s78
	v_add_u32_e32 v179, s74, v185
	v_mul_u32_u24_e32 v179, 0x400, v179
	v_lshl_add_u32 v179, v186, 3, v179
	v_add_lshl_u32 v182, v179, s75, 1
	s_waitcnt lgkmcnt(0)
	s_add_u32 s66, s66, 0x20400
	s_addc_u32 s67, s67, 0
	v_lshlrev_b32_e32 v179, 2, v178
	global_load_dword v183, v179, s[66:67]
	global_load_dword v184, v179, s[66:67] offset:128
	s_waitcnt vmcnt(0)
	v_mul_f32_e32 v183, 0x3a800000, v183
	v_mul_f32_e32 v184, 0x3a800000, v184
	v_add_f32_e32 v183, 0x358637bd, v183
	v_add_f32_e32 v184, 0x358637bd, v184
	v_rsq_f32_e32 v183, v183
	v_rsq_f32_e32 v184, v184
	s_nop 1
	v_mul_f32_e32 v112, v183, v112
	v_mul_f32_e32 v113, v183, v113
	v_mul_f32_e32 v114, v183, v114
	v_mul_f32_e32 v115, v183, v115
	v_cvt_pk_bf16_f32 v112, v112, v113
	v_cvt_pk_bf16_f32 v113, v114, v115
	ds_write_b64 v180, v[112:113]
	v_mul_f32_e32 v116, v183, v116
	v_mul_f32_e32 v117, v183, v117
	v_mul_f32_e32 v118, v183, v118
	v_mul_f32_e32 v119, v183, v119
	v_cvt_pk_bf16_f32 v116, v116, v117
	v_cvt_pk_bf16_f32 v117, v118, v119
	ds_write_b64 v180, v[116:117] offset:16
	v_mul_f32_e32 v120, v183, v120
	v_mul_f32_e32 v121, v183, v121
	v_mul_f32_e32 v122, v183, v122
	v_mul_f32_e32 v123, v183, v123
	v_cvt_pk_bf16_f32 v120, v120, v121
	v_cvt_pk_bf16_f32 v121, v122, v123
	ds_write_b64 v180, v[120:121] offset:32
	v_mul_f32_e32 v124, v183, v124
	v_mul_f32_e32 v125, v183, v125
	v_mul_f32_e32 v126, v183, v126
	v_mul_f32_e32 v127, v183, v127
	v_cvt_pk_bf16_f32 v124, v124, v125
	v_cvt_pk_bf16_f32 v125, v126, v127
	ds_write_b64 v180, v[124:125] offset:48
	v_mul_f32_e32 v96, v183, v96
	v_mul_f32_e32 v97, v183, v97
	v_mul_f32_e32 v98, v183, v98
	v_mul_f32_e32 v99, v183, v99
	v_cvt_pk_bf16_f32 v96, v96, v97
	v_cvt_pk_bf16_f32 v97, v98, v99
	ds_write_b64 v180, v[96:97] offset:64
	v_mul_f32_e32 v100, v183, v100
	v_mul_f32_e32 v101, v183, v101
	v_mul_f32_e32 v102, v183, v102
	v_mul_f32_e32 v103, v183, v103
	v_cvt_pk_bf16_f32 v100, v100, v101
	v_cvt_pk_bf16_f32 v101, v102, v103
	ds_write_b64 v180, v[100:101] offset:80
	v_mul_f32_e32 v104, v183, v104
	v_mul_f32_e32 v105, v183, v105
	v_mul_f32_e32 v106, v183, v106
	v_mul_f32_e32 v107, v183, v107
	v_cvt_pk_bf16_f32 v104, v104, v105
	v_cvt_pk_bf16_f32 v105, v106, v107
	ds_write_b64 v180, v[104:105] offset:96
	v_mul_f32_e32 v108, v183, v108
	v_mul_f32_e32 v109, v183, v109
	v_mul_f32_e32 v110, v183, v110
	v_mul_f32_e32 v111, v183, v111
	v_cvt_pk_bf16_f32 v108, v108, v109
	v_cvt_pk_bf16_f32 v109, v110, v111
; DI bfr f2bf(float a) { return (bfr)(pack2(a, 0.f) & 0xffffu); }
; DI void phase_gemm_bf16out(const Params& p, const bfr* A, const bfr* Wt, bfr* C, int N, const float* ss, char* smem) {
;     ...
;   for (int t0 = blockIdx.x; t0 < 128 * ntn; t0 += gridDim.x) {
;     const int t = ((gridDim.x & 7) == 0) ? xcd_tile(t0, ntn) : t0;
;     int mt = t / ntn, nt = t % ntn;
;     gemm_tile<1024>(A, Wt, N, 1024, mt * 128, nt * 256, smem,
;               [=](int row, int col, float v) {
;                 float inv = rsqrtf(ss[row] * (1.0f / 1024.0f) + EPSF);
;                 C[(size_t)row * N + col] = f2bf(v * inv);
;               });
	ds_write_b64 v180, v[108:109] offset:112
	v_mul_f32_e32 v80, v183, v80
	v_mul_f32_e32 v81, v183, v81
	v_mul_f32_e32 v82, v183, v82
	v_mul_f32_e32 v83, v183, v83
	v_cvt_pk_bf16_f32 v80, v80, v81
	v_cvt_pk_bf16_f32 v81, v82, v83
	ds_write_b64 v180, v[80:81] offset:128
	v_mul_f32_e32 v84, v183, v84
	v_mul_f32_e32 v85, v183, v85
	v_mul_f32_e32 v86, v183, v86
	v_mul_f32_e32 v87, v183, v87
	v_cvt_pk_bf16_f32 v84, v84, v85
	v_cvt_pk_bf16_f32 v85, v86, v87
	ds_write_b64 v180, v[84:85] offset:144
	v_mul_f32_e32 v88, v183, v88
	v_mul_f32_e32 v89, v183, v89
	v_mul_f32_e32 v90, v183, v90
	v_mul_f32_e32 v91, v183, v91
	v_cvt_pk_bf16_f32 v88, v88, v89
	v_cvt_pk_bf16_f32 v89, v90, v91
	ds_write_b64 v180, v[88:89] offset:160
	v_mul_f32_e32 v92, v183, v92
	v_mul_f32_e32 v93, v183, v93
	v_mul_f32_e32 v94, v183, v94
	v_mul_f32_e32 v95, v183, v95
	v_cvt_pk_bf16_f32 v92, v92, v93
	v_cvt_pk_bf16_f32 v93, v94, v95
	ds_write_b64 v180, v[92:93] offset:176
	v_mul_f32_e32 v64, v183, v64
	v_mul_f32_e32 v65, v183, v65
	v_mul_f32_e32 v66, v183, v66
	v_mul_f32_e32 v67, v183, v67
	v_cvt_pk_bf16_f32 v64, v64, v65
	v_cvt_pk_bf16_f32 v65, v66, v67
	ds_write_b64 v180, v[64:65] offset:192
	v_mul_f32_e32 v68, v183, v68
	v_mul_f32_e32 v69, v183, v69
	v_mul_f32_e32 v70, v183, v70
	v_mul_f32_e32 v71, v183, v71
	v_cvt_pk_bf16_f32 v68, v68, v69
	v_cvt_pk_bf16_f32 v69, v70, v71
	ds_write_b64 v180, v[68:69] offset:208
	v_mul_f32_e32 v72, v183, v72
	v_mul_f32_e32 v73, v183, v73
	v_mul_f32_e32 v74, v183, v74
	v_mul_f32_e32 v75, v183, v75
	v_cvt_pk_bf16_f32 v72, v72, v73
	v_cvt_pk_bf16_f32 v73, v74, v75
	ds_write_b64 v180, v[72:73] offset:224
	v_mul_f32_e32 v76, v183, v76
	v_mul_f32_e32 v77, v183, v77
	v_mul_f32_e32 v78, v183, v78
	v_mul_f32_e32 v79, v183, v79
	v_cvt_pk_bf16_f32 v76, v76, v77
	v_cvt_pk_bf16_f32 v77, v78, v79
	ds_write_b64 v180, v[76:77] offset:240
	s_waitcnt lgkmcnt(0)
	ds_read_b128 v[112:115], v181
	ds_read_b128 v[116:119], v181 offset:1088
	ds_read_b128 v[120:123], v181 offset:2176
	ds_read_b128 v[124:127], v181 offset:3264
	ds_read_b128 v[96:99], v181 offset:4352
	ds_read_b128 v[100:103], v181 offset:5440
	ds_read_b128 v[104:107], v181 offset:6528
	ds_read_b128 v[108:111], v181 offset:7616
	s_add_u32 s66, s64, 0x0
	s_addc_u32 s67, s65, 0
	s_waitcnt lgkmcnt(7)
	global_store_dwordx4 v182, v[112:115], s[66:67]  sc1
	s_add_u32 s66, s64, 0x2000
	s_addc_u32 s67, s65, 0
	s_waitcnt lgkmcnt(6)
	global_store_dwordx4 v182, v[116:119], s[66:67]  sc1
	s_add_u32 s66, s64, 0x4000
	s_addc_u32 s67, s65, 0
	s_waitcnt lgkmcnt(5)
	global_store_dwordx4 v182, v[120:123], s[66:67]  sc1
	s_add_u32 s66, s64, 0x6000
	s_addc_u32 s67, s65, 0
	s_waitcnt lgkmcnt(4)
	global_store_dwordx4 v182, v[124:127], s[66:67]  sc1
	s_add_u32 s66, s64, 0x8000
	s_addc_u32 s67, s65, 0
	s_waitcnt lgkmcnt(3)
	global_store_dwordx4 v182, v[96:99], s[66:67]  sc1
	s_add_u32 s66, s64, 0xa000
	s_addc_u32 s67, s65, 0
	s_waitcnt lgkmcnt(2)
	global_store_dwordx4 v182, v[100:103], s[66:67]  sc1
	s_add_u32 s66, s64, 0xc000
	s_addc_u32 s67, s65, 0
	s_waitcnt lgkmcnt(1)
	global_store_dwordx4 v182, v[104:107], s[66:67]  sc1
	s_add_u32 s66, s64, 0xe000
	s_addc_u32 s67, s65, 0
	s_waitcnt lgkmcnt(0)
; DI bfr f2bf(float a) { return (bfr)(pack2(a, 0.f) & 0xffffu); }
; DI void phase_gemm_bf16out(const Params& p, const bfr* A, const bfr* Wt, bfr* C, int N, const float* ss, char* smem) {
;     ...
;   for (int t0 = blockIdx.x; t0 < 128 * ntn; t0 += gridDim.x) {
;     const int t = ((gridDim.x & 7) == 0) ? xcd_tile(t0, ntn) : t0;
;     int mt = t / ntn, nt = t % ntn;
;     gemm_tile<1024>(A, Wt, N, 1024, mt * 128, nt * 256, smem,
;               [=](int row, int col, float v) {
;                 float inv = rsqrtf(ss[row] * (1.0f / 1024.0f) + EPSF);
;                 C[(size_t)row * N + col] = f2bf(v * inv);
;               });
;   }
	global_store_dwordx4 v182, v[108:111], s[66:67]  sc1
	v_mul_f32_e32 v48, v184, v48
	v_mul_f32_e32 v49, v184, v49
	v_mul_f32_e32 v50, v184, v50
	v_mul_f32_e32 v51, v184, v51
	v_cvt_pk_bf16_f32 v48, v48, v49
	v_cvt_pk_bf16_f32 v49, v50, v51
	ds_write_b64 v180, v[48:49]
	v_mul_f32_e32 v52, v184, v52
	v_mul_f32_e32 v53, v184, v53
	v_mul_f32_e32 v54, v184, v54
	v_mul_f32_e32 v55, v184, v55
	v_cvt_pk_bf16_f32 v52, v52, v53
	v_cvt_pk_bf16_f32 v53, v54, v55
	ds_write_b64 v180, v[52:53] offset:16
	v_mul_f32_e32 v56, v184, v56
	v_mul_f32_e32 v57, v184, v57
	v_mul_f32_e32 v58, v184, v58
	v_mul_f32_e32 v59, v184, v59
	v_cvt_pk_bf16_f32 v56, v56, v57
	v_cvt_pk_bf16_f32 v57, v58, v59
	ds_write_b64 v180, v[56:57] offset:32
	v_mul_f32_e32 v60, v184, v60
	v_mul_f32_e32 v61, v184, v61
	v_mul_f32_e32 v62, v184, v62
	v_mul_f32_e32 v63, v184, v63
	v_cvt_pk_bf16_f32 v60, v60, v61
	v_cvt_pk_bf16_f32 v61, v62, v63
	ds_write_b64 v180, v[60:61] offset:48
	v_mul_f32_e32 v32, v184, v32
	v_mul_f32_e32 v33, v184, v33
	v_mul_f32_e32 v34, v184, v34
	v_mul_f32_e32 v35, v184, v35
	v_cvt_pk_bf16_f32 v32, v32, v33
	v_cvt_pk_bf16_f32 v33, v34, v35
	ds_write_b64 v180, v[32:33] offset:64
	v_mul_f32_e32 v36, v184, v36
	v_mul_f32_e32 v37, v184, v37
	v_mul_f32_e32 v38, v184, v38
	v_mul_f32_e32 v39, v184, v39
	v_cvt_pk_bf16_f32 v36, v36, v37
	v_cvt_pk_bf16_f32 v37, v38, v39
	ds_write_b64 v180, v[36:37] offset:80
	v_mul_f32_e32 v40, v184, v40
	v_mul_f32_e32 v41, v184, v41
	v_mul_f32_e32 v42, v184, v42
	v_mul_f32_e32 v43, v184, v43
	v_cvt_pk_bf16_f32 v40, v40, v41
	v_cvt_pk_bf16_f32 v41, v42, v43
	ds_write_b64 v180, v[40:41] offset:96
	v_mul_f32_e32 v44, v184, v44
	v_mul_f32_e32 v45, v184, v45
	v_mul_f32_e32 v46, v184, v46
	v_mul_f32_e32 v47, v184, v47
	v_cvt_pk_bf16_f32 v44, v44, v45
	v_cvt_pk_bf16_f32 v45, v46, v47
	ds_write_b64 v180, v[44:45] offset:112
	v_mul_f32_e32 v16, v184, v16
	v_mul_f32_e32 v17, v184, v17
	v_mul_f32_e32 v18, v184, v18
	v_mul_f32_e32 v19, v184, v19
	v_cvt_pk_bf16_f32 v16, v16, v17
	v_cvt_pk_bf16_f32 v17, v18, v19
	ds_write_b64 v180, v[16:17] offset:128
	v_mul_f32_e32 v20, v184, v20
	v_mul_f32_e32 v21, v184, v21
	v_mul_f32_e32 v22, v184, v22
	v_mul_f32_e32 v23, v184, v23
	v_cvt_pk_bf16_f32 v20, v20, v21
	v_cvt_pk_bf16_f32 v21, v22, v23
	ds_write_b64 v180, v[20:21] offset:144
	v_mul_f32_e32 v24, v184, v24
	v_mul_f32_e32 v25, v184, v25
	v_mul_f32_e32 v26, v184, v26
	v_mul_f32_e32 v27, v184, v27
	v_cvt_pk_bf16_f32 v24, v24, v25
	v_cvt_pk_bf16_f32 v25, v26, v27
	ds_write_b64 v180, v[24:25] offset:160
	v_mul_f32_e32 v28, v184, v28
	v_mul_f32_e32 v29, v184, v29
	v_mul_f32_e32 v30, v184, v30
	v_mul_f32_e32 v31, v184, v31
	v_cvt_pk_bf16_f32 v28, v28, v29
	v_cvt_pk_bf16_f32 v29, v30, v31
	ds_write_b64 v180, v[28:29] offset:176
	v_mul_f32_e32 v0, v184, v0
	v_mul_f32_e32 v1, v184, v1
	v_mul_f32_e32 v2, v184, v2
	v_mul_f32_e32 v3, v184, v3
	v_cvt_pk_bf16_f32 v0, v0, v1
	v_cvt_pk_bf16_f32 v1, v2, v3
	ds_write_b64 v180, v[0:1] offset:192
	v_mul_f32_e32 v4, v184, v4
	v_mul_f32_e32 v5, v184, v5
	v_mul_f32_e32 v6, v184, v6
	v_mul_f32_e32 v7, v184, v7
	v_cvt_pk_bf16_f32 v4, v4, v5
	v_cvt_pk_bf16_f32 v5, v6, v7
	ds_write_b64 v180, v[4:5] offset:208
	v_mul_f32_e32 v8, v184, v8
	v_mul_f32_e32 v9, v184, v9
	v_mul_f32_e32 v10, v184, v10
	v_mul_f32_e32 v11, v184, v11
	v_cvt_pk_bf16_f32 v8, v8, v9
	v_cvt_pk_bf16_f32 v9, v10, v11
	ds_write_b64 v180, v[8:9] offset:224
	v_mul_f32_e32 v12, v184, v12
	v_mul_f32_e32 v13, v184, v13
	v_mul_f32_e32 v14, v184, v14
	v_mul_f32_e32 v15, v184, v15
	v_cvt_pk_bf16_f32 v12, v12, v13
	v_cvt_pk_bf16_f32 v13, v14, v15
	ds_write_b64 v180, v[12:13] offset:240
	s_waitcnt lgkmcnt(0)
	ds_read_b128 v[48:51], v181
	ds_read_b128 v[52:55], v181 offset:1088
	ds_read_b128 v[56:59], v181 offset:2176
	ds_read_b128 v[60:63], v181 offset:3264
	ds_read_b128 v[32:35], v181 offset:4352
	ds_read_b128 v[36:39], v181 offset:5440
	ds_read_b128 v[40:43], v181 offset:6528
	ds_read_b128 v[44:47], v181 offset:7616
	s_add_u32 s66, s64, 0x10000
	s_addc_u32 s67, s65, 0
	s_waitcnt lgkmcnt(7)
	global_store_dwordx4 v182, v[48:51], s[66:67]  sc1
	s_add_u32 s66, s64, 0x12000
	s_addc_u32 s67, s65, 0
	s_waitcnt lgkmcnt(6)
	global_store_dwordx4 v182, v[52:55], s[66:67]  sc1
	s_add_u32 s66, s64, 0x14000
	s_addc_u32 s67, s65, 0
	s_waitcnt lgkmcnt(5)
	global_store_dwordx4 v182, v[56:59], s[66:67]  sc1
	s_add_u32 s66, s64, 0x16000
	s_addc_u32 s67, s65, 0
	s_waitcnt lgkmcnt(4)
	global_store_dwordx4 v182, v[60:63], s[66:67]  sc1
	s_add_u32 s66, s64, 0x18000
	s_addc_u32 s67, s65, 0
	s_waitcnt lgkmcnt(3)
	global_store_dwordx4 v182, v[32:35], s[66:67]  sc1
	s_add_u32 s66, s64, 0x1a000
	s_addc_u32 s67, s65, 0
	s_waitcnt lgkmcnt(2)
	global_store_dwordx4 v182, v[36:39], s[66:67]  sc1
	s_add_u32 s66, s64, 0x1c000
	s_addc_u32 s67, s65, 0
	s_waitcnt lgkmcnt(1)
	global_store_dwordx4 v182, v[40:43], s[66:67]  sc1
	s_add_u32 s66, s64, 0x1e000
	s_addc_u32 s67, s65, 0
	s_waitcnt lgkmcnt(0)
	global_store_dwordx4 v182, v[44:47], s[66:67]  sc1
	v_readlane_b32 s64, v187, 0
	v_readlane_b32 s65, v187, 1
	v_readlane_b32 s66, v187, 2
	v_readlane_b32 s67, v187, 3
	v_readlane_b32 s68, v187, 4
	v_readlane_b32 s69, v187, 5
	v_readlane_b32 s70, v187, 6
	v_readlane_b32 s71, v187, 7
	v_readlane_b32 s72, v187, 8
	v_readlane_b32 s73, v187, 9
	v_readlane_b32 s74, v187, 10
	v_readlane_b32 s75, v187, 11
	v_readlane_b32 s76, v187, 12
	v_readlane_b32 s77, v187, 13
	v_readlane_b32 s78, v187, 14
	v_readlane_b32 s79, v187, 15
	s_nop 7
	s_add_i32 s30, s30, s34
	s_cmpk_lt_i32 s30, 0x200
	s_cbranch_scc0 .LBB0_1559
	s_branch .LBB0_1546

; #define MFMA32(a, b, c) __builtin_amdgcn_mfma_f32_32x32x16_bf16((a), (b), (c), 0, 0, 0)
; #define GA_LOAD(pr_) do { _Pragma("unroll") for (int i = 0; i < 4; ++i) ra[i] = *(const u32x4*)(Ab + (i * 32) * lda + (pr_) * 64); } while (0)
; #define GB_LOAD(kt_) do { const bfr* bk_ = Bb + (kt_) * NB * 32; \
;     _Pragma("unroll") for (int i = 0; i < 4; ++i) rb[i] = *(const u32x4*)(bk_ + (i * 64) * 32); } while (0)
; #define G_STORE(kt_) do { bfr* as_ = S0 + ((kt_) & 1) * GSTAGE; bfr* bs_ = as_ + 128 * 40; \
;     if (apar == ((kt_) & 1)) { _Pragma("unroll") for (int i = 0; i < 4; ++i) *(u32x4*)(as_ + asoff + i * 32 * 40) = ra[i]; } \
;     _Pragma("unroll") for (int i = 0; i < 4; ++i) *(u32x4*)(bs_ + bsoff + i * 64 * 40) = rb[i]; } while (0)
; template <int lda>
; DI void gemm_mainloop(const bfr* __restrict__ A, const bfr* __restrict__ Bt, int NB, int K, int m0, int n0, char* smem, f32x16 (&acc)[2][4]) {
;     ...
;   for (int kt = 0; kt < nk; ++kt) {
;     if (kt + 1 < nk) G_STORE(kt + 1);
;     if (kt + 2 < nk) {
;       GB_LOAD(kt + 2);
;       if ((kt & 1) == 0) GA_LOAD((kt >> 1) + 1);
;     }
;     const bfr* As = S0 + (kt & 1) * GSTAGE;
;     const bfr* Bs = As + 128 * 40;
; #pragma unroll
;     for (int ks = 0; ks < 2; ++ks) {
;       bf16x8 af[2], bfg[4];
; #pragma unroll
;       for (int i = 0; i < 2; ++i) af[i] = *(const bf16x8*)(As + (wr * 64 + i * 32 + r) * 40 + ks * 16 + hl * 8);
; #pragma unroll
;       for (int j = 0; j < 4; ++j) bfg[j] = *(const bf16x8*)(Bs + (wc * 128 + j * 32 + r) * 40 + ks * 16 + hl * 8);
; #pragma unroll
;       for (int i = 0; i < 2; ++i)
; #pragma unroll
;         for (int j = 0; j < 4; ++j) acc[i][j] = MFMA32(af[i], bfg[j], acc[i][j]);
;     }
;     __syncthreads();
;   }
.Lp19_loop:
	s_waitcnt vmcnt(6) lgkmcnt(0)
	s_barrier
	s_mul_i32 s74, s71, 0x6000
	s_add_u32 s75, s74, 0x2000
	s_cmp_eq_u32 s71, 2
	s_cselect_b32 s75, 0x10000, s75
	v_add_u32_e32 v205, s74, v192
	v_add_u32_e32 v207, s75, v194
	v_add_u32_e32 v206, s74, v193
	v_add_u32_e32 v208, s75, v204
	s_add_u32 s71, s71, 1
	s_cmp_eq_u32 s71, 3
	s_cselect_b32 s71, 0, s71
	ds_read_b128 v[128:131], v205
	ds_read_b128 v[144:147], v207
	ds_read_b128 v[148:151], v207 offset:2048
	ds_read_b128 v[152:155], v207 offset:4096
	ds_read_b128 v[156:159], v207 offset:6144
	ds_read_b128 v[132:135], v205 offset:2048
	v_mfma_f32_32x32x16_bf16 v[112:127], v[160:163], v[136:139], v[112:127]
	s_mul_i32 s74, s70, 0x6000
	s_add_u32 s75, s74, s68
	s_mov_b32 m0, s75
	s_add_u32 s76, s74, 0x2000
	s_cmp_eq_u32 s70, 2
	s_cselect_b32 s76, 0x10000, s76
	global_load_lds_dwordx4 v180, s[64:65]
	v_mfma_f32_32x32x16_bf16 v[96:111], v[164:167], v[136:139], v[96:111]
	s_add_u32 m0, s75, 0x400
	s_add_u32 s76, s76, s69
	global_load_lds_dwordx4 v182, s[64:65]
	v_mfma_f32_32x32x16_bf16 v[80:95], v[168:171], v[136:139], v[80:95]
	s_mov_b32 m0, s76
	s_add_u32 s64, s64, 64
	s_addc_u32 s65, s65, 0
	global_load_lds_dwordx4 v183, s[66:67]
	v_mfma_f32_32x32x16_bf16 v[64:79], v[172:175], v[136:139], v[64:79]
	global_load_lds_dwordx4 v183, s[66:67] offset:1024
	v_mfma_f32_32x32x16_bf16 v[48:63], v[160:163], v[140:143], v[48:63]
	global_load_lds_dwordx4 v183, s[66:67] offset:2048
	v_mfma_f32_32x32x16_bf16 v[32:47], v[164:167], v[140:143], v[32:47]
	global_load_lds_dwordx4 v183, s[66:67] offset:3072
	s_add_u32 s66, s66, 0x10000
	s_addc_u32 s67, s67, 0
	v_mfma_f32_32x32x16_bf16 v[16:31], v[168:171], v[140:143], v[16:31]
	s_add_u32 s70, s70, 1
	s_cmp_eq_u32 s70, 3
	s_cselect_b32 s70, 0, s70
	v_mfma_f32_32x32x16_bf16 v[0:15], v[172:175], v[140:143], v[0:15]
	ds_read_b128 v[136:139], v206
	ds_read_b128 v[160:163], v208
	ds_read_b128 v[164:167], v208 offset:2048
	ds_read_b128 v[168:171], v208 offset:4096
	ds_read_b128 v[172:175], v208 offset:6144
	ds_read_b128 v[140:143], v206 offset:2048
	s_waitcnt lgkmcnt(10)
	v_mfma_f32_32x32x16_bf16 v[112:127], v[144:147], v[128:131], v[112:127]
	s_waitcnt lgkmcnt(9)
	v_mfma_f32_32x32x16_bf16 v[96:111], v[148:151], v[128:131], v[96:111]
	s_waitcnt lgkmcnt(8)
	v_mfma_f32_32x32x16_bf16 v[80:95], v[152:155], v[128:131], v[80:95]
	s_waitcnt lgkmcnt(7)
	v_mfma_f32_32x32x16_bf16 v[64:79], v[156:159], v[128:131], v[64:79]
	s_waitcnt lgkmcnt(6)
	v_mfma_f32_32x32x16_bf16 v[48:63], v[144:147], v[132:135], v[48:63]
	v_mfma_f32_32x32x16_bf16 v[32:47], v[148:151], v[132:135], v[32:47]
	v_mfma_f32_32x32x16_bf16 v[16:31], v[152:155], v[132:135], v[16:31]
	v_mfma_f32_32x32x16_bf16 v[0:15], v[156:159], v[132:135], v[0:15]
	s_add_u32 s72, s72, 1
	s_cmp_lt_u32 s72, 29
	s_cbranch_scc1 .Lp19_loop
	s_waitcnt vmcnt(6) lgkmcnt(0)
	s_barrier
	s_mul_i32 s74, s71, 0x6000
	s_add_u32 s75, s74, 0x2000
	s_cmp_eq_u32 s71, 2
	s_cselect_b32 s75, 0x10000, s75
	v_add_u32_e32 v205, s74, v192
	v_add_u32_e32 v207, s75, v194
	v_add_u32_e32 v206, s74, v193
	v_add_u32_e32 v208, s75, v204
	s_add_u32 s71, s71, 1
	s_cmp_eq_u32 s71, 3
	s_cselect_b32 s71, 0, s71
	ds_read_b128 v[128:131], v205
	ds_read_b128 v[144:147], v207
	ds_read_b128 v[148:151], v207 offset:2048
	ds_read_b128 v[152:155], v207 offset:4096
	ds_read_b128 v[156:159], v207 offset:6144
	ds_read_b128 v[132:135], v205 offset:2048
	v_mfma_f32_32x32x16_bf16 v[112:127], v[160:163], v[136:139], v[112:127]
	v_mfma_f32_32x32x16_bf16 v[96:111], v[164:167], v[136:139], v[96:111]
	v_mfma_f32_32x32x16_bf16 v[80:95], v[168:171], v[136:139], v[80:95]
	v_mfma_f32_32x32x16_bf16 v[64:79], v[172:175], v[136:139], v[64:79]
	v_mfma_f32_32x32x16_bf16 v[48:63], v[160:163], v[140:143], v[48:63]
	v_mfma_f32_32x32x16_bf16 v[32:47], v[164:167], v[140:143], v[32:47]
	v_mfma_f32_32x32x16_bf16 v[16:31], v[168:171], v[140:143], v[16:31]
	v_mfma_f32_32x32x16_bf16 v[0:15], v[172:175], v[140:143], v[0:15]
	ds_read_b128 v[136:139], v206
	ds_read_b128 v[160:163], v208
	ds_read_b128 v[164:167], v208 offset:2048
	ds_read_b128 v[168:171], v208 offset:4096
	ds_read_b128 v[172:175], v208 offset:6144
	ds_read_b128 v[140:143], v206 offset:2048
	s_waitcnt lgkmcnt(10)
	v_mfma_f32_32x32x16_bf16 v[112:127], v[144:147], v[128:131], v[112:127]
	s_waitcnt lgkmcnt(9)
	v_mfma_f32_32x32x16_bf16 v[96:111], v[148:151], v[128:131], v[96:111]
	s_waitcnt lgkmcnt(8)
	v_mfma_f32_32x32x16_bf16 v[80:95], v[152:155], v[128:131], v[80:95]
	s_waitcnt lgkmcnt(7)
	v_mfma_f32_32x32x16_bf16 v[64:79], v[156:159], v[128:131], v[64:79]
	s_waitcnt lgkmcnt(6)
	v_mfma_f32_32x32x16_bf16 v[48:63], v[144:147], v[132:135], v[48:63]
	v_mfma_f32_32x32x16_bf16 v[32:47], v[148:151], v[132:135], v[32:47]
	v_mfma_f32_32x32x16_bf16 v[16:31], v[152:155], v[132:135], v[16:31]
	v_mfma_f32_32x32x16_bf16 v[0:15], v[156:159], v[132:135], v[0:15]
	s_waitcnt vmcnt(0) lgkmcnt(0)
	s_barrier
; #define MFMA32(a, b, c) __builtin_amdgcn_mfma_f32_32x32x16_bf16((a), (b), (c), 0, 0, 0)
; DI int crow(int reg, int h) { return (reg & 3) + 8 * (reg >> 2) + 4 * h; }
; template <int lda>
; DI void gemm_mainloop(const bfr* __restrict__ A, const bfr* __restrict__ Bt, int NB, int K, int m0, int n0, char* smem, f32x16 (&acc)[2][4]) {
;     ...
; #pragma unroll
;     for (int ks = 0; ks < 2; ++ks) {
;       bf16x8 af[2], bfg[4];
; #pragma unroll
;       for (int i = 0; i < 2; ++i) af[i] = *(const bf16x8*)(As + (wr * 64 + i * 32 + r) * 40 + ks * 16 + hl * 8);
; #pragma unroll
;       for (int j = 0; j < 4; ++j) bfg[j] = *(const bf16x8*)(Bs + (wc * 128 + j * 32 + r) * 40 + ks * 16 + hl * 8);
; #pragma unroll
;       for (int i = 0; i < 2; ++i)
; #pragma unroll
;         for (int j = 0; j < 4; ++j) acc[i][j] = MFMA32(af[i], bfg[j], acc[i][j]);
;     }
;     __syncthreads();
; template <bool FIRST, bool HAS_H>
; DI void phase_gemm_resid(const Params& p, const bfr* A, const bfr* Wt, const float* gnext, float* ss, char* smem) {
;     ...
;     int tid2 = threadIdx.x;
;     asm volatile("" : "+v"(tid2));
;     const int lane = tid2 & 63, wid = tid2 >> 6, wr = wid >> 1, wc = wid & 1, r = lane & 31, hl = lane >> 5;
;     const float* xsrc = FIRST ? p.x_prompt : X;
;     const int rbase = m0 + wr * 64 + 4 * hl, cbase = n0 + wc * 128 + r;
; #pragma unroll
;     for (int i = 0; i < 2; ++i) {
; #pragma unroll
;       for (int qh = 0; qh < 2; ++qh) {
;         float rs[8];
; #pragma unroll
;         for (int q = 0; q < 8; ++q) rs[q] = 0.f;
; #pragma unroll
;         for (int jh = 0; jh < 2; ++jh) {
;           float xo[2][8];
; #pragma unroll
;           for (int jj = 0; jj < 2; ++jj)
; #pragma unroll
;             for (int q = 0; q < 8; ++q)
;               xo[jj][q] = xsrc[(rbase + i * 32 + crow(qh * 8 + q, 0)) * 1024 + cbase + (jh * 2 + jj) * 32];
	s_mul_i32 s74, s71, 0x6000
	s_add_u32 s75, s74, 0x2000
	s_cmp_eq_u32 s71, 2
	s_cselect_b32 s75, 0x10000, s75
	v_add_u32_e32 v205, s74, v192
	v_add_u32_e32 v207, s75, v194
	v_add_u32_e32 v206, s74, v193
	v_add_u32_e32 v208, s75, v204
	s_add_u32 s71, s71, 1
	s_cmp_eq_u32 s71, 3
	s_cselect_b32 s71, 0, s71
	ds_read_b128 v[128:131], v205
	ds_read_b128 v[144:147], v207
	ds_read_b128 v[148:151], v207 offset:2048
	ds_read_b128 v[152:155], v207 offset:4096
	ds_read_b128 v[156:159], v207 offset:6144
	ds_read_b128 v[132:135], v205 offset:2048
	v_mfma_f32_32x32x16_bf16 v[112:127], v[160:163], v[136:139], v[112:127]
	v_mfma_f32_32x32x16_bf16 v[96:111], v[164:167], v[136:139], v[96:111]
	v_mfma_f32_32x32x16_bf16 v[80:95], v[168:171], v[136:139], v[80:95]
	v_mfma_f32_32x32x16_bf16 v[64:79], v[172:175], v[136:139], v[64:79]
	v_mfma_f32_32x32x16_bf16 v[48:63], v[160:163], v[140:143], v[48:63]
	v_mfma_f32_32x32x16_bf16 v[32:47], v[164:167], v[140:143], v[32:47]
	v_mfma_f32_32x32x16_bf16 v[16:31], v[168:171], v[140:143], v[16:31]
	v_mfma_f32_32x32x16_bf16 v[0:15], v[172:175], v[140:143], v[0:15]
	ds_read_b128 v[136:139], v206
	ds_read_b128 v[160:163], v208
	ds_read_b128 v[164:167], v208 offset:2048
	ds_read_b128 v[168:171], v208 offset:4096
	ds_read_b128 v[172:175], v208 offset:6144
	ds_read_b128 v[140:143], v206 offset:2048
	s_waitcnt lgkmcnt(10)
	v_mfma_f32_32x32x16_bf16 v[112:127], v[144:147], v[128:131], v[112:127]
	s_waitcnt lgkmcnt(9)
	v_mfma_f32_32x32x16_bf16 v[96:111], v[148:151], v[128:131], v[96:111]
	s_waitcnt lgkmcnt(8)
	v_mfma_f32_32x32x16_bf16 v[80:95], v[152:155], v[128:131], v[80:95]
	s_waitcnt lgkmcnt(7)
	v_mfma_f32_32x32x16_bf16 v[64:79], v[156:159], v[128:131], v[64:79]
	s_waitcnt lgkmcnt(6)
	v_mfma_f32_32x32x16_bf16 v[48:63], v[144:147], v[132:135], v[48:63]
	v_mfma_f32_32x32x16_bf16 v[32:47], v[148:151], v[132:135], v[32:47]
	v_mfma_f32_32x32x16_bf16 v[16:31], v[152:155], v[132:135], v[16:31]
	v_mfma_f32_32x32x16_bf16 v[0:15], v[156:159], v[132:135], v[0:15]
	s_waitcnt lgkmcnt(0)
	v_mfma_f32_32x32x16_bf16 v[112:127], v[160:163], v[136:139], v[112:127]
	v_mfma_f32_32x32x16_bf16 v[96:111], v[164:167], v[136:139], v[96:111]
	v_mfma_f32_32x32x16_bf16 v[80:95], v[168:171], v[136:139], v[80:95]
	v_mfma_f32_32x32x16_bf16 v[64:79], v[172:175], v[136:139], v[64:79]
	v_mfma_f32_32x32x16_bf16 v[48:63], v[160:163], v[140:143], v[48:63]
	v_mfma_f32_32x32x16_bf16 v[32:47], v[164:167], v[140:143], v[32:47]
	v_mfma_f32_32x32x16_bf16 v[16:31], v[168:171], v[140:143], v[16:31]
	v_mfma_f32_32x32x16_bf16 v[0:15], v[172:175], v[140:143], v[0:15]
	s_nop 7
	s_nop 3
	s_load_dwordx2 s[64:65], s[92:93], 0x100
	s_load_dwordx2 s[66:67], s[92:93], 0x100
	s_mul_i32 s76, s73, 8704
	s_lshr_b32 s74, s73, 1
	s_lshl_b32 s74, s74, 6
	s_add_u32 s74, s74, s77
	s_and_b32 s75, s73, 1
	s_lshl_b32 s75, s75, 7
	s_add_u32 s75, s75, s78
	v_and_b32_e32 v210, 31, v196
	v_bfe_u32 v211, v196, 5, 1
	v_mul_u32_u24_e32 v212, 272, v210
	v_add_u32_e32 v212, s76, v212
	v_lshl_add_u32 v180, v211, 4, v212
	v_lshl_add_u32 v182, v211, 3, v212
	v_lshlrev_b32_e32 v212, 2, v211
	v_add_lshl_u32 v204, v212, s75, 2
	v_add_lshl_u32 v207, v210, s74, 2
	v_and_b32_e32 v212, 63, v196
	v_xor_b32_e32 v212, 32, v212
	v_lshlrev_b32_e32 v208, 2, v212
	v_bfe_u32 v210, v196, 4, 2
	v_and_b32_e32 v211, 15, v196
	v_mul_u32_u24_e32 v212, 272, v210
	v_lshl_add_u32 v212, v211, 4, v212
	v_add_u32_e32 v183, s76, v212
	v_add_u32_e32 v212, s74, v210
	v_lshlrev_b32_e32 v212, 10, v212
	v_lshl_add_u32 v212, v211, 2, v212
	v_add_lshl_u32 v193, v212, s75, 2
	s_mov_b32 s79, s74
	s_mov_b32 s72, s75
	s_waitcnt lgkmcnt(0)
	s_add_u32 s74, s64, 0x0
	s_addc_u32 s75, s65, 0
	global_load_dwordx4 v[128:131], v193, s[74:75]
	s_add_u32 s74, s64, 0x4000
	s_addc_u32 s75, s65, 0
	global_load_dwordx4 v[132:135], v193, s[74:75]
	s_add_u32 s74, s64, 0x8000
	s_addc_u32 s75, s65, 0
	global_load_dwordx4 v[136:139], v193, s[74:75]
	s_add_u32 s74, s64, 0xc000
	s_addc_u32 s75, s65, 0
	global_load_dwordx4 v[140:143], v193, s[74:75]
	s_add_u32 s74, s64, 0x10000
	s_addc_u32 s75, s65, 0
	global_load_dwordx4 v[144:147], v193, s[74:75]
	s_add_u32 s74, s64, 0x14000
	s_addc_u32 s75, s65, 0
	global_load_dwordx4 v[148:151], v193, s[74:75]
	s_add_u32 s74, s64, 0x18000
	s_addc_u32 s75, s65, 0
	global_load_dwordx4 v[152:155], v193, s[74:75]
	s_add_u32 s74, s64, 0x1c000
	s_addc_u32 s75, s65, 0
	global_load_dwordx4 v[156:159], v193, s[74:75]
	s_mov_b32 s74, s79
	s_mov_b32 s75, s72
	v_bfe_u32 v210, v196, 3, 3
	v_and_b32_e32 v211, 7, v196
	v_mul_u32_u24_e32 v212, 272, v210
	v_lshl_add_u32 v212, v211, 4, v212
	v_add_u32_e32 v192, s76, v212
	v_add_u32_e32 v212, s74, v210
	v_lshlrev_b32_e32 v212, 10, v212
	v_lshl_add_u32 v212, v211, 3, v212
	v_add_lshl_u32 v194, v212, s75, 1
	v_mov_b32_e32 v205, 0
	v_mov_b32_e32 v206, 0
	s_waitcnt lgkmcnt(0)
	s_barrier
; DI bfr f2bf(float a) { return (bfr)(pack2(a, 0.f) & 0xffffu); }
; DI int crow(int reg, int h) { return (reg & 3) + 8 * (reg >> 2) + 4 * h; }
; template <bool FIRST, bool HAS_H>
; DI void phase_gemm_resid(const Params& p, const bfr* A, const bfr* Wt, const float* gnext, float* ss, char* smem) {
;     ...
; #pragma unroll
;     for (int i = 0; i < 2; ++i) {
; #pragma unroll
;       for (int qh = 0; qh < 2; ++qh) {
;         float rs[8];
; #pragma unroll
;         for (int q = 0; q < 8; ++q) rs[q] = 0.f;
; #pragma unroll
;         for (int jh = 0; jh < 2; ++jh) {
;           float xo[2][8];
; #pragma unroll
;           for (int jj = 0; jj < 2; ++jj)
; #pragma unroll
;             for (int q = 0; q < 8; ++q)
;               xo[jj][q] = xsrc[(rbase + i * 32 + crow(qh * 8 + q, 0)) * 1024 + cbase + (jh * 2 + jj) * 32];
; #pragma unroll
;           for (int q = 0; q < 8; ++q) {
;             const int o = (rbase + i * 32 + crow(qh * 8 + q, 0)) * 1024 + cbase;
; #pragma unroll
;             for (int jj = 0; jj < 2; ++jj) {
;               const int j = jh * 2 + jj;
;               const float xn = xo[jj][q] + acc[i][j][qh * 8 + q];
;               X[o + j * 32] = xn;
;               if (HAS_H) Hn[o + j * 32] = f2bf(xn * gnext[cbase + j * 32]);
;               rs[q] += xn * xn;
;             }
;           }
;         }
	s_waitcnt vmcnt(7)
	ds_write_b128 v183, v[128:131]
	s_waitcnt vmcnt(6)
	ds_write_b128 v183, v[132:135] offset:1088
	s_waitcnt vmcnt(5)
	ds_write_b128 v183, v[136:139] offset:2176
	s_waitcnt vmcnt(4)
	ds_write_b128 v183, v[140:143] offset:3264
	s_waitcnt vmcnt(3)
	ds_write_b128 v183, v[144:147] offset:4352
	s_waitcnt vmcnt(2)
	ds_write_b128 v183, v[148:151] offset:5440
	s_waitcnt vmcnt(1)
	ds_write_b128 v183, v[152:155] offset:6528
	s_waitcnt vmcnt(0)
	ds_write_b128 v183, v[156:159] offset:7616
	s_add_u32 s74, s64, 0x100
	s_addc_u32 s75, s65, 0
	global_load_dwordx4 v[128:131], v193, s[74:75]
	s_add_u32 s74, s64, 0x4100
	s_addc_u32 s75, s65, 0
	global_load_dwordx4 v[132:135], v193, s[74:75]
	s_add_u32 s74, s64, 0x8100
	s_addc_u32 s75, s65, 0
	global_load_dwordx4 v[136:139], v193, s[74:75]
	s_add_u32 s74, s64, 0xc100
	s_addc_u32 s75, s65, 0
	global_load_dwordx4 v[140:143], v193, s[74:75]
	s_add_u32 s74, s64, 0x10100
	s_addc_u32 s75, s65, 0
	global_load_dwordx4 v[144:147], v193, s[74:75]
	s_add_u32 s74, s64, 0x14100
	s_addc_u32 s75, s65, 0
	global_load_dwordx4 v[148:151], v193, s[74:75]
	s_add_u32 s74, s64, 0x18100
	s_addc_u32 s75, s65, 0
	global_load_dwordx4 v[152:155], v193, s[74:75]
	s_add_u32 s74, s64, 0x1c100
	s_addc_u32 s75, s65, 0
	global_load_dwordx4 v[156:159], v193, s[74:75]
	ds_read_b128 v[160:163], v180
	ds_read_b128 v[164:167], v180 offset:32
	ds_read_b128 v[168:171], v180 offset:64
	ds_read_b128 v[172:175], v180 offset:96
	ds_read_b128 v[176:179], v180 offset:128
	ds_read_b128 v[184:187], v180 offset:160
	ds_read_b128 v[188:191], v180 offset:192
	ds_read_b128 v[200:203], v180 offset:224
	s_waitcnt lgkmcnt(7)
	v_add_f32_e32 v112, v160, v112
	v_add_f32_e32 v113, v161, v113
	v_add_f32_e32 v114, v162, v114
	v_add_f32_e32 v115, v163, v115
	v_fmac_f32_e32 v205, v112, v112
	v_fmac_f32_e32 v205, v113, v113
	v_fmac_f32_e32 v205, v114, v114
	v_fmac_f32_e32 v205, v115, v115
	ds_write_b128 v180, v[112:115]
	s_waitcnt lgkmcnt(7)
	v_add_f32_e32 v116, v164, v116
	v_add_f32_e32 v117, v165, v117
	v_add_f32_e32 v118, v166, v118
	v_add_f32_e32 v119, v167, v119
	v_fmac_f32_e32 v205, v116, v116
	v_fmac_f32_e32 v205, v117, v117
	v_fmac_f32_e32 v205, v118, v118
	v_fmac_f32_e32 v205, v119, v119
	ds_write_b128 v180, v[116:119] offset:32
	s_waitcnt lgkmcnt(7)
	v_add_f32_e32 v120, v168, v120
	v_add_f32_e32 v121, v169, v121
	v_add_f32_e32 v122, v170, v122
	v_add_f32_e32 v123, v171, v123
	v_fmac_f32_e32 v205, v120, v120
	v_fmac_f32_e32 v205, v121, v121
	v_fmac_f32_e32 v205, v122, v122
	v_fmac_f32_e32 v205, v123, v123
	ds_write_b128 v180, v[120:123] offset:64
	s_waitcnt lgkmcnt(7)
	v_add_f32_e32 v124, v172, v124
	v_add_f32_e32 v125, v173, v125
	v_add_f32_e32 v126, v174, v126
	v_add_f32_e32 v127, v175, v127
	v_fmac_f32_e32 v205, v124, v124
	v_fmac_f32_e32 v205, v125, v125
	v_fmac_f32_e32 v205, v126, v126
	v_fmac_f32_e32 v205, v127, v127
	ds_write_b128 v180, v[124:127] offset:96
	s_waitcnt lgkmcnt(7)
	v_add_f32_e32 v96, v176, v96
	v_add_f32_e32 v97, v177, v97
	v_add_f32_e32 v98, v178, v98
	v_add_f32_e32 v99, v179, v99
	v_fmac_f32_e32 v205, v96, v96
	v_fmac_f32_e32 v205, v97, v97
	v_fmac_f32_e32 v205, v98, v98
	v_fmac_f32_e32 v205, v99, v99
	ds_write_b128 v180, v[96:99] offset:128
	s_waitcnt lgkmcnt(7)
	v_add_f32_e32 v100, v184, v100
	v_add_f32_e32 v101, v185, v101
	v_add_f32_e32 v102, v186, v102
	v_add_f32_e32 v103, v187, v103
	v_fmac_f32_e32 v205, v100, v100
	v_fmac_f32_e32 v205, v101, v101
	v_fmac_f32_e32 v205, v102, v102
	v_fmac_f32_e32 v205, v103, v103
	ds_write_b128 v180, v[100:103] offset:160
	s_waitcnt lgkmcnt(7)
	v_add_f32_e32 v104, v188, v104
	v_add_f32_e32 v105, v189, v105
	v_add_f32_e32 v106, v190, v106
	v_add_f32_e32 v107, v191, v107
	v_fmac_f32_e32 v205, v104, v104
	v_fmac_f32_e32 v205, v105, v105
	v_fmac_f32_e32 v205, v106, v106
	v_fmac_f32_e32 v205, v107, v107
	ds_write_b128 v180, v[104:107] offset:192
	s_waitcnt lgkmcnt(7)
	v_add_f32_e32 v108, v200, v108
	v_add_f32_e32 v109, v201, v109
	v_add_f32_e32 v110, v202, v110
	v_add_f32_e32 v111, v203, v111
	v_fmac_f32_e32 v205, v108, v108
	v_fmac_f32_e32 v205, v109, v109
	v_fmac_f32_e32 v205, v110, v110
	v_fmac_f32_e32 v205, v111, v111
	ds_write_b128 v180, v[108:111] offset:224
	ds_read_b128 v[160:163], v183
	ds_read_b128 v[164:167], v183 offset:1088
	ds_read_b128 v[168:171], v183 offset:2176
	ds_read_b128 v[172:175], v183 offset:3264
	ds_read_b128 v[176:179], v183 offset:4352
	ds_read_b128 v[184:187], v183 offset:5440
	ds_read_b128 v[188:191], v183 offset:6528
	ds_read_b128 v[200:203], v183 offset:7616
	s_add_u32 s74, s66, 0x0
	s_addc_u32 s75, s67, 0
	s_waitcnt lgkmcnt(7)
	global_store_dwordx4 v193, v[160:163], s[74:75]  sc1
	s_add_u32 s74, s66, 0x4000
	s_addc_u32 s75, s67, 0
	s_waitcnt lgkmcnt(6)
	global_store_dwordx4 v193, v[164:167], s[74:75]  sc1
	s_add_u32 s74, s66, 0x8000
	s_addc_u32 s75, s67, 0
	s_waitcnt lgkmcnt(5)
	global_store_dwordx4 v193, v[168:171], s[74:75]  sc1
	s_add_u32 s74, s66, 0xc000
	s_addc_u32 s75, s67, 0
	s_waitcnt lgkmcnt(4)
	global_store_dwordx4 v193, v[172:175], s[74:75]  sc1
	s_add_u32 s74, s66, 0x10000
	s_addc_u32 s75, s67, 0
	s_waitcnt lgkmcnt(3)
	global_store_dwordx4 v193, v[176:179], s[74:75]  sc1
	s_add_u32 s74, s66, 0x14000
	s_addc_u32 s75, s67, 0
	s_waitcnt lgkmcnt(2)
	global_store_dwordx4 v193, v[184:187], s[74:75]  sc1
	s_add_u32 s74, s66, 0x18000
	s_addc_u32 s75, s67, 0
	s_waitcnt lgkmcnt(1)
	global_store_dwordx4 v193, v[188:191], s[74:75]  sc1
	s_add_u32 s74, s66, 0x1c000
	s_addc_u32 s75, s67, 0
	s_waitcnt lgkmcnt(0)
	global_store_dwordx4 v193, v[200:203], s[74:75]  sc1
	s_waitcnt vmcnt(15)
	ds_write_b128 v183, v[128:131]
	s_waitcnt vmcnt(14)
; DI bfr f2bf(float a) { return (bfr)(pack2(a, 0.f) & 0xffffu); }
; DI int crow(int reg, int h) { return (reg & 3) + 8 * (reg >> 2) + 4 * h; }
; template <bool FIRST, bool HAS_H>
; DI void phase_gemm_resid(const Params& p, const bfr* A, const bfr* Wt, const float* gnext, float* ss, char* smem) {
;     ...
; #pragma unroll
;     for (int i = 0; i < 2; ++i) {
; #pragma unroll
;       for (int qh = 0; qh < 2; ++qh) {
;         float rs[8];
; #pragma unroll
;         for (int q = 0; q < 8; ++q) rs[q] = 0.f;
; #pragma unroll
;         for (int jh = 0; jh < 2; ++jh) {
;           float xo[2][8];
; #pragma unroll
;           for (int jj = 0; jj < 2; ++jj)
; #pragma unroll
;             for (int q = 0; q < 8; ++q)
;               xo[jj][q] = xsrc[(rbase + i * 32 + crow(qh * 8 + q, 0)) * 1024 + cbase + (jh * 2 + jj) * 32];
; #pragma unroll
;           for (int q = 0; q < 8; ++q) {
;             const int o = (rbase + i * 32 + crow(qh * 8 + q, 0)) * 1024 + cbase;
; #pragma unroll
;             for (int jj = 0; jj < 2; ++jj) {
;               const int j = jh * 2 + jj;
;               const float xn = xo[jj][q] + acc[i][j][qh * 8 + q];
;               X[o + j * 32] = xn;
;               if (HAS_H) Hn[o + j * 32] = f2bf(xn * gnext[cbase + j * 32]);
;               rs[q] += xn * xn;
;             }
;           }
;         }
	ds_write_b128 v183, v[132:135] offset:1088
	s_waitcnt vmcnt(13)
	ds_write_b128 v183, v[136:139] offset:2176
	s_waitcnt vmcnt(12)
	ds_write_b128 v183, v[140:143] offset:3264
	s_waitcnt vmcnt(11)
	ds_write_b128 v183, v[144:147] offset:4352
	s_waitcnt vmcnt(10)
	ds_write_b128 v183, v[148:151] offset:5440
	s_waitcnt vmcnt(9)
	ds_write_b128 v183, v[152:155] offset:6528
	s_waitcnt vmcnt(8)
	ds_write_b128 v183, v[156:159] offset:7616
	s_add_u32 s74, s64, 0x20000
	s_addc_u32 s75, s65, 0
	global_load_dwordx4 v[128:131], v193, s[74:75]
	s_add_u32 s74, s64, 0x24000
	s_addc_u32 s75, s65, 0
	global_load_dwordx4 v[132:135], v193, s[74:75]
	s_add_u32 s74, s64, 0x28000
	s_addc_u32 s75, s65, 0
	global_load_dwordx4 v[136:139], v193, s[74:75]
	s_add_u32 s74, s64, 0x2c000
	s_addc_u32 s75, s65, 0
	global_load_dwordx4 v[140:143], v193, s[74:75]
	s_add_u32 s74, s64, 0x30000
	s_addc_u32 s75, s65, 0
	global_load_dwordx4 v[144:147], v193, s[74:75]
	s_add_u32 s74, s64, 0x34000
	s_addc_u32 s75, s65, 0
	global_load_dwordx4 v[148:151], v193, s[74:75]
	s_add_u32 s74, s64, 0x38000
	s_addc_u32 s75, s65, 0
	global_load_dwordx4 v[152:155], v193, s[74:75]
	s_add_u32 s74, s64, 0x3c000
	s_addc_u32 s75, s65, 0
	global_load_dwordx4 v[156:159], v193, s[74:75]
	ds_read_b128 v[160:163], v180
	ds_read_b128 v[164:167], v180 offset:32
	ds_read_b128 v[168:171], v180 offset:64
	ds_read_b128 v[172:175], v180 offset:96
	ds_read_b128 v[176:179], v180 offset:128
	ds_read_b128 v[184:187], v180 offset:160
	ds_read_b128 v[188:191], v180 offset:192
	ds_read_b128 v[200:203], v180 offset:224
	s_waitcnt lgkmcnt(7)
	v_add_f32_e32 v80, v160, v80
	v_add_f32_e32 v81, v161, v81
	v_add_f32_e32 v82, v162, v82
	v_add_f32_e32 v83, v163, v83
	v_fmac_f32_e32 v205, v80, v80
	v_fmac_f32_e32 v205, v81, v81
	v_fmac_f32_e32 v205, v82, v82
	v_fmac_f32_e32 v205, v83, v83
	ds_write_b128 v180, v[80:83]
	s_waitcnt lgkmcnt(7)
	v_add_f32_e32 v84, v164, v84
	v_add_f32_e32 v85, v165, v85
	v_add_f32_e32 v86, v166, v86
	v_add_f32_e32 v87, v167, v87
	v_fmac_f32_e32 v205, v84, v84
	v_fmac_f32_e32 v205, v85, v85
	v_fmac_f32_e32 v205, v86, v86
	v_fmac_f32_e32 v205, v87, v87
	ds_write_b128 v180, v[84:87] offset:32
	s_waitcnt lgkmcnt(7)
	v_add_f32_e32 v88, v168, v88
	v_add_f32_e32 v89, v169, v89
	v_add_f32_e32 v90, v170, v90
	v_add_f32_e32 v91, v171, v91
	v_fmac_f32_e32 v205, v88, v88
	v_fmac_f32_e32 v205, v89, v89
	v_fmac_f32_e32 v205, v90, v90
	v_fmac_f32_e32 v205, v91, v91
	ds_write_b128 v180, v[88:91] offset:64
	s_waitcnt lgkmcnt(7)
	v_add_f32_e32 v92, v172, v92
	v_add_f32_e32 v93, v173, v93
	v_add_f32_e32 v94, v174, v94
	v_add_f32_e32 v95, v175, v95
	v_fmac_f32_e32 v205, v92, v92
	v_fmac_f32_e32 v205, v93, v93
	v_fmac_f32_e32 v205, v94, v94
	v_fmac_f32_e32 v205, v95, v95
	ds_write_b128 v180, v[92:95] offset:96
	s_waitcnt lgkmcnt(7)
	v_add_f32_e32 v64, v176, v64
	v_add_f32_e32 v65, v177, v65
	v_add_f32_e32 v66, v178, v66
	v_add_f32_e32 v67, v179, v67
	v_fmac_f32_e32 v205, v64, v64
	v_fmac_f32_e32 v205, v65, v65
	v_fmac_f32_e32 v205, v66, v66
	v_fmac_f32_e32 v205, v67, v67
	ds_write_b128 v180, v[64:67] offset:128
	s_waitcnt lgkmcnt(7)
	v_add_f32_e32 v68, v184, v68
	v_add_f32_e32 v69, v185, v69
	v_add_f32_e32 v70, v186, v70
	v_add_f32_e32 v71, v187, v71
	v_fmac_f32_e32 v205, v68, v68
	v_fmac_f32_e32 v205, v69, v69
	v_fmac_f32_e32 v205, v70, v70
	v_fmac_f32_e32 v205, v71, v71
	ds_write_b128 v180, v[68:71] offset:160
	s_waitcnt lgkmcnt(7)
	v_add_f32_e32 v72, v188, v72
	v_add_f32_e32 v73, v189, v73
	v_add_f32_e32 v74, v190, v74
	v_add_f32_e32 v75, v191, v75
	v_fmac_f32_e32 v205, v72, v72
	v_fmac_f32_e32 v205, v73, v73
	v_fmac_f32_e32 v205, v74, v74
	v_fmac_f32_e32 v205, v75, v75
	ds_write_b128 v180, v[72:75] offset:192
	s_waitcnt lgkmcnt(7)
	v_add_f32_e32 v76, v200, v76
	v_add_f32_e32 v77, v201, v77
	v_add_f32_e32 v78, v202, v78
	v_add_f32_e32 v79, v203, v79
	v_fmac_f32_e32 v205, v76, v76
	v_fmac_f32_e32 v205, v77, v77
	v_fmac_f32_e32 v205, v78, v78
	v_fmac_f32_e32 v205, v79, v79
	ds_write_b128 v180, v[76:79] offset:224
	ds_read_b128 v[160:163], v183
	ds_read_b128 v[164:167], v183 offset:1088
	ds_read_b128 v[168:171], v183 offset:2176
	ds_read_b128 v[172:175], v183 offset:3264
	ds_read_b128 v[176:179], v183 offset:4352
	ds_read_b128 v[184:187], v183 offset:5440
	ds_read_b128 v[188:191], v183 offset:6528
	ds_read_b128 v[200:203], v183 offset:7616
	s_add_u32 s74, s66, 0x100
	s_addc_u32 s75, s67, 0
	s_waitcnt lgkmcnt(7)
	global_store_dwordx4 v193, v[160:163], s[74:75]  sc1
	s_add_u32 s74, s66, 0x4100
	s_addc_u32 s75, s67, 0
	s_waitcnt lgkmcnt(6)
	global_store_dwordx4 v193, v[164:167], s[74:75]  sc1
	s_add_u32 s74, s66, 0x8100
	s_addc_u32 s75, s67, 0
	s_waitcnt lgkmcnt(5)
	global_store_dwordx4 v193, v[168:171], s[74:75]  sc1
	s_add_u32 s74, s66, 0xc100
	s_addc_u32 s75, s67, 0
	s_waitcnt lgkmcnt(4)
	global_store_dwordx4 v193, v[172:175], s[74:75]  sc1
	s_add_u32 s74, s66, 0x10100
	s_addc_u32 s75, s67, 0
	s_waitcnt lgkmcnt(3)
	global_store_dwordx4 v193, v[176:179], s[74:75]  sc1
	s_add_u32 s74, s66, 0x14100
	s_addc_u32 s75, s67, 0
	s_waitcnt lgkmcnt(2)
	global_store_dwordx4 v193, v[184:187], s[74:75]  sc1
	s_add_u32 s74, s66, 0x18100
	s_addc_u32 s75, s67, 0
	s_waitcnt lgkmcnt(1)
	global_store_dwordx4 v193, v[188:191], s[74:75]  sc1
	s_add_u32 s74, s66, 0x1c100
	s_addc_u32 s75, s67, 0
	s_waitcnt lgkmcnt(0)
	global_store_dwordx4 v193, v[200:203], s[74:75]  sc1
	s_waitcnt vmcnt(15)
	ds_write_b128 v183, v[128:131]
	s_waitcnt vmcnt(14)
	ds_write_b128 v183, v[132:135] offset:1088
	s_waitcnt vmcnt(13)
	ds_write_b128 v183, v[136:139] offset:2176
	s_waitcnt vmcnt(12)
	ds_write_b128 v183, v[140:143] offset:3264
	s_waitcnt vmcnt(11)
; DI bfr f2bf(float a) { return (bfr)(pack2(a, 0.f) & 0xffffu); }
; DI int crow(int reg, int h) { return (reg & 3) + 8 * (reg >> 2) + 4 * h; }
; template <bool FIRST, bool HAS_H>
; DI void phase_gemm_resid(const Params& p, const bfr* A, const bfr* Wt, const float* gnext, float* ss, char* smem) {
;     ...
; #pragma unroll
;     for (int i = 0; i < 2; ++i) {
; #pragma unroll
;       for (int qh = 0; qh < 2; ++qh) {
;         float rs[8];
; #pragma unroll
;         for (int q = 0; q < 8; ++q) rs[q] = 0.f;
; #pragma unroll
;         for (int jh = 0; jh < 2; ++jh) {
;           float xo[2][8];
; #pragma unroll
;           for (int jj = 0; jj < 2; ++jj)
; #pragma unroll
;             for (int q = 0; q < 8; ++q)
;               xo[jj][q] = xsrc[(rbase + i * 32 + crow(qh * 8 + q, 0)) * 1024 + cbase + (jh * 2 + jj) * 32];
; #pragma unroll
;           for (int q = 0; q < 8; ++q) {
;             const int o = (rbase + i * 32 + crow(qh * 8 + q, 0)) * 1024 + cbase;
; #pragma unroll
;             for (int jj = 0; jj < 2; ++jj) {
;               const int j = jh * 2 + jj;
;               const float xn = xo[jj][q] + acc[i][j][qh * 8 + q];
;               X[o + j * 32] = xn;
;               if (HAS_H) Hn[o + j * 32] = f2bf(xn * gnext[cbase + j * 32]);
;               rs[q] += xn * xn;
;             }
;           }
;         }
	ds_write_b128 v183, v[144:147] offset:4352
	s_waitcnt vmcnt(10)
	ds_write_b128 v183, v[148:151] offset:5440
	s_waitcnt vmcnt(9)
	ds_write_b128 v183, v[152:155] offset:6528
	s_waitcnt vmcnt(8)
	ds_write_b128 v183, v[156:159] offset:7616
	s_add_u32 s74, s64, 0x20100
	s_addc_u32 s75, s65, 0
	global_load_dwordx4 v[128:131], v193, s[74:75]
	s_add_u32 s74, s64, 0x24100
	s_addc_u32 s75, s65, 0
	global_load_dwordx4 v[132:135], v193, s[74:75]
	s_add_u32 s74, s64, 0x28100
	s_addc_u32 s75, s65, 0
	global_load_dwordx4 v[136:139], v193, s[74:75]
	s_add_u32 s74, s64, 0x2c100
	s_addc_u32 s75, s65, 0
	global_load_dwordx4 v[140:143], v193, s[74:75]
	s_add_u32 s74, s64, 0x30100
	s_addc_u32 s75, s65, 0
	global_load_dwordx4 v[144:147], v193, s[74:75]
	s_add_u32 s74, s64, 0x34100
	s_addc_u32 s75, s65, 0
	global_load_dwordx4 v[148:151], v193, s[74:75]
	s_add_u32 s74, s64, 0x38100
	s_addc_u32 s75, s65, 0
	global_load_dwordx4 v[152:155], v193, s[74:75]
	s_add_u32 s74, s64, 0x3c100
	s_addc_u32 s75, s65, 0
	global_load_dwordx4 v[156:159], v193, s[74:75]
	ds_read_b128 v[160:163], v180
	ds_read_b128 v[164:167], v180 offset:32
	ds_read_b128 v[168:171], v180 offset:64
	ds_read_b128 v[172:175], v180 offset:96
	ds_read_b128 v[176:179], v180 offset:128
	ds_read_b128 v[184:187], v180 offset:160
	ds_read_b128 v[188:191], v180 offset:192
	ds_read_b128 v[200:203], v180 offset:224
	s_waitcnt lgkmcnt(7)
	v_add_f32_e32 v48, v160, v48
	v_add_f32_e32 v49, v161, v49
	v_add_f32_e32 v50, v162, v50
	v_add_f32_e32 v51, v163, v51
	v_fmac_f32_e32 v206, v48, v48
	v_fmac_f32_e32 v206, v49, v49
	v_fmac_f32_e32 v206, v50, v50
	v_fmac_f32_e32 v206, v51, v51
	ds_write_b128 v180, v[48:51]
	s_waitcnt lgkmcnt(7)
	v_add_f32_e32 v52, v164, v52
	v_add_f32_e32 v53, v165, v53
	v_add_f32_e32 v54, v166, v54
	v_add_f32_e32 v55, v167, v55
	v_fmac_f32_e32 v206, v52, v52
	v_fmac_f32_e32 v206, v53, v53
	v_fmac_f32_e32 v206, v54, v54
	v_fmac_f32_e32 v206, v55, v55
	ds_write_b128 v180, v[52:55] offset:32
	s_waitcnt lgkmcnt(7)
	v_add_f32_e32 v56, v168, v56
	v_add_f32_e32 v57, v169, v57
	v_add_f32_e32 v58, v170, v58
	v_add_f32_e32 v59, v171, v59
	v_fmac_f32_e32 v206, v56, v56
	v_fmac_f32_e32 v206, v57, v57
	v_fmac_f32_e32 v206, v58, v58
	v_fmac_f32_e32 v206, v59, v59
	ds_write_b128 v180, v[56:59] offset:64
	s_waitcnt lgkmcnt(7)
	v_add_f32_e32 v60, v172, v60
	v_add_f32_e32 v61, v173, v61
	v_add_f32_e32 v62, v174, v62
	v_add_f32_e32 v63, v175, v63
	v_fmac_f32_e32 v206, v60, v60
	v_fmac_f32_e32 v206, v61, v61
	v_fmac_f32_e32 v206, v62, v62
	v_fmac_f32_e32 v206, v63, v63
	ds_write_b128 v180, v[60:63] offset:96
	s_waitcnt lgkmcnt(7)
	v_add_f32_e32 v32, v176, v32
	v_add_f32_e32 v33, v177, v33
	v_add_f32_e32 v34, v178, v34
	v_add_f32_e32 v35, v179, v35
	v_fmac_f32_e32 v206, v32, v32
	v_fmac_f32_e32 v206, v33, v33
	v_fmac_f32_e32 v206, v34, v34
	v_fmac_f32_e32 v206, v35, v35
	ds_write_b128 v180, v[32:35] offset:128
	s_waitcnt lgkmcnt(7)
	v_add_f32_e32 v36, v184, v36
	v_add_f32_e32 v37, v185, v37
	v_add_f32_e32 v38, v186, v38
	v_add_f32_e32 v39, v187, v39
	v_fmac_f32_e32 v206, v36, v36
	v_fmac_f32_e32 v206, v37, v37
	v_fmac_f32_e32 v206, v38, v38
	v_fmac_f32_e32 v206, v39, v39
	ds_write_b128 v180, v[36:39] offset:160
	s_waitcnt lgkmcnt(7)
	v_add_f32_e32 v40, v188, v40
	v_add_f32_e32 v41, v189, v41
	v_add_f32_e32 v42, v190, v42
	v_add_f32_e32 v43, v191, v43
	v_fmac_f32_e32 v206, v40, v40
	v_fmac_f32_e32 v206, v41, v41
	v_fmac_f32_e32 v206, v42, v42
	v_fmac_f32_e32 v206, v43, v43
	ds_write_b128 v180, v[40:43] offset:192
	s_waitcnt lgkmcnt(7)
	v_add_f32_e32 v44, v200, v44
	v_add_f32_e32 v45, v201, v45
	v_add_f32_e32 v46, v202, v46
	v_add_f32_e32 v47, v203, v47
	v_fmac_f32_e32 v206, v44, v44
	v_fmac_f32_e32 v206, v45, v45
	v_fmac_f32_e32 v206, v46, v46
	v_fmac_f32_e32 v206, v47, v47
	ds_write_b128 v180, v[44:47] offset:224
	ds_read_b128 v[160:163], v183
	ds_read_b128 v[164:167], v183 offset:1088
	ds_read_b128 v[168:171], v183 offset:2176
	ds_read_b128 v[172:175], v183 offset:3264
	ds_read_b128 v[176:179], v183 offset:4352
	ds_read_b128 v[184:187], v183 offset:5440
	ds_read_b128 v[188:191], v183 offset:6528
	ds_read_b128 v[200:203], v183 offset:7616
	s_add_u32 s74, s66, 0x20000
	s_addc_u32 s75, s67, 0
	s_waitcnt lgkmcnt(7)
	global_store_dwordx4 v193, v[160:163], s[74:75]  sc1
	s_add_u32 s74, s66, 0x24000
	s_addc_u32 s75, s67, 0
	s_waitcnt lgkmcnt(6)
	global_store_dwordx4 v193, v[164:167], s[74:75]  sc1
	s_add_u32 s74, s66, 0x28000
	s_addc_u32 s75, s67, 0
	s_waitcnt lgkmcnt(5)
	global_store_dwordx4 v193, v[168:171], s[74:75]  sc1
	s_add_u32 s74, s66, 0x2c000
	s_addc_u32 s75, s67, 0
	s_waitcnt lgkmcnt(4)
	global_store_dwordx4 v193, v[172:175], s[74:75]  sc1
	s_add_u32 s74, s66, 0x30000
	s_addc_u32 s75, s67, 0
	s_waitcnt lgkmcnt(3)
	global_store_dwordx4 v193, v[176:179], s[74:75]  sc1
	s_add_u32 s74, s66, 0x34000
	s_addc_u32 s75, s67, 0
	s_waitcnt lgkmcnt(2)
	global_store_dwordx4 v193, v[184:187], s[74:75]  sc1
	s_add_u32 s74, s66, 0x38000
	s_addc_u32 s75, s67, 0
	s_waitcnt lgkmcnt(1)
	global_store_dwordx4 v193, v[188:191], s[74:75]  sc1
	s_add_u32 s74, s66, 0x3c000
	s_addc_u32 s75, s67, 0
	s_waitcnt lgkmcnt(0)
	global_store_dwordx4 v193, v[200:203], s[74:75]  sc1
	s_waitcnt vmcnt(15)
	ds_write_b128 v183, v[128:131]
	s_waitcnt vmcnt(14)
	ds_write_b128 v183, v[132:135] offset:1088
	s_waitcnt vmcnt(13)
; DI bfr f2bf(float a) { return (bfr)(pack2(a, 0.f) & 0xffffu); }
; DI int crow(int reg, int h) { return (reg & 3) + 8 * (reg >> 2) + 4 * h; }
; template <bool FIRST, bool HAS_H>
; DI void phase_gemm_resid(const Params& p, const bfr* A, const bfr* Wt, const float* gnext, float* ss, char* smem) {
;     ...
; #pragma unroll
;     for (int i = 0; i < 2; ++i) {
; #pragma unroll
;       for (int qh = 0; qh < 2; ++qh) {
;         float rs[8];
; #pragma unroll
;         for (int q = 0; q < 8; ++q) rs[q] = 0.f;
; #pragma unroll
;         for (int jh = 0; jh < 2; ++jh) {
;           float xo[2][8];
; #pragma unroll
;           for (int jj = 0; jj < 2; ++jj)
; #pragma unroll
;             for (int q = 0; q < 8; ++q)
;               xo[jj][q] = xsrc[(rbase + i * 32 + crow(qh * 8 + q, 0)) * 1024 + cbase + (jh * 2 + jj) * 32];
; #pragma unroll
;           for (int q = 0; q < 8; ++q) {
;             const int o = (rbase + i * 32 + crow(qh * 8 + q, 0)) * 1024 + cbase;
; #pragma unroll
;             for (int jj = 0; jj < 2; ++jj) {
;               const int j = jh * 2 + jj;
;               const float xn = xo[jj][q] + acc[i][j][qh * 8 + q];
;               X[o + j * 32] = xn;
;               if (HAS_H) Hn[o + j * 32] = f2bf(xn * gnext[cbase + j * 32]);
;               rs[q] += xn * xn;
;             }
;           }
;         }
; #pragma unroll
;         for (int q = 0; q < 8; ++q) rs[q] = half32_sum_hi(rs[q]);
;         if (r == 31) {
; #pragma unroll
;           for (int q = 0; q < 8; ++q) unsafeAtomicAdd(ss + rbase + i * 32 + crow(qh * 8 + q, 0), rs[q]);
;         }
;       }
;     }
;   }
	ds_write_b128 v183, v[136:139] offset:2176
	s_waitcnt vmcnt(12)
	ds_write_b128 v183, v[140:143] offset:3264
	s_waitcnt vmcnt(11)
	ds_write_b128 v183, v[144:147] offset:4352
	s_waitcnt vmcnt(10)
	ds_write_b128 v183, v[148:151] offset:5440
	s_waitcnt vmcnt(9)
	ds_write_b128 v183, v[152:155] offset:6528
	s_waitcnt vmcnt(8)
	ds_write_b128 v183, v[156:159] offset:7616
	ds_read_b128 v[160:163], v180
	ds_read_b128 v[164:167], v180 offset:32
	ds_read_b128 v[168:171], v180 offset:64
	ds_read_b128 v[172:175], v180 offset:96
	ds_read_b128 v[176:179], v180 offset:128
	ds_read_b128 v[184:187], v180 offset:160
	ds_read_b128 v[188:191], v180 offset:192
	ds_read_b128 v[200:203], v180 offset:224
	s_waitcnt lgkmcnt(7)
	v_add_f32_e32 v16, v160, v16
	v_add_f32_e32 v17, v161, v17
	v_add_f32_e32 v18, v162, v18
	v_add_f32_e32 v19, v163, v19
	v_fmac_f32_e32 v206, v16, v16
	v_fmac_f32_e32 v206, v17, v17
	v_fmac_f32_e32 v206, v18, v18
	v_fmac_f32_e32 v206, v19, v19
	ds_write_b128 v180, v[16:19]
	s_waitcnt lgkmcnt(7)
	v_add_f32_e32 v20, v164, v20
	v_add_f32_e32 v21, v165, v21
	v_add_f32_e32 v22, v166, v22
	v_add_f32_e32 v23, v167, v23
	v_fmac_f32_e32 v206, v20, v20
	v_fmac_f32_e32 v206, v21, v21
	v_fmac_f32_e32 v206, v22, v22
	v_fmac_f32_e32 v206, v23, v23
	ds_write_b128 v180, v[20:23] offset:32
	s_waitcnt lgkmcnt(7)
	v_add_f32_e32 v24, v168, v24
	v_add_f32_e32 v25, v169, v25
	v_add_f32_e32 v26, v170, v26
	v_add_f32_e32 v27, v171, v27
	v_fmac_f32_e32 v206, v24, v24
	v_fmac_f32_e32 v206, v25, v25
	v_fmac_f32_e32 v206, v26, v26
	v_fmac_f32_e32 v206, v27, v27
	ds_write_b128 v180, v[24:27] offset:64
	s_waitcnt lgkmcnt(7)
	v_add_f32_e32 v28, v172, v28
	v_add_f32_e32 v29, v173, v29
	v_add_f32_e32 v30, v174, v30
	v_add_f32_e32 v31, v175, v31
	v_fmac_f32_e32 v206, v28, v28
	v_fmac_f32_e32 v206, v29, v29
	v_fmac_f32_e32 v206, v30, v30
	v_fmac_f32_e32 v206, v31, v31
	ds_write_b128 v180, v[28:31] offset:96
	s_waitcnt lgkmcnt(7)
	v_add_f32_e32 v0, v176, v0
	v_add_f32_e32 v1, v177, v1
	v_add_f32_e32 v2, v178, v2
	v_add_f32_e32 v3, v179, v3
	v_fmac_f32_e32 v206, v0, v0
	v_fmac_f32_e32 v206, v1, v1
	v_fmac_f32_e32 v206, v2, v2
	v_fmac_f32_e32 v206, v3, v3
	ds_write_b128 v180, v[0:3] offset:128
	s_waitcnt lgkmcnt(7)
	v_add_f32_e32 v4, v184, v4
	v_add_f32_e32 v5, v185, v5
	v_add_f32_e32 v6, v186, v6
	v_add_f32_e32 v7, v187, v7
	v_fmac_f32_e32 v206, v4, v4
	v_fmac_f32_e32 v206, v5, v5
	v_fmac_f32_e32 v206, v6, v6
	v_fmac_f32_e32 v206, v7, v7
	ds_write_b128 v180, v[4:7] offset:160
	s_waitcnt lgkmcnt(7)
	v_add_f32_e32 v8, v188, v8
	v_add_f32_e32 v9, v189, v9
	v_add_f32_e32 v10, v190, v10
	v_add_f32_e32 v11, v191, v11
	v_fmac_f32_e32 v206, v8, v8
	v_fmac_f32_e32 v206, v9, v9
	v_fmac_f32_e32 v206, v10, v10
	v_fmac_f32_e32 v206, v11, v11
	ds_write_b128 v180, v[8:11] offset:192
	s_waitcnt lgkmcnt(7)
	v_add_f32_e32 v12, v200, v12
	v_add_f32_e32 v13, v201, v13
	v_add_f32_e32 v14, v202, v14
	v_add_f32_e32 v15, v203, v15
	v_fmac_f32_e32 v206, v12, v12
	v_fmac_f32_e32 v206, v13, v13
	v_fmac_f32_e32 v206, v14, v14
	v_fmac_f32_e32 v206, v15, v15
	ds_write_b128 v180, v[12:15] offset:224
	ds_read_b128 v[160:163], v183
	ds_read_b128 v[164:167], v183 offset:1088
	ds_read_b128 v[168:171], v183 offset:2176
	ds_read_b128 v[172:175], v183 offset:3264
	ds_read_b128 v[176:179], v183 offset:4352
	ds_read_b128 v[184:187], v183 offset:5440
	ds_read_b128 v[188:191], v183 offset:6528
	ds_read_b128 v[200:203], v183 offset:7616
	s_add_u32 s74, s66, 0x20100
	s_addc_u32 s75, s67, 0
	s_waitcnt lgkmcnt(7)
	global_store_dwordx4 v193, v[160:163], s[74:75]  sc1
	s_add_u32 s74, s66, 0x24100
	s_addc_u32 s75, s67, 0
	s_waitcnt lgkmcnt(6)
	global_store_dwordx4 v193, v[164:167], s[74:75]  sc1
	s_add_u32 s74, s66, 0x28100
	s_addc_u32 s75, s67, 0
	s_waitcnt lgkmcnt(5)
	global_store_dwordx4 v193, v[168:171], s[74:75]  sc1
	s_add_u32 s74, s66, 0x2c100
	s_addc_u32 s75, s67, 0
	s_waitcnt lgkmcnt(4)
	global_store_dwordx4 v193, v[172:175], s[74:75]  sc1
	s_add_u32 s74, s66, 0x30100
	s_addc_u32 s75, s67, 0
	s_waitcnt lgkmcnt(3)
	global_store_dwordx4 v193, v[176:179], s[74:75]  sc1
	s_add_u32 s74, s66, 0x34100
	s_addc_u32 s75, s67, 0
	s_waitcnt lgkmcnt(2)
	global_store_dwordx4 v193, v[184:187], s[74:75]  sc1
	s_add_u32 s74, s66, 0x38100
	s_addc_u32 s75, s67, 0
	s_waitcnt lgkmcnt(1)
	global_store_dwordx4 v193, v[188:191], s[74:75]  sc1
	s_add_u32 s74, s66, 0x3c100
	s_addc_u32 s75, s67, 0
	s_waitcnt lgkmcnt(0)
	global_store_dwordx4 v193, v[200:203], s[74:75]  sc1
	s_load_dwordx2 s[64:65], s[92:93], 0x140
	ds_bpermute_b32 v210, v208, v205
	ds_bpermute_b32 v211, v208, v206
	s_waitcnt lgkmcnt(0)
	s_add_u32 s64, s64, 0x30600
	s_addc_u32 s65, s65, 0
	v_add_f32_e32 v210, v210, v205
	v_add_f32_e32 v211, v211, v206
	s_mov_b32 exec_hi, 0
	s_nop 1
	global_atomic_add_f32 v207, v210, s[64:65]
	global_atomic_add_f32 v207, v211, s[64:65] offset:128
	s_mov_b64 exec, -1
	v_readlane_b32 s64, v209, 0
	v_readlane_b32 s65, v209, 1
	v_readlane_b32 s66, v209, 2
	v_readlane_b32 s67, v209, 3
	v_readlane_b32 s68, v209, 4
	v_readlane_b32 s69, v209, 5
	v_readlane_b32 s70, v209, 6
	v_readlane_b32 s71, v209, 7
	v_readlane_b32 s72, v209, 8
	v_readlane_b32 s73, v209, 9
	v_readlane_b32 s74, v209, 10
	v_readlane_b32 s75, v209, 11
	v_readlane_b32 s76, v209, 12
	v_readlane_b32 s77, v209, 13
	v_readlane_b32 s78, v209, 14
	v_readlane_b32 s79, v209, 15
	s_nop 7
	s_branch .LBB0_1718
